# all global stores made agent-scope write-through (sc1) so the grid barrier needs no L2 write-back (buffer_wbl2 removed)
# speedup vs baseline: 1.0031x; 1.0002x over previous
.LBB0_57:
	s_or_b64 exec, exec, s[40:41]
	s_waitcnt vmcnt(0)
	ds_write2_b32 v79, v6, v7 offset1:1
	ds_write2_b32 v79, v8, v9 offset0:2 offset1:3
	v_add_u32_e32 v6, 0x410, v79
	ds_write2_b32 v6, v2, v3 offset1:1
	v_add_u32_e32 v2, 0x418, v79
	ds_write2_b32 v2, v4, v5 offset1:1
	v_add_u32_e32 v2, 0x820, v79
	ds_write2_b32 v2, v14, v15 offset1:1
	v_add_u32_e32 v2, 0x828, v79
	ds_write2_b32 v2, v16, v17 offset1:1
	v_add_u32_e32 v2, 0xc30, v79
	ds_write2_b32 v2, v10, v11 offset1:1
	v_add_u32_e32 v2, 0xc38, v79
	ds_write2_b32 v2, v12, v13 offset1:1
	v_add_u32_e32 v2, 0x1040, v79
	ds_write2_b32 v2, v22, v23 offset1:1
	v_add_u32_e32 v2, 0x1048, v79
	ds_write2_b32 v2, v24, v25 offset1:1
	v_add_u32_e32 v2, 0x1450, v79
	ds_write2_b32 v2, v18, v19 offset1:1
	v_add_u32_e32 v2, 0x1458, v79
	ds_write2_b32 v2, v20, v21 offset1:1
	v_add_u32_e32 v2, 0x1860, v79
	ds_write2_b32 v2, v30, v31 offset1:1
	v_add_u32_e32 v2, 0x1868, v79
	ds_write2_b32 v2, v32, v33 offset1:1
	v_add_u32_e32 v2, 0x1c70, v79
	ds_write2_b32 v2, v26, v27 offset1:1
	v_add_u32_e32 v2, 0x1c78, v79
	ds_write2_b32 v2, v28, v29 offset1:1
	v_add_u32_e32 v2, 0x2080, v79
	ds_write2_b32 v2, v38, v39 offset1:1
	v_add_u32_e32 v2, 0x2088, v79
	ds_write2_b32 v2, v40, v41 offset1:1
	v_add_u32_e32 v2, 0x2490, v79
	ds_write2_b32 v2, v34, v35 offset1:1
	v_add_u32_e32 v2, 0x2498, v79
	ds_write2_b32 v2, v36, v37 offset1:1
	v_add_u32_e32 v2, 0x28a0, v79
	ds_write2_b32 v2, v46, v47 offset1:1
	v_add_u32_e32 v2, 0x28a8, v79
	ds_write2_b32 v2, v48, v49 offset1:1
	v_add_u32_e32 v2, 0x2cb0, v79
	ds_write2_b32 v2, v42, v43 offset1:1
	v_add_u32_e32 v2, 0x2cb8, v79
	ds_write2_b32 v2, v44, v45 offset1:1
	v_add_u32_e32 v2, 0x30c0, v79
	ds_write2_b32 v2, v54, v55 offset1:1
	v_add_u32_e32 v2, 0x30c8, v79
	ds_write2_b32 v2, v56, v57 offset1:1
	v_add_u32_e32 v2, 0x34d0, v79
	ds_write2_b32 v2, v50, v51 offset1:1
	v_add_u32_e32 v2, 0x34d8, v79
	ds_write2_b32 v2, v52, v53 offset1:1
	v_add_u32_e32 v2, 0x38e0, v79
	ds_write2_b32 v2, v62, v63 offset1:1
	v_add_u32_e32 v2, 0x38e8, v79
	ds_write2_b32 v2, v64, v65 offset1:1
	v_add_u32_e32 v2, 0x3cf0, v79
	ds_write2_b32 v2, v58, v59 offset1:1
	v_add_u32_e32 v2, 0x3cf8, v79
	ds_write2_b32 v2, v60, v61 offset1:1
	s_waitcnt lgkmcnt(0)
	ds_read2_b32 v[8:9], v77 offset1:8
	ds_read2_b32 v[10:11], v77 offset0:65 offset1:73
	ds_read2_b32 v[12:13], v77 offset0:130 offset1:138
	ds_read2_b32 v[14:15], v77 offset0:195 offset1:203
	v_add_u32_e32 v28, 0x400, v77
	s_waitcnt lgkmcnt(3)
	v_bfe_u32 v4, v8, 16, 1
	v_add3_u32 v4, v8, v4, s46
	s_waitcnt lgkmcnt(2)
	v_bfe_u32 v5, v10, 16, 1
	ds_read2_b32 v[16:17], v28 offset0:4 offset1:12
	v_lshrrev_b32_e32 v4, 16, v4
	v_add3_u32 v5, v10, v5, s46
	ds_read2_b32 v[18:19], v28 offset0:69 offset1:77
	v_and_or_b32 v4, v5, s47, v4
	s_waitcnt lgkmcnt(3)
	v_bfe_u32 v5, v12, 16, 1
	v_add3_u32 v5, v12, v5, s46
	s_waitcnt lgkmcnt(2)
	v_bfe_u32 v6, v14, 16, 1
	ds_read2_b32 v[20:21], v28 offset0:134 offset1:142
	v_lshrrev_b32_e32 v5, 16, v5
	v_add3_u32 v6, v14, v6, s46
	ds_read2_b32 v[22:23], v28 offset0:199 offset1:207
	v_and_or_b32 v5, v6, s47, v5
	s_waitcnt lgkmcnt(3)
	v_bfe_u32 v6, v16, 16, 1
	v_add3_u32 v6, v16, v6, s46
	s_waitcnt lgkmcnt(2)
	v_bfe_u32 v7, v18, 16, 1
	v_lshrrev_b32_e32 v6, 16, v6
	v_add3_u32 v7, v18, v7, s46
	v_and_or_b32 v6, v7, s47, v6
	s_waitcnt lgkmcnt(1)
	v_bfe_u32 v7, v20, 16, 1
	v_add3_u32 v7, v20, v7, s46
	s_waitcnt lgkmcnt(0)
	v_bfe_u32 v8, v22, 16, 1
	v_add_u32_e32 v29, s73, v76
	v_lshl_add_u64 v[2:3], s[38:39], 1, v[70:71]
	v_lshrrev_b32_e32 v7, 16, v7
	v_add3_u32 v8, v22, v8, s46
	v_mad_u64_u32 v[24:25], s[38:39], v29, s61, 0
	v_and_or_b32 v7, v8, s47, v7
	v_ashrrev_i32_e32 v10, 31, v29
	v_mov_b32_e32 v8, v25
	v_mad_u64_u32 v[26:27], s[38:39], v10, s61, v[8:9]
	v_mov_b32_e32 v25, v26
	v_lshl_add_u64 v[24:25], v[24:25], 1, v[2:3]
	global_store_dwordx4 v[24:25], v[4:7], off sc1
	v_bfe_u32 v8, v23, 16, 1
	v_add3_u32 v8, v23, v8, s46
	v_bfe_u32 v4, v9, 16, 1
	v_add3_u32 v4, v9, v4, s46
	v_bfe_u32 v5, v11, 16, 1
	v_lshrrev_b32_e32 v4, 16, v4
	v_add3_u32 v5, v11, v5, s46
	v_and_or_b32 v4, v5, s47, v4
	v_bfe_u32 v5, v13, 16, 1
	v_add3_u32 v5, v13, v5, s46
	v_bfe_u32 v6, v15, 16, 1
	v_lshrrev_b32_e32 v5, 16, v5
	v_add3_u32 v6, v15, v6, s46
	v_and_or_b32 v5, v6, s47, v5
	v_bfe_u32 v6, v17, 16, 1
	v_add3_u32 v6, v17, v6, s46
	v_bfe_u32 v7, v19, 16, 1
	v_lshrrev_b32_e32 v6, 16, v6
	v_add3_u32 v7, v19, v7, s46
	v_and_or_b32 v6, v7, s47, v6
	v_bfe_u32 v7, v21, 16, 1
	v_add3_u32 v7, v21, v7, s46
	v_lshrrev_b32_e32 v7, 16, v7
	v_and_or_b32 v7, v8, s47, v7
	v_add_u32_e32 v8, 8, v29
	v_ashrrev_i32_e32 v11, 31, v8
	v_mad_u64_u32 v[8:9], s[38:39], v8, s61, 0
	v_mov_b32_e32 v10, v9
	v_mad_u64_u32 v[10:11], s[38:39], v11, s61, v[10:11]
	v_mov_b32_e32 v9, v10
	ds_read2_b32 v[12:13], v77 offset0:16 offset1:24
	v_lshl_add_u64 v[8:9], v[8:9], 1, v[2:3]
	global_store_dwordx4 v[8:9], v[4:7], off sc1
	ds_read2_b32 v[8:9], v77 offset0:81 offset1:89
	ds_read2_b32 v[10:11], v77 offset0:146 offset1:154
	ds_read2_b32 v[14:15], v77 offset0:211 offset1:219
	s_waitcnt lgkmcnt(3)
	v_bfe_u32 v4, v12, 16, 1
	v_add3_u32 v4, v12, v4, s46
	s_waitcnt lgkmcnt(2)
	v_bfe_u32 v5, v8, 16, 1
	ds_read2_b32 v[16:17], v28 offset0:20 offset1:28
	v_lshrrev_b32_e32 v4, 16, v4
	v_add3_u32 v5, v8, v5, s46
	ds_read2_b32 v[18:19], v28 offset0:85 offset1:93
	v_and_or_b32 v4, v5, s47, v4
	s_waitcnt lgkmcnt(3)
	v_bfe_u32 v5, v10, 16, 1
	v_add3_u32 v5, v10, v5, s46
	s_waitcnt lgkmcnt(2)
	v_bfe_u32 v6, v14, 16, 1
	ds_read2_b32 v[20:21], v28 offset0:150 offset1:158
	v_lshrrev_b32_e32 v5, 16, v5
	v_add3_u32 v6, v14, v6, s46
	ds_read2_b32 v[22:23], v28 offset0:215 offset1:223
	v_and_or_b32 v5, v6, s47, v5
	s_waitcnt lgkmcnt(3)
	v_bfe_u32 v6, v16, 16, 1
	v_add3_u32 v6, v16, v6, s46
	s_waitcnt lgkmcnt(2)
	v_bfe_u32 v7, v18, 16, 1
	v_lshrrev_b32_e32 v6, 16, v6
	v_add3_u32 v7, v18, v7, s46
	v_and_or_b32 v6, v7, s47, v6
	s_waitcnt lgkmcnt(1)
	v_bfe_u32 v7, v20, 16, 1
	v_add3_u32 v7, v20, v7, s46
	s_waitcnt lgkmcnt(0)
	v_bfe_u32 v8, v22, 16, 1
	v_lshrrev_b32_e32 v7, 16, v7
	v_add3_u32 v8, v22, v8, s46
	v_and_or_b32 v7, v8, s47, v7
	v_add_u32_e32 v8, 16, v29
	v_mad_u64_u32 v[24:25], s[38:39], v8, s61, 0
	v_ashrrev_i32_e32 v10, 31, v8
	v_mov_b32_e32 v8, v25
	v_mad_u64_u32 v[26:27], s[38:39], v10, s61, v[8:9]
	v_mov_b32_e32 v25, v26
	v_lshl_add_u64 v[24:25], v[24:25], 1, v[2:3]
	global_store_dwordx4 v[24:25], v[4:7], off sc1
	v_bfe_u32 v8, v23, 16, 1
	v_add3_u32 v8, v23, v8, s46
	v_bfe_u32 v4, v13, 16, 1
	v_add3_u32 v4, v13, v4, s46
	v_bfe_u32 v5, v9, 16, 1
	v_lshrrev_b32_e32 v4, 16, v4
	v_add3_u32 v5, v9, v5, s46
	v_and_or_b32 v4, v5, s47, v4
	v_bfe_u32 v5, v11, 16, 1
	v_add3_u32 v5, v11, v5, s46
	v_bfe_u32 v6, v15, 16, 1
	v_lshrrev_b32_e32 v5, 16, v5
	v_add3_u32 v6, v15, v6, s46
	v_and_or_b32 v5, v6, s47, v5
	v_bfe_u32 v6, v17, 16, 1
	v_add3_u32 v6, v17, v6, s46
	v_bfe_u32 v7, v19, 16, 1
	v_lshrrev_b32_e32 v6, 16, v6
	v_add3_u32 v7, v19, v7, s46
	v_and_or_b32 v6, v7, s47, v6
	v_bfe_u32 v7, v21, 16, 1
	v_add3_u32 v7, v21, v7, s46
	v_lshrrev_b32_e32 v7, 16, v7
	v_and_or_b32 v7, v8, s47, v7
	v_add_u32_e32 v8, 24, v29
	v_ashrrev_i32_e32 v11, 31, v8
	v_mad_u64_u32 v[8:9], s[38:39], v8, s61, 0
	v_mov_b32_e32 v10, v9
	v_mad_u64_u32 v[10:11], s[38:39], v11, s61, v[10:11]
	v_mov_b32_e32 v9, v10
	ds_read2_b32 v[12:13], v77 offset0:32 offset1:40
	v_lshl_add_u64 v[8:9], v[8:9], 1, v[2:3]
	global_store_dwordx4 v[8:9], v[4:7], off sc1
	ds_read2_b32 v[8:9], v77 offset0:97 offset1:105
	ds_read2_b32 v[10:11], v77 offset0:162 offset1:170
	ds_read2_b32 v[14:15], v77 offset0:227 offset1:235
	s_waitcnt lgkmcnt(3)
	v_bfe_u32 v4, v12, 16, 1
	v_add3_u32 v4, v12, v4, s46
	s_waitcnt lgkmcnt(2)
	v_bfe_u32 v5, v8, 16, 1
	ds_read2_b32 v[16:17], v28 offset0:36 offset1:44
	v_lshrrev_b32_e32 v4, 16, v4
	v_add3_u32 v5, v8, v5, s46
	ds_read2_b32 v[18:19], v28 offset0:101 offset1:109
	v_and_or_b32 v4, v5, s47, v4
	s_waitcnt lgkmcnt(3)
	v_bfe_u32 v5, v10, 16, 1
	v_add3_u32 v5, v10, v5, s46
	s_waitcnt lgkmcnt(2)
	v_bfe_u32 v6, v14, 16, 1
	ds_read2_b32 v[20:21], v28 offset0:166 offset1:174
	v_lshrrev_b32_e32 v5, 16, v5
	v_add3_u32 v6, v14, v6, s46
	ds_read2_b32 v[22:23], v28 offset0:231 offset1:239
	v_and_or_b32 v5, v6, s47, v5
	s_waitcnt lgkmcnt(3)
	v_bfe_u32 v6, v16, 16, 1
	v_add3_u32 v6, v16, v6, s46
	s_waitcnt lgkmcnt(2)
	v_bfe_u32 v7, v18, 16, 1
	v_lshrrev_b32_e32 v6, 16, v6
	v_add3_u32 v7, v18, v7, s46
	v_and_or_b32 v6, v7, s47, v6
	s_waitcnt lgkmcnt(1)
	v_bfe_u32 v7, v20, 16, 1
	v_add3_u32 v7, v20, v7, s46
	s_waitcnt lgkmcnt(0)
	v_bfe_u32 v8, v22, 16, 1
	v_lshrrev_b32_e32 v7, 16, v7
	v_add3_u32 v8, v22, v8, s46
	v_and_or_b32 v7, v8, s47, v7
	v_add_u32_e32 v8, 32, v29
	v_mad_u64_u32 v[24:25], s[38:39], v8, s61, 0
	v_ashrrev_i32_e32 v10, 31, v8
	v_mov_b32_e32 v8, v25
	v_mad_u64_u32 v[26:27], s[38:39], v10, s61, v[8:9]
	v_mov_b32_e32 v25, v26
	v_lshl_add_u64 v[24:25], v[24:25], 1, v[2:3]
	global_store_dwordx4 v[24:25], v[4:7], off sc1
	v_bfe_u32 v8, v23, 16, 1
	v_add3_u32 v8, v23, v8, s46
	v_bfe_u32 v4, v13, 16, 1
	v_add3_u32 v4, v13, v4, s46
	v_bfe_u32 v5, v9, 16, 1
	v_lshrrev_b32_e32 v4, 16, v4
	v_add3_u32 v5, v9, v5, s46
	v_and_or_b32 v4, v5, s47, v4
	v_bfe_u32 v5, v11, 16, 1
	v_add3_u32 v5, v11, v5, s46
	v_bfe_u32 v6, v15, 16, 1
	v_lshrrev_b32_e32 v5, 16, v5
	v_add3_u32 v6, v15, v6, s46
	v_and_or_b32 v5, v6, s47, v5
	v_bfe_u32 v6, v17, 16, 1
	v_add3_u32 v6, v17, v6, s46
	v_bfe_u32 v7, v19, 16, 1
	v_lshrrev_b32_e32 v6, 16, v6
	v_add3_u32 v7, v19, v7, s46
	v_and_or_b32 v6, v7, s47, v6
	v_bfe_u32 v7, v21, 16, 1
	v_add3_u32 v7, v21, v7, s46
	v_lshrrev_b32_e32 v7, 16, v7
	v_and_or_b32 v7, v8, s47, v7
	v_add_u32_e32 v8, 40, v29
	v_ashrrev_i32_e32 v11, 31, v8
	v_mad_u64_u32 v[8:9], s[38:39], v8, s61, 0
	v_mov_b32_e32 v10, v9
	v_mad_u64_u32 v[10:11], s[38:39], v11, s61, v[10:11]
	v_mov_b32_e32 v9, v10
	ds_read2_b32 v[12:13], v77 offset0:48 offset1:56
	v_lshl_add_u64 v[8:9], v[8:9], 1, v[2:3]
	global_store_dwordx4 v[8:9], v[4:7], off sc1
	ds_read2_b32 v[8:9], v77 offset0:113 offset1:121
	ds_read2_b32 v[10:11], v77 offset0:178 offset1:186
	ds_read2_b32 v[14:15], v77 offset0:243 offset1:251
	s_waitcnt lgkmcnt(3)
	v_bfe_u32 v4, v12, 16, 1
	v_add3_u32 v4, v12, v4, s46
	s_waitcnt lgkmcnt(2)
	v_bfe_u32 v5, v8, 16, 1
	ds_read2_b32 v[16:17], v28 offset0:52 offset1:60
	v_lshrrev_b32_e32 v4, 16, v4
	v_add3_u32 v5, v8, v5, s46
	ds_read2_b32 v[18:19], v28 offset0:117 offset1:125
	v_and_or_b32 v4, v5, s47, v4
	s_waitcnt lgkmcnt(3)
	v_bfe_u32 v5, v10, 16, 1
	v_add3_u32 v5, v10, v5, s46
	s_waitcnt lgkmcnt(2)
	v_bfe_u32 v6, v14, 16, 1
	ds_read2_b32 v[20:21], v28 offset0:182 offset1:190
	v_lshrrev_b32_e32 v5, 16, v5
	v_add3_u32 v6, v14, v6, s46
	ds_read2_b32 v[22:23], v28 offset0:247 offset1:255
	v_and_or_b32 v5, v6, s47, v5
	s_waitcnt lgkmcnt(3)
	v_bfe_u32 v6, v16, 16, 1
	v_add3_u32 v6, v16, v6, s46
	s_waitcnt lgkmcnt(2)
	v_bfe_u32 v7, v18, 16, 1
	v_lshrrev_b32_e32 v6, 16, v6
	v_add3_u32 v7, v18, v7, s46
	v_and_or_b32 v6, v7, s47, v6
	s_waitcnt lgkmcnt(1)
	v_bfe_u32 v7, v20, 16, 1
	v_add3_u32 v7, v20, v7, s46
	s_waitcnt lgkmcnt(0)
	v_bfe_u32 v8, v22, 16, 1
	v_lshrrev_b32_e32 v7, 16, v7
	v_add3_u32 v8, v22, v8, s46
	v_and_or_b32 v7, v8, s47, v7
	v_add_u32_e32 v8, 48, v29
	v_mad_u64_u32 v[24:25], s[38:39], v8, s61, 0
	v_ashrrev_i32_e32 v10, 31, v8
	v_mov_b32_e32 v8, v25
	v_mad_u64_u32 v[26:27], s[38:39], v10, s61, v[8:9]
	v_mov_b32_e32 v25, v26
	v_lshl_add_u64 v[24:25], v[24:25], 1, v[2:3]
	global_store_dwordx4 v[24:25], v[4:7], off sc1
	v_bfe_u32 v8, v23, 16, 1
	v_add3_u32 v8, v23, v8, s46
	v_bfe_u32 v4, v13, 16, 1
	v_add3_u32 v4, v13, v4, s46
	v_bfe_u32 v5, v9, 16, 1
	v_lshrrev_b32_e32 v4, 16, v4
	v_add3_u32 v5, v9, v5, s46
	v_and_or_b32 v4, v5, s47, v4
	v_bfe_u32 v5, v11, 16, 1
	v_add3_u32 v5, v11, v5, s46
	v_bfe_u32 v6, v15, 16, 1
	v_lshrrev_b32_e32 v5, 16, v5
	v_add3_u32 v6, v15, v6, s46
	v_and_or_b32 v5, v6, s47, v5
	v_bfe_u32 v6, v17, 16, 1
	v_add3_u32 v6, v17, v6, s46
	v_bfe_u32 v7, v19, 16, 1
	v_lshrrev_b32_e32 v6, 16, v6
	v_add3_u32 v7, v19, v7, s46
	v_and_or_b32 v6, v7, s47, v6
	v_bfe_u32 v7, v21, 16, 1
	v_add3_u32 v7, v21, v7, s46
	v_lshrrev_b32_e32 v7, 16, v7
	v_and_or_b32 v7, v8, s47, v7
	v_add_u32_e32 v8, 56, v29
	v_ashrrev_i32_e32 v11, 31, v8
	v_mad_u64_u32 v[8:9], s[38:39], v8, s61, 0
	v_mov_b32_e32 v10, v9
	v_mad_u64_u32 v[10:11], s[38:39], v11, s61, v[10:11]
	v_mov_b32_e32 v9, v10
	v_lshl_add_u64 v[2:3], v[8:9], 1, v[2:3]
	global_store_dwordx4 v[2:3], v[4:7], off sc1
	s_waitcnt lgkmcnt(0)
	s_add_i32 s63, s63, s42
	s_add_i32 s66, s66, s67
	s_add_i32 s71, s71, s72
	s_cmp_ge_i32 s63, s62
	v_add_u32_e32 v69, s69, v69
	s_cbranch_scc1 .LBB0_7

.LBB0_116:
	global_load_dwordx4 v[10:13], v[6:7], off
	v_lshl_add_u64 v[14:15], v[6:7], 0, s[18:19]
	v_add_u32_e32 v18, s22, v8
	v_add_u32_e32 v20, s23, v8
	v_add_u32_e32 v22, s24, v8
	v_add_u32_e32 v24, s25, v8
	v_add_u32_e32 v26, s26, v8
	v_add_u32_e32 v28, s27, v8
	global_load_dwordx4 v[14:17], v[14:15], off
	v_ashrrev_i32_e32 v19, 31, v18
	v_ashrrev_i32_e32 v21, 31, v20
	v_ashrrev_i32_e32 v23, 31, v22
	v_ashrrev_i32_e32 v25, 31, v24
	v_ashrrev_i32_e32 v27, 31, v26
	v_ashrrev_i32_e32 v29, 31, v28
	v_lshl_add_u64 v[30:31], v[18:19], 4, s[6:7]
	v_lshl_add_u64 v[32:33], v[20:21], 4, s[6:7]
	v_lshl_add_u64 v[34:35], v[22:23], 4, s[6:7]
	v_lshl_add_u64 v[36:37], v[24:25], 4, s[6:7]
	v_lshl_add_u64 v[38:39], v[26:27], 4, s[6:7]
	v_lshl_add_u64 v[40:41], v[28:29], 4, s[6:7]
	v_lshl_add_u64 v[44:45], v[18:19], 3, s[8:9]
	v_lshl_add_u64 v[46:47], v[20:21], 3, s[8:9]
	v_lshl_add_u64 v[48:49], v[22:23], 3, s[8:9]
	v_lshl_add_u64 v[50:51], v[24:25], 3, s[8:9]
	v_lshl_add_u64 v[52:53], v[26:27], 3, s[8:9]
	v_lshl_add_u64 v[54:55], v[28:29], 3, s[8:9]
	global_load_dwordx4 v[18:21], v[30:31], off
	global_load_dwordx4 v[22:25], v[32:33], off
	global_load_dwordx4 v[26:29], v[34:35], off
	s_nop 0
	global_load_dwordx4 v[30:33], v[36:37], off
	s_nop 0
	global_load_dwordx4 v[34:37], v[38:39], off
	s_nop 0
	global_load_dwordx4 v[38:41], v[40:41], off
	v_lshl_add_u64 v[42:43], v[4:5], 0, s[14:15]
	v_add_u32_e32 v8, s10, v8
	v_cmp_lt_i32_e32 vcc, s29, v8
	v_lshl_add_u64 v[6:7], v[6:7], 0, s[20:21]
	s_or_b64 s[0:1], vcc, s[0:1]
	s_waitcnt vmcnt(7)
	v_bfe_u32 v9, v10, 16, 1
	v_bfe_u32 v56, v11, 16, 1
	v_bfe_u32 v57, v12, 16, 1
	v_bfe_u32 v58, v13, 16, 1
	v_add3_u32 v9, v10, v9, s11
	v_add3_u32 v10, v11, v56, s11
	v_add3_u32 v11, v12, v57, s11
	v_add3_u32 v12, v13, v58, s11
	s_waitcnt vmcnt(6)
	v_bfe_u32 v13, v14, 16, 1
	v_bfe_u32 v56, v15, 16, 1
	v_bfe_u32 v57, v16, 16, 1
	v_bfe_u32 v58, v17, 16, 1
	v_lshrrev_b32_e32 v9, 16, v9
	v_lshrrev_b32_e32 v11, 16, v11
	v_add3_u32 v13, v14, v13, s11
	v_add3_u32 v14, v15, v56, s11
	v_add3_u32 v15, v16, v57, s11
	v_add3_u32 v16, v17, v58, s11
	v_and_or_b32 v10, v10, s28, v9
	v_and_or_b32 v11, v12, s28, v11
	v_lshrrev_b32_e32 v9, 16, v13
	v_lshrrev_b32_e32 v12, 16, v15
	s_waitcnt vmcnt(5)
	v_bfe_u32 v13, v18, 16, 1
	v_bfe_u32 v17, v20, 16, 1
	v_bfe_u32 v15, v19, 16, 1
	v_bfe_u32 v56, v21, 16, 1
	s_waitcnt vmcnt(4)
	v_bfe_u32 v57, v22, 16, 1
	v_bfe_u32 v58, v23, 16, 1
	v_bfe_u32 v59, v24, 16, 1
	v_bfe_u32 v60, v25, 16, 1
	s_waitcnt vmcnt(3)
	v_bfe_u32 v61, v26, 16, 1
	v_bfe_u32 v62, v27, 16, 1
	v_bfe_u32 v63, v28, 16, 1
	v_bfe_u32 v64, v29, 16, 1
	s_waitcnt vmcnt(2)
	v_bfe_u32 v65, v30, 16, 1
	v_bfe_u32 v66, v31, 16, 1
	v_bfe_u32 v67, v32, 16, 1
	v_bfe_u32 v68, v33, 16, 1
	s_waitcnt vmcnt(1)
	v_bfe_u32 v69, v34, 16, 1
	v_bfe_u32 v71, v36, 16, 1
	s_waitcnt vmcnt(0)
	v_bfe_u32 v73, v38, 16, 1
	v_bfe_u32 v75, v40, 16, 1
	global_store_dwordx2 v[4:5], v[10:11], off sc1
	v_and_or_b32 v10, v14, s28, v9
	v_and_or_b32 v11, v16, s28, v12
	v_add3_u32 v9, v18, v13, s11
	v_add3_u32 v13, v20, v17, s11
	v_bfe_u32 v70, v35, 16, 1
	v_bfe_u32 v72, v37, 16, 1
	v_bfe_u32 v74, v39, 16, 1
	v_bfe_u32 v76, v41, 16, 1
	v_add3_u32 v12, v19, v15, s11
	v_add3_u32 v14, v21, v56, s11
	v_add3_u32 v15, v22, v57, s11
	v_add3_u32 v16, v23, v58, s11
	v_add3_u32 v17, v24, v59, s11
	v_add3_u32 v18, v25, v60, s11
	v_add3_u32 v19, v26, v61, s11
	v_add3_u32 v20, v27, v62, s11
	v_add3_u32 v21, v28, v63, s11
	v_add3_u32 v22, v29, v64, s11
	v_add3_u32 v23, v30, v65, s11
	v_add3_u32 v24, v31, v66, s11
	v_add3_u32 v25, v32, v67, s11
	v_add3_u32 v26, v33, v68, s11
	v_add3_u32 v27, v34, v69, s11
	v_add3_u32 v29, v36, v71, s11
	v_add3_u32 v31, v38, v73, s11
	v_add3_u32 v33, v40, v75, s11
	global_store_dwordx2 v[42:43], v[10:11], off sc1
	v_lshrrev_b32_e32 v9, 16, v9
	v_lshrrev_b32_e32 v11, 16, v13
	v_add3_u32 v28, v35, v70, s11
	v_add3_u32 v30, v37, v72, s11
	v_add3_u32 v32, v39, v74, s11
	v_add3_u32 v34, v41, v76, s11
	v_lshl_add_u64 v[4:5], v[4:5], 0, s[16:17]
	v_lshrrev_b32_e32 v13, 16, v15
	v_lshrrev_b32_e32 v15, 16, v17
	v_lshrrev_b32_e32 v17, 16, v19
	v_lshrrev_b32_e32 v19, 16, v21
	v_lshrrev_b32_e32 v21, 16, v23
	v_lshrrev_b32_e32 v23, 16, v25
	v_lshrrev_b32_e32 v25, 16, v27
	v_lshrrev_b32_e32 v27, 16, v29
	v_lshrrev_b32_e32 v29, 16, v31
	v_lshrrev_b32_e32 v31, 16, v33
	v_and_or_b32 v10, v12, s28, v9
	v_and_or_b32 v11, v14, s28, v11
	v_and_or_b32 v12, v16, s28, v13
	v_and_or_b32 v13, v18, s28, v15
	v_and_or_b32 v14, v20, s28, v17
	v_and_or_b32 v15, v22, s28, v19
	v_and_or_b32 v16, v24, s28, v21
	v_and_or_b32 v17, v26, s28, v23
	v_and_or_b32 v18, v28, s28, v25
	v_and_or_b32 v19, v30, s28, v27
	v_and_or_b32 v20, v32, s28, v29
	v_and_or_b32 v21, v34, s28, v31
	global_store_dwordx2 v[44:45], v[10:11], off sc1
	global_store_dwordx2 v[46:47], v[12:13], off sc1
	global_store_dwordx2 v[48:49], v[14:15], off sc1
	global_store_dwordx2 v[50:51], v[16:17], off sc1
	global_store_dwordx2 v[52:53], v[18:19], off sc1
	global_store_dwordx2 v[54:55], v[20:21], off sc1
	s_andn2_b64 exec, exec, s[0:1]
	s_cbranch_execnz .LBB0_116
.LBB0_117:
	s_or_b64 exec, exec, s[4:5]
	v_readlane_b32 s0, v253, 39
	s_mov_b64 s[4:5], 0
	s_mov_b64 s[6:7], 0
	v_readlane_b32 s1, v253, 40
	v_cmp_gt_i32_e32 vcc, s0, v2
	s_and_saveexec_b64 s[0:1], vcc
	s_cbranch_execz .LBB0_119
	s_add_u32 s4, s74, s4
	v_readlane_b32 s16, v253, 6
	s_addc_u32 s5, s75, s5
	v_readlane_b32 s17, v253, 7
	s_add_u32 s4, s4, 0xb00000
	v_readlane_b32 s18, v253, 8
	v_readlane_b32 s19, v253, 9
	s_mov_b64 s[8:9], s[16:17]
	s_addc_u32 s5, s5, 0
	s_lshl_b64 s[6:7], s[6:7], 2
	s_mov_b64 s[10:11], s[18:19]
	v_readlane_b32 s8, v253, 39
	s_add_u32 s6, s10, s6
	s_mov_b32 s10, s8
	s_addc_u32 s7, s11, s7
	s_ashr_i32 s11, s8, 31
	s_add_i32 s8, s10, s10
	v_add_u32_e32 v20, s8, v2
	v_ashrrev_i32_e32 v21, 31, v20
	v_lshl_add_u64 v[8:9], v[2:3], 4, s[6:7]
	v_lshl_add_u64 v[12:13], v[20:21], 4, s[6:7]
	global_load_dwordx4 v[4:7], v[8:9], off
	v_add_u32_e32 v22, s10, v20
	global_load_dwordx4 v[12:15], v[12:13], off
	v_lshl_add_u64 v[8:9], s[10:11], 4, v[8:9]
	global_load_dwordx4 v[8:11], v[8:9], off
	v_ashrrev_i32_e32 v23, 31, v22
	v_lshl_add_u64 v[16:17], v[22:23], 4, s[6:7]
	global_load_dwordx4 v[16:19], v[16:17], off
	s_movk_i32 s6, 0x7fff
	s_mov_b32 s7, 0xffff0000
	v_lshl_add_u64 v[24:25], v[2:3], 3, s[4:5]
	v_readlane_b32 s9, v253, 40
	s_mov_b32 s8, s10
	v_lshl_add_u64 v[26:27], s[10:11], 3, v[24:25]
	v_readlane_b32 s20, v253, 10
	v_readlane_b32 s21, v253, 11
	v_readlane_b32 s22, v253, 12
	v_readlane_b32 s23, v253, 13
	v_readlane_b32 s24, v253, 14
	v_readlane_b32 s25, v253, 15
	v_readlane_b32 s26, v253, 16
	v_readlane_b32 s27, v253, 17
	v_readlane_b32 s28, v253, 18
	v_readlane_b32 s29, v253, 19
	v_readlane_b32 s30, v253, 20
	v_readlane_b32 s31, v253, 21
	v_writelane_b32 v253, s8, 39
	v_lshl_add_u64 v[20:21], v[20:21], 3, s[4:5]
	s_waitcnt vmcnt(3)
	v_bfe_u32 v28, v4, 16, 1
	v_bfe_u32 v30, v6, 16, 1
	v_bfe_u32 v29, v5, 16, 1
	v_bfe_u32 v31, v7, 16, 1
	v_add3_u32 v4, v4, v28, s6
	v_add3_u32 v6, v6, v30, s6
	s_waitcnt vmcnt(1)
	v_bfe_u32 v28, v8, 16, 1
	v_bfe_u32 v30, v10, 16, 1
	v_add3_u32 v5, v5, v29, s6
	v_add3_u32 v7, v7, v31, s6
	v_bfe_u32 v29, v9, 16, 1
	v_bfe_u32 v31, v11, 16, 1
	v_lshrrev_b32_e32 v4, 16, v4
	v_lshrrev_b32_e32 v6, 16, v6
	v_add3_u32 v8, v8, v28, s6
	v_add3_u32 v10, v10, v30, s6
	v_bfe_u32 v28, v12, 16, 1
	v_bfe_u32 v30, v14, 16, 1
	v_add3_u32 v9, v9, v29, s6
	v_add3_u32 v11, v11, v31, s6
	v_bfe_u32 v29, v13, 16, 1
	v_bfe_u32 v31, v15, 16, 1
	v_and_or_b32 v4, v5, s7, v4
	v_and_or_b32 v5, v7, s7, v6
	v_lshrrev_b32_e32 v6, 16, v8
	v_lshrrev_b32_e32 v7, 16, v10
	v_add3_u32 v8, v12, v28, s6
	v_add3_u32 v12, v14, v30, s6
	s_waitcnt vmcnt(0)
	v_bfe_u32 v14, v16, 16, 1
	v_bfe_u32 v28, v18, 16, 1
	v_add3_u32 v10, v13, v29, s6
	v_add3_u32 v13, v15, v31, s6
	v_bfe_u32 v15, v17, 16, 1
	v_bfe_u32 v29, v19, 16, 1
	global_store_dwordx2 v[24:25], v[4:5], off sc1
	v_and_or_b32 v4, v9, s7, v6
	v_and_or_b32 v5, v11, s7, v7
	v_lshrrev_b32_e32 v6, 16, v8
	v_lshrrev_b32_e32 v7, 16, v12
	v_add3_u32 v8, v16, v14, s6
	v_add3_u32 v11, v18, v28, s6
	v_add3_u32 v9, v17, v15, s6
	v_add3_u32 v12, v19, v29, s6
	global_store_dwordx2 v[26:27], v[4:5], off sc1
	v_and_or_b32 v4, v10, s7, v6
	v_and_or_b32 v5, v13, s7, v7
	v_lshrrev_b32_e32 v6, 16, v8
	v_lshrrev_b32_e32 v7, 16, v11
	v_writelane_b32 v253, s9, 40
	global_store_dwordx2 v[20:21], v[4:5], off sc1
	v_and_or_b32 v4, v9, s7, v6
	v_and_or_b32 v5, v12, s7, v7
	v_lshl_add_u64 v[6:7], v[22:23], 3, s[4:5]
	global_store_dwordx2 v[6:7], v[4:5], off sc1

.LBB0_121:
	s_or_b64 exec, exec, s[4:5]
	v_mul_f32_e32 v6, v21, v21
	v_fmamk_f32 v18, v6, 0xb94c1982, v11
	v_fmaak_f32 v18, v6, v18, 0xbe2aaa9d
	v_mul_f32_e32 v18, v6, v18
	v_fmac_f32_e32 v21, v21, v18
	v_fmamk_f32 v18, v6, 0x37d75334, v12
	v_fmaak_f32 v18, v6, v18, 0x3d2aabf7
	v_fmaak_f32 v18, v6, v18, 0xbf000004
	v_fma_f32 v6, v6, v18, 1.0
	v_and_b32_e32 v18, 1, v20
	v_cmp_eq_u32_e64 s[4:5], 0, v18
	v_lshlrev_b32_e32 v18, 30, v20
	v_and_b32_e32 v18, 0x80000000, v18
	v_xor_b32_e32 v16, v17, v16
	v_cndmask_b32_e64 v6, v6, v21, s[4:5]
	v_xor_b32_e32 v16, v16, v18
	s_mov_b64 s[4:5], 0
	v_xor_b32_e32 v6, v16, v6
	v_cndmask_b32_e32 v6, v15, v6, vcc
	v_lshl_add_u64 v[16:17], v[4:5], 0, s[4:5]
	v_add_co_u32_e32 v16, vcc, 0x40000, v16
	v_readlane_b32 s4, v253, 39
	s_nop 0
	v_addc_co_u32_e32 v17, vcc, 0, v17, vcc
	v_add_u32_e32 v2, s4, v2
	v_cmp_lt_i32_e32 vcc, s43, v2
	v_lshl_add_u64 v[4:5], v[4:5], 0, s[14:15]
	s_or_b64 s[16:17], vcc, s[16:17]
	v_add_u32_e32 v1, s20, v1
	global_store_dword v[16:17], v6, off sc1
	v_readlane_b32 s5, v253, 40
	s_andn2_b64 exec, exec, s[16:17]
	s_cbranch_execz .LBB0_130

.LBB0_124:
	s_or_saveexec_b64 s[4:5], s[18:19]
	v_mul_f32_e64 v6, |v16|, s39
	v_rndne_f32_e32 v6, v6
	s_xor_b64 exec, exec, s[4:5]
	v_cvt_i32_f32_e32 v20, v6
	v_fma_f32 v21, v6, s40, |v16|
	v_fmac_f32_e32 v21, 0xb3a22168, v6
	v_fmac_f32_e32 v21, 0xa7c234c4, v6
	s_or_b64 exec, exec, s[4:5]
	v_mul_f32_e32 v22, v21, v21
	v_fmamk_f32 v23, v22, 0xb94c1982, v11
	v_fmaak_f32 v23, v22, v23, 0xbe2aaa9d
	v_mul_f32_e32 v23, v22, v23
	v_fmac_f32_e32 v21, v21, v23
	v_fmamk_f32 v23, v22, 0x37d75334, v12
	v_fmaak_f32 v23, v22, v23, 0x3d2aabf7
	v_fmaak_f32 v23, v22, v23, 0xbf000004
	v_fma_f32 v22, v22, v23, 1.0
	v_and_b32_e32 v23, 1, v20
	v_cmp_eq_u32_e32 vcc, 0, v23
	v_lshlrev_b32_e32 v20, 30, v20
	s_mov_b64 s[4:5], 0
	v_cndmask_b32_e64 v21, -v21, v22, vcc
	v_bitop3_b32 v20, v20, v21, s41 bitop3:0x6c
	v_cmp_class_f32_e64 vcc, v16, s42
	s_nop 1
	v_cndmask_b32_e32 v22, v15, v20, vcc
	v_lshl_add_u64 v[20:21], v[4:5], 0, s[4:5]
	global_store_dword v[20:21], v22, off sc1
	s_and_saveexec_b64 s[4:5], s[10:11]
	s_xor_b64 s[18:19], exec, s[4:5]
	s_cbranch_execz .LBB0_128
	v_cmp_lt_u32_e64 s[4:5], 63, v19
	v_mad_u64_u32 v[20:21], s[10:11], v18, s29, 0
	s_nop 0
	v_cndmask_b32_e64 v6, 0, v13, s[4:5]
	v_add_u32_e32 v6, v6, v19
	v_cmp_lt_u32_e64 s[6:7], 31, v6
	s_nop 1
	v_cndmask_b32_e64 v19, 0, v14, s[6:7]
	v_add_u32_e32 v6, v19, v6
	v_cmp_lt_u32_e64 s[8:9], 31, v6
	s_nop 1
	v_cndmask_b32_e64 v19, 0, v14, s[8:9]
	v_add_u32_e32 v32, v19, v6
	v_mov_b32_e32 v6, v21
	v_mad_u64_u32 v[22:23], s[10:11], v18, s30, v[6:7]
	v_mov_b32_e32 v6, v23
	v_mad_u64_u32 v[24:25], s[10:11], v18, s31, v[6:7]
	v_mov_b32_e32 v6, v25
	v_mad_u64_u32 v[26:27], s[10:11], v18, s34, v[6:7]
	v_mov_b32_e32 v6, v27
	v_mad_u64_u32 v[28:29], s[10:11], v18, s35, v[6:7]
	v_mov_b32_e32 v6, v29
	v_mad_u64_u32 v[30:31], s[10:11], v18, s36, v[6:7]
	v_mov_b32_e32 v6, v31
	v_mad_u64_u32 v[18:19], s[10:11], v18, s37, v[6:7]
	v_cndmask_b32_e64 v21, v30, v26, s[4:5]
	v_cndmask_b32_e64 v6, v18, v28, s[4:5]
	v_cndmask_b32_e64 v19, v19, v30, s[4:5]
	v_cndmask_b32_e64 v18, v6, v21, s[6:7]
	v_cndmask_b32_e64 v6, v19, v6, s[6:7]
	v_cndmask_b32_e64 v19, v28, v24, s[4:5]
	v_cndmask_b32_e64 v21, v21, v19, s[6:7]
	v_cndmask_b32_e64 v22, v26, v22, s[4:5]
	v_cndmask_b32_e64 v6, v6, v18, s[8:9]
	v_cndmask_b32_e64 v18, v18, v21, s[8:9]
	v_sub_u32_e32 v23, 32, v32
	v_cndmask_b32_e64 v19, v19, v22, s[6:7]
	v_alignbit_b32 v25, v6, v18, v23
	v_cmp_eq_u32_e64 s[10:11], 0, v32
	v_cndmask_b32_e64 v21, v21, v19, s[8:9]
	v_cndmask_b32_e64 v20, v24, v20, s[4:5]
	v_cndmask_b32_e64 v6, v25, v6, s[10:11]
	v_alignbit_b32 v25, v18, v21, v23
	v_cndmask_b32_e64 v18, v25, v18, s[10:11]
	v_bfe_u32 v27, v6, 29, 1
	v_cndmask_b32_e64 v20, v22, v20, s[6:7]
	v_alignbit_b32 v25, v6, v18, 30
	v_sub_u32_e32 v28, 0, v27
	v_cndmask_b32_e64 v19, v19, v20, s[8:9]
	v_xor_b32_e32 v25, v25, v28
	v_alignbit_b32 v20, v21, v19, v23
	v_cndmask_b32_e64 v20, v20, v21, s[10:11]
	v_ffbh_u32_e32 v21, v25
	v_alignbit_b32 v18, v18, v20, 30
	v_min_u32_e32 v21, 32, v21
	v_alignbit_b32 v19, v20, v19, 30
	v_xor_b32_e32 v18, v18, v28
	v_sub_u32_e32 v22, 31, v21
	v_xor_b32_e32 v19, v19, v28
	v_alignbit_b32 v23, v25, v18, v22
	v_alignbit_b32 v18, v18, v19, v22
	v_alignbit_b32 v19, v23, v18, 9
	v_ffbh_u32_e32 v20, v19
	v_min_u32_e32 v20, 32, v20
	v_lshrrev_b32_e32 v26, 29, v6
	v_not_b32_e32 v22, v20
	v_alignbit_b32 v18, v19, v18, v22
	v_lshlrev_b32_e32 v19, 31, v26
	v_or_b32_e32 v22, 0x33000000, v19
	v_add_lshl_u32 v20, v20, v21, 23
	v_lshrrev_b32_e32 v18, 9, v18
	v_sub_u32_e32 v20, v22, v20
	v_or_b32_e32 v19, 0.5, v19
	v_lshlrev_b32_e32 v21, 23, v21
	v_or_b32_e32 v18, v20, v18
	v_lshrrev_b32_e32 v20, 9, v23
	v_sub_u32_e32 v19, v19, v21
	v_or_b32_e32 v19, v20, v19
	v_mul_f32_e32 v20, 0x3fc90fda, v19
	v_fma_f32 v21, v19, s38, -v20
	v_fmac_f32_e32 v21, 0x33a22168, v19
	v_fmac_f32_e32 v21, 0x3fc90fda, v18
	v_lshrrev_b32_e32 v6, 30, v6
	v_add_f32_e32 v21, v20, v21
	v_add_u32_e32 v20, v27, v6

.LBB0_162:
	s_andn2_saveexec_b64 s[4:5], s[4:5]
	s_cbranch_execz .LBB0_182
	s_mov_b64 s[4:5], exec
	s_waitcnt lgkmcnt(0)
	s_waitcnt vmcnt(0)
	v_mbcnt_lo_u32_b32 v2, s4, 0
	v_mbcnt_hi_u32_b32 v2, s5, v2
	v_cmp_eq_u32_e32 vcc, 0, v2
	s_and_saveexec_b64 s[6:7], vcc
	s_cbranch_execz .LBB0_165
	s_bcnt1_i32_b64 s4, s[4:5]
	v_mov_b32_e32 v3, 0x7000
	v_mov_b32_e32 v4, s4
	global_atomic_add v3, v3, v4, s[12:13] offset:1024 sc0

.LBB0_201:
	v_lshl_add_u32 v146, s43, 8, v142
	v_lshl_or_b32 v140, s42, 8, v144
	v_ashrrev_i32_e32 v141, 31, v140
	v_ashrrev_i32_e32 v147, 31, v146
	v_lshl_add_u64 v[148:149], v[140:141], 1, s[4:5]
	v_lshlrev_b64 v[140:141], 12, v[146:147]
	v_lshl_add_u64 v[140:141], v[148:149], 0, v[140:141]
	v_pk_add_f32 v[128:129], v[128:129], 0 op_sel_hi:[1,0]
	v_pk_add_f32 v[126:127], v[126:127], 0 op_sel_hi:[1,0]
	v_pk_add_f32 v[150:151], v[124:125], 0 op_sel_hi:[1,0]
	v_pk_add_f32 v[124:125], v[122:123], 0 op_sel_hi:[1,0]
	v_cvt_pk_bf16_f32 v122, v126, v127
	v_cvt_pk_bf16_f32 v123, v128, v129
	v_pk_add_f32 v[118:119], v[118:119], 0 op_sel_hi:[1,0]
	v_cvt_pk_bf16_f32 v124, v124, v125
	v_cvt_pk_bf16_f32 v125, v150, v151
	global_store_dwordx4 v[140:141], v[122:125], off sc1
	v_pk_add_f32 v[120:121], v[120:121], 0 op_sel_hi:[1,0]
	v_pk_add_f32 v[114:115], v[114:115], 0 op_sel_hi:[1,0]
	v_pk_add_f32 v[122:123], v[112:113], 0 op_sel_hi:[1,0]
	v_pk_add_f32 v[112:113], v[110:111], 0 op_sel_hi:[1,0]
	v_cvt_pk_bf16_f32 v110, v118, v119
	v_cvt_pk_bf16_f32 v111, v120, v121
	v_pk_add_f32 v[102:103], v[102:103], 0 op_sel_hi:[1,0]
	v_cvt_pk_bf16_f32 v112, v112, v113
	v_cvt_pk_bf16_f32 v113, v122, v123
	global_store_dwordx4 v[140:141], v[110:113], off offset:256 sc1
	v_pk_add_f32 v[104:105], v[104:105], 0 op_sel_hi:[1,0]
	v_pk_add_f32 v[98:99], v[98:99], 0 op_sel_hi:[1,0]
	v_or_b32_e32 v110, 16, v146
	v_ashrrev_i32_e32 v111, 31, v110
	v_lshlrev_b64 v[110:111], 12, v[110:111]
	v_lshl_add_u64 v[110:111], v[148:149], 0, v[110:111]
	v_pk_add_f32 v[112:113], v[116:117], 0 op_sel_hi:[1,0]
	v_pk_add_f32 v[116:117], v[108:109], 0 op_sel_hi:[1,0]
	v_pk_add_f32 v[108:109], v[106:107], 0 op_sel_hi:[1,0]
	v_cvt_pk_bf16_f32 v106, v114, v115
	v_cvt_pk_bf16_f32 v107, v112, v113
	v_pk_add_f32 v[86:87], v[86:87], 0 op_sel_hi:[1,0]
	v_cvt_pk_bf16_f32 v108, v108, v109
	v_cvt_pk_bf16_f32 v109, v116, v117
	global_store_dwordx4 v[110:111], v[106:109], off sc1
	v_pk_add_f32 v[88:89], v[88:89], 0 op_sel_hi:[1,0]
	v_pk_add_f32 v[82:83], v[82:83], 0 op_sel_hi:[1,0]
	v_pk_add_f32 v[106:107], v[96:97], 0 op_sel_hi:[1,0]
	v_pk_add_f32 v[96:97], v[94:95], 0 op_sel_hi:[1,0]
	v_cvt_pk_bf16_f32 v94, v102, v103
	v_cvt_pk_bf16_f32 v95, v104, v105
	v_pk_add_f32 v[72:73], v[72:73], 0 op_sel_hi:[1,0]
	v_cvt_pk_bf16_f32 v96, v96, v97
	v_cvt_pk_bf16_f32 v97, v106, v107
	global_store_dwordx4 v[110:111], v[94:97], off offset:256 sc1
	v_pk_add_f32 v[70:71], v[70:71], 0 op_sel_hi:[1,0]
	v_pk_add_f32 v[62:63], v[62:63], 0 op_sel_hi:[1,0]
	v_or_b32_e32 v94, 32, v146
	v_ashrrev_i32_e32 v95, 31, v94
	v_lshlrev_b64 v[94:95], 12, v[94:95]
	v_lshl_add_u64 v[94:95], v[148:149], 0, v[94:95]
	v_pk_add_f32 v[96:97], v[100:101], 0 op_sel_hi:[1,0]
	v_pk_add_f32 v[100:101], v[92:93], 0 op_sel_hi:[1,0]
	v_pk_add_f32 v[92:93], v[90:91], 0 op_sel_hi:[1,0]
	v_cvt_pk_bf16_f32 v90, v98, v99
	v_cvt_pk_bf16_f32 v91, v96, v97
	s_mov_b32 s11, 0x80000
	v_cvt_pk_bf16_f32 v92, v92, v93
	v_cvt_pk_bf16_f32 v93, v100, v101
	global_store_dwordx4 v[94:95], v[90:93], off sc1
	v_pk_add_f32 v[64:65], v[64:65], 0 op_sel_hi:[1,0]
	s_mov_b64 s[16:17], 0x80000
	v_pk_add_f32 v[90:91], v[80:81], 0 op_sel_hi:[1,0]
	v_pk_add_f32 v[80:81], v[78:79], 0 op_sel_hi:[1,0]
	v_cvt_pk_bf16_f32 v78, v86, v87
	v_cvt_pk_bf16_f32 v79, v88, v89
	v_pk_add_f32 v[56:57], v[56:57], 0 op_sel_hi:[1,0]
	v_cvt_pk_bf16_f32 v80, v80, v81
	v_cvt_pk_bf16_f32 v81, v90, v91
	global_store_dwordx4 v[94:95], v[78:81], off offset:256 sc1
	v_pk_add_f32 v[54:55], v[54:55], 0 op_sel_hi:[1,0]
	v_pk_add_f32 v[50:51], v[50:51], 0 op_sel_hi:[1,0]
	v_or_b32_e32 v78, 48, v146
	v_ashrrev_i32_e32 v79, 31, v78
	v_lshlrev_b64 v[78:79], 12, v[78:79]
	v_lshl_add_u64 v[78:79], v[148:149], 0, v[78:79]
	v_pk_add_f32 v[80:81], v[84:85], 0 op_sel_hi:[1,0]
	v_pk_add_f32 v[84:85], v[76:77], 0 op_sel_hi:[1,0]
	v_pk_add_f32 v[76:77], v[74:75], 0 op_sel_hi:[1,0]
	v_cvt_pk_bf16_f32 v74, v82, v83
	v_cvt_pk_bf16_f32 v75, v80, v81
	v_pk_add_f32 v[40:41], v[40:41], 0 op_sel_hi:[1,0]
	v_cvt_pk_bf16_f32 v76, v76, v77
	v_cvt_pk_bf16_f32 v77, v84, v85
	global_store_dwordx4 v[78:79], v[74:77], off sc1
	v_pk_add_f32 v[38:39], v[38:39], 0 op_sel_hi:[1,0]
	v_pk_add_f32 v[34:35], v[34:35], 0 op_sel_hi:[1,0]
	v_pk_add_f32 v[74:75], v[68:69], 0 op_sel_hi:[1,0]
	v_pk_add_f32 v[68:69], v[66:67], 0 op_sel_hi:[1,0]
	v_cvt_pk_bf16_f32 v66, v70, v71
	v_cvt_pk_bf16_f32 v67, v72, v73
	v_pk_add_f32 v[24:25], v[24:25], 0 op_sel_hi:[1,0]
	v_cvt_pk_bf16_f32 v68, v68, v69
	v_cvt_pk_bf16_f32 v69, v74, v75
	global_store_dwordx4 v[78:79], v[66:69], off offset:256 sc1
	v_pk_add_f32 v[22:23], v[22:23], 0 op_sel_hi:[1,0]
	v_pk_add_f32 v[18:19], v[18:19], 0 op_sel_hi:[1,0]
	v_pk_add_f32 v[68:69], v[60:61], 0 op_sel_hi:[1,0]
	v_pk_add_f32 v[60:61], v[58:59], 0 op_sel_hi:[1,0]
	v_cvt_pk_bf16_f32 v58, v62, v63
	v_add_co_u32_e32 v62, vcc, s11, v140
	v_cvt_pk_bf16_f32 v59, v64, v65
	v_cvt_pk_bf16_f32 v60, v60, v61
	v_cvt_pk_bf16_f32 v61, v68, v69
	v_lshl_add_u64 v[66:67], v[140:141], 0, s[16:17]
	s_nop 0
	v_addc_co_u32_e32 v63, vcc, 0, v141, vcc
	global_store_dwordx4 v[62:63], v[58:61], off sc1
	s_mov_b32 s11, 0x90000
	s_mov_b64 s[16:17], 0x90000
	v_pk_add_f32 v[58:59], v[48:49], 0 op_sel_hi:[1,0]
	v_pk_add_f32 v[48:49], v[46:47], 0 op_sel_hi:[1,0]
	v_cvt_pk_bf16_f32 v46, v54, v55
	v_cvt_pk_bf16_f32 v47, v56, v57
	v_pk_add_f32 v[8:9], v[8:9], 0 op_sel_hi:[1,0]
	v_cvt_pk_bf16_f32 v48, v48, v49
	v_cvt_pk_bf16_f32 v49, v58, v59
	global_store_dwordx4 v[66:67], v[46:49], off offset:256 sc1
	v_pk_add_f32 v[6:7], v[6:7], 0 op_sel_hi:[1,0]
	s_nop 0
	v_pk_add_f32 v[48:49], v[52:53], 0 op_sel_hi:[1,0]
	v_pk_add_f32 v[52:53], v[44:45], 0 op_sel_hi:[1,0]
	v_pk_add_f32 v[44:45], v[42:43], 0 op_sel_hi:[1,0]
	v_cvt_pk_bf16_f32 v42, v50, v51
	v_cvt_pk_bf16_f32 v43, v48, v49
	v_add_co_u32_e32 v48, vcc, s11, v140
	v_cvt_pk_bf16_f32 v44, v44, v45
	v_cvt_pk_bf16_f32 v45, v52, v53
	v_lshl_add_u64 v[46:47], v[140:141], 0, s[16:17]
	s_nop 0
	v_addc_co_u32_e32 v49, vcc, 0, v141, vcc
	global_store_dwordx4 v[48:49], v[42:45], off sc1
	s_mov_b32 s11, 0xa0000
	s_mov_b64 s[16:17], 0xa0000
	v_pk_add_f32 v[42:43], v[32:33], 0 op_sel_hi:[1,0]
	v_pk_add_f32 v[32:33], v[30:31], 0 op_sel_hi:[1,0]
	v_cvt_pk_bf16_f32 v30, v38, v39
	v_cvt_pk_bf16_f32 v31, v40, v41
	s_nop 0
	v_cvt_pk_bf16_f32 v32, v32, v33
	v_cvt_pk_bf16_f32 v33, v42, v43
	global_store_dwordx4 v[46:47], v[30:33], off offset:256 sc1
	s_nop 1
	v_pk_add_f32 v[32:33], v[36:37], 0 op_sel_hi:[1,0]
	v_pk_add_f32 v[36:37], v[28:29], 0 op_sel_hi:[1,0]
	v_pk_add_f32 v[28:29], v[26:27], 0 op_sel_hi:[1,0]
	v_cvt_pk_bf16_f32 v26, v34, v35
	v_cvt_pk_bf16_f32 v27, v32, v33
	v_add_co_u32_e32 v32, vcc, s11, v140
	v_cvt_pk_bf16_f32 v28, v28, v29
	v_cvt_pk_bf16_f32 v29, v36, v37
	v_lshl_add_u64 v[30:31], v[140:141], 0, s[16:17]
	s_nop 0
	v_addc_co_u32_e32 v33, vcc, 0, v141, vcc
	global_store_dwordx4 v[32:33], v[26:29], off sc1
	s_mov_b32 s11, 0xb0000
	s_mov_b64 s[16:17], 0xb0000
	v_pk_add_f32 v[26:27], v[16:17], 0 op_sel_hi:[1,0]
	v_pk_add_f32 v[16:17], v[14:15], 0 op_sel_hi:[1,0]
	v_cvt_pk_bf16_f32 v14, v22, v23
	v_cvt_pk_bf16_f32 v15, v24, v25
	s_nop 0
	v_cvt_pk_bf16_f32 v16, v16, v17
	v_cvt_pk_bf16_f32 v17, v26, v27
	global_store_dwordx4 v[30:31], v[14:17], off offset:256 sc1
	s_nop 1
	v_pk_add_f32 v[16:17], v[20:21], 0 op_sel_hi:[1,0]
	v_pk_add_f32 v[20:21], v[12:13], 0 op_sel_hi:[1,0]
	v_pk_add_f32 v[12:13], v[10:11], 0 op_sel_hi:[1,0]
	v_cvt_pk_bf16_f32 v10, v18, v19
	v_cvt_pk_bf16_f32 v11, v16, v17
	v_add_co_u32_e32 v16, vcc, s11, v140
	v_lshl_add_u64 v[14:15], v[140:141], 0, s[16:17]
	s_nop 0
	v_addc_co_u32_e32 v17, vcc, 0, v141, vcc
	v_cvt_pk_bf16_f32 v12, v12, v13
	v_cvt_pk_bf16_f32 v13, v20, v21
	global_store_dwordx4 v[16:17], v[10:13], off sc1
	s_andn2_b64 vcc, exec, s[8:9]
	s_mov_b64 s[8:9], -1
	v_pk_add_f32 v[10:11], v[4:5], 0 op_sel_hi:[1,0]
	v_pk_add_f32 v[4:5], v[2:3], 0 op_sel_hi:[1,0]
	v_cvt_pk_bf16_f32 v2, v6, v7
	v_cvt_pk_bf16_f32 v3, v8, v9
	s_nop 0
	v_cvt_pk_bf16_f32 v4, v4, v5
	v_cvt_pk_bf16_f32 v5, v10, v11
	global_store_dwordx4 v[14:15], v[2:5], off offset:256 sc1
	s_cbranch_vccnz .LBB0_190
	s_andn2_b64 vcc, exec, s[0:1]
	s_cbranch_vccnz .LBB0_189
	s_barrier
	s_branch .LBB0_189

.LBB0_221:
	v_mov_b64_e32 v[148:149], s[10:11]
	s_movk_i32 s15, 0x1800
	v_mad_i64_i32 v[162:163], s[0:1], v147, s15, v[148:149]
	v_lshl_or_b32 v178, s28, 9, v153
	v_lshl_add_u64 v[166:167], v[162:163], 0, v[178:179]
	v_cvt_pk_bf16_f32 v162, v126, v127
	v_cvt_pk_bf16_f32 v163, v128, v129
	v_cvt_pk_bf16_f32 v164, v122, v123
	v_cvt_pk_bf16_f32 v165, v124, v125
	global_store_dwordx4 v[166:167], v[162:165], off sc1
	s_nop 1
	v_cvt_pk_bf16_f32 v162, v118, v119
	v_cvt_pk_bf16_f32 v163, v120, v121
	v_cvt_pk_bf16_f32 v164, v114, v115
	v_cvt_pk_bf16_f32 v165, v116, v117
	global_store_dwordx4 v[166:167], v[162:165], off offset:256 sc1
	s_nop 1
	v_mad_i64_i32 v[162:163], s[0:1], v160, s15, v[148:149]
	v_lshl_add_u64 v[166:167], v[162:163], 0, v[178:179]
	v_cvt_pk_bf16_f32 v162, v110, v111
	v_cvt_pk_bf16_f32 v163, v112, v113
	v_cvt_pk_bf16_f32 v164, v106, v107
	v_cvt_pk_bf16_f32 v165, v108, v109
	global_store_dwordx4 v[166:167], v[162:165], off sc1
	s_nop 1
	v_cvt_pk_bf16_f32 v162, v102, v103
	v_cvt_pk_bf16_f32 v163, v104, v105
	v_cvt_pk_bf16_f32 v164, v98, v99
	v_cvt_pk_bf16_f32 v165, v100, v101
	global_store_dwordx4 v[166:167], v[162:165], off offset:256 sc1
	s_nop 1
	v_mad_i64_i32 v[162:163], s[0:1], v159, s15, v[148:149]
	v_lshl_add_u64 v[166:167], v[162:163], 0, v[178:179]
	v_cvt_pk_bf16_f32 v162, v94, v95
	v_cvt_pk_bf16_f32 v163, v96, v97
	v_cvt_pk_bf16_f32 v164, v90, v91
	v_cvt_pk_bf16_f32 v165, v92, v93
	global_store_dwordx4 v[166:167], v[162:165], off sc1
	s_nop 1
	v_cvt_pk_bf16_f32 v162, v86, v87
	v_cvt_pk_bf16_f32 v163, v88, v89
	v_cvt_pk_bf16_f32 v164, v82, v83
	v_cvt_pk_bf16_f32 v165, v84, v85
	global_store_dwordx4 v[166:167], v[162:165], off offset:256 sc1
	s_nop 1
	v_mad_i64_i32 v[162:163], s[0:1], v158, s15, v[148:149]
	v_lshl_add_u64 v[166:167], v[162:163], 0, v[178:179]
	v_cvt_pk_bf16_f32 v162, v78, v79
	v_cvt_pk_bf16_f32 v163, v80, v81
	v_cvt_pk_bf16_f32 v164, v74, v75
	v_cvt_pk_bf16_f32 v165, v76, v77
	global_store_dwordx4 v[166:167], v[162:165], off sc1
	s_nop 1
	v_cvt_pk_bf16_f32 v162, v70, v71
	v_cvt_pk_bf16_f32 v163, v72, v73
	v_cvt_pk_bf16_f32 v164, v66, v67
	v_cvt_pk_bf16_f32 v165, v68, v69
	global_store_dwordx4 v[166:167], v[162:165], off offset:256 sc1
	s_nop 1
	v_mad_i64_i32 v[162:163], s[0:1], v157, s15, v[148:149]
	v_lshl_add_u64 v[166:167], v[162:163], 0, v[178:179]
	v_cvt_pk_bf16_f32 v162, v62, v63
	v_cvt_pk_bf16_f32 v163, v64, v65
	v_cvt_pk_bf16_f32 v164, v58, v59
	v_cvt_pk_bf16_f32 v165, v60, v61
	global_store_dwordx4 v[166:167], v[162:165], off sc1
	s_nop 1
	v_cvt_pk_bf16_f32 v162, v54, v55
	v_cvt_pk_bf16_f32 v163, v56, v57
	v_cvt_pk_bf16_f32 v164, v50, v51
	v_cvt_pk_bf16_f32 v165, v52, v53
	global_store_dwordx4 v[166:167], v[162:165], off offset:256 sc1
	s_nop 1
	v_mad_i64_i32 v[162:163], s[0:1], v156, s15, v[148:149]
	v_lshl_add_u64 v[166:167], v[162:163], 0, v[178:179]
	v_cvt_pk_bf16_f32 v162, v46, v47
	v_cvt_pk_bf16_f32 v163, v48, v49
	v_cvt_pk_bf16_f32 v164, v42, v43
	v_cvt_pk_bf16_f32 v165, v44, v45
	global_store_dwordx4 v[166:167], v[162:165], off sc1
	s_nop 1
	v_cvt_pk_bf16_f32 v162, v38, v39
	v_cvt_pk_bf16_f32 v163, v40, v41
	v_cvt_pk_bf16_f32 v164, v34, v35
	v_cvt_pk_bf16_f32 v165, v36, v37
	global_store_dwordx4 v[166:167], v[162:165], off offset:256 sc1
	s_nop 1
	v_mad_i64_i32 v[162:163], s[0:1], v155, s15, v[148:149]
	v_lshl_add_u64 v[166:167], v[162:163], 0, v[178:179]
	v_cvt_pk_bf16_f32 v162, v30, v31
	v_cvt_pk_bf16_f32 v163, v32, v33
	v_cvt_pk_bf16_f32 v164, v26, v27
	v_cvt_pk_bf16_f32 v165, v28, v29
	global_store_dwordx4 v[166:167], v[162:165], off sc1
	v_mad_i64_i32 v[148:149], s[0:1], v154, s15, v[148:149]
	s_nop 0
	v_cvt_pk_bf16_f32 v162, v22, v23
	v_cvt_pk_bf16_f32 v163, v24, v25
	v_cvt_pk_bf16_f32 v164, v18, v19
	v_cvt_pk_bf16_f32 v165, v20, v21
	global_store_dwordx4 v[166:167], v[162:165], off offset:256 sc1
	v_lshl_add_u64 v[148:149], v[148:149], 0, v[178:179]
	s_nop 0
	v_cvt_pk_bf16_f32 v162, v14, v15
	v_cvt_pk_bf16_f32 v163, v16, v17
	v_cvt_pk_bf16_f32 v164, v10, v11
	v_cvt_pk_bf16_f32 v165, v12, v13
	global_store_dwordx4 v[148:149], v[162:165], off sc1
	s_nop 1
	v_cvt_pk_bf16_f32 v162, v6, v7
	v_cvt_pk_bf16_f32 v163, v8, v9
	v_cvt_pk_bf16_f32 v164, v2, v3
	v_cvt_pk_bf16_f32 v165, v4, v5
	global_store_dwordx4 v[148:149], v[162:165], off offset:256 sc1
	s_cbranch_execnz .LBB0_220
.LBB0_222:
	v_lshlrev_b32_e32 v149, 7, v147
	v_and_b32_e32 v178, 0x3e780, v149
	v_lshl_add_u64 v[166:167], v[138:139], 0, v[178:179]
	v_lshl_add_u64 v[174:175], v[140:141], 0, v[178:179]
	global_load_dwordx4 v[162:165], v[166:167], off offset:16
	s_nop 0
	global_load_dwordx4 v[166:169], v[166:167], off
	s_nop 0
	global_load_dwordx4 v[170:173], v[174:175], off offset:16
	s_nop 0
	global_load_dwordx4 v[174:177], v[174:175], off
	s_cmp_lt_i32 s28, 4
	s_cselect_b64 vcc, -1, 0
	v_cndmask_b32_e32 v148, 1.0, v201, vcc
	s_lshl_b32 s0, s28, 8
	s_ashr_i32 s1, s0, 31
	s_movk_i32 s15, 0x1800
	s_lshl_b64 s[28:29], s[0:1], 1
	s_waitcnt vmcnt(0)
	v_pk_mul_f32 v[206:207], v[114:115], v[170:171]
	v_pk_mul_f32 v[198:199], v[118:119], v[174:175]
	v_pk_fma_f32 v[206:207], v[122:123], v[162:163], v[206:207] neg_lo:[0,0,1] neg_hi:[0,0,1]
	v_pk_fma_f32 v[198:199], v[126:127], v[166:167], v[198:199] neg_lo:[0,0,1] neg_hi:[0,0,1]
	v_pk_mul_f32 v[126:127], v[126:127], v[174:175]
	v_pk_mul_f32 v[122:123], v[122:123], v[170:171]
	v_pk_fma_f32 v[118:119], v[118:119], v[166:167], v[126:127]
	v_pk_mul_f32 v[202:203], v[116:117], v[172:173]
	v_pk_mul_f32 v[126:127], v[148:149], v[118:119] op_sel_hi:[0,1]
	v_pk_mul_f32 v[118:119], v[124:125], v[172:173]
	v_pk_fma_f32 v[114:115], v[114:115], v[162:163], v[122:123]
	v_pk_fma_f32 v[202:203], v[124:125], v[164:165], v[202:203] neg_lo:[0,0,1] neg_hi:[0,0,1]
	v_pk_fma_f32 v[116:117], v[116:117], v[164:165], v[118:119]
	v_pk_mul_f32 v[124:125], v[148:149], v[114:115] op_sel_hi:[0,1]
	v_mov_b64_e32 v[114:115], s[10:11]
	v_pk_mul_f32 v[122:123], v[148:149], v[116:117] op_sel_hi:[0,1]
	v_mad_i64_i32 v[116:117], s[16:17], v147, s15, v[114:115]
	v_pk_mul_f32 v[196:197], v[120:121], v[176:177]
	v_lshl_add_u64 v[116:117], v[116:117], 0, s[28:29]
	v_pk_fma_f32 v[196:197], v[128:129], v[168:169], v[196:197] neg_lo:[0,0,1] neg_hi:[0,0,1]
	v_pk_mul_f32 v[128:129], v[128:129], v[176:177]
	v_lshl_add_u64 v[116:117], v[116:117], 0, s[82:83]
	v_mov_b32_e32 v147, v179
	v_pk_mul_f32 v[198:199], v[148:149], v[198:199] op_sel_hi:[0,1]
	v_pk_fma_f32 v[120:121], v[120:121], v[168:169], v[128:129]
	v_lshl_add_u64 v[128:129], v[116:117], 0, v[146:147]
	v_cvt_pk_bf16_f32 v116, v198, v199
	v_pk_mul_f32 v[196:197], v[148:149], v[196:197] op_sel_hi:[0,1]
	v_pk_mul_f32 v[202:203], v[148:149], v[202:203] op_sel_hi:[0,1]
	v_pk_mul_f32 v[206:207], v[148:149], v[206:207] op_sel_hi:[0,1]
	v_cvt_pk_bf16_f32 v117, v196, v197
	v_cvt_pk_bf16_f32 v118, v206, v207
	v_cvt_pk_bf16_f32 v119, v202, v203
	global_store_dwordx4 v[128:129], v[116:119], off sc1
	v_pk_mul_f32 v[120:121], v[148:149], v[120:121] op_sel_hi:[0,1]
	s_nop 0
	v_cvt_pk_bf16_f32 v116, v126, v127
	v_cvt_pk_bf16_f32 v117, v120, v121
	v_cvt_pk_bf16_f32 v118, v124, v125
	v_cvt_pk_bf16_f32 v119, v122, v123
	global_store_dwordx4 v[128:129], v[116:119], off offset:64 sc1
	s_nop 1
	v_lshlrev_b32_e32 v116, 7, v160
	v_and_b32_e32 v178, 0x3ef80, v116
	v_lshl_add_u64 v[120:121], v[138:139], 0, v[178:179]
	v_lshl_add_u64 v[128:129], v[140:141], 0, v[178:179]
	global_load_dwordx4 v[116:119], v[120:121], off offset:16
	s_nop 0
	global_load_dwordx4 v[120:123], v[120:121], off
	s_nop 0
	global_load_dwordx4 v[124:127], v[128:129], off offset:16
	global_load_dwordx4 v[162:165], v[128:129], off
	s_waitcnt vmcnt(1)
	v_pk_mul_f32 v[170:171], v[98:99], v[124:125]
	v_pk_mul_f32 v[168:169], v[100:101], v[126:127]
	v_pk_fma_f32 v[170:171], v[106:107], v[116:117], v[170:171] neg_lo:[0,0,1] neg_hi:[0,0,1]
	v_pk_mul_f32 v[106:107], v[106:107], v[124:125]
	v_pk_fma_f32 v[168:169], v[108:109], v[118:119], v[168:169] neg_lo:[0,0,1] neg_hi:[0,0,1]
	v_pk_mul_f32 v[108:109], v[108:109], v[126:127]
	v_pk_fma_f32 v[98:99], v[98:99], v[116:117], v[106:107]
	v_pk_fma_f32 v[100:101], v[100:101], v[118:119], v[108:109]
	v_pk_mul_f32 v[108:109], v[148:149], v[98:99] op_sel_hi:[0,1]
	v_mad_i64_i32 v[98:99], s[0:1], v160, s15, v[114:115]
	s_waitcnt vmcnt(0)
	v_pk_mul_f32 v[166:167], v[102:103], v[162:163]
	v_lshl_add_u64 v[98:99], v[98:99], 0, s[28:29]
	v_pk_mul_f32 v[128:129], v[104:105], v[164:165]
	v_pk_fma_f32 v[166:167], v[110:111], v[120:121], v[166:167] neg_lo:[0,0,1] neg_hi:[0,0,1]
	v_pk_mul_f32 v[110:111], v[110:111], v[162:163]
	v_lshl_add_u64 v[98:99], v[98:99], 0, s[82:83]
	v_pk_fma_f32 v[128:129], v[112:113], v[122:123], v[128:129] neg_lo:[0,0,1] neg_hi:[0,0,1]
	v_pk_mul_f32 v[166:167], v[148:149], v[166:167] op_sel_hi:[0,1]
	v_pk_mul_f32 v[112:113], v[112:113], v[164:165]
	v_pk_fma_f32 v[102:103], v[102:103], v[120:121], v[110:111]
	v_lshl_add_u64 v[110:111], v[98:99], 0, v[146:147]
	v_cvt_pk_bf16_f32 v98, v166, v167
	v_pk_mul_f32 v[128:129], v[148:149], v[128:129] op_sel_hi:[0,1]
	v_pk_mul_f32 v[168:169], v[148:149], v[168:169] op_sel_hi:[0,1]
	v_pk_mul_f32 v[170:171], v[148:149], v[170:171] op_sel_hi:[0,1]
	v_pk_fma_f32 v[104:105], v[104:105], v[122:123], v[112:113]
	v_pk_mul_f32 v[102:103], v[148:149], v[102:103] op_sel_hi:[0,1]
	v_pk_mul_f32 v[106:107], v[148:149], v[100:101] op_sel_hi:[0,1]
	v_cvt_pk_bf16_f32 v99, v128, v129
	v_cvt_pk_bf16_f32 v100, v170, v171
	v_cvt_pk_bf16_f32 v101, v168, v169
	global_store_dwordx4 v[110:111], v[98:101], off sc1
	v_pk_mul_f32 v[104:105], v[148:149], v[104:105] op_sel_hi:[0,1]
	s_nop 0
	v_cvt_pk_bf16_f32 v98, v102, v103
	v_cvt_pk_bf16_f32 v99, v104, v105
	v_cvt_pk_bf16_f32 v100, v108, v109
	v_cvt_pk_bf16_f32 v101, v106, v107
	global_store_dwordx4 v[110:111], v[98:101], off offset:64 sc1
	s_nop 1
	v_lshlrev_b32_e32 v98, 7, v159
	v_and_b32_e32 v178, 0x3f780, v98
	v_lshl_add_u64 v[102:103], v[138:139], 0, v[178:179]
	v_lshl_add_u64 v[110:111], v[140:141], 0, v[178:179]
	global_load_dwordx4 v[98:101], v[102:103], off offset:16
	s_nop 0
	global_load_dwordx4 v[102:105], v[102:103], off
	s_nop 0
	global_load_dwordx4 v[106:109], v[110:111], off offset:16
	s_nop 0
	global_load_dwordx4 v[110:113], v[110:111], off
	s_waitcnt vmcnt(1)
	v_pk_mul_f32 v[122:123], v[82:83], v[106:107]
	v_pk_mul_f32 v[120:121], v[84:85], v[108:109]
	v_pk_fma_f32 v[122:123], v[90:91], v[98:99], v[122:123] neg_lo:[0,0,1] neg_hi:[0,0,1]
	v_pk_mul_f32 v[90:91], v[90:91], v[106:107]
	v_pk_fma_f32 v[120:121], v[92:93], v[100:101], v[120:121] neg_lo:[0,0,1] neg_hi:[0,0,1]
	v_pk_mul_f32 v[92:93], v[92:93], v[108:109]
	v_pk_fma_f32 v[82:83], v[82:83], v[98:99], v[90:91]
	v_pk_fma_f32 v[84:85], v[84:85], v[100:101], v[92:93]
	v_pk_mul_f32 v[92:93], v[148:149], v[82:83] op_sel_hi:[0,1]
	v_mad_i64_i32 v[82:83], s[0:1], v159, s15, v[114:115]
	s_waitcnt vmcnt(0)
	v_pk_mul_f32 v[118:119], v[86:87], v[110:111]
	v_lshl_add_u64 v[82:83], v[82:83], 0, s[28:29]
	v_pk_mul_f32 v[116:117], v[88:89], v[112:113]
	v_pk_fma_f32 v[118:119], v[94:95], v[102:103], v[118:119] neg_lo:[0,0,1] neg_hi:[0,0,1]
	v_pk_mul_f32 v[94:95], v[94:95], v[110:111]
	v_lshl_add_u64 v[82:83], v[82:83], 0, s[82:83]
	v_pk_fma_f32 v[116:117], v[96:97], v[104:105], v[116:117] neg_lo:[0,0,1] neg_hi:[0,0,1]
	v_pk_mul_f32 v[118:119], v[148:149], v[118:119] op_sel_hi:[0,1]
	v_pk_mul_f32 v[96:97], v[96:97], v[112:113]
	v_pk_fma_f32 v[86:87], v[86:87], v[102:103], v[94:95]
	v_lshl_add_u64 v[94:95], v[82:83], 0, v[146:147]
	v_cvt_pk_bf16_f32 v82, v118, v119
	v_pk_mul_f32 v[116:117], v[148:149], v[116:117] op_sel_hi:[0,1]
	v_pk_mul_f32 v[120:121], v[148:149], v[120:121] op_sel_hi:[0,1]
	v_pk_mul_f32 v[122:123], v[148:149], v[122:123] op_sel_hi:[0,1]
	v_pk_fma_f32 v[88:89], v[88:89], v[104:105], v[96:97]
	v_pk_mul_f32 v[86:87], v[148:149], v[86:87] op_sel_hi:[0,1]
	v_pk_mul_f32 v[90:91], v[148:149], v[84:85] op_sel_hi:[0,1]
	v_cvt_pk_bf16_f32 v83, v116, v117
	v_cvt_pk_bf16_f32 v84, v122, v123
	v_cvt_pk_bf16_f32 v85, v120, v121
	global_store_dwordx4 v[94:95], v[82:85], off sc1
	v_pk_mul_f32 v[88:89], v[148:149], v[88:89] op_sel_hi:[0,1]
	s_nop 0
	v_cvt_pk_bf16_f32 v82, v86, v87
	v_cvt_pk_bf16_f32 v83, v88, v89
	v_cvt_pk_bf16_f32 v84, v92, v93
	v_cvt_pk_bf16_f32 v85, v90, v91
	global_store_dwordx4 v[94:95], v[82:85], off offset:64 sc1
	s_nop 1
	v_lshlrev_b32_e32 v82, 7, v158
	v_and_b32_e32 v178, 0x3ff80, v82
	v_lshl_add_u64 v[86:87], v[138:139], 0, v[178:179]
	v_lshl_add_u64 v[94:95], v[140:141], 0, v[178:179]
	global_load_dwordx4 v[82:85], v[86:87], off offset:16
	s_nop 0
	global_load_dwordx4 v[86:89], v[86:87], off
	s_nop 0
	global_load_dwordx4 v[90:93], v[94:95], off offset:16
	s_nop 0
	global_load_dwordx4 v[94:97], v[94:95], off
	s_waitcnt vmcnt(1)
	v_pk_mul_f32 v[104:105], v[66:67], v[90:91]
	v_pk_mul_f32 v[102:103], v[68:69], v[92:93]
	v_pk_fma_f32 v[104:105], v[74:75], v[82:83], v[104:105] neg_lo:[0,0,1] neg_hi:[0,0,1]
	v_pk_mul_f32 v[74:75], v[74:75], v[90:91]
	v_pk_fma_f32 v[102:103], v[76:77], v[84:85], v[102:103] neg_lo:[0,0,1] neg_hi:[0,0,1]
	v_pk_mul_f32 v[76:77], v[76:77], v[92:93]
	v_pk_fma_f32 v[66:67], v[66:67], v[82:83], v[74:75]
	v_pk_fma_f32 v[68:69], v[68:69], v[84:85], v[76:77]
	v_pk_mul_f32 v[76:77], v[148:149], v[66:67] op_sel_hi:[0,1]
	v_mad_i64_i32 v[66:67], s[0:1], v158, s15, v[114:115]
	s_waitcnt vmcnt(0)
	v_pk_mul_f32 v[100:101], v[70:71], v[94:95]
	v_lshl_add_u64 v[66:67], v[66:67], 0, s[28:29]
	v_pk_mul_f32 v[98:99], v[72:73], v[96:97]
	v_pk_fma_f32 v[100:101], v[78:79], v[86:87], v[100:101] neg_lo:[0,0,1] neg_hi:[0,0,1]
	v_pk_mul_f32 v[78:79], v[78:79], v[94:95]
	v_lshl_add_u64 v[66:67], v[66:67], 0, s[82:83]
	v_pk_fma_f32 v[98:99], v[80:81], v[88:89], v[98:99] neg_lo:[0,0,1] neg_hi:[0,0,1]
	v_pk_mul_f32 v[100:101], v[148:149], v[100:101] op_sel_hi:[0,1]
	v_pk_mul_f32 v[80:81], v[80:81], v[96:97]
	v_pk_fma_f32 v[70:71], v[70:71], v[86:87], v[78:79]
	v_lshl_add_u64 v[78:79], v[66:67], 0, v[146:147]
	v_cvt_pk_bf16_f32 v66, v100, v101
	v_pk_mul_f32 v[98:99], v[148:149], v[98:99] op_sel_hi:[0,1]
	v_pk_mul_f32 v[102:103], v[148:149], v[102:103] op_sel_hi:[0,1]
	v_pk_mul_f32 v[104:105], v[148:149], v[104:105] op_sel_hi:[0,1]
	v_pk_fma_f32 v[72:73], v[72:73], v[88:89], v[80:81]
	v_pk_mul_f32 v[70:71], v[148:149], v[70:71] op_sel_hi:[0,1]
	v_pk_mul_f32 v[74:75], v[148:149], v[68:69] op_sel_hi:[0,1]
	v_cvt_pk_bf16_f32 v67, v98, v99
	v_cvt_pk_bf16_f32 v68, v104, v105
	v_cvt_pk_bf16_f32 v69, v102, v103
	global_store_dwordx4 v[78:79], v[66:69], off sc1
	v_pk_mul_f32 v[72:73], v[148:149], v[72:73] op_sel_hi:[0,1]
	s_nop 0
	v_cvt_pk_bf16_f32 v66, v70, v71
	v_cvt_pk_bf16_f32 v67, v72, v73
	v_cvt_pk_bf16_f32 v68, v76, v77
	v_cvt_pk_bf16_f32 v69, v74, v75
	global_store_dwordx4 v[78:79], v[66:69], off offset:64 sc1
	s_nop 1
	v_lshlrev_b32_e32 v66, 7, v157
	v_and_b32_e32 v178, 0x3e780, v66
	v_lshl_add_u64 v[70:71], v[138:139], 0, v[178:179]
	v_lshl_add_u64 v[78:79], v[140:141], 0, v[178:179]
	global_load_dwordx4 v[66:69], v[70:71], off offset:16
	s_nop 0
	global_load_dwordx4 v[70:73], v[70:71], off
	s_nop 0
	global_load_dwordx4 v[74:77], v[78:79], off offset:16
	s_nop 0
	global_load_dwordx4 v[78:81], v[78:79], off
	s_waitcnt vmcnt(1)
	v_pk_mul_f32 v[88:89], v[50:51], v[74:75]
	v_pk_mul_f32 v[86:87], v[52:53], v[76:77]
	v_pk_fma_f32 v[88:89], v[58:59], v[66:67], v[88:89] neg_lo:[0,0,1] neg_hi:[0,0,1]
	v_pk_mul_f32 v[58:59], v[58:59], v[74:75]
	v_pk_fma_f32 v[86:87], v[60:61], v[68:69], v[86:87] neg_lo:[0,0,1] neg_hi:[0,0,1]
	v_pk_mul_f32 v[60:61], v[60:61], v[76:77]
	v_pk_fma_f32 v[50:51], v[50:51], v[66:67], v[58:59]
	v_pk_fma_f32 v[52:53], v[52:53], v[68:69], v[60:61]
	v_pk_mul_f32 v[60:61], v[148:149], v[50:51] op_sel_hi:[0,1]
	v_mad_i64_i32 v[50:51], s[0:1], v157, s15, v[114:115]
	s_waitcnt vmcnt(0)
	v_pk_mul_f32 v[84:85], v[54:55], v[78:79]
	v_lshl_add_u64 v[50:51], v[50:51], 0, s[28:29]
	v_pk_mul_f32 v[82:83], v[56:57], v[80:81]
	v_pk_fma_f32 v[84:85], v[62:63], v[70:71], v[84:85] neg_lo:[0,0,1] neg_hi:[0,0,1]
	v_pk_mul_f32 v[62:63], v[62:63], v[78:79]
	v_lshl_add_u64 v[50:51], v[50:51], 0, s[82:83]
	v_pk_fma_f32 v[82:83], v[64:65], v[72:73], v[82:83] neg_lo:[0,0,1] neg_hi:[0,0,1]
	v_pk_mul_f32 v[84:85], v[148:149], v[84:85] op_sel_hi:[0,1]
	v_pk_mul_f32 v[64:65], v[64:65], v[80:81]
	v_pk_fma_f32 v[54:55], v[54:55], v[70:71], v[62:63]
	v_lshl_add_u64 v[62:63], v[50:51], 0, v[146:147]
	v_cvt_pk_bf16_f32 v50, v84, v85
	v_pk_mul_f32 v[82:83], v[148:149], v[82:83] op_sel_hi:[0,1]
	v_pk_mul_f32 v[86:87], v[148:149], v[86:87] op_sel_hi:[0,1]
	v_pk_mul_f32 v[88:89], v[148:149], v[88:89] op_sel_hi:[0,1]
	v_pk_fma_f32 v[56:57], v[56:57], v[72:73], v[64:65]
	v_pk_mul_f32 v[54:55], v[148:149], v[54:55] op_sel_hi:[0,1]
	v_pk_mul_f32 v[58:59], v[148:149], v[52:53] op_sel_hi:[0,1]
	v_cvt_pk_bf16_f32 v51, v82, v83
	v_cvt_pk_bf16_f32 v52, v88, v89
	v_cvt_pk_bf16_f32 v53, v86, v87
	global_store_dwordx4 v[62:63], v[50:53], off sc1
	v_pk_mul_f32 v[56:57], v[148:149], v[56:57] op_sel_hi:[0,1]
	s_nop 0
	v_cvt_pk_bf16_f32 v50, v54, v55
	v_cvt_pk_bf16_f32 v51, v56, v57
	v_cvt_pk_bf16_f32 v52, v60, v61
	v_cvt_pk_bf16_f32 v53, v58, v59
	global_store_dwordx4 v[62:63], v[50:53], off offset:64 sc1
	s_nop 1
	v_lshlrev_b32_e32 v50, 7, v156
	v_and_b32_e32 v178, 0x3ef80, v50
	v_lshl_add_u64 v[54:55], v[138:139], 0, v[178:179]
	v_lshl_add_u64 v[62:63], v[140:141], 0, v[178:179]
	global_load_dwordx4 v[50:53], v[54:55], off offset:16
	s_nop 0
	global_load_dwordx4 v[54:57], v[54:55], off
	s_nop 0
	global_load_dwordx4 v[58:61], v[62:63], off offset:16
	s_nop 0
	global_load_dwordx4 v[62:65], v[62:63], off
	s_waitcnt vmcnt(1)
	v_pk_mul_f32 v[72:73], v[34:35], v[58:59]
	v_pk_mul_f32 v[70:71], v[36:37], v[60:61]
	v_pk_fma_f32 v[72:73], v[42:43], v[50:51], v[72:73] neg_lo:[0,0,1] neg_hi:[0,0,1]
	v_pk_mul_f32 v[42:43], v[42:43], v[58:59]
	v_pk_fma_f32 v[70:71], v[44:45], v[52:53], v[70:71] neg_lo:[0,0,1] neg_hi:[0,0,1]
	v_pk_mul_f32 v[44:45], v[44:45], v[60:61]
	v_pk_fma_f32 v[34:35], v[34:35], v[50:51], v[42:43]
	v_pk_fma_f32 v[36:37], v[36:37], v[52:53], v[44:45]
	v_pk_mul_f32 v[44:45], v[148:149], v[34:35] op_sel_hi:[0,1]
	v_mad_i64_i32 v[34:35], s[0:1], v156, s15, v[114:115]
	s_waitcnt vmcnt(0)
	v_pk_mul_f32 v[68:69], v[38:39], v[62:63]
	v_lshl_add_u64 v[34:35], v[34:35], 0, s[28:29]
	v_pk_mul_f32 v[66:67], v[40:41], v[64:65]
	v_pk_fma_f32 v[68:69], v[46:47], v[54:55], v[68:69] neg_lo:[0,0,1] neg_hi:[0,0,1]
	v_pk_mul_f32 v[46:47], v[46:47], v[62:63]
	v_lshl_add_u64 v[34:35], v[34:35], 0, s[82:83]
	v_pk_fma_f32 v[66:67], v[48:49], v[56:57], v[66:67] neg_lo:[0,0,1] neg_hi:[0,0,1]
	v_pk_mul_f32 v[68:69], v[148:149], v[68:69] op_sel_hi:[0,1]
	v_pk_mul_f32 v[48:49], v[48:49], v[64:65]
	v_pk_fma_f32 v[38:39], v[38:39], v[54:55], v[46:47]
	v_lshl_add_u64 v[46:47], v[34:35], 0, v[146:147]
	v_cvt_pk_bf16_f32 v34, v68, v69
	v_pk_mul_f32 v[66:67], v[148:149], v[66:67] op_sel_hi:[0,1]
	v_pk_mul_f32 v[70:71], v[148:149], v[70:71] op_sel_hi:[0,1]
	v_pk_mul_f32 v[72:73], v[148:149], v[72:73] op_sel_hi:[0,1]
	v_pk_fma_f32 v[40:41], v[40:41], v[56:57], v[48:49]
	v_pk_mul_f32 v[38:39], v[148:149], v[38:39] op_sel_hi:[0,1]
	v_pk_mul_f32 v[42:43], v[148:149], v[36:37] op_sel_hi:[0,1]
	v_cvt_pk_bf16_f32 v35, v66, v67
	v_cvt_pk_bf16_f32 v36, v72, v73
	v_cvt_pk_bf16_f32 v37, v70, v71
	global_store_dwordx4 v[46:47], v[34:37], off sc1
	v_pk_mul_f32 v[40:41], v[148:149], v[40:41] op_sel_hi:[0,1]
	s_nop 0
	v_cvt_pk_bf16_f32 v34, v38, v39
	v_cvt_pk_bf16_f32 v35, v40, v41
	v_cvt_pk_bf16_f32 v36, v44, v45
	v_cvt_pk_bf16_f32 v37, v42, v43
	global_store_dwordx4 v[46:47], v[34:37], off offset:64 sc1
	s_nop 1
	v_lshlrev_b32_e32 v34, 7, v155
	v_and_b32_e32 v178, 0x3f780, v34
	v_lshl_add_u64 v[38:39], v[138:139], 0, v[178:179]
	v_lshl_add_u64 v[46:47], v[140:141], 0, v[178:179]
	global_load_dwordx4 v[34:37], v[38:39], off offset:16
	s_nop 0
	global_load_dwordx4 v[38:41], v[38:39], off
	s_nop 0
	global_load_dwordx4 v[42:45], v[46:47], off offset:16
	s_nop 0
	global_load_dwordx4 v[46:49], v[46:47], off
	s_waitcnt vmcnt(1)
	v_pk_mul_f32 v[56:57], v[18:19], v[42:43]
	v_pk_mul_f32 v[54:55], v[20:21], v[44:45]
	v_pk_fma_f32 v[56:57], v[26:27], v[34:35], v[56:57] neg_lo:[0,0,1] neg_hi:[0,0,1]
	v_pk_mul_f32 v[26:27], v[26:27], v[42:43]
	v_pk_fma_f32 v[54:55], v[28:29], v[36:37], v[54:55] neg_lo:[0,0,1] neg_hi:[0,0,1]
	v_pk_mul_f32 v[28:29], v[28:29], v[44:45]
	v_pk_fma_f32 v[18:19], v[18:19], v[34:35], v[26:27]
	v_pk_fma_f32 v[20:21], v[20:21], v[36:37], v[28:29]
	v_pk_mul_f32 v[28:29], v[148:149], v[18:19] op_sel_hi:[0,1]
	v_mad_i64_i32 v[18:19], s[0:1], v155, s15, v[114:115]
	s_waitcnt vmcnt(0)
	v_pk_mul_f32 v[52:53], v[22:23], v[46:47]
	v_lshl_add_u64 v[18:19], v[18:19], 0, s[28:29]
	v_pk_mul_f32 v[50:51], v[24:25], v[48:49]
	v_pk_fma_f32 v[52:53], v[30:31], v[38:39], v[52:53] neg_lo:[0,0,1] neg_hi:[0,0,1]
	v_pk_mul_f32 v[30:31], v[30:31], v[46:47]
	v_lshl_add_u64 v[18:19], v[18:19], 0, s[82:83]
	v_pk_fma_f32 v[50:51], v[32:33], v[40:41], v[50:51] neg_lo:[0,0,1] neg_hi:[0,0,1]
	v_pk_mul_f32 v[52:53], v[148:149], v[52:53] op_sel_hi:[0,1]
	v_pk_mul_f32 v[32:33], v[32:33], v[48:49]
	v_pk_fma_f32 v[22:23], v[22:23], v[38:39], v[30:31]
	v_lshl_add_u64 v[30:31], v[18:19], 0, v[146:147]
	v_cvt_pk_bf16_f32 v18, v52, v53
	v_pk_mul_f32 v[50:51], v[148:149], v[50:51] op_sel_hi:[0,1]
	v_pk_mul_f32 v[54:55], v[148:149], v[54:55] op_sel_hi:[0,1]
	v_pk_mul_f32 v[56:57], v[148:149], v[56:57] op_sel_hi:[0,1]
	v_pk_fma_f32 v[24:25], v[24:25], v[40:41], v[32:33]
	v_pk_mul_f32 v[22:23], v[148:149], v[22:23] op_sel_hi:[0,1]
	v_pk_mul_f32 v[26:27], v[148:149], v[20:21] op_sel_hi:[0,1]
	v_cvt_pk_bf16_f32 v19, v50, v51
	v_cvt_pk_bf16_f32 v20, v56, v57
	v_cvt_pk_bf16_f32 v21, v54, v55
	global_store_dwordx4 v[30:31], v[18:21], off sc1
	v_pk_mul_f32 v[24:25], v[148:149], v[24:25] op_sel_hi:[0,1]
	s_nop 0
	v_cvt_pk_bf16_f32 v18, v22, v23
	v_cvt_pk_bf16_f32 v19, v24, v25
	v_cvt_pk_bf16_f32 v20, v28, v29
	v_cvt_pk_bf16_f32 v21, v26, v27
	global_store_dwordx4 v[30:31], v[18:21], off offset:64 sc1
	s_nop 1
	v_lshlrev_b32_e32 v18, 7, v154
	v_and_b32_e32 v178, 0x3ff80, v18
	v_lshl_add_u64 v[18:19], v[138:139], 0, v[178:179]
	global_load_dwordx4 v[22:25], v[18:19], off offset:16
	global_load_dwordx4 v[26:29], v[18:19], off
	v_lshl_add_u64 v[18:19], v[140:141], 0, v[178:179]
	global_load_dwordx4 v[30:33], v[18:19], off offset:16
	global_load_dwordx4 v[34:37], v[18:19], off
	s_waitcnt vmcnt(1)
	v_pk_mul_f32 v[40:41], v[2:3], v[30:31]
	s_waitcnt vmcnt(0)
	v_pk_mul_f32 v[20:21], v[6:7], v[34:35]
	v_pk_fma_f32 v[40:41], v[10:11], v[22:23], v[40:41] neg_lo:[0,0,1] neg_hi:[0,0,1]
	v_pk_fma_f32 v[20:21], v[14:15], v[26:27], v[20:21] neg_lo:[0,0,1] neg_hi:[0,0,1]
	v_pk_mul_f32 v[10:11], v[10:11], v[30:31]
	v_pk_mul_f32 v[38:39], v[148:149], v[20:21] op_sel_hi:[0,1]
	v_pk_mul_f32 v[20:21], v[4:5], v[32:33]
	v_pk_fma_f32 v[10:11], v[2:3], v[22:23], v[10:11]
	v_pk_fma_f32 v[20:21], v[12:13], v[24:25], v[20:21] neg_lo:[0,0,1] neg_hi:[0,0,1]
	v_pk_mul_f32 v[12:13], v[12:13], v[32:33]
	v_pk_mul_f32 v[18:19], v[8:9], v[36:37]
	v_pk_fma_f32 v[4:5], v[4:5], v[24:25], v[12:13]
	v_pk_fma_f32 v[18:19], v[16:17], v[28:29], v[18:19] neg_lo:[0,0,1] neg_hi:[0,0,1]
	v_pk_mul_f32 v[2:3], v[148:149], v[4:5] op_sel_hi:[0,1]
	v_pk_mul_f32 v[4:5], v[148:149], v[10:11] op_sel_hi:[0,1]
	v_mad_i64_i32 v[10:11], s[0:1], v154, s15, v[114:115]
	v_pk_mul_f32 v[16:17], v[16:17], v[36:37]
	v_pk_mul_f32 v[14:15], v[14:15], v[34:35]
	v_lshl_add_u64 v[10:11], v[10:11], 0, s[28:29]
	v_pk_fma_f32 v[8:9], v[8:9], v[28:29], v[16:17]
	v_pk_fma_f32 v[14:15], v[6:7], v[26:27], v[14:15]
	v_lshl_add_u64 v[10:11], v[10:11], 0, s[82:83]
	v_pk_mul_f32 v[18:19], v[148:149], v[18:19] op_sel_hi:[0,1]
	v_pk_mul_f32 v[6:7], v[148:149], v[8:9] op_sel_hi:[0,1]
	v_pk_mul_f32 v[8:9], v[148:149], v[14:15] op_sel_hi:[0,1]
	v_lshl_add_u64 v[14:15], v[10:11], 0, v[146:147]
	v_cvt_pk_bf16_f32 v10, v38, v39
	v_cvt_pk_bf16_f32 v11, v18, v19
	v_pk_mul_f32 v[20:21], v[148:149], v[20:21] op_sel_hi:[0,1]
	v_pk_mul_f32 v[40:41], v[148:149], v[40:41] op_sel_hi:[0,1]
	v_cvt_pk_bf16_f32 v12, v40, v41
	v_cvt_pk_bf16_f32 v13, v20, v21
	global_store_dwordx4 v[14:15], v[10:13], off sc1
	v_cvt_pk_bf16_f32 v8, v8, v9
	v_cvt_pk_bf16_f32 v9, v6, v7
	s_nop 1
	v_cvt_pk_bf16_f32 v10, v4, v5
	v_cvt_pk_bf16_f32 v11, v2, v3
	global_store_dwordx4 v[14:15], v[8:11], off offset:64 sc1
	s_andn2_b64 vcc, exec, s[4:5]
	s_mov_b64 s[0:1], -1
	s_cbranch_vccnz .LBB0_211

.LBB0_258:
	s_andn2_saveexec_b64 s[4:5], s[4:5]
	s_cbranch_execz .LBB0_278
	s_mov_b64 s[4:5], exec
	s_waitcnt lgkmcnt(0)
	s_waitcnt vmcnt(0)
	v_mbcnt_lo_u32_b32 v3, s4, 0
	v_mbcnt_hi_u32_b32 v3, s5, v3
	v_cmp_eq_u32_e32 vcc, 0, v3
	s_and_saveexec_b64 s[6:7], vcc
	s_cbranch_execz .LBB0_261
	s_bcnt1_i32_b64 s4, s[4:5]
	v_mov_b32_e32 v4, s4
	v_readlane_b32 s4, v253, 60
	v_readlane_b32 s5, v253, 61
	s_nop 4
	global_atomic_add v4, v179, v4, s[4:5] sc0

.LBB0_289:
	s_cmpk_gt_u32 s24, 0xff
	s_waitcnt lgkmcnt(0)
	s_barrier
	s_cbranch_scc1 .LBB0_280
	ds_read2st64_b32 v[10:11], v104 offset1:1
	ds_read2st64_b32 v[14:15], v104 offset0:16 offset1:17
	ds_read2st64_b32 v[20:21], v104 offset0:32 offset1:33
	ds_read2st64_b32 v[22:23], v104 offset0:48 offset1:49
	s_mov_b32 s0, 0x3727c5ac
	v_lshlrev_b32_e32 v178, 1, v162
	s_waitcnt lgkmcnt(3)
	v_mov_b32_e32 v8, v10
	s_waitcnt lgkmcnt(2)
	v_mov_b32_e32 v9, v14
	v_mov_b32_e32 v14, v11
	v_pk_fma_f32 v[12:13], s[6:7], v[8:9], v[92:93] neg_lo:[1,0,0] neg_hi:[1,0,0]
	s_waitcnt lgkmcnt(1)
	v_mov_b32_e32 v8, v20
	s_waitcnt lgkmcnt(0)
	v_mov_b32_e32 v9, v22
	v_pk_fma_f32 v[14:15], s[6:7], v[14:15], v[96:97] neg_lo:[1,0,0] neg_hi:[1,0,0]
	v_mov_b32_e32 v22, v21
	v_pk_mul_f32 v[16:17], v[12:13], v[12:13]
	v_pk_fma_f32 v[8:9], s[6:7], v[8:9], v[94:95] neg_lo:[1,0,0] neg_hi:[1,0,0]
	v_pk_mul_f32 v[28:29], v[14:15], v[14:15]
	v_pk_fma_f32 v[10:11], s[6:7], v[22:23], v[98:99] neg_lo:[1,0,0] neg_hi:[1,0,0]
	v_pk_mul_f32 v[24:25], v[8:9], v[8:9]
	v_pk_mul_f32 v[20:21], v[10:11], v[10:11]
	v_mov_b32_e32 v22, v28
	v_mov_b32_e32 v23, v16
	v_mov_b32_e32 v16, v29
	v_pk_add_f32 v[16:17], v[22:23], v[16:17]
	v_mov_b32_e32 v22, v20
	v_mov_b32_e32 v23, v24
	v_pk_add_f32 v[16:17], v[16:17], v[22:23]
	v_mov_b32_e32 v24, v21
	v_pk_add_f32 v[16:17], v[16:17], v[24:25]
	ds_bpermute_b32 v21, v163, v17
	ds_bpermute_b32 v20, v163, v16
	ds_read2st64_b32 v[24:25], v104 offset0:2 offset1:3
	ds_read2st64_b32 v[28:29], v104 offset0:18 offset1:19
	ds_read2st64_b32 v[32:33], v104 offset0:34 offset1:35
	ds_read2st64_b32 v[46:47], v104 offset0:50 offset1:51
	s_waitcnt lgkmcnt(4)
	v_pk_add_f32 v[16:17], v[16:17], v[20:21]
	ds_bpermute_b32 v21, v165, v17
	ds_bpermute_b32 v20, v165, v16
	s_waitcnt lgkmcnt(0)
	v_pk_add_f32 v[16:17], v[16:17], v[20:21]
	ds_bpermute_b32 v21, v168, v17
	ds_bpermute_b32 v20, v168, v16
	s_waitcnt lgkmcnt(0)
	v_pk_add_f32 v[16:17], v[16:17], v[20:21]
	ds_bpermute_b32 v21, v169, v17
	ds_bpermute_b32 v20, v169, v16
	s_waitcnt lgkmcnt(0)
	v_pk_add_f32 v[16:17], v[16:17], v[20:21]
	ds_bpermute_b32 v21, v170, v17
	ds_bpermute_b32 v20, v170, v16
	s_waitcnt lgkmcnt(0)
	v_pk_add_f32 v[16:17], v[16:17], v[20:21]
	v_mov_b64_e32 v[20:21], s[0:1]
	v_pk_fma_f32 v[16:17], v[16:17], s[42:43], v[20:21] op_sel_hi:[1,0,0]
	s_lshl_b32 s0, s23, 14
	v_mul_f32_e32 v22, 0x4b800000, v17
	v_cmp_gt_f32_e64 s[4:5], s41, v17
	v_cmp_gt_f32_e32 vcc, s41, v16
	s_add_i32 s0, s0, 0
	v_cndmask_b32_e64 v17, v17, v22, s[4:5]
	v_rsq_f32_e32 v17, v17
	s_nop 0
	v_mul_f32_e32 v22, 0x45800000, v17
	v_cndmask_b32_e64 v17, v17, v22, s[4:5]
	v_mul_f32_e32 v92, v171, v17
	v_mul_f32_e32 v17, 0x4b800000, v16
	v_cndmask_b32_e32 v16, v16, v17, vcc
	v_rsq_f32_e32 v16, v16
	v_mul_f32_e32 v12, v12, v92
	s_waitcnt vmcnt(3)
	v_mul_f32_e32 v12, v103, v12
	v_mul_f32_e32 v17, 0x45800000, v16
	v_cndmask_b32_e32 v16, v16, v17, vcc
	v_mul_f32_e32 v93, v171, v16
	v_mov_b32_e32 v16, v24
	v_mov_b32_e32 v17, v28
	v_mov_b32_e32 v28, v25
	v_pk_fma_f32 v[22:23], s[6:7], v[16:17], v[90:91] neg_lo:[1,0,0] neg_hi:[1,0,0]
	v_mov_b32_e32 v16, v32
	v_mov_b32_e32 v17, v46
	v_pk_fma_f32 v[24:25], s[6:7], v[28:29], v[88:89] neg_lo:[1,0,0] neg_hi:[1,0,0]
	v_mov_b32_e32 v46, v33
	v_pk_mul_f32 v[30:31], v[22:23], v[22:23]
	v_pk_fma_f32 v[16:17], s[6:7], v[16:17], v[18:19] neg_lo:[1,0,0] neg_hi:[1,0,0]
	v_pk_mul_f32 v[28:29], v[24:25], v[24:25]
	v_pk_fma_f32 v[18:19], s[6:7], v[46:47], v[86:87] neg_lo:[1,0,0] neg_hi:[1,0,0]
	v_pk_mul_f32 v[48:49], v[16:17], v[16:17]
	v_pk_mul_f32 v[32:33], v[18:19], v[18:19]
	v_mov_b32_e32 v46, v28
	v_mov_b32_e32 v47, v30
	v_mov_b32_e32 v30, v29
	v_pk_add_f32 v[28:29], v[46:47], v[30:31]
	v_mov_b32_e32 v30, v32
	v_mov_b32_e32 v31, v48
	v_pk_add_f32 v[28:29], v[28:29], v[30:31]
	v_mov_b32_e32 v48, v33
	v_pk_add_f32 v[28:29], v[28:29], v[48:49]
	ds_bpermute_b32 v31, v163, v29
	ds_bpermute_b32 v30, v163, v28
	s_waitcnt lgkmcnt(0)
	v_pk_add_f32 v[28:29], v[28:29], v[30:31]
	ds_bpermute_b32 v31, v165, v29
	ds_bpermute_b32 v30, v165, v28
	s_waitcnt lgkmcnt(0)
	v_pk_add_f32 v[28:29], v[28:29], v[30:31]
	ds_bpermute_b32 v31, v168, v29
	ds_bpermute_b32 v30, v168, v28
	s_waitcnt lgkmcnt(0)
	v_pk_add_f32 v[28:29], v[28:29], v[30:31]
	ds_bpermute_b32 v31, v169, v29
	ds_bpermute_b32 v30, v169, v28
	s_waitcnt lgkmcnt(0)
	v_pk_add_f32 v[28:29], v[28:29], v[30:31]
	ds_bpermute_b32 v31, v170, v29
	ds_bpermute_b32 v30, v170, v28
	s_waitcnt lgkmcnt(0)
	v_pk_add_f32 v[28:29], v[28:29], v[30:31]
	s_nop 0
	v_pk_fma_f32 v[28:29], v[28:29], s[42:43], v[20:21] op_sel_hi:[1,0,0]
	s_nop 0
	v_mul_f32_e32 v30, 0x4b800000, v29
	v_cmp_gt_f32_e64 s[4:5], s41, v29
	v_cmp_gt_f32_e32 vcc, s41, v28
	s_nop 0
	v_cndmask_b32_e64 v29, v29, v30, s[4:5]
	v_rsq_f32_e32 v29, v29
	s_nop 0
	v_mul_f32_e32 v30, 0x45800000, v29
	v_cndmask_b32_e64 v29, v29, v30, s[4:5]
	v_mul_f32_e32 v86, v171, v29
	v_mul_f32_e32 v29, 0x4b800000, v28
	v_cndmask_b32_e32 v28, v28, v29, vcc
	v_rsq_f32_e32 v28, v28
	ds_read2st64_b32 v[30:31], v104 offset0:4 offset1:5
	ds_read2st64_b32 v[46:47], v104 offset0:20 offset1:21
	ds_read2st64_b32 v[58:59], v104 offset0:36 offset1:37
	ds_read2st64_b32 v[60:61], v104 offset0:52 offset1:53
	v_mul_f32_e32 v29, 0x45800000, v28
	v_cndmask_b32_e32 v28, v28, v29, vcc
	v_mul_f32_e32 v87, v171, v28
	s_waitcnt lgkmcnt(3)
	v_mov_b32_e32 v28, v30
	s_waitcnt lgkmcnt(2)
	v_mov_b32_e32 v29, v46
	v_pk_fma_f32 v[32:33], s[6:7], v[28:29], v[84:85] neg_lo:[1,0,0] neg_hi:[1,0,0]
	s_waitcnt lgkmcnt(1)
	v_mov_b32_e32 v28, v58
	s_waitcnt lgkmcnt(0)
	v_mov_b32_e32 v29, v60
	v_mov_b32_e32 v46, v31
	v_pk_fma_f32 v[28:29], s[6:7], v[28:29], v[34:35] neg_lo:[1,0,0] neg_hi:[1,0,0]
	v_pk_fma_f32 v[34:35], s[6:7], v[46:47], v[82:83] neg_lo:[1,0,0] neg_hi:[1,0,0]
	v_mov_b32_e32 v60, v59
	v_pk_mul_f32 v[48:49], v[32:33], v[32:33]
	v_pk_mul_f32 v[46:47], v[34:35], v[34:35]
	v_pk_fma_f32 v[30:31], s[6:7], v[60:61], v[80:81] neg_lo:[1,0,0] neg_hi:[1,0,0]
	v_pk_mul_f32 v[62:63], v[28:29], v[28:29]
	v_pk_mul_f32 v[58:59], v[30:31], v[30:31]
	v_mov_b32_e32 v60, v46
	v_mov_b32_e32 v61, v48
	v_mov_b32_e32 v48, v47
	v_pk_add_f32 v[46:47], v[60:61], v[48:49]
	v_mov_b32_e32 v48, v58
	v_mov_b32_e32 v49, v62
	v_pk_add_f32 v[46:47], v[46:47], v[48:49]
	v_mov_b32_e32 v62, v59
	v_pk_add_f32 v[46:47], v[46:47], v[62:63]
	ds_bpermute_b32 v49, v163, v47
	ds_bpermute_b32 v48, v163, v46
	ds_read2st64_b32 v[58:59], v104 offset0:6 offset1:7
	ds_read2st64_b32 v[60:61], v104 offset0:22 offset1:23
	s_waitcnt lgkmcnt(2)
	v_pk_add_f32 v[46:47], v[46:47], v[48:49]
	ds_bpermute_b32 v49, v165, v47
	ds_bpermute_b32 v48, v165, v46
	s_waitcnt lgkmcnt(0)
	v_pk_add_f32 v[46:47], v[46:47], v[48:49]
	ds_bpermute_b32 v49, v168, v47
	ds_bpermute_b32 v48, v168, v46
	s_waitcnt lgkmcnt(0)
	v_pk_add_f32 v[46:47], v[46:47], v[48:49]
	ds_bpermute_b32 v49, v169, v47
	ds_bpermute_b32 v48, v169, v46
	s_waitcnt lgkmcnt(0)
	v_pk_add_f32 v[46:47], v[46:47], v[48:49]
	ds_bpermute_b32 v49, v170, v47
	ds_bpermute_b32 v48, v170, v46
	s_waitcnt lgkmcnt(0)
	v_pk_add_f32 v[46:47], v[46:47], v[48:49]
	s_nop 0
	v_pk_fma_f32 v[46:47], v[46:47], s[42:43], v[20:21] op_sel_hi:[1,0,0]
	s_nop 0
	v_mul_f32_e32 v48, 0x4b800000, v47
	v_cmp_gt_f32_e64 s[4:5], s41, v47
	v_cmp_gt_f32_e32 vcc, s41, v46
	s_nop 0
	v_cndmask_b32_e64 v47, v47, v48, s[4:5]
	v_rsq_f32_e32 v47, v47
	s_nop 0
	v_mul_f32_e32 v48, 0x45800000, v47
	v_cndmask_b32_e64 v47, v47, v48, s[4:5]
	v_mul_f32_e32 v80, v171, v47
	v_mul_f32_e32 v47, 0x4b800000, v46
	v_cndmask_b32_e32 v46, v46, v47, vcc
	v_rsq_f32_e32 v46, v46
	s_nop 0
	v_mul_f32_e32 v47, 0x45800000, v46
	v_cndmask_b32_e32 v46, v46, v47, vcc
	v_mul_f32_e32 v81, v171, v46
	v_mov_b32_e32 v46, v58
	v_mov_b32_e32 v47, v60
	v_pk_fma_f32 v[46:47], s[6:7], v[46:47], v[78:79] neg_lo:[1,0,0] neg_hi:[1,0,0]
	ds_read2st64_b32 v[64:65], v104 offset0:38 offset1:39
	ds_read2st64_b32 v[78:79], v104 offset0:54 offset1:55
	v_mov_b32_e32 v60, v59
	v_pk_fma_f32 v[60:61], s[6:7], v[60:61], v[74:75] neg_lo:[1,0,0] neg_hi:[1,0,0]
	v_pk_mul_f32 v[62:63], v[46:47], v[46:47]
	s_waitcnt lgkmcnt(1)
	v_mov_b32_e32 v48, v64
	s_waitcnt lgkmcnt(0)
	v_mov_b32_e32 v49, v78
	v_mov_b32_e32 v78, v65
	v_pk_fma_f32 v[48:49], s[6:7], v[48:49], v[76:77] neg_lo:[1,0,0] neg_hi:[1,0,0]
	v_pk_mul_f32 v[74:75], v[60:61], v[60:61]
	v_pk_fma_f32 v[58:59], s[6:7], v[78:79], v[72:73] neg_lo:[1,0,0] neg_hi:[1,0,0]
	v_pk_mul_f32 v[76:77], v[48:49], v[48:49]
	v_pk_mul_f32 v[64:65], v[58:59], v[58:59]
	v_mov_b32_e32 v72, v74
	v_mov_b32_e32 v73, v62
	v_mov_b32_e32 v62, v75
	v_pk_add_f32 v[62:63], v[72:73], v[62:63]
	v_mov_b32_e32 v72, v64
	v_mov_b32_e32 v73, v76
	v_pk_add_f32 v[62:63], v[62:63], v[72:73]
	v_mov_b32_e32 v76, v65
	v_pk_add_f32 v[62:63], v[62:63], v[76:77]
	ds_bpermute_b32 v65, v163, v63
	ds_bpermute_b32 v64, v163, v62
	ds_read2st64_b32 v[72:73], v104 offset0:8 offset1:9
	ds_read2st64_b32 v[74:75], v104 offset0:24 offset1:25
	ds_read2st64_b32 v[76:77], v104 offset0:40 offset1:41
	ds_read2st64_b32 v[82:83], v104 offset0:56 offset1:57
	s_waitcnt lgkmcnt(4)
	v_pk_add_f32 v[62:63], v[62:63], v[64:65]
	ds_bpermute_b32 v65, v165, v63
	ds_bpermute_b32 v64, v165, v62
	s_waitcnt lgkmcnt(0)
	v_pk_add_f32 v[62:63], v[62:63], v[64:65]
	ds_bpermute_b32 v65, v168, v63
	ds_bpermute_b32 v64, v168, v62
	s_waitcnt lgkmcnt(0)
	v_pk_add_f32 v[62:63], v[62:63], v[64:65]
	ds_bpermute_b32 v65, v169, v63
	ds_bpermute_b32 v64, v169, v62
	s_waitcnt lgkmcnt(0)
	v_pk_add_f32 v[62:63], v[62:63], v[64:65]
	ds_bpermute_b32 v65, v170, v63
	ds_bpermute_b32 v64, v170, v62
	s_waitcnt lgkmcnt(0)
	v_pk_add_f32 v[62:63], v[62:63], v[64:65]
	s_nop 0
	v_pk_fma_f32 v[62:63], v[62:63], s[42:43], v[20:21] op_sel_hi:[1,0,0]
	s_nop 0
	v_mul_f32_e32 v64, 0x4b800000, v63
	v_cmp_gt_f32_e64 s[4:5], s41, v63
	v_cmp_gt_f32_e32 vcc, s41, v62
	s_nop 0
	v_cndmask_b32_e64 v63, v63, v64, s[4:5]
	v_rsq_f32_e32 v63, v63
	s_nop 0
	v_mul_f32_e32 v64, 0x45800000, v63
	v_cndmask_b32_e64 v63, v63, v64, s[4:5]
	v_mul_f32_e32 v78, v171, v63
	v_mul_f32_e32 v63, 0x4b800000, v62
	v_cndmask_b32_e32 v62, v62, v63, vcc
	v_rsq_f32_e32 v62, v62
	s_nop 0
	v_mul_f32_e32 v63, 0x45800000, v62
	v_cndmask_b32_e32 v62, v62, v63, vcc
	v_mul_f32_e32 v79, v171, v62
	v_mov_b32_e32 v62, v72
	v_mov_b32_e32 v63, v74
	v_pk_fma_f32 v[64:65], s[6:7], v[62:63], v[70:71] neg_lo:[1,0,0] neg_hi:[1,0,0]
	v_mov_b32_e32 v62, v76
	v_mov_b32_e32 v63, v82
	v_mov_b32_e32 v74, v73
	v_pk_fma_f32 v[62:63], s[6:7], v[62:63], v[66:67] neg_lo:[1,0,0] neg_hi:[1,0,0]
	v_pk_fma_f32 v[66:67], s[6:7], v[74:75], v[68:69] neg_lo:[1,0,0] neg_hi:[1,0,0]
	v_mov_b32_e32 v82, v77
	v_pk_mul_f32 v[70:71], v[64:65], v[64:65]
	v_pk_mul_f32 v[68:69], v[66:67], v[66:67]
	v_pk_fma_f32 v[56:57], s[6:7], v[82:83], v[56:57] neg_lo:[1,0,0] neg_hi:[1,0,0]
	v_pk_mul_f32 v[84:85], v[62:63], v[62:63]
	v_pk_mul_f32 v[72:73], v[56:57], v[56:57]
	v_mov_b32_e32 v74, v68
	v_mov_b32_e32 v75, v70
	v_mov_b32_e32 v70, v69
	v_pk_add_f32 v[68:69], v[74:75], v[70:71]
	v_mov_b32_e32 v70, v72
	v_mov_b32_e32 v71, v84
	v_pk_add_f32 v[68:69], v[68:69], v[70:71]
	v_mov_b32_e32 v84, v73
	v_pk_add_f32 v[68:69], v[68:69], v[84:85]
	ds_bpermute_b32 v71, v163, v69
	ds_bpermute_b32 v70, v163, v68
	s_waitcnt lgkmcnt(0)
	v_pk_add_f32 v[68:69], v[68:69], v[70:71]
	ds_bpermute_b32 v71, v165, v69
	ds_bpermute_b32 v70, v165, v68
	s_waitcnt lgkmcnt(0)
	v_pk_add_f32 v[68:69], v[68:69], v[70:71]
	ds_bpermute_b32 v71, v168, v69
	ds_bpermute_b32 v70, v168, v68
	s_waitcnt lgkmcnt(0)
	v_pk_add_f32 v[68:69], v[68:69], v[70:71]
	ds_bpermute_b32 v71, v169, v69
	ds_bpermute_b32 v70, v169, v68
	s_waitcnt lgkmcnt(0)
	v_pk_add_f32 v[68:69], v[68:69], v[70:71]
	ds_bpermute_b32 v71, v170, v69
	ds_bpermute_b32 v70, v170, v68
	s_waitcnt lgkmcnt(0)
	v_pk_add_f32 v[68:69], v[68:69], v[70:71]
	s_nop 0
	v_pk_fma_f32 v[68:69], v[68:69], s[42:43], v[20:21] op_sel_hi:[1,0,0]
	s_nop 0
	v_mul_f32_e32 v70, 0x4b800000, v69
	v_cmp_gt_f32_e64 s[4:5], s41, v69
	v_cmp_gt_f32_e32 vcc, s41, v68
	s_nop 0
	v_cndmask_b32_e64 v69, v69, v70, s[4:5]
	v_rsq_f32_e32 v69, v69
	s_nop 0
	v_mul_f32_e32 v70, 0x45800000, v69
	v_cndmask_b32_e64 v69, v69, v70, s[4:5]
	v_mul_f32_e32 v82, v171, v69
	v_mul_f32_e32 v69, 0x4b800000, v68
	v_cndmask_b32_e32 v68, v68, v69, vcc
	v_rsq_f32_e32 v68, v68
	s_nop 0
	v_mul_f32_e32 v69, 0x45800000, v68
	v_cndmask_b32_e32 v68, v68, v69, vcc
	v_mul_f32_e32 v83, v171, v68
	ds_read2st64_b32 v[68:69], v104 offset0:10 offset1:11
	ds_read2st64_b32 v[70:71], v104 offset0:26 offset1:27
	ds_read2st64_b32 v[74:75], v104 offset0:42 offset1:43
	ds_read2st64_b32 v[76:77], v104 offset0:58 offset1:59
	s_waitcnt lgkmcnt(3)
	v_mov_b32_e32 v72, v68
	s_waitcnt lgkmcnt(2)
	v_mov_b32_e32 v73, v70
	v_mov_b32_e32 v70, v69
	v_pk_fma_f32 v[54:55], s[6:7], v[72:73], v[54:55] neg_lo:[1,0,0] neg_hi:[1,0,0]
	s_waitcnt lgkmcnt(1)
	v_mov_b32_e32 v84, v74
	s_waitcnt lgkmcnt(0)
	v_mov_b32_e32 v85, v76
	v_pk_fma_f32 v[52:53], s[6:7], v[70:71], v[52:53] neg_lo:[1,0,0] neg_hi:[1,0,0]
	v_mov_b32_e32 v76, v75
	v_pk_mul_f32 v[72:73], v[54:55], v[54:55]
	v_pk_fma_f32 v[50:51], s[6:7], v[84:85], v[50:51] neg_lo:[1,0,0] neg_hi:[1,0,0]
	v_pk_mul_f32 v[68:69], v[52:53], v[52:53]
	v_pk_fma_f32 v[44:45], s[6:7], v[76:77], v[44:45] neg_lo:[1,0,0] neg_hi:[1,0,0]
	v_pk_mul_f32 v[84:85], v[50:51], v[50:51]
	v_pk_mul_f32 v[70:71], v[44:45], v[44:45]
	v_mov_b32_e32 v74, v68
	v_mov_b32_e32 v75, v72
	v_mov_b32_e32 v72, v69
	v_pk_add_f32 v[68:69], v[74:75], v[72:73]
	v_mov_b32_e32 v72, v70
	v_mov_b32_e32 v73, v84
	v_pk_add_f32 v[68:69], v[68:69], v[72:73]
	v_mov_b32_e32 v84, v71
	v_pk_add_f32 v[68:69], v[68:69], v[84:85]
	ds_bpermute_b32 v71, v163, v69
	ds_bpermute_b32 v70, v163, v68
	s_waitcnt lgkmcnt(0)
	v_pk_add_f32 v[68:69], v[68:69], v[70:71]
	ds_bpermute_b32 v71, v165, v69
	ds_bpermute_b32 v70, v165, v68
	s_waitcnt lgkmcnt(0)
	v_pk_add_f32 v[68:69], v[68:69], v[70:71]
	ds_bpermute_b32 v71, v168, v69
	ds_bpermute_b32 v70, v168, v68
	s_waitcnt lgkmcnt(0)
	v_pk_add_f32 v[68:69], v[68:69], v[70:71]
	ds_bpermute_b32 v71, v169, v69
	ds_bpermute_b32 v70, v169, v68
	s_waitcnt lgkmcnt(0)
	v_pk_add_f32 v[68:69], v[68:69], v[70:71]
	ds_bpermute_b32 v71, v170, v69
	ds_bpermute_b32 v70, v170, v68
	s_waitcnt lgkmcnt(0)
	v_pk_add_f32 v[68:69], v[68:69], v[70:71]
	s_nop 0
	v_pk_fma_f32 v[68:69], v[68:69], s[42:43], v[20:21] op_sel_hi:[1,0,0]
	s_nop 0
	v_mul_f32_e32 v70, 0x4b800000, v69
	v_cmp_gt_f32_e64 s[4:5], s41, v69
	v_cmp_gt_f32_e32 vcc, s41, v68
	s_nop 0
	v_cndmask_b32_e64 v69, v69, v70, s[4:5]
	v_rsq_f32_e32 v69, v69
	s_nop 0
	v_mul_f32_e32 v70, 0x45800000, v69
	v_cndmask_b32_e64 v69, v69, v70, s[4:5]
	v_mul_f32_e32 v84, v171, v69
	v_mul_f32_e32 v69, 0x4b800000, v68
	v_cndmask_b32_e32 v68, v68, v69, vcc
	v_rsq_f32_e32 v68, v68
	s_nop 0
	v_mul_f32_e32 v69, 0x45800000, v68
	v_cndmask_b32_e32 v68, v68, v69, vcc
	v_mul_f32_e32 v85, v171, v68
	ds_read2st64_b32 v[68:69], v104 offset0:12 offset1:13
	ds_read2st64_b32 v[70:71], v104 offset0:28 offset1:29
	ds_read2st64_b32 v[74:75], v104 offset0:44 offset1:45
	ds_read2st64_b32 v[76:77], v104 offset0:60 offset1:61
	s_waitcnt lgkmcnt(3)
	v_mov_b32_e32 v72, v68
	s_waitcnt lgkmcnt(2)
	v_mov_b32_e32 v73, v70
	v_mov_b32_e32 v70, v69
	v_pk_fma_f32 v[42:43], s[6:7], v[72:73], v[42:43] neg_lo:[1,0,0] neg_hi:[1,0,0]
	s_waitcnt lgkmcnt(1)
	v_mov_b32_e32 v88, v74
	s_waitcnt lgkmcnt(0)
	v_mov_b32_e32 v89, v76
	v_pk_fma_f32 v[40:41], s[6:7], v[70:71], v[40:41] neg_lo:[1,0,0] neg_hi:[1,0,0]
	v_mov_b32_e32 v76, v75
	v_pk_mul_f32 v[72:73], v[42:43], v[42:43]
	v_pk_fma_f32 v[38:39], s[6:7], v[88:89], v[38:39] neg_lo:[1,0,0] neg_hi:[1,0,0]
	v_pk_mul_f32 v[68:69], v[40:41], v[40:41]
	v_pk_fma_f32 v[36:37], s[6:7], v[76:77], v[36:37] neg_lo:[1,0,0] neg_hi:[1,0,0]
	v_pk_mul_f32 v[88:89], v[38:39], v[38:39]
	v_pk_mul_f32 v[70:71], v[36:37], v[36:37]
	v_mov_b32_e32 v74, v68
	v_mov_b32_e32 v75, v72
	v_mov_b32_e32 v72, v69
	v_pk_add_f32 v[68:69], v[74:75], v[72:73]
	v_mov_b32_e32 v72, v70
	v_mov_b32_e32 v73, v88
	v_pk_add_f32 v[68:69], v[68:69], v[72:73]
	v_mov_b32_e32 v88, v71
	v_pk_add_f32 v[68:69], v[68:69], v[88:89]
	ds_bpermute_b32 v71, v163, v69
	ds_bpermute_b32 v70, v163, v68
	s_waitcnt lgkmcnt(0)
	v_pk_add_f32 v[68:69], v[68:69], v[70:71]
	ds_bpermute_b32 v71, v165, v69
	ds_bpermute_b32 v70, v165, v68
	s_waitcnt lgkmcnt(0)
	v_pk_add_f32 v[68:69], v[68:69], v[70:71]
	ds_bpermute_b32 v71, v168, v69
	ds_bpermute_b32 v70, v168, v68
	s_waitcnt lgkmcnt(0)
	v_pk_add_f32 v[68:69], v[68:69], v[70:71]
	ds_bpermute_b32 v71, v169, v69
	ds_bpermute_b32 v70, v169, v68
	s_waitcnt lgkmcnt(0)
	v_pk_add_f32 v[68:69], v[68:69], v[70:71]
	ds_bpermute_b32 v71, v170, v69
	ds_bpermute_b32 v70, v170, v68
	s_waitcnt lgkmcnt(0)
	v_pk_add_f32 v[68:69], v[68:69], v[70:71]
	s_nop 0
	v_pk_fma_f32 v[68:69], v[68:69], s[42:43], v[20:21] op_sel_hi:[1,0,0]
	s_nop 0
	v_mul_f32_e32 v70, 0x4b800000, v69
	v_cmp_gt_f32_e64 s[4:5], s41, v69
	v_cmp_gt_f32_e32 vcc, s41, v68
	s_nop 0
	v_cndmask_b32_e64 v69, v69, v70, s[4:5]
	v_rsq_f32_e32 v69, v69
	s_nop 0
	v_mul_f32_e32 v70, 0x45800000, v69
	v_cndmask_b32_e64 v69, v69, v70, s[4:5]
	v_mul_f32_e32 v88, v171, v69
	v_mul_f32_e32 v69, 0x4b800000, v68
	v_cndmask_b32_e32 v68, v68, v69, vcc
	v_rsq_f32_e32 v68, v68
	s_nop 0
	v_mul_f32_e32 v69, 0x45800000, v68
	v_cndmask_b32_e32 v68, v68, v69, vcc
	v_mul_f32_e32 v89, v171, v68
	ds_read2st64_b32 v[68:69], v104 offset0:14 offset1:15
	ds_read2st64_b32 v[72:73], v104 offset0:30 offset1:31
	ds_read2st64_b32 v[74:75], v104 offset0:46 offset1:47
	ds_read2st64_b32 v[76:77], v104 offset0:62 offset1:63
	s_waitcnt lgkmcnt(0)
	s_waitcnt lgkmcnt(3)
	v_mov_b32_e32 v70, v68
	s_waitcnt lgkmcnt(2)
	v_mov_b32_e32 v71, v72
	v_mov_b32_e32 v72, v69
	v_pk_fma_f32 v[26:27], s[6:7], v[70:71], v[26:27] neg_lo:[1,0,0] neg_hi:[1,0,0]
	s_waitcnt lgkmcnt(1)
	v_mov_b32_e32 v90, v74
	s_waitcnt lgkmcnt(0)
	v_mov_b32_e32 v91, v76
	v_pk_fma_f32 v[4:5], s[6:7], v[72:73], v[4:5] neg_lo:[1,0,0] neg_hi:[1,0,0]
	v_mov_b32_e32 v76, v75
	v_pk_mul_f32 v[70:71], v[26:27], v[26:27]
	v_pk_fma_f32 v[6:7], s[6:7], v[90:91], v[6:7] neg_lo:[1,0,0] neg_hi:[1,0,0]
	v_pk_mul_f32 v[68:69], v[4:5], v[4:5]
	v_pk_fma_f32 v[2:3], s[6:7], v[76:77], v[2:3] neg_lo:[1,0,0] neg_hi:[1,0,0]
	v_pk_mul_f32 v[90:91], v[6:7], v[6:7]
	v_pk_mul_f32 v[72:73], v[2:3], v[2:3]
	v_mov_b32_e32 v74, v68
	v_mov_b32_e32 v75, v70
	v_mov_b32_e32 v70, v69
	v_pk_add_f32 v[68:69], v[74:75], v[70:71]
	v_mov_b32_e32 v70, v72
	v_mov_b32_e32 v71, v90
	v_pk_add_f32 v[68:69], v[68:69], v[70:71]
	v_mov_b32_e32 v90, v73
	v_pk_add_f32 v[68:69], v[68:69], v[90:91]
	ds_bpermute_b32 v71, v163, v69
	ds_bpermute_b32 v70, v163, v68
	s_waitcnt lgkmcnt(0)
	v_pk_add_f32 v[68:69], v[68:69], v[70:71]
	ds_bpermute_b32 v71, v165, v69
	ds_bpermute_b32 v70, v165, v68
	s_waitcnt lgkmcnt(0)
	v_pk_add_f32 v[68:69], v[68:69], v[70:71]
	ds_bpermute_b32 v71, v168, v69
	ds_bpermute_b32 v70, v168, v68
	s_waitcnt lgkmcnt(0)
	v_pk_add_f32 v[68:69], v[68:69], v[70:71]
	ds_bpermute_b32 v71, v169, v69
	ds_bpermute_b32 v70, v169, v68
	s_waitcnt lgkmcnt(0)
	v_pk_add_f32 v[68:69], v[68:69], v[70:71]
	ds_bpermute_b32 v71, v170, v69
	ds_bpermute_b32 v70, v170, v68
	s_waitcnt lgkmcnt(0)
	v_pk_add_f32 v[68:69], v[68:69], v[70:71]
	s_nop 0
	v_pk_fma_f32 v[20:21], v[68:69], s[42:43], v[20:21] op_sel_hi:[1,0,0]
	v_lshlrev_b32_e32 v69, 1, v164
	v_mul_f32_e32 v68, 0x4b800000, v21
	v_cmp_gt_f32_e64 s[4:5], s41, v21
	v_cmp_gt_f32_e32 vcc, s41, v20
	s_nop 0
	v_cndmask_b32_e64 v21, v21, v68, s[4:5]
	v_rsq_f32_e32 v21, v21
	s_nop 0
	v_mul_f32_e32 v68, 0x45800000, v21
	v_cndmask_b32_e64 v21, v21, v68, s[4:5]
	v_mul_f32_e32 v68, 0x4b800000, v20
	v_cndmask_b32_e32 v20, v20, v68, vcc
	v_rsq_f32_e32 v20, v20
	v_mul_f32_e32 v21, v171, v21
	s_lshl_b64 s[4:5], s[18:19], 11
	s_add_u32 s1, s9, s4
	v_mul_f32_e32 v68, 0x45800000, v20
	v_cndmask_b32_e32 v20, v20, v68, vcc
	v_lshlrev_b32_e32 v68, 10, v173
	v_add3_u32 v68, s0, v68, v69
	v_bfe_u32 v69, v12, 16, 1
	v_add3_u32 v12, v12, v69, s97
	ds_write_b16_d16_hi v68, v12
	v_mul_f32_e32 v12, v14, v93
	v_mul_f32_e32 v12, v103, v12
	v_bfe_u32 v14, v12, 16, 1
	v_add3_u32 v12, v12, v14, s97
	ds_write_b16_d16_hi v68, v12 offset:256
	v_mul_f32_e32 v12, v22, v86
	v_mul_f32_e32 v12, v103, v12
	v_bfe_u32 v14, v12, 16, 1
	v_add3_u32 v12, v12, v14, s97
	ds_write_b16_d16_hi v68, v12 offset:512
	v_mul_f32_e32 v12, v24, v87
	v_mul_f32_e32 v12, v103, v12
	v_bfe_u32 v14, v12, 16, 1
	v_add3_u32 v12, v12, v14, s97
	ds_write_b16_d16_hi v68, v12 offset:768
	v_mul_f32_e32 v12, v32, v80
	v_mul_f32_e32 v12, v103, v12
	v_bfe_u32 v14, v12, 16, 1
	v_add3_u32 v12, v12, v14, s97
	ds_write_b16_d16_hi v68, v12 offset:2048
	v_mul_f32_e32 v12, v34, v81
	v_mul_f32_e32 v12, v103, v12
	v_bfe_u32 v14, v12, 16, 1
	v_add3_u32 v12, v12, v14, s97
	ds_write_b16_d16_hi v68, v12 offset:2304
	v_mul_f32_e32 v12, v46, v78
	v_mul_f32_e32 v12, v103, v12
	v_bfe_u32 v14, v12, 16, 1
	v_add3_u32 v12, v12, v14, s97
	ds_write_b16_d16_hi v68, v12 offset:2560
	v_mul_f32_e32 v12, v60, v79
	v_mul_f32_e32 v12, v103, v12
	v_bfe_u32 v14, v12, 16, 1
	v_add3_u32 v12, v12, v14, s97
	ds_write_b16_d16_hi v68, v12 offset:2816
	v_mul_f32_e32 v12, v64, v82
	v_mul_f32_e32 v12, v103, v12
	v_bfe_u32 v14, v12, 16, 1
	v_add3_u32 v12, v12, v14, s97
	ds_write_b16_d16_hi v68, v12 offset:4096
	v_mul_f32_e32 v12, v66, v83
	v_mul_f32_e32 v12, v103, v12
	v_bfe_u32 v14, v12, 16, 1
	v_add3_u32 v12, v12, v14, s97
	ds_write_b16_d16_hi v68, v12 offset:4352
	v_mul_f32_e32 v12, v54, v84
	v_mul_f32_e32 v12, v103, v12
	v_bfe_u32 v14, v12, 16, 1
	v_add3_u32 v12, v12, v14, s97
	ds_write_b16_d16_hi v68, v12 offset:4608
	v_mul_f32_e32 v12, v52, v85
	v_mul_f32_e32 v12, v103, v12
	v_bfe_u32 v14, v12, 16, 1
	v_add3_u32 v12, v12, v14, s97
	ds_write_b16_d16_hi v68, v12 offset:4864
	v_mul_f32_e32 v12, v42, v88
	v_mul_f32_e32 v12, v103, v12
	v_bfe_u32 v14, v12, 16, 1
	v_add3_u32 v12, v12, v14, s97
	ds_write_b16_d16_hi v68, v12 offset:6144
	v_mul_f32_e32 v12, v40, v89
	v_mul_f32_e32 v12, v103, v12
	v_bfe_u32 v14, v12, 16, 1
	v_add3_u32 v12, v12, v14, s97
	ds_write_b16_d16_hi v68, v12 offset:6400
	v_mul_f32_e32 v12, v26, v21
	v_mul_f32_e32 v20, v171, v20
	v_mul_f32_e32 v12, v103, v12
	v_bfe_u32 v14, v12, 16, 1
	v_mul_f32_e32 v4, v4, v20
	v_add3_u32 v12, v12, v14, s97
	v_mul_f32_e32 v4, v103, v4
	ds_write_b16_d16_hi v68, v12 offset:6656
	v_bfe_u32 v12, v4, 16, 1
	v_add3_u32 v4, v4, v12, s97
	ds_write_b16_d16_hi v68, v4 offset:6912
	v_mul_f32_e32 v4, v13, v92
	s_waitcnt vmcnt(2)
	v_mul_f32_e32 v4, v102, v4
	v_bfe_u32 v12, v4, 16, 1
	v_add3_u32 v4, v4, v12, s97
	ds_write_b16_d16_hi v68, v4 offset:64
	v_mul_f32_e32 v4, v15, v93
	v_mul_f32_e32 v4, v102, v4
	v_bfe_u32 v12, v4, 16, 1
	v_add3_u32 v4, v4, v12, s97
	ds_write_b16_d16_hi v68, v4 offset:320
	v_mul_f32_e32 v4, v23, v86
	v_mul_f32_e32 v4, v102, v4
	v_bfe_u32 v12, v4, 16, 1
	v_add3_u32 v4, v4, v12, s97
	ds_write_b16_d16_hi v68, v4 offset:576
	v_mul_f32_e32 v4, v25, v87
	v_mul_f32_e32 v4, v102, v4
	v_bfe_u32 v12, v4, 16, 1
	v_add3_u32 v4, v4, v12, s97
	ds_write_b16_d16_hi v68, v4 offset:832
	v_mul_f32_e32 v4, v33, v80
	v_mul_f32_e32 v4, v102, v4
	v_bfe_u32 v12, v4, 16, 1
	v_add3_u32 v4, v4, v12, s97
	ds_write_b16_d16_hi v68, v4 offset:2112
	v_mul_f32_e32 v4, v35, v81
	v_mul_f32_e32 v4, v102, v4
	v_bfe_u32 v12, v4, 16, 1
	v_add3_u32 v4, v4, v12, s97
	ds_write_b16_d16_hi v68, v4 offset:2368
	v_mul_f32_e32 v4, v47, v78
	v_mul_f32_e32 v4, v102, v4
	v_bfe_u32 v12, v4, 16, 1
	v_add3_u32 v4, v4, v12, s97
	ds_write_b16_d16_hi v68, v4 offset:2624
	v_mul_f32_e32 v4, v61, v79
	v_mul_f32_e32 v4, v102, v4
	v_bfe_u32 v12, v4, 16, 1
	v_add3_u32 v4, v4, v12, s97
	ds_write_b16_d16_hi v68, v4 offset:2880
	v_mul_f32_e32 v4, v65, v82
	v_mul_f32_e32 v4, v102, v4
	v_bfe_u32 v12, v4, 16, 1
	v_add3_u32 v4, v4, v12, s97
	ds_write_b16_d16_hi v68, v4 offset:4160
	v_mul_f32_e32 v4, v67, v83
	v_mul_f32_e32 v4, v102, v4
	v_bfe_u32 v12, v4, 16, 1
	v_add3_u32 v4, v4, v12, s97
	ds_write_b16_d16_hi v68, v4 offset:4416
	v_mul_f32_e32 v4, v55, v84
	v_mul_f32_e32 v4, v102, v4
	v_bfe_u32 v12, v4, 16, 1
	v_add3_u32 v4, v4, v12, s97
	ds_write_b16_d16_hi v68, v4 offset:4672
	v_mul_f32_e32 v4, v53, v85
	v_mul_f32_e32 v4, v102, v4
	v_bfe_u32 v12, v4, 16, 1
	v_add3_u32 v4, v4, v12, s97
	ds_write_b16_d16_hi v68, v4 offset:4928
	v_mul_f32_e32 v4, v43, v88
	v_mul_f32_e32 v4, v102, v4
	v_bfe_u32 v12, v4, 16, 1
	v_add3_u32 v4, v4, v12, s97
	ds_write_b16_d16_hi v68, v4 offset:6208
	v_mul_f32_e32 v4, v41, v89
	v_mul_f32_e32 v4, v102, v4
	v_bfe_u32 v12, v4, 16, 1
	v_add3_u32 v4, v4, v12, s97
	ds_write_b16_d16_hi v68, v4 offset:6464
	v_mul_f32_e32 v4, v27, v21
	v_mul_f32_e32 v4, v102, v4
	v_bfe_u32 v12, v4, 16, 1
	v_add3_u32 v4, v4, v12, s97
	ds_write_b16_d16_hi v68, v4 offset:6720
	v_mul_f32_e32 v4, v5, v20
	v_mul_f32_e32 v4, v102, v4
	v_bfe_u32 v5, v4, 16, 1
	v_add3_u32 v4, v4, v5, s97
	ds_write_b16_d16_hi v68, v4 offset:6976
	v_mul_f32_e32 v4, v8, v92
	s_waitcnt vmcnt(1)
	v_mul_f32_e32 v4, v101, v4
	v_bfe_u32 v5, v4, 16, 1
	v_add3_u32 v4, v4, v5, s97
	ds_write_b16_d16_hi v68, v4 offset:128
	v_mul_f32_e32 v4, v10, v93
	v_mul_f32_e32 v4, v101, v4
	v_bfe_u32 v5, v4, 16, 1
	v_add3_u32 v4, v4, v5, s97
	ds_write_b16_d16_hi v68, v4 offset:384
	v_mul_f32_e32 v4, v16, v86
	v_mul_f32_e32 v4, v101, v4
	v_bfe_u32 v5, v4, 16, 1
	v_add3_u32 v4, v4, v5, s97
	ds_write_b16_d16_hi v68, v4 offset:640
	v_mul_f32_e32 v4, v18, v87
	v_mul_f32_e32 v4, v101, v4
	v_bfe_u32 v5, v4, 16, 1
	v_add3_u32 v4, v4, v5, s97
	ds_write_b16_d16_hi v68, v4 offset:896
	v_mul_f32_e32 v4, v28, v80
	v_mul_f32_e32 v4, v101, v4
	v_bfe_u32 v5, v4, 16, 1
	v_add3_u32 v4, v4, v5, s97
	ds_write_b16_d16_hi v68, v4 offset:2176
	v_mul_f32_e32 v4, v30, v81
	v_mul_f32_e32 v4, v101, v4
	v_bfe_u32 v5, v4, 16, 1
	v_add3_u32 v4, v4, v5, s97
	ds_write_b16_d16_hi v68, v4 offset:2432
	v_mul_f32_e32 v4, v48, v78
	v_mul_f32_e32 v4, v101, v4
	v_bfe_u32 v5, v4, 16, 1
	v_add3_u32 v4, v4, v5, s97
	ds_write_b16_d16_hi v68, v4 offset:2688
	v_mul_f32_e32 v4, v58, v79
	v_mul_f32_e32 v4, v101, v4
	v_bfe_u32 v5, v4, 16, 1
	v_add3_u32 v4, v4, v5, s97
	ds_write_b16_d16_hi v68, v4 offset:2944
	v_mul_f32_e32 v4, v62, v82
	v_mul_f32_e32 v4, v101, v4
	v_bfe_u32 v5, v4, 16, 1
	v_add3_u32 v4, v4, v5, s97
	ds_write_b16_d16_hi v68, v4 offset:4224
	v_mul_f32_e32 v4, v56, v83
	v_mul_f32_e32 v4, v101, v4
	v_bfe_u32 v5, v4, 16, 1
	v_add3_u32 v4, v4, v5, s97
	ds_write_b16_d16_hi v68, v4 offset:4480
	v_mul_f32_e32 v4, v50, v84
	v_mul_f32_e32 v4, v101, v4
	v_bfe_u32 v5, v4, 16, 1
	v_add3_u32 v4, v4, v5, s97
	ds_write_b16_d16_hi v68, v4 offset:4736
	v_mul_f32_e32 v4, v44, v85
	v_mul_f32_e32 v4, v101, v4
	v_bfe_u32 v5, v4, 16, 1
	v_add3_u32 v4, v4, v5, s97
	ds_write_b16_d16_hi v68, v4 offset:4992
	v_mul_f32_e32 v4, v38, v88
	v_mul_f32_e32 v4, v101, v4
	v_bfe_u32 v5, v4, 16, 1
	v_add3_u32 v4, v4, v5, s97
	ds_write_b16_d16_hi v68, v4 offset:6272
	v_mul_f32_e32 v4, v36, v89
	v_mul_f32_e32 v4, v101, v4
	v_bfe_u32 v5, v4, 16, 1
	v_add3_u32 v4, v4, v5, s97
	ds_write_b16_d16_hi v68, v4 offset:6528
	v_mul_f32_e32 v4, v6, v21
	v_mul_f32_e32 v4, v101, v4
	v_bfe_u32 v5, v4, 16, 1
	v_mul_f32_e32 v2, v2, v20
	v_add3_u32 v4, v4, v5, s97
	v_mul_f32_e32 v2, v101, v2
	ds_write_b16_d16_hi v68, v4 offset:6784
	v_bfe_u32 v4, v2, 16, 1
	v_add3_u32 v2, v2, v4, s97
	ds_write_b16_d16_hi v68, v2 offset:7040
	v_mul_f32_e32 v2, v9, v92
	s_waitcnt vmcnt(0)
	v_mul_f32_e32 v2, v100, v2
	v_bfe_u32 v4, v2, 16, 1
	v_add3_u32 v2, v2, v4, s97
	ds_write_b16_d16_hi v68, v2 offset:192
	v_mul_f32_e32 v2, v11, v93
	v_mul_f32_e32 v2, v100, v2
	v_bfe_u32 v4, v2, 16, 1
	v_add3_u32 v2, v2, v4, s97
	ds_write_b16_d16_hi v68, v2 offset:448
	v_mul_f32_e32 v2, v17, v86
	v_mul_f32_e32 v2, v100, v2
	v_bfe_u32 v4, v2, 16, 1
	v_add3_u32 v2, v2, v4, s97
	ds_write_b16_d16_hi v68, v2 offset:704
	v_mul_f32_e32 v2, v19, v87
	v_mul_f32_e32 v2, v100, v2
	v_bfe_u32 v4, v2, 16, 1
	v_add3_u32 v2, v2, v4, s97
	ds_write_b16_d16_hi v68, v2 offset:960
	v_mul_f32_e32 v2, v29, v80
	v_mul_f32_e32 v2, v100, v2
	v_bfe_u32 v4, v2, 16, 1
	v_add3_u32 v2, v2, v4, s97
	ds_write_b16_d16_hi v68, v2 offset:2240
	v_mul_f32_e32 v2, v31, v81
	v_mul_f32_e32 v2, v100, v2
	v_bfe_u32 v4, v2, 16, 1
	v_add3_u32 v2, v2, v4, s97
	ds_write_b16_d16_hi v68, v2 offset:2496
	v_mul_f32_e32 v2, v49, v78
	v_mul_f32_e32 v2, v100, v2
	v_bfe_u32 v4, v2, 16, 1
	v_add3_u32 v2, v2, v4, s97
	ds_write_b16_d16_hi v68, v2 offset:2752
	v_mul_f32_e32 v2, v59, v79
	v_mul_f32_e32 v2, v100, v2
	v_bfe_u32 v4, v2, 16, 1
	v_add3_u32 v2, v2, v4, s97
	ds_write_b16_d16_hi v68, v2 offset:3008
	v_mul_f32_e32 v2, v63, v82
	v_mul_f32_e32 v2, v100, v2
	v_bfe_u32 v4, v2, 16, 1
	v_add3_u32 v2, v2, v4, s97
	ds_write_b16_d16_hi v68, v2 offset:4288
	v_mul_f32_e32 v2, v57, v83
	v_mul_f32_e32 v2, v100, v2
	v_bfe_u32 v4, v2, 16, 1
	v_add3_u32 v2, v2, v4, s97
	ds_write_b16_d16_hi v68, v2 offset:4544
	v_mul_f32_e32 v2, v51, v84
	v_mul_f32_e32 v2, v100, v2
	v_bfe_u32 v4, v2, 16, 1
	v_add3_u32 v2, v2, v4, s97
	ds_write_b16_d16_hi v68, v2 offset:4800
	v_mul_f32_e32 v2, v45, v85
	v_mul_f32_e32 v2, v100, v2
	v_bfe_u32 v4, v2, 16, 1
	v_add3_u32 v2, v2, v4, s97
	ds_write_b16_d16_hi v68, v2 offset:5056
	v_mul_f32_e32 v2, v39, v88
	v_mul_f32_e32 v2, v100, v2
	v_bfe_u32 v4, v2, 16, 1
	v_add3_u32 v2, v2, v4, s97
	ds_write_b16_d16_hi v68, v2 offset:6336
	v_mul_f32_e32 v2, v37, v89
	v_mul_f32_e32 v2, v100, v2
	v_bfe_u32 v4, v2, 16, 1
	v_add3_u32 v2, v2, v4, s97
	ds_write_b16_d16_hi v68, v2 offset:6592
	v_mul_f32_e32 v2, v7, v21
	v_mul_f32_e32 v2, v100, v2
	v_bfe_u32 v4, v2, 16, 1
	v_add3_u32 v2, v2, v4, s97
	ds_write_b16_d16_hi v68, v2 offset:6848
	v_mul_f32_e32 v2, v3, v20
	v_mul_f32_e32 v2, v100, v2
	v_bfe_u32 v3, v2, 16, 1
	v_add3_u32 v2, v2, v3, s97
	ds_write_b16_d16_hi v68, v2 offset:7104
	v_lshrrev_b32_e32 v10, 4, v172
	v_add_u32_e32 v11, s0, v178
	s_waitcnt lgkmcnt(0)
	v_lshl_add_u32 v2, v10, 8, v11
	s_addc_u32 s5, s16, s5
	s_lshl_b32 s4, s22, 1
	ds_read_b128 v[2:5], v2
	s_add_u32 s4, s1, s4
	s_addc_u32 s5, s5, 0
	v_lshl_add_u64 v[6:7], s[4:5], 0, v[178:179]
	v_lshlrev_b32_e32 v178, 11, v10
	v_lshl_add_u64 v[8:9], v[6:7], 0, v[178:179]
	s_waitcnt lgkmcnt(0)
	global_store_dwordx4 v[8:9], v[2:5], off sc1
	v_or_b32_e32 v8, 4, v10
	v_lshlrev_b32_e32 v178, 11, v8
	v_lshl_add_u32 v2, v8, 8, v11
	ds_read_b128 v[2:5], v2
	v_lshl_add_u64 v[8:9], v[6:7], 0, v[178:179]
	s_waitcnt lgkmcnt(0)
	global_store_dwordx4 v[8:9], v[2:5], off sc1
	v_or_b32_e32 v8, 8, v10
	s_nop 0
	v_lshl_add_u32 v2, v8, 8, v11
	ds_read_b128 v[2:5], v2
	v_lshlrev_b32_e32 v178, 11, v8
	v_lshl_add_u64 v[8:9], v[6:7], 0, v[178:179]
	s_waitcnt lgkmcnt(0)
	global_store_dwordx4 v[8:9], v[2:5], off sc1
	v_or_b32_e32 v8, 12, v10
	s_nop 0
	v_lshl_add_u32 v2, v8, 8, v11
	ds_read_b128 v[2:5], v2
	v_lshlrev_b32_e32 v178, 11, v8
	v_lshl_add_u64 v[8:9], v[6:7], 0, v[178:179]
	s_waitcnt lgkmcnt(0)
	global_store_dwordx4 v[8:9], v[2:5], off sc1
	v_or_b32_e32 v8, 16, v10
	s_nop 0
	v_lshl_add_u32 v2, v8, 8, v11
	ds_read_b128 v[2:5], v2
	v_lshlrev_b32_e32 v178, 11, v8
	v_lshl_add_u64 v[8:9], v[6:7], 0, v[178:179]
	s_waitcnt lgkmcnt(0)
	global_store_dwordx4 v[8:9], v[2:5], off sc1
	v_or_b32_e32 v8, 20, v10
	s_nop 0
	v_lshl_add_u32 v2, v8, 8, v11
	ds_read_b128 v[2:5], v2
	v_lshlrev_b32_e32 v178, 11, v8
	v_lshl_add_u64 v[8:9], v[6:7], 0, v[178:179]
	s_waitcnt lgkmcnt(0)
	global_store_dwordx4 v[8:9], v[2:5], off sc1
	v_or_b32_e32 v8, 24, v10
	s_nop 0
	v_lshl_add_u32 v2, v8, 8, v11
	ds_read_b128 v[2:5], v2
	v_lshlrev_b32_e32 v178, 11, v8
	v_lshl_add_u64 v[8:9], v[6:7], 0, v[178:179]
	s_waitcnt lgkmcnt(0)
	global_store_dwordx4 v[8:9], v[2:5], off sc1
	v_or_b32_e32 v8, 28, v10
	s_nop 0
	v_lshl_add_u32 v2, v8, 8, v11
	ds_read_b128 v[2:5], v2
	v_lshlrev_b32_e32 v178, 11, v8
	v_lshl_add_u64 v[6:7], v[6:7], 0, v[178:179]
	s_waitcnt lgkmcnt(0)
	global_store_dwordx4 v[6:7], v[2:5], off sc1
	s_branch .LBB0_280

.LBB0_361:
	s_and_saveexec_b64 s[0:1], s[14:15]
	s_cbranch_execz .LBB0_363
	global_load_dwordx4 v[130:133], v[146:147], off offset:16
	global_load_dwordx4 v[134:137], v[146:147], off
	v_ashrrev_i32_e32 v153, 31, v152
	v_lshlrev_b64 v[154:155], 6, v[152:153]
	v_or_b32_e32 v156, 16, v152
	v_lshl_add_u64 v[154:155], v[144:145], 0, v[154:155]
	v_ashrrev_i32_e32 v157, 31, v156
	v_lshlrev_b64 v[156:157], 6, v[156:157]
	v_lshl_add_u64 v[156:157], v[144:145], 0, v[156:157]
	s_mov_b64 s[16:17], 0x2000
	v_lshl_add_u64 v[166:167], v[154:155], 0, s[16:17]
	s_movk_i32 s16, 0x2000
	s_waitcnt vmcnt(0)
	v_pk_add_f32 v[164:165], v[128:129], v[136:137]
	v_pk_add_f32 v[162:163], v[126:127], v[134:135]
	global_store_dwordx4 v[154:155], v[162:165], off sc1
	s_nop 1
	v_pk_add_f32 v[164:165], v[124:125], v[132:133]
	v_pk_add_f32 v[162:163], v[122:123], v[130:131]
	global_store_dwordx4 v[154:155], v[162:165], off offset:16 sc1
	s_nop 1
	v_pk_add_f32 v[164:165], v[116:117], v[136:137]
	v_pk_add_f32 v[162:163], v[114:115], v[134:135]
	global_store_dwordx4 v[156:157], v[162:165], off sc1
	s_nop 1
	v_pk_add_f32 v[164:165], v[108:109], v[132:133]
	v_pk_add_f32 v[162:163], v[106:107], v[130:131]
	global_store_dwordx4 v[156:157], v[162:165], off offset:16 sc1
	v_or_b32_e32 v156, 32, v152
	v_ashrrev_i32_e32 v157, 31, v156
	v_lshlrev_b64 v[156:157], 6, v[156:157]
	v_lshl_add_u64 v[156:157], v[144:145], 0, v[156:157]
	v_pk_add_f32 v[164:165], v[100:101], v[136:137]
	v_pk_add_f32 v[162:163], v[98:99], v[134:135]
	global_store_dwordx4 v[156:157], v[162:165], off sc1
	s_nop 1
	v_pk_add_f32 v[164:165], v[92:93], v[132:133]
	v_pk_add_f32 v[162:163], v[90:91], v[130:131]
	global_store_dwordx4 v[156:157], v[162:165], off offset:16 sc1
	v_or_b32_e32 v156, 48, v152
	v_ashrrev_i32_e32 v157, 31, v156
	v_lshlrev_b64 v[156:157], 6, v[156:157]
	v_lshl_add_u64 v[156:157], v[144:145], 0, v[156:157]
	v_pk_add_f32 v[164:165], v[84:85], v[136:137]
	v_pk_add_f32 v[162:163], v[82:83], v[134:135]
	global_store_dwordx4 v[156:157], v[162:165], off sc1
	s_nop 1
	v_pk_add_f32 v[164:165], v[76:77], v[132:133]
	v_pk_add_f32 v[162:163], v[74:75], v[130:131]
	global_store_dwordx4 v[156:157], v[162:165], off offset:16 sc1
	v_add_co_u32_e32 v156, vcc, s16, v154
	s_nop 0
	v_pk_add_f32 v[164:165], v[64:65], v[136:137]
	v_pk_add_f32 v[162:163], v[62:63], v[134:135]
	v_addc_co_u32_e32 v157, vcc, 0, v155, vcc
	global_store_dwordx4 v[156:157], v[162:165], off sc1
	s_mov_b64 s[16:17], 0x2400
	s_nop 0
	v_pk_add_f32 v[164:165], v[60:61], v[132:133]
	v_pk_add_f32 v[162:163], v[58:59], v[130:131]
	global_store_dwordx4 v[166:167], v[162:165], off offset:16 sc1
	v_lshl_add_u64 v[166:167], v[154:155], 0, s[16:17]
	s_mov_b64 s[16:17], 0x2800
	v_pk_add_f32 v[164:165], v[52:53], v[136:137]
	v_pk_add_f32 v[162:163], v[50:51], v[134:135]
	global_store_dwordx4 v[156:157], v[162:165], off offset:1024 sc1
	s_nop 1
	v_pk_add_f32 v[164:165], v[44:45], v[132:133]
	v_pk_add_f32 v[162:163], v[42:43], v[130:131]
	global_store_dwordx4 v[166:167], v[162:165], off offset:16 sc1
	v_lshl_add_u64 v[166:167], v[154:155], 0, s[16:17]
	s_mov_b64 s[16:17], 0x2c00
	v_pk_add_f32 v[164:165], v[36:37], v[136:137]
	v_pk_add_f32 v[162:163], v[34:35], v[134:135]
	global_store_dwordx4 v[156:157], v[162:165], off offset:2048 sc1
	v_lshl_add_u64 v[154:155], v[154:155], 0, s[16:17]
	v_pk_add_f32 v[136:137], v[20:21], v[136:137]
	v_pk_add_f32 v[164:165], v[28:29], v[132:133]
	v_pk_add_f32 v[162:163], v[26:27], v[130:131]
	v_pk_add_f32 v[134:135], v[18:19], v[134:135]
	v_pk_add_f32 v[132:133], v[12:13], v[132:133]
	v_pk_add_f32 v[130:131], v[10:11], v[130:131]
	global_store_dwordx4 v[166:167], v[162:165], off offset:16 sc1
	global_store_dwordx4 v[156:157], v[134:137], off offset:3072 sc1
	global_store_dwordx4 v[154:155], v[130:133], off offset:16 sc1

.LBB0_364:
	s_and_b32 s0, s33, -2
	s_cmp_eq_u32 s0, 8
	v_lshl_or_b32 v134, s33, 8, v160
	s_cselect_b64 vcc, -1, 0
	v_ashrrev_i32_e32 v135, 31, v134
	v_mov_b64_e32 v[132:133], s[10:11]
	v_cndmask_b32_e32 v130, 1.0, v201, vcc
	v_mad_i64_i32 v[136:137], s[0:1], v152, s36, v[132:133]
	v_lshlrev_b64 v[134:135], 1, v[134:135]
	v_lshl_add_u64 v[136:137], v[136:137], 0, v[134:135]
	v_pk_mul_f32 v[128:129], v[130:131], v[128:129] op_sel_hi:[0,1]
	v_pk_mul_f32 v[126:127], v[130:131], v[126:127] op_sel_hi:[0,1]
	v_pk_mul_f32 v[154:155], v[130:131], v[124:125] op_sel_hi:[0,1]
	v_pk_mul_f32 v[124:125], v[130:131], v[122:123] op_sel_hi:[0,1]
	v_cvt_pk_bf16_f32 v122, v126, v127
	v_cvt_pk_bf16_f32 v123, v128, v129
	v_cvt_pk_bf16_f32 v124, v124, v125
	v_cvt_pk_bf16_f32 v125, v154, v155
	global_store_dwordx4 v[136:137], v[122:125], off sc1
	v_pk_mul_f32 v[118:119], v[130:131], v[118:119] op_sel_hi:[0,1]
	v_pk_mul_f32 v[120:121], v[130:131], v[120:121] op_sel_hi:[0,1]
	v_pk_mul_f32 v[122:123], v[130:131], v[112:113] op_sel_hi:[0,1]
	v_pk_mul_f32 v[112:113], v[130:131], v[110:111] op_sel_hi:[0,1]
	v_cvt_pk_bf16_f32 v110, v118, v119
	v_cvt_pk_bf16_f32 v111, v120, v121
	v_cvt_pk_bf16_f32 v112, v112, v113
	v_cvt_pk_bf16_f32 v113, v122, v123
	global_store_dwordx4 v[136:137], v[110:113], off offset:256 sc1
	v_pk_mul_f32 v[114:115], v[130:131], v[114:115] op_sel_hi:[0,1]
	v_pk_mul_f32 v[102:103], v[130:131], v[102:103] op_sel_hi:[0,1]
	v_or_b32_e32 v110, 16, v152
	v_mad_i64_i32 v[110:111], s[0:1], v110, s36, v[132:133]
	v_lshl_add_u64 v[110:111], v[110:111], 0, v[134:135]
	v_pk_mul_f32 v[112:113], v[130:131], v[116:117] op_sel_hi:[0,1]
	v_pk_mul_f32 v[116:117], v[130:131], v[108:109] op_sel_hi:[0,1]
	v_pk_mul_f32 v[108:109], v[130:131], v[106:107] op_sel_hi:[0,1]
	v_cvt_pk_bf16_f32 v106, v114, v115
	v_cvt_pk_bf16_f32 v107, v112, v113
	v_cvt_pk_bf16_f32 v108, v108, v109
	v_cvt_pk_bf16_f32 v109, v116, v117
	global_store_dwordx4 v[110:111], v[106:109], off sc1
	v_pk_mul_f32 v[104:105], v[130:131], v[104:105] op_sel_hi:[0,1]
	v_pk_mul_f32 v[98:99], v[130:131], v[98:99] op_sel_hi:[0,1]
	v_pk_mul_f32 v[106:107], v[130:131], v[96:97] op_sel_hi:[0,1]
	v_pk_mul_f32 v[96:97], v[130:131], v[94:95] op_sel_hi:[0,1]
	v_cvt_pk_bf16_f32 v94, v102, v103
	v_cvt_pk_bf16_f32 v95, v104, v105
	v_cvt_pk_bf16_f32 v96, v96, v97
	v_cvt_pk_bf16_f32 v97, v106, v107
	global_store_dwordx4 v[110:111], v[94:97], off offset:256 sc1
	v_pk_mul_f32 v[86:87], v[130:131], v[86:87] op_sel_hi:[0,1]
	v_pk_mul_f32 v[88:89], v[130:131], v[88:89] op_sel_hi:[0,1]
	v_or_b32_e32 v94, 32, v152
	v_mad_i64_i32 v[94:95], s[0:1], v94, s36, v[132:133]
	v_lshl_add_u64 v[94:95], v[94:95], 0, v[134:135]
	v_pk_mul_f32 v[96:97], v[130:131], v[100:101] op_sel_hi:[0,1]
	v_pk_mul_f32 v[100:101], v[130:131], v[92:93] op_sel_hi:[0,1]
	v_pk_mul_f32 v[92:93], v[130:131], v[90:91] op_sel_hi:[0,1]
	v_cvt_pk_bf16_f32 v90, v98, v99
	v_cvt_pk_bf16_f32 v91, v96, v97
	v_cvt_pk_bf16_f32 v92, v92, v93
	v_cvt_pk_bf16_f32 v93, v100, v101
	global_store_dwordx4 v[94:95], v[90:93], off sc1
	v_pk_mul_f32 v[82:83], v[130:131], v[82:83] op_sel_hi:[0,1]
	v_pk_mul_f32 v[70:71], v[130:131], v[70:71] op_sel_hi:[0,1]
	v_pk_mul_f32 v[90:91], v[130:131], v[80:81] op_sel_hi:[0,1]
	v_pk_mul_f32 v[80:81], v[130:131], v[78:79] op_sel_hi:[0,1]
	v_cvt_pk_bf16_f32 v78, v86, v87
	v_cvt_pk_bf16_f32 v79, v88, v89
	v_cvt_pk_bf16_f32 v80, v80, v81
	v_cvt_pk_bf16_f32 v81, v90, v91
	global_store_dwordx4 v[94:95], v[78:81], off offset:256 sc1
	v_pk_mul_f32 v[72:73], v[130:131], v[72:73] op_sel_hi:[0,1]
	v_pk_mul_f32 v[64:65], v[130:131], v[64:65] op_sel_hi:[0,1]
	v_or_b32_e32 v78, 48, v152
	v_mad_i64_i32 v[78:79], s[0:1], v78, s36, v[132:133]
	v_lshl_add_u64 v[78:79], v[78:79], 0, v[134:135]
	v_pk_mul_f32 v[80:81], v[130:131], v[84:85] op_sel_hi:[0,1]
	v_pk_mul_f32 v[84:85], v[130:131], v[76:77] op_sel_hi:[0,1]
	v_pk_mul_f32 v[76:77], v[130:131], v[74:75] op_sel_hi:[0,1]
	v_cvt_pk_bf16_f32 v74, v82, v83
	v_cvt_pk_bf16_f32 v75, v80, v81
	v_cvt_pk_bf16_f32 v76, v76, v77
	v_cvt_pk_bf16_f32 v77, v84, v85
	global_store_dwordx4 v[78:79], v[74:77], off sc1
	v_pk_mul_f32 v[62:63], v[130:131], v[62:63] op_sel_hi:[0,1]
	v_pk_mul_f32 v[54:55], v[130:131], v[54:55] op_sel_hi:[0,1]
	v_pk_mul_f32 v[74:75], v[130:131], v[68:69] op_sel_hi:[0,1]
	v_pk_mul_f32 v[68:69], v[130:131], v[66:67] op_sel_hi:[0,1]
	v_cvt_pk_bf16_f32 v66, v70, v71
	v_cvt_pk_bf16_f32 v67, v72, v73
	v_cvt_pk_bf16_f32 v68, v68, v69
	v_cvt_pk_bf16_f32 v69, v74, v75
	global_store_dwordx4 v[78:79], v[66:69], off offset:256 sc1
	v_pk_mul_f32 v[56:57], v[130:131], v[56:57] op_sel_hi:[0,1]
	v_pk_mul_f32 v[50:51], v[130:131], v[50:51] op_sel_hi:[0,1]
	v_add_u32_e32 v66, 0x80, v152
	v_mad_i64_i32 v[66:67], s[0:1], v66, s36, v[132:133]
	v_lshl_add_u64 v[66:67], v[66:67], 0, v[134:135]
	v_pk_mul_f32 v[68:69], v[130:131], v[60:61] op_sel_hi:[0,1]
	v_pk_mul_f32 v[60:61], v[130:131], v[58:59] op_sel_hi:[0,1]
	v_cvt_pk_bf16_f32 v58, v62, v63
	v_cvt_pk_bf16_f32 v59, v64, v65
	v_cvt_pk_bf16_f32 v60, v60, v61
	v_cvt_pk_bf16_f32 v61, v68, v69
	global_store_dwordx4 v[66:67], v[58:61], off sc1
	v_pk_mul_f32 v[38:39], v[130:131], v[38:39] op_sel_hi:[0,1]
	v_pk_mul_f32 v[40:41], v[130:131], v[40:41] op_sel_hi:[0,1]
	v_pk_mul_f32 v[58:59], v[130:131], v[48:49] op_sel_hi:[0,1]
	v_pk_mul_f32 v[48:49], v[130:131], v[46:47] op_sel_hi:[0,1]
	v_cvt_pk_bf16_f32 v46, v54, v55
	v_cvt_pk_bf16_f32 v47, v56, v57
	v_cvt_pk_bf16_f32 v48, v48, v49
	v_cvt_pk_bf16_f32 v49, v58, v59
	global_store_dwordx4 v[66:67], v[46:49], off offset:256 sc1
	v_pk_mul_f32 v[34:35], v[130:131], v[34:35] op_sel_hi:[0,1]
	v_pk_mul_f32 v[22:23], v[130:131], v[22:23] op_sel_hi:[0,1]
	v_add_u32_e32 v46, 0x90, v152
	v_mad_i64_i32 v[46:47], s[0:1], v46, s36, v[132:133]
	v_lshl_add_u64 v[46:47], v[46:47], 0, v[134:135]
	v_pk_mul_f32 v[48:49], v[130:131], v[52:53] op_sel_hi:[0,1]
	v_pk_mul_f32 v[52:53], v[130:131], v[44:45] op_sel_hi:[0,1]
	v_pk_mul_f32 v[44:45], v[130:131], v[42:43] op_sel_hi:[0,1]
	v_cvt_pk_bf16_f32 v42, v50, v51
	v_cvt_pk_bf16_f32 v43, v48, v49
	v_cvt_pk_bf16_f32 v44, v44, v45
	v_cvt_pk_bf16_f32 v45, v52, v53
	global_store_dwordx4 v[46:47], v[42:45], off sc1
	v_pk_mul_f32 v[24:25], v[130:131], v[24:25] op_sel_hi:[0,1]
	v_pk_mul_f32 v[18:19], v[130:131], v[18:19] op_sel_hi:[0,1]
	v_pk_mul_f32 v[42:43], v[130:131], v[32:33] op_sel_hi:[0,1]
	v_pk_mul_f32 v[32:33], v[130:131], v[30:31] op_sel_hi:[0,1]
	v_cvt_pk_bf16_f32 v30, v38, v39
	v_cvt_pk_bf16_f32 v31, v40, v41
	v_cvt_pk_bf16_f32 v32, v32, v33
	v_cvt_pk_bf16_f32 v33, v42, v43
	global_store_dwordx4 v[46:47], v[30:33], off offset:256 sc1
	v_pk_mul_f32 v[8:9], v[130:131], v[8:9] op_sel_hi:[0,1]
	v_pk_mul_f32 v[6:7], v[130:131], v[6:7] op_sel_hi:[0,1]
	v_add_u32_e32 v30, 0xa0, v152
	v_mad_i64_i32 v[30:31], s[0:1], v30, s36, v[132:133]
	v_lshl_add_u64 v[30:31], v[30:31], 0, v[134:135]
	v_pk_mul_f32 v[32:33], v[130:131], v[36:37] op_sel_hi:[0,1]
	v_pk_mul_f32 v[36:37], v[130:131], v[28:29] op_sel_hi:[0,1]
	v_pk_mul_f32 v[28:29], v[130:131], v[26:27] op_sel_hi:[0,1]
	v_cvt_pk_bf16_f32 v26, v34, v35
	v_cvt_pk_bf16_f32 v27, v32, v33
	v_cvt_pk_bf16_f32 v28, v28, v29
	v_cvt_pk_bf16_f32 v29, v36, v37
	global_store_dwordx4 v[30:31], v[26:29], off sc1
	s_nop 1
	v_pk_mul_f32 v[26:27], v[130:131], v[16:17] op_sel_hi:[0,1]
	v_pk_mul_f32 v[16:17], v[130:131], v[14:15] op_sel_hi:[0,1]
	v_cvt_pk_bf16_f32 v14, v22, v23
	v_cvt_pk_bf16_f32 v15, v24, v25
	v_cvt_pk_bf16_f32 v16, v16, v17
	v_cvt_pk_bf16_f32 v17, v26, v27
	global_store_dwordx4 v[30:31], v[14:17], off offset:256 sc1
	s_nop 1
	v_add_u32_e32 v14, 0xb0, v152
	v_mad_i64_i32 v[14:15], s[0:1], v14, s36, v[132:133]
	v_lshl_add_u64 v[14:15], v[14:15], 0, v[134:135]
	v_pk_mul_f32 v[16:17], v[130:131], v[20:21] op_sel_hi:[0,1]
	v_pk_mul_f32 v[20:21], v[130:131], v[12:13] op_sel_hi:[0,1]
	v_pk_mul_f32 v[12:13], v[130:131], v[10:11] op_sel_hi:[0,1]
	v_cvt_pk_bf16_f32 v10, v18, v19
	v_cvt_pk_bf16_f32 v11, v16, v17
	v_cvt_pk_bf16_f32 v12, v12, v13
	v_cvt_pk_bf16_f32 v13, v20, v21
	global_store_dwordx4 v[14:15], v[10:13], off sc1
	s_nop 1
	v_pk_mul_f32 v[10:11], v[130:131], v[4:5] op_sel_hi:[0,1]
	v_pk_mul_f32 v[4:5], v[130:131], v[2:3] op_sel_hi:[0,1]
	v_cvt_pk_bf16_f32 v2, v6, v7
	v_cvt_pk_bf16_f32 v3, v8, v9
	v_cvt_pk_bf16_f32 v4, v4, v5
	v_cvt_pk_bf16_f32 v5, v10, v11
	global_store_dwordx4 v[14:15], v[2:5], off offset:256 sc1
	s_andn2_b64 vcc, exec, s[4:5]
	s_mov_b64 s[0:1], -1
	s_cbranch_vccnz .LBB0_351

.LBB0_423:
	s_or_b64 exec, exec, s[0:1]
	v_lshl_add_u32 v42, v129, 2, s14
	s_waitcnt lgkmcnt(0)
	s_waitcnt lgkmcnt(0)
	s_barrier
	ds_read_b128 v[34:37], v42 offset:26624
	ds_read_b128 v[38:41], v42 offset:26656
	s_lshl_b32 s0, s24, 12
	s_add_i32 s0, s0, 0
	v_lshl_add_u32 v43, v106, 1, s0
	s_waitcnt lgkmcnt(1)
	v_rcp_f32_e32 v34, v34
	s_or_b32 s12, s22, s12
	s_lshl_b64 s[12:13], s[12:13], 11
	s_add_u32 s1, s9, s12
	v_mul_f32_e32 v18, v18, v34
	v_bfe_u32 v44, v18, 16, 1
	v_add3_u32 v18, v18, v44, s97
	v_lshl_add_u32 v44, v128, 9, v43
	ds_write_b16_d16_hi v44, v18
	v_rcp_f32_e32 v18, v35
	v_mul_f32_e32 v2, v2, v34
	v_bfe_u32 v34, v2, 16, 1
	v_add3_u32 v2, v2, v34, s97
	ds_write_b16_d16_hi v44, v2 offset:64
	v_mul_f32_e32 v2, v19, v18
	v_bfe_u32 v19, v2, 16, 1
	v_add3_u32 v2, v2, v19, s97
	v_lshl_add_u32 v19, v127, 7, v43
	ds_write_b16_d16_hi v19, v2
	v_mul_f32_e32 v2, v3, v18
	v_rcp_f32_e32 v3, v36
	v_bfe_u32 v18, v2, 16, 1
	v_add3_u32 v2, v2, v18, s97
	ds_write_b16_d16_hi v19, v2 offset:64
	v_mul_f32_e32 v2, v20, v3
	v_bfe_u32 v18, v2, 16, 1
	v_add3_u32 v2, v2, v18, s97
	v_lshl_add_u32 v18, v126, 7, v43
	ds_write_b16_d16_hi v18, v2
	v_mul_f32_e32 v2, v4, v3
	v_rcp_f32_e32 v3, v37
	v_bfe_u32 v4, v2, 16, 1
	v_add3_u32 v2, v2, v4, s97
	ds_write_b16_d16_hi v18, v2 offset:64
	v_mul_f32_e32 v2, v21, v3
	v_bfe_u32 v4, v2, 16, 1
	v_add3_u32 v2, v2, v4, s97
	v_lshl_add_u32 v4, v125, 7, v43
	ds_write_b16_d16_hi v4, v2
	v_mul_f32_e32 v2, v5, v3
	s_waitcnt lgkmcnt(7)
	v_rcp_f32_e32 v3, v38
	v_bfe_u32 v5, v2, 16, 1
	v_add3_u32 v2, v2, v5, s97
	ds_write_b16_d16_hi v4, v2 offset:64
	v_mul_f32_e32 v2, v22, v3
	v_bfe_u32 v4, v2, 16, 1
	v_add3_u32 v2, v2, v4, s97
	v_lshl_add_u32 v4, v124, 7, v43
	ds_write_b16_d16_hi v4, v2
	v_mul_f32_e32 v2, v6, v3
	v_rcp_f32_e32 v3, v39
	v_bfe_u32 v5, v2, 16, 1
	v_add3_u32 v2, v2, v5, s97
	ds_write_b16_d16_hi v4, v2 offset:64
	v_mul_f32_e32 v2, v23, v3
	v_bfe_u32 v4, v2, 16, 1
	v_add3_u32 v2, v2, v4, s97
	v_lshl_add_u32 v4, v123, 7, v43
	ds_write_b16_d16_hi v4, v2
	v_mul_f32_e32 v2, v7, v3
	v_rcp_f32_e32 v3, v40
	v_bfe_u32 v5, v2, 16, 1
	v_add3_u32 v2, v2, v5, s97
	ds_write_b16_d16_hi v4, v2 offset:64
	v_mul_f32_e32 v2, v24, v3
	v_bfe_u32 v4, v2, 16, 1
	v_add3_u32 v2, v2, v4, s97
	v_lshl_add_u32 v4, v122, 7, v43
	v_rcp_f32_e32 v6, v41
	ds_write_b16_d16_hi v4, v2
	v_mul_f32_e32 v2, v8, v3
	v_bfe_u32 v3, v2, 16, 1
	v_add3_u32 v2, v2, v3, s97
	ds_write_b16_d16_hi v4, v2 offset:64
	v_mul_f32_e32 v2, v25, v6
	v_bfe_u32 v3, v2, 16, 1
	v_add3_u32 v7, v2, v3, s97
	ds_read_b128 v[2:5], v42 offset:26688
	v_lshl_add_u32 v18, v121, 7, v43
	ds_write_b16_d16_hi v18, v7
	v_mul_f32_e32 v19, v9, v6
	ds_read_b128 v[6:9], v42 offset:26720
	s_waitcnt lgkmcnt(2)
	v_rcp_f32_e32 v2, v2
	v_bfe_u32 v20, v19, 16, 1
	v_add3_u32 v19, v19, v20, s97
	v_rcp_f32_e32 v3, v3
	ds_write_b16_d16_hi v18, v19 offset:64
	v_mul_f32_e32 v18, v26, v2
	v_mul_f32_e32 v2, v10, v2
	v_bfe_u32 v19, v18, 16, 1
	v_bfe_u32 v10, v2, 16, 1
	v_add3_u32 v18, v18, v19, s97
	v_lshl_add_u32 v19, v120, 7, v43
	v_add3_u32 v2, v2, v10, s97
	ds_write_b16_d16_hi v19, v2 offset:64
	v_mul_f32_e32 v2, v27, v3
	v_bfe_u32 v10, v2, 16, 1
	v_add3_u32 v2, v2, v10, s97
	v_lshl_add_u32 v10, v119, 7, v43
	ds_write_b16_d16_hi v10, v2
	v_mul_f32_e32 v2, v11, v3
	v_rcp_f32_e32 v3, v4
	v_bfe_u32 v4, v2, 16, 1
	v_add3_u32 v2, v2, v4, s97
	ds_write_b16_d16_hi v10, v2 offset:64
	v_mul_f32_e32 v2, v28, v3
	v_bfe_u32 v4, v2, 16, 1
	v_add3_u32 v2, v2, v4, s97
	v_lshl_add_u32 v4, v118, 7, v43
	ds_write_b16_d16_hi v4, v2
	v_mul_f32_e32 v2, v12, v3
	v_rcp_f32_e32 v3, v5
	v_bfe_u32 v5, v2, 16, 1
	v_add3_u32 v2, v2, v5, s97
	ds_write_b16_d16_hi v4, v2 offset:64
	v_mul_f32_e32 v2, v29, v3
	v_bfe_u32 v4, v2, 16, 1
	v_add3_u32 v2, v2, v4, s97
	v_lshl_add_u32 v4, v117, 7, v43
	ds_write_b16_d16_hi v4, v2
	v_mul_f32_e32 v2, v13, v3
	s_waitcnt lgkmcnt(7)
	v_rcp_f32_e32 v3, v6
	v_bfe_u32 v5, v2, 16, 1
	v_add3_u32 v2, v2, v5, s97
	ds_write_b16_d16_hi v4, v2 offset:64
	v_mul_f32_e32 v2, v30, v3
	v_bfe_u32 v4, v2, 16, 1
	v_add3_u32 v2, v2, v4, s97
	v_lshl_add_u32 v4, v116, 7, v43
	ds_write_b16_d16_hi v4, v2
	v_mul_f32_e32 v2, v14, v3
	v_rcp_f32_e32 v3, v7
	v_bfe_u32 v5, v2, 16, 1
	v_add3_u32 v2, v2, v5, s97
	ds_write_b16_d16_hi v4, v2 offset:64
	v_mul_f32_e32 v2, v31, v3
	v_bfe_u32 v4, v2, 16, 1
	v_add3_u32 v2, v2, v4, s97
	v_lshl_add_u32 v4, v115, 7, v43
	ds_write_b16_d16_hi v4, v2
	v_mul_f32_e32 v2, v15, v3
	v_rcp_f32_e32 v3, v8
	v_bfe_u32 v5, v2, 16, 1
	v_add3_u32 v2, v2, v5, s97
	ds_write_b16_d16_hi v4, v2 offset:64
	v_mul_f32_e32 v2, v32, v3
	v_bfe_u32 v4, v2, 16, 1
	v_add3_u32 v2, v2, v4, s97
	v_lshl_add_u32 v4, v114, 7, v43
	ds_write_b16_d16_hi v4, v2
	v_mul_f32_e32 v2, v16, v3
	v_rcp_f32_e32 v3, v9
	v_bfe_u32 v5, v2, 16, 1
	v_add3_u32 v2, v2, v5, s97
	ds_write_b16_d16_hi v4, v2 offset:64
	v_mul_f32_e32 v2, v33, v3
	v_bfe_u32 v4, v2, 16, 1
	v_add3_u32 v2, v2, v4, s97
	v_lshl_add_u32 v4, v113, 7, v43
	ds_write_b16_d16_hi v4, v2
	v_mul_f32_e32 v2, v17, v3
	v_bfe_u32 v3, v2, 16, 1
	v_add3_u32 v2, v2, v3, s97
	s_addc_u32 s13, s16, s13
	s_lshl_b32 s12, s21, 1
	ds_write_b16_d16_hi v4, v2 offset:64
	s_add_u32 s12, s1, s12
	v_lshlrev_b32_e32 v2, 4, v107
	s_addc_u32 s13, s13, 0
	v_and_b32_e32 v178, 0x70, v2
	ds_write_b16_d16_hi v19, v18
	v_lshrrev_b32_e32 v14, 3, v112
	v_add_u32_e32 v15, s0, v178
	v_lshl_add_u64 v[2:3], s[12:13], 0, v[178:179]
	s_mov_b64 s[0:1], 0x12c00400
	s_waitcnt lgkmcnt(0)
	v_lshl_add_u64 v[10:11], v[2:3], 0, s[0:1]
	v_lshl_add_u32 v2, v14, 7, v15
	v_or_b32_e32 v16, 8, v14
	ds_read_b128 v[2:5], v2
	v_lshl_add_u32 v6, v16, 7, v15
	ds_read_b128 v[6:9], v6
	v_lshlrev_b32_e32 v178, 11, v14
	v_lshl_add_u64 v[12:13], v[10:11], 0, v[178:179]
	v_lshlrev_b32_e32 v178, 11, v16
	s_waitcnt lgkmcnt(1)
	global_store_dwordx4 v[12:13], v[2:5], off sc1
	s_add_i32 s20, s20, s3
	s_add_i32 s17, s17, s40
	v_lshl_add_u64 v[2:3], v[10:11], 0, v[178:179]
	s_waitcnt lgkmcnt(0)
	global_store_dwordx4 v[2:3], v[6:9], off sc1
	s_cmpk_lt_i32 s20, 0x200
	s_nop 0
	v_or_b32_e32 v6, 16, v14
	v_lshl_add_u32 v2, v6, 7, v15
	v_or_b32_e32 v14, 24, v14
	ds_read_b128 v[2:5], v2
	v_lshlrev_b32_e32 v178, 11, v6
	v_lshl_add_u32 v6, v14, 7, v15
	ds_read_b128 v[6:9], v6
	v_lshl_add_u64 v[12:13], v[10:11], 0, v[178:179]
	v_lshlrev_b32_e32 v178, 11, v14
	s_waitcnt lgkmcnt(1)
	global_store_dwordx4 v[12:13], v[2:5], off sc1
	s_nop 1
	v_lshl_add_u64 v[2:3], v[10:11], 0, v[178:179]
	s_waitcnt lgkmcnt(0)
	global_store_dwordx4 v[2:3], v[6:9], off sc1
	s_barrier
	s_cbranch_scc0 .LBB0_443

.LBB0_446:
	s_or_b64 exec, exec, s[0:1]
	v_bfe_u32 v69, v50, 16, 1
	v_and_b32_e32 v68, 31, v100
	s_lshl_b32 s0, s82, 13
	v_add3_u32 v50, v50, v69, s97
	v_lshlrev_b32_e32 v69, 5, v100
	s_add_i32 s0, s0, 0
	v_lshlrev_b32_e32 v68, 1, v68
	v_and_b32_e32 v69, 0x400, v69
	v_add3_u32 v68, s0, v68, v69
	ds_write_b16_d16_hi v68, v50
	v_bfe_u32 v50, v51, 16, 1
	v_add3_u32 v50, v51, v50, s97
	ds_write_b16_d16_hi v68, v50 offset:256
	v_bfe_u32 v50, v52, 16, 1
	v_add3_u32 v50, v52, v50, s97
	ds_write_b16_d16_hi v68, v50 offset:512
	v_bfe_u32 v50, v53, 16, 1
	v_add3_u32 v50, v53, v50, s97
	ds_write_b16_d16_hi v68, v50 offset:768
	v_bfe_u32 v50, v54, 16, 1
	v_add3_u32 v50, v54, v50, s97
	ds_write_b16_d16_hi v68, v50 offset:2048
	v_bfe_u32 v50, v55, 16, 1
	v_add3_u32 v50, v55, v50, s97
	ds_write_b16_d16_hi v68, v50 offset:2304
	v_bfe_u32 v50, v56, 16, 1
	v_add3_u32 v50, v56, v50, s97
	ds_write_b16_d16_hi v68, v50 offset:2560
	v_bfe_u32 v50, v57, 16, 1
	v_add3_u32 v50, v57, v50, s97
	ds_write_b16_d16_hi v68, v50 offset:2816
	v_bfe_u32 v50, v58, 16, 1
	v_add3_u32 v50, v58, v50, s97
	ds_write_b16_d16_hi v68, v50 offset:4096
	v_bfe_u32 v50, v59, 16, 1
	v_add3_u32 v50, v59, v50, s97
	ds_write_b16_d16_hi v68, v50 offset:4352
	v_bfe_u32 v50, v60, 16, 1
	v_add3_u32 v50, v60, v50, s97
	ds_write_b16_d16_hi v68, v50 offset:4608
	v_bfe_u32 v50, v61, 16, 1
	v_add3_u32 v50, v61, v50, s97
	ds_write_b16_d16_hi v68, v50 offset:4864
	v_bfe_u32 v50, v62, 16, 1
	v_add3_u32 v50, v62, v50, s97
	ds_write_b16_d16_hi v68, v50 offset:6144
	v_bfe_u32 v50, v63, 16, 1
	v_add3_u32 v50, v63, v50, s97
	ds_write_b16_d16_hi v68, v50 offset:6400
	v_bfe_u32 v50, v64, 16, 1
	v_add3_u32 v50, v64, v50, s97
	ds_write_b16_d16_hi v68, v50 offset:6656
	v_bfe_u32 v50, v65, 16, 1
	v_add3_u32 v50, v65, v50, s97
	ds_write_b16_d16_hi v68, v50 offset:6912
	v_bfe_u32 v50, v34, 16, 1
	v_add3_u32 v34, v34, v50, s97
	ds_write_b16_d16_hi v68, v34 offset:64
	v_bfe_u32 v34, v35, 16, 1
	v_add3_u32 v34, v35, v34, s97
	ds_write_b16_d16_hi v68, v34 offset:320
	v_bfe_u32 v34, v36, 16, 1
	v_add3_u32 v34, v36, v34, s97
	ds_write_b16_d16_hi v68, v34 offset:576
	v_bfe_u32 v34, v37, 16, 1
	v_add3_u32 v34, v37, v34, s97
	ds_write_b16_d16_hi v68, v34 offset:832
	v_bfe_u32 v34, v38, 16, 1
	v_add3_u32 v34, v38, v34, s97
	ds_write_b16_d16_hi v68, v34 offset:2112
	v_bfe_u32 v34, v39, 16, 1
	v_add3_u32 v34, v39, v34, s97
	ds_write_b16_d16_hi v68, v34 offset:2368
	v_bfe_u32 v34, v40, 16, 1
	v_add3_u32 v34, v40, v34, s97
	ds_write_b16_d16_hi v68, v34 offset:2624
	v_bfe_u32 v34, v41, 16, 1
	v_add3_u32 v34, v41, v34, s97
	ds_write_b16_d16_hi v68, v34 offset:2880
	v_bfe_u32 v34, v42, 16, 1
	v_add3_u32 v34, v42, v34, s97
	ds_write_b16_d16_hi v68, v34 offset:4160
	v_bfe_u32 v34, v43, 16, 1
	v_add3_u32 v34, v43, v34, s97
	ds_write_b16_d16_hi v68, v34 offset:4416
	v_bfe_u32 v34, v44, 16, 1
	v_add3_u32 v34, v44, v34, s97
	ds_write_b16_d16_hi v68, v34 offset:4672
	v_bfe_u32 v34, v45, 16, 1
	v_add3_u32 v34, v45, v34, s97
	ds_write_b16_d16_hi v68, v34 offset:4928
	v_bfe_u32 v34, v46, 16, 1
	v_add3_u32 v34, v46, v34, s97
	ds_write_b16_d16_hi v68, v34 offset:6208
	v_bfe_u32 v34, v47, 16, 1
	v_add3_u32 v34, v47, v34, s97
	ds_write_b16_d16_hi v68, v34 offset:6464
	v_bfe_u32 v34, v48, 16, 1
	v_add3_u32 v34, v48, v34, s97
	ds_write_b16_d16_hi v68, v34 offset:6720
	v_bfe_u32 v34, v49, 16, 1
	v_add3_u32 v34, v49, v34, s97
	ds_write_b16_d16_hi v68, v34 offset:6976
	v_bfe_u32 v34, v18, 16, 1
	v_add3_u32 v18, v18, v34, s97
	ds_write_b16_d16_hi v68, v18 offset:128
	v_bfe_u32 v18, v19, 16, 1
	v_add3_u32 v18, v19, v18, s97
	ds_write_b16_d16_hi v68, v18 offset:384
	v_bfe_u32 v18, v20, 16, 1
	v_add3_u32 v18, v20, v18, s97
	ds_write_b16_d16_hi v68, v18 offset:640
	v_bfe_u32 v18, v21, 16, 1
	v_add3_u32 v18, v21, v18, s97
	ds_write_b16_d16_hi v68, v18 offset:896
	v_bfe_u32 v18, v22, 16, 1
	v_add3_u32 v18, v22, v18, s97
	ds_write_b16_d16_hi v68, v18 offset:2176
	v_bfe_u32 v18, v23, 16, 1
	v_add3_u32 v18, v23, v18, s97
	ds_write_b16_d16_hi v68, v18 offset:2432
	v_bfe_u32 v18, v24, 16, 1
	v_add3_u32 v18, v24, v18, s97
	ds_write_b16_d16_hi v68, v18 offset:2688
	v_bfe_u32 v18, v25, 16, 1
	v_add3_u32 v18, v25, v18, s97
	ds_write_b16_d16_hi v68, v18 offset:2944
	v_bfe_u32 v18, v26, 16, 1
	v_add3_u32 v18, v26, v18, s97
	ds_write_b16_d16_hi v68, v18 offset:4224
	v_bfe_u32 v18, v27, 16, 1
	v_add3_u32 v18, v27, v18, s97
	ds_write_b16_d16_hi v68, v18 offset:4480
	v_bfe_u32 v18, v28, 16, 1
	v_add3_u32 v18, v28, v18, s97
	ds_write_b16_d16_hi v68, v18 offset:4736
	v_bfe_u32 v18, v29, 16, 1
	v_add3_u32 v18, v29, v18, s97
	ds_write_b16_d16_hi v68, v18 offset:4992
	v_bfe_u32 v18, v30, 16, 1
	v_add3_u32 v18, v30, v18, s97
	ds_write_b16_d16_hi v68, v18 offset:6272
	v_bfe_u32 v18, v31, 16, 1
	v_add3_u32 v18, v31, v18, s97
	ds_write_b16_d16_hi v68, v18 offset:6528
	v_bfe_u32 v18, v32, 16, 1
	v_add3_u32 v18, v32, v18, s97
	ds_write_b16_d16_hi v68, v18 offset:6784
	v_bfe_u32 v18, v33, 16, 1
	v_add3_u32 v18, v33, v18, s97
	ds_write_b16_d16_hi v68, v18 offset:7040
	v_bfe_u32 v18, v2, 16, 1
	v_add3_u32 v2, v2, v18, s97
	ds_write_b16_d16_hi v68, v2 offset:192
	v_bfe_u32 v2, v3, 16, 1
	v_add3_u32 v2, v3, v2, s97
	ds_write_b16_d16_hi v68, v2 offset:448
	v_bfe_u32 v2, v4, 16, 1
	v_add3_u32 v2, v4, v2, s97
	ds_write_b16_d16_hi v68, v2 offset:704
	v_bfe_u32 v2, v5, 16, 1
	v_add3_u32 v2, v5, v2, s97
	ds_write_b16_d16_hi v68, v2 offset:960
	v_bfe_u32 v2, v6, 16, 1
	v_add3_u32 v2, v6, v2, s97
	ds_write_b16_d16_hi v68, v2 offset:2240
	v_bfe_u32 v2, v7, 16, 1
	v_add3_u32 v2, v7, v2, s97
	ds_write_b16_d16_hi v68, v2 offset:2496
	v_bfe_u32 v2, v8, 16, 1
	v_add3_u32 v2, v8, v2, s97
	ds_write_b16_d16_hi v68, v2 offset:2752
	v_bfe_u32 v2, v9, 16, 1
	v_add3_u32 v2, v9, v2, s97
	ds_write_b16_d16_hi v68, v2 offset:3008
	v_bfe_u32 v2, v10, 16, 1
	v_add3_u32 v2, v10, v2, s97
	ds_write_b16_d16_hi v68, v2 offset:4288
	v_bfe_u32 v2, v11, 16, 1
	v_add3_u32 v2, v11, v2, s97
	ds_write_b16_d16_hi v68, v2 offset:4544
	v_bfe_u32 v2, v12, 16, 1
	v_add3_u32 v2, v12, v2, s97
	ds_write_b16_d16_hi v68, v2 offset:4800
	v_bfe_u32 v2, v13, 16, 1
	v_add3_u32 v2, v13, v2, s97
	ds_write_b16_d16_hi v68, v2 offset:5056
	v_bfe_u32 v2, v14, 16, 1
	v_add3_u32 v2, v14, v2, s97
	ds_write_b16_d16_hi v68, v2 offset:6336
	v_bfe_u32 v2, v15, 16, 1
	v_add3_u32 v2, v15, v2, s97
	ds_write_b16_d16_hi v68, v2 offset:6592
	v_bfe_u32 v2, v16, 16, 1
	v_add3_u32 v2, v16, v2, s97
	ds_write_b16_d16_hi v68, v2 offset:6848
	v_bfe_u32 v2, v17, 16, 1
	v_add3_u32 v2, v17, v2, s97
	s_cmpk_lt_u32 s60, 0x100
	ds_write_b16_d16_hi v68, v2 offset:7104
	v_lshl_add_u32 v2, s5, 5, v67
	v_mov_b32_e32 v3, s21
	s_cselect_b64 vcc, -1, 0
	v_or_b32_e32 v2, s31, v2
	v_cndmask_b32_e32 v3, v66, v3, vcc
	v_lshl_add_u32 v2, v2, 4, v3
	v_ashrrev_i32_e32 v3, 31, v2
	v_lshlrev_b64 v[2:3], 15, v[2:3]
	v_and_b32_e32 v4, 0x180, v78
	v_lshl_add_u64 v[2:3], s[34:35], 0, v[2:3]
	s_lshl_b32 s82, s4, 13
	v_lshlrev_b32_e32 v20, 1, v4
	s_waitcnt lgkmcnt(0)
	v_lshl_add_u64 v[2:3], v[2:3], 0, s[82:83]
	v_add3_u32 v24, s0, v178, v20
	v_lshl_add_u64 v[18:19], v[2:3], 0, v[178:179]
	ds_read_b128 v[2:5], v24
	ds_read_b128 v[6:9], v24 offset:1024
	ds_read_b128 v[10:13], v24 offset:2048
	v_mov_b32_e32 v21, v179
	v_lshl_add_u64 v[22:23], v[18:19], 0, v[20:21]
	ds_read_b128 v[14:17], v24 offset:3072
	s_waitcnt lgkmcnt(3)
	global_store_dwordx4 v[22:23], v[2:5], off sc1
	s_waitcnt lgkmcnt(2)
	global_store_dwordx4 v[22:23], v[6:9], off offset:1024 sc1
	s_waitcnt lgkmcnt(1)
	global_store_dwordx4 v[22:23], v[10:13], off offset:2048 sc1
	ds_read_b128 v[2:5], v24 offset:4096
	ds_read_b128 v[6:9], v24 offset:5120
	v_or_b32_e32 v178, 0x1000, v20
	v_lshl_add_u64 v[10:11], v[18:19], 0, v[178:179]
	v_or_b32_e32 v178, 0x1400, v20
	s_waitcnt lgkmcnt(1)
	global_store_dwordx4 v[10:11], v[2:5], off sc1
	v_lshl_add_u64 v[10:11], v[18:19], 0, v[178:179]
	ds_read_b128 v[2:5], v24 offset:6144
	s_waitcnt lgkmcnt(1)
	global_store_dwordx4 v[10:11], v[6:9], off sc1
	ds_read_b128 v[6:9], v24 offset:7168
	v_or_b32_e32 v178, 0x1800, v20
	v_lshl_add_u64 v[10:11], v[18:19], 0, v[178:179]
	v_or_b32_e32 v178, 0x1c00, v20
	s_add_i32 s20, s20, s3
	s_waitcnt lgkmcnt(1)
	global_store_dwordx4 v[10:11], v[2:5], off sc1
	s_cmpk_lt_i32 s20, 0x200
	global_store_dwordx4 v[22:23], v[14:17], off offset:3072 sc1
	v_lshl_add_u64 v[2:3], v[18:19], 0, v[178:179]
	s_waitcnt lgkmcnt(0)
	global_store_dwordx4 v[2:3], v[6:9], off sc1
	s_barrier
	s_cbranch_scc0 .LBB0_479

.LBB0_472:
	s_or_b64 exec, exec, s[0:1]
	v_and_b32_e32 v58, 64, v205
	v_add_u32_e32 v50, -1, v205
	v_cmp_lt_i32_e64 s[4:5], v50, v58
	v_add_u32_e32 v60, -2, v205
	v_cmp_lt_i32_e64 s[8:9], v60, v58
	v_cndmask_b32_e64 v50, v50, v205, s[4:5]
	v_lshlrev_b32_e32 v50, 2, v50
	ds_bpermute_b32 v59, v50, v57
	v_cmp_eq_u32_e64 s[4:5], 0, v104
	ds_bpermute_b32 v50, v50, v51
	s_and_b64 s[0:1], vcc, exec
	s_mov_b32 s0, 0x18800
	s_waitcnt lgkmcnt(1)
	v_add_f32_e32 v59, v57, v59
	v_cndmask_b32_e64 v57, v59, v57, s[4:5]
	v_cndmask_b32_e64 v59, v60, v205, s[8:9]
	v_lshlrev_b32_e32 v59, 2, v59
	ds_bpermute_b32 v60, v59, v57
	v_cmp_gt_u32_e64 s[8:9], 2, v104
	s_waitcnt lgkmcnt(1)
	v_add_f32_e32 v50, v51, v50
	v_cndmask_b32_e64 v50, v50, v51, s[4:5]
	ds_bpermute_b32 v51, v59, v50
	s_waitcnt lgkmcnt(1)
	v_add_f32_e32 v60, v57, v60
	v_cndmask_b32_e64 v57, v60, v57, s[8:9]
	v_add_u32_e32 v60, -4, v205
	v_cmp_lt_i32_e64 s[10:11], v60, v58
	s_waitcnt lgkmcnt(0)
	v_add_f32_e32 v51, v50, v51
	v_cndmask_b32_e64 v50, v51, v50, s[8:9]
	v_cndmask_b32_e64 v60, v60, v205, s[10:11]
	v_lshlrev_b32_e32 v60, 2, v60
	ds_bpermute_b32 v61, v60, v57
	v_cmp_gt_u32_e64 s[10:11], 4, v104
	ds_bpermute_b32 v51, v60, v50
	v_cmp_gt_u32_e64 s[8:9], 16, v104
	s_cselect_b32 s0, s0, 0x18a00
	s_waitcnt lgkmcnt(1)
	v_add_f32_e32 v61, v57, v61
	v_cndmask_b32_e64 v57, v61, v57, s[10:11]
	v_add_u32_e32 v61, -8, v205
	v_cmp_lt_i32_e64 s[12:13], v61, v58
	s_waitcnt lgkmcnt(0)
	v_add_f32_e32 v51, v50, v51
	v_cndmask_b32_e64 v50, v51, v50, s[10:11]
	v_cndmask_b32_e64 v61, v61, v205, s[12:13]
	v_lshlrev_b32_e32 v61, 2, v61
	ds_bpermute_b32 v62, v61, v57
	v_cmp_gt_u32_e64 s[12:13], 8, v104
	ds_bpermute_b32 v51, v61, v50
	s_add_i32 s0, s0, 0
	v_lshl_add_u32 v53, v53, 2, s0
	s_waitcnt lgkmcnt(1)
	v_add_f32_e32 v62, v57, v62
	v_cndmask_b32_e64 v57, v62, v57, s[12:13]
	v_add_u32_e32 v62, -16, v205
	v_cmp_lt_i32_e64 s[14:15], v62, v58
	s_waitcnt lgkmcnt(0)
	v_add_f32_e32 v51, v50, v51
	v_cndmask_b32_e64 v50, v51, v50, s[12:13]
	v_cndmask_b32_e64 v59, v62, v205, s[14:15]
	v_lshlrev_b32_e32 v59, 2, v59
	ds_bpermute_b32 v62, v59, v57
	ds_bpermute_b32 v51, v59, v50
	s_waitcnt lgkmcnt(1)
	v_add_f32_e32 v60, v57, v62
	v_cndmask_b32_e64 v57, v60, v57, s[8:9]
	v_subrev_u32_e32 v60, 32, v205
	v_cmp_lt_i32_e64 s[10:11], v60, v58
	s_waitcnt lgkmcnt(0)
	v_add_f32_e32 v51, v50, v51
	v_cndmask_b32_e64 v50, v51, v50, s[8:9]
	v_cndmask_b32_e64 v60, v60, v205, s[10:11]
	v_lshlrev_b32_e32 v60, 2, v60
	ds_bpermute_b32 v61, v60, v57
	v_cmp_gt_u32_e64 s[10:11], 32, v104
	ds_bpermute_b32 v51, v60, v50
	s_waitcnt lgkmcnt(1)
	v_add_f32_e32 v59, v57, v61
	v_cndmask_b32_e64 v57, v59, v57, s[10:11]
	v_lshl_or_b32 v59, v205, 2, v210
	ds_bpermute_b32 v60, v59, v57
	s_waitcnt lgkmcnt(1)
	v_add_f32_e32 v51, v50, v51
	v_cndmask_b32_e64 v50, v51, v50, s[10:11]
	s_waitcnt lgkmcnt(0)
	v_add_f32_e32 v51, v50, v60
	ds_bpermute_b32 v50, v59, v51
	s_waitcnt lgkmcnt(0)
	v_sub_f32_e32 v57, v50, v57
	v_add_f32_e32 v55, v55, v57
	v_add_u32_e32 v57, 64, v58
	v_xor_b32_e32 v58, 1, v205
	v_sub_f32_e32 v51, v50, v51
	v_cmp_lt_i32_e64 s[8:9], v58, v57
	v_add_f32_e32 v56, v56, v51
	v_max_f32_e32 v51, v55, v56
	v_cndmask_b32_e64 v58, v205, v58, s[8:9]
	v_lshlrev_b32_e32 v58, 2, v58
	ds_bpermute_b32 v58, v58, v51
	s_waitcnt lgkmcnt(0)
	v_max_f32_e32 v58, v58, v58
	v_max_f32_e32 v51, v51, v58
	v_xor_b32_e32 v58, 2, v205
	v_cmp_lt_i32_e64 s[8:9], v58, v57
	s_nop 1
	v_cndmask_b32_e64 v58, v205, v58, s[8:9]
	v_lshlrev_b32_e32 v58, 2, v58
	ds_bpermute_b32 v58, v58, v51
	s_waitcnt lgkmcnt(0)
	v_max_f32_e32 v58, v58, v58
	v_max_f32_e32 v51, v51, v58
	v_xor_b32_e32 v58, 4, v205
	v_cmp_lt_i32_e64 s[8:9], v58, v57
	s_nop 1
	v_cndmask_b32_e64 v58, v205, v58, s[8:9]
	v_lshlrev_b32_e32 v58, 2, v58
	ds_bpermute_b32 v58, v58, v51
	s_waitcnt lgkmcnt(0)
	v_max_f32_e32 v58, v58, v58
	v_max_f32_e32 v51, v51, v58
	v_xor_b32_e32 v58, 8, v205
	v_cmp_lt_i32_e64 s[8:9], v58, v57
	s_nop 1
	v_cndmask_b32_e64 v58, v205, v58, s[8:9]
	v_lshlrev_b32_e32 v58, 2, v58
	ds_bpermute_b32 v58, v58, v51
	s_waitcnt lgkmcnt(0)
	v_max_f32_e32 v58, v58, v58
	v_max_f32_e32 v51, v51, v58
	v_xor_b32_e32 v58, 16, v205
	v_cmp_lt_i32_e64 s[8:9], v58, v57
	s_nop 1
	v_cndmask_b32_e64 v58, v205, v58, s[8:9]
	v_lshlrev_b32_e32 v58, 2, v58
	ds_bpermute_b32 v58, v58, v51
	s_waitcnt lgkmcnt(0)
	v_max_f32_e32 v58, v58, v58
	v_max_f32_e32 v51, v51, v58
	v_xor_b32_e32 v58, 32, v205
	v_cmp_lt_i32_e64 s[8:9], v58, v57
	s_nop 1
	v_cndmask_b32_e64 v57, v205, v58, s[8:9]
	v_lshlrev_b32_e32 v57, 2, v57
	ds_bpermute_b32 v57, v57, v51
	s_waitcnt lgkmcnt(0)
	v_max_f32_e32 v57, v57, v57
	v_max_f32_e32 v51, v51, v57
	v_sub_f32_e32 v55, v55, v51
	v_mul_f32_e32 v55, 0x3fb8aa3b, v55
	v_sub_f32_e32 v56, v56, v51
	v_exp_f32_e32 v55, v55
	v_mul_f32_e32 v56, 0x3fb8aa3b, v56
	v_exp_f32_e32 v56, v56
	ds_write_b32 v53, v55
	v_lshl_add_u32 v53, v54, 2, s0
	ds_write_b32 v53, v56
	s_and_saveexec_b64 s[0:1], s[4:5]
	s_cbranch_execz .LBB0_474
	s_lshl_b32 s4, s82, 5
	s_lshl_b32 s5, s61, 2
	s_add_i32 s4, s4, s5
	s_or_b32 s4, s4, s31
	s_lshl_b32 s9, s21, 1
	s_lshl_b32 s8, s4, 5
	s_xor_b32 s10, s9, 30
	s_and_b64 s[4:5], vcc, exec
	s_cselect_b32 s4, s9, s10
	s_or_b32 s4, s8, s4
	s_ashr_i32 s5, s4, 31
	s_lshl_b64 s[4:5], s[4:5], 2
	s_add_u32 s4, s16, s4
	s_addc_u32 s5, s17, s5
	global_store_dwordx2 v179, v[50:51], s[4:5] sc1

.LBB0_475:
	v_lshlrev_b32_e32 v54, 2, v52
	v_mov_b32_e32 v55, v179
	v_lshl_add_u64 v[66:67], s[28:29], 0, v[54:55]
	s_mov_b64 s[0:1], 0x1800
	s_waitcnt lgkmcnt(0)
	s_barrier
	global_load_dwordx4 v[50:53], v54, s[28:29] offset:2064
	global_load_dwordx4 v[70:73], v54, s[28:29] offset:2048
	v_lshl_add_u64 v[54:55], v[66:67], 0, s[0:1]
	v_add_co_u32_e32 v56, vcc, 0x1000, v66
	s_mov_b64 s[0:1], 0x2800
	s_nop 0
	v_addc_co_u32_e32 v57, vcc, 0, v67, vcc
	v_lshl_add_u64 v[58:59], v[66:67], 0, s[0:1]
	s_movk_i32 s0, 0x2000
	v_add_co_u32_e32 v60, vcc, s0, v66
	s_mov_b64 s[0:1], 0x3800
	s_nop 0
	v_addc_co_u32_e32 v61, vcc, 0, v67, vcc
	v_lshl_add_u64 v[62:63], v[66:67], 0, s[0:1]
	v_add_co_u32_e32 v64, vcc, 0x3000, v66
	s_mov_b64 s[0:1], 0x4800
	global_load_dwordx4 v[74:77], v[56:57], off offset:2048
	s_nop 0
	global_load_dwordx4 v[54:57], v[54:55], off offset:16
	v_addc_co_u32_e32 v65, vcc, 0, v67, vcc
	v_lshl_add_u64 v[68:69], v[66:67], 0, s[0:1]
	s_movk_i32 s0, 0x4000
	global_load_dwordx4 v[78:81], v[60:61], off offset:2048
	s_nop 0
	global_load_dwordx4 v[58:61], v[58:59], off offset:16
	v_add_co_u32_e32 v66, vcc, s0, v66
	global_load_dwordx4 v[82:85], v[64:65], off offset:2048
	s_nop 0
	global_load_dwordx4 v[62:65], v[62:63], off offset:16
	v_addc_co_u32_e32 v67, vcc, 0, v67, vcc
	global_load_dwordx4 v[86:89], v[66:67], off offset:2048
	s_nop 0
	global_load_dwordx4 v[66:69], v[68:69], off offset:16
	s_waitcnt vmcnt(14)
	v_lshlrev_b32_e32 v112, 16, v22
	v_and_b32_e32 v113, 0xffff0000, v22
	v_lshlrev_b32_e32 v108, 16, v26
	v_and_b32_e32 v109, 0xffff0000, v26
	v_lshlrev_b32_e32 v106, 16, v30
	v_and_b32_e32 v107, 0xffff0000, v30
	v_lshlrev_b32_e32 v90, 16, v34
	v_and_b32_e32 v91, 0xffff0000, v34
	v_lshlrev_b32_e32 v92, 16, v42
	v_and_b32_e32 v93, 0xffff0000, v42
	v_lshlrev_b32_e32 v94, 16, v38
	v_and_b32_e32 v95, 0xffff0000, v38
	v_lshlrev_b32_e32 v96, 16, v46
	v_and_b32_e32 v97, 0xffff0000, v46
	v_lshlrev_b32_e32 v42, 16, v43
	v_and_b32_e32 v43, 0xffff0000, v43
	v_lshlrev_b32_e32 v46, 16, v47
	v_and_b32_e32 v47, 0xffff0000, v47
	s_add_i32 s8, 0, 0x18a00
	s_ashr_i32 s5, s60, 8
	s_and_b32 s4, s82, 3
	s_waitcnt vmcnt(8)
	v_pk_fma_f32 v[112:113], v[70:71], v[112:113], 0 op_sel_hi:[1,1,0]
	v_pk_fma_f32 v[110:111], v[70:71], v[108:109], 0 op_sel_hi:[1,1,0]
	v_pk_fma_f32 v[98:99], v[70:71], v[106:107], 0 op_sel_hi:[1,1,0]
	v_pk_fma_f32 v[70:71], v[70:71], v[90:91], 0 op_sel_hi:[1,1,0]
	s_waitcnt vmcnt(7)
	v_pk_fma_f32 v[108:109], v[74:75], v[108:109], v[112:113]
	v_pk_fma_f32 v[110:111], v[74:75], v[106:107], v[110:111]
	v_pk_fma_f32 v[98:99], v[74:75], v[90:91], v[98:99]
	v_pk_fma_f32 v[70:71], v[74:75], v[92:93], v[70:71]
	v_lshlrev_b32_e32 v74, 16, v18
	s_waitcnt vmcnt(5)
	v_pk_fma_f32 v[106:107], v[78:79], v[106:107], v[108:109]
	v_pk_fma_f32 v[98:99], v[78:79], v[92:93], v[98:99]
	v_pk_fma_f32 v[70:71], v[78:79], v[94:95], v[70:71]
	s_waitcnt vmcnt(3)
	v_pk_fma_f32 v[106:107], v[82:83], v[90:91], v[106:107]
	v_pk_fma_f32 v[98:99], v[82:83], v[94:95], v[98:99]
	v_pk_fma_f32 v[70:71], v[82:83], v[96:97], v[70:71]
	s_waitcnt vmcnt(1)
	v_pk_fma_f32 v[106:107], v[86:87], v[92:93], v[106:107]
	v_pk_fma_f32 v[98:99], v[86:87], v[96:97], v[98:99]
	v_mul_f32_e32 v22, 0xbfb8aa3b, v106
	v_exp_f32_e32 v108, v22
	v_mul_f32_e32 v22, 0xbfb8aa3b, v107
	v_exp_f32_e32 v109, v22
	v_and_b32_e32 v75, 0xffff0000, v18
	v_pk_fma_f32 v[70:71], v[86:87], v[74:75], v[70:71]
	v_pk_add_f32 v[108:109], v[108:109], 1.0 op_sel_hi:[1,0]
	s_nop 0
	v_div_scale_f32 v22, s[0:1], v109, v109, v107
	v_rcp_f32_e32 v26, v22
	v_mul_f32_e32 v18, 0xbfb8aa3b, v70
	v_exp_f32_e32 v74, v18
	v_mul_f32_e32 v18, 0xbfb8aa3b, v71
	v_fma_f32 v30, -v22, v26, 1.0
	v_fmac_f32_e32 v26, v30, v26
	v_div_scale_f32 v30, vcc, v107, v109, v107
	v_mul_f32_e32 v34, v30, v26
	v_fma_f32 v38, -v22, v34, v30
	v_fmac_f32_e32 v34, v38, v26
	v_fma_f32 v22, -v22, v34, v30
	v_div_fmas_f32 v22, v22, v26, v34
	v_div_fixup_f32 v107, v22, v109, v107
	v_div_scale_f32 v22, s[0:1], v108, v108, v106
	v_rcp_f32_e32 v26, v22
	v_exp_f32_e32 v75, v18
	v_fma_f32 v30, -v22, v26, 1.0
	v_fmac_f32_e32 v26, v30, v26
	v_div_scale_f32 v30, vcc, v106, v108, v106
	v_mul_f32_e32 v34, v30, v26
	v_fma_f32 v38, -v22, v34, v30
	v_fmac_f32_e32 v34, v38, v26
	v_fma_f32 v22, -v22, v34, v30
	v_div_fmas_f32 v22, v22, v26, v34
	v_div_fixup_f32 v106, v22, v108, v106
	v_pk_mul_f32 v[106:107], v[106:107], s[26:27] op_sel_hi:[1,0]
	v_pk_add_f32 v[74:75], v[74:75], 1.0 op_sel_hi:[1,0]
	v_cvt_pk_bf16_f32 v105, v106, v107
	v_pk_fma_f32 v[106:107], v[78:79], v[90:91], v[110:111]
	v_div_scale_f32 v18, s[0:1], v75, v75, v71
	v_pk_fma_f32 v[106:107], v[82:83], v[92:93], v[106:107]
	s_nop 0
	v_pk_fma_f32 v[106:107], v[86:87], v[94:95], v[106:107]
	s_nop 0
	v_mul_f32_e32 v22, 0xbfb8aa3b, v106
	v_exp_f32_e32 v108, v22
	v_mul_f32_e32 v22, 0xbfb8aa3b, v107
	v_exp_f32_e32 v109, v22
	s_nop 0
	v_pk_add_f32 v[108:109], v[108:109], 1.0 op_sel_hi:[1,0]
	s_nop 0
	v_div_scale_f32 v22, s[0:1], v109, v109, v107
	v_rcp_f32_e32 v26, v22
	s_nop 0
	v_fma_f32 v30, -v22, v26, 1.0
	v_fmac_f32_e32 v26, v30, v26
	v_div_scale_f32 v30, vcc, v107, v109, v107
	v_mul_f32_e32 v34, v30, v26
	v_fma_f32 v38, -v22, v34, v30
	v_fmac_f32_e32 v34, v38, v26
	v_fma_f32 v22, -v22, v34, v30
	v_div_fmas_f32 v22, v22, v26, v34
	v_div_fixup_f32 v107, v22, v109, v107
	v_div_scale_f32 v22, s[0:1], v108, v108, v106
	v_rcp_f32_e32 v26, v22
	s_nop 0
	v_fma_f32 v30, -v22, v26, 1.0
	v_fmac_f32_e32 v26, v30, v26
	v_div_scale_f32 v30, vcc, v106, v108, v106
	v_mul_f32_e32 v34, v30, v26
	v_fma_f32 v38, -v22, v34, v30
	v_fmac_f32_e32 v34, v38, v26
	v_fma_f32 v22, -v22, v34, v30
	v_div_fmas_f32 v22, v22, v26, v34
	v_div_fixup_f32 v106, v22, v108, v106
	v_mul_f32_e32 v22, 0xbfb8aa3b, v98
	v_exp_f32_e32 v108, v22
	v_mul_f32_e32 v22, 0xbfb8aa3b, v99
	v_exp_f32_e32 v109, v22
	v_pk_mul_f32 v[106:107], v[106:107], s[26:27] op_sel_hi:[1,0]
	v_pk_add_f32 v[108:109], v[108:109], 1.0 op_sel_hi:[1,0]
	s_nop 0
	v_div_scale_f32 v22, s[0:1], v109, v109, v99
	v_rcp_f32_e32 v26, v22
	v_cvt_pk_bf16_f32 v106, v106, v107
	v_fma_f32 v30, -v22, v26, 1.0
	v_fmac_f32_e32 v26, v30, v26
	v_div_scale_f32 v30, vcc, v99, v109, v99
	v_mul_f32_e32 v34, v30, v26
	v_fma_f32 v38, -v22, v34, v30
	v_fmac_f32_e32 v34, v38, v26
	v_fma_f32 v22, -v22, v34, v30
	v_div_fmas_f32 v22, v22, v26, v34
	v_div_fixup_f32 v99, v22, v109, v99
	v_div_scale_f32 v22, s[0:1], v108, v108, v98
	v_rcp_f32_e32 v26, v22
	s_nop 0
	v_fma_f32 v30, -v22, v26, 1.0
	v_fmac_f32_e32 v26, v30, v26
	v_div_scale_f32 v30, vcc, v98, v108, v98
	v_mul_f32_e32 v34, v30, v26
	v_fma_f32 v38, -v22, v34, v30
	v_fmac_f32_e32 v34, v38, v26
	v_fma_f32 v22, -v22, v34, v30
	v_div_fmas_f32 v22, v22, v26, v34
	v_div_fixup_f32 v98, v22, v108, v98
	v_rcp_f32_e32 v22, v18
	v_lshlrev_b32_e32 v38, 16, v39
	v_and_b32_e32 v39, 0xffff0000, v39
	v_pk_mul_f32 v[98:99], v[98:99], s[26:27] op_sel_hi:[1,0]
	v_fma_f32 v26, -v18, v22, 1.0
	v_fmac_f32_e32 v22, v26, v22
	v_div_scale_f32 v26, vcc, v71, v75, v71
	v_mul_f32_e32 v30, v26, v22
	v_fma_f32 v34, -v18, v30, v26
	v_fmac_f32_e32 v30, v34, v22
	v_fma_f32 v18, -v18, v30, v26
	v_div_fmas_f32 v18, v18, v22, v30
	v_div_fixup_f32 v71, v18, v75, v71
	v_div_scale_f32 v18, s[0:1], v74, v74, v70
	v_rcp_f32_e32 v22, v18
	v_and_b32_e32 v75, 0xffff0000, v31
	v_cvt_pk_bf16_f32 v98, v98, v99
	v_fma_f32 v26, -v18, v22, 1.0
	v_fmac_f32_e32 v22, v26, v22
	v_div_scale_f32 v26, vcc, v70, v74, v70
	v_mul_f32_e32 v30, v26, v22
	v_fma_f32 v34, -v18, v30, v26
	v_fmac_f32_e32 v30, v34, v22
	v_fma_f32 v18, -v18, v30, v26
	v_div_fmas_f32 v18, v18, v22, v30
	v_lshlrev_b32_e32 v22, 16, v23
	v_and_b32_e32 v23, 0xffff0000, v23
	v_lshlrev_b32_e32 v26, 16, v27
	v_and_b32_e32 v27, 0xffff0000, v27
	v_pk_fma_f32 v[22:23], v[72:73], v[22:23], 0 op_sel_hi:[1,1,0]
	v_div_fixup_f32 v70, v18, v74, v70
	v_lshlrev_b32_e32 v74, 16, v31
	v_pk_fma_f32 v[22:23], v[76:77], v[26:27], v[22:23]
	v_lshlrev_b32_e32 v34, 16, v35
	v_and_b32_e32 v35, 0xffff0000, v35
	v_pk_fma_f32 v[22:23], v[80:81], v[74:75], v[22:23]
	v_pk_fma_f32 v[78:79], v[72:73], v[26:27], 0 op_sel_hi:[1,1,0]
	v_pk_fma_f32 v[22:23], v[84:85], v[34:35], v[22:23]
	v_pk_fma_f32 v[30:31], v[72:73], v[74:75], 0 op_sel_hi:[1,1,0]
	v_pk_fma_f32 v[22:23], v[88:89], v[42:43], v[22:23]
	v_pk_fma_f32 v[78:79], v[76:77], v[74:75], v[78:79]
	v_mul_f32_e32 v18, 0xbfb8aa3b, v22
	v_exp_f32_e32 v26, v18
	v_mul_f32_e32 v18, 0xbfb8aa3b, v23
	v_exp_f32_e32 v27, v18
	v_pk_mul_f32 v[70:71], v[70:71], s[26:27] op_sel_hi:[1,0]
	v_pk_add_f32 v[26:27], v[26:27], 1.0 op_sel_hi:[1,0]
	s_nop 0
	v_div_scale_f32 v18, s[0:1], v27, v27, v23
	v_rcp_f32_e32 v74, v18
	s_nop 0
	v_fma_f32 v75, -v18, v74, 1.0
	v_fmac_f32_e32 v74, v75, v74
	v_div_scale_f32 v75, vcc, v23, v27, v23
	v_mul_f32_e32 v82, v75, v74
	v_fma_f32 v83, -v18, v82, v75
	v_fmac_f32_e32 v82, v83, v74
	v_fma_f32 v18, -v18, v82, v75
	v_div_fmas_f32 v18, v18, v74, v82
	v_div_fixup_f32 v23, v18, v27, v23
	v_div_scale_f32 v18, s[0:1], v26, v26, v22
	v_rcp_f32_e32 v27, v18
	s_nop 0
	v_fma_f32 v74, -v18, v27, 1.0
	v_fmac_f32_e32 v27, v74, v27
	v_div_scale_f32 v74, vcc, v22, v26, v22
	v_mul_f32_e32 v75, v74, v27
	v_fma_f32 v82, -v18, v75, v74
	v_fmac_f32_e32 v75, v82, v27
	v_fma_f32 v18, -v18, v75, v74
	v_div_fmas_f32 v18, v18, v27, v75
	v_div_fixup_f32 v22, v18, v26, v22
	v_pk_mul_f32 v[22:23], v[22:23], s[26:27] op_sel_hi:[1,0]
	s_nop 0
	v_cvt_pk_bf16_f32 v74, v22, v23
	v_pk_fma_f32 v[22:23], v[80:81], v[34:35], v[78:79]
	s_nop 0
	v_pk_fma_f32 v[22:23], v[84:85], v[42:43], v[22:23]
	s_nop 0
	v_pk_fma_f32 v[22:23], v[88:89], v[38:39], v[22:23]
	s_nop 0
	v_mul_f32_e32 v18, 0xbfb8aa3b, v22
	v_exp_f32_e32 v26, v18
	v_mul_f32_e32 v18, 0xbfb8aa3b, v23
	v_exp_f32_e32 v27, v18
	s_nop 0
	v_pk_add_f32 v[26:27], v[26:27], 1.0 op_sel_hi:[1,0]
	s_nop 0
	v_div_scale_f32 v18, s[0:1], v27, v27, v23
	v_rcp_f32_e32 v75, v18
	s_nop 0
	v_fma_f32 v78, -v18, v75, 1.0
	v_fmac_f32_e32 v75, v78, v75
	v_div_scale_f32 v78, vcc, v23, v27, v23
	v_mul_f32_e32 v79, v78, v75
	v_fma_f32 v82, -v18, v79, v78
	v_fmac_f32_e32 v79, v82, v75
	v_fma_f32 v18, -v18, v79, v78
	v_div_fmas_f32 v18, v18, v75, v79
	v_div_fixup_f32 v23, v18, v27, v23
	v_div_scale_f32 v18, s[0:1], v26, v26, v22
	v_rcp_f32_e32 v27, v18
	s_nop 0
	v_fma_f32 v75, -v18, v27, 1.0
	v_fmac_f32_e32 v27, v75, v27
	v_div_scale_f32 v75, vcc, v22, v26, v22
	v_mul_f32_e32 v78, v75, v27
	v_fma_f32 v79, -v18, v78, v75
	v_fmac_f32_e32 v78, v79, v27
	v_fma_f32 v18, -v18, v78, v75
	v_div_fmas_f32 v18, v18, v27, v78
	v_div_fixup_f32 v22, v18, v26, v22
	v_pk_mul_f32 v[22:23], v[22:23], s[26:27] op_sel_hi:[1,0]
	s_nop 0
	v_cvt_pk_bf16_f32 v75, v22, v23
	v_pk_fma_f32 v[22:23], v[76:77], v[34:35], v[30:31]
	s_nop 0
	v_pk_fma_f32 v[22:23], v[80:81], v[42:43], v[22:23]
	s_nop 0
	v_pk_fma_f32 v[22:23], v[84:85], v[38:39], v[22:23]
	s_nop 0
	v_pk_fma_f32 v[22:23], v[88:89], v[46:47], v[22:23]
	s_nop 0
	v_mul_f32_e32 v18, 0xbfb8aa3b, v22
	v_exp_f32_e32 v26, v18
	v_mul_f32_e32 v18, 0xbfb8aa3b, v23
	v_exp_f32_e32 v27, v18
	s_nop 0
	v_pk_add_f32 v[26:27], v[26:27], 1.0 op_sel_hi:[1,0]
	s_nop 0
	v_div_scale_f32 v18, s[0:1], v27, v27, v23
	v_rcp_f32_e32 v30, v18
	s_nop 0
	v_fma_f32 v31, -v18, v30, 1.0
	v_fmac_f32_e32 v30, v31, v30
	v_div_scale_f32 v31, vcc, v23, v27, v23
	v_mul_f32_e32 v78, v31, v30
	v_fma_f32 v79, -v18, v78, v31
	v_fmac_f32_e32 v78, v79, v30
	v_fma_f32 v18, -v18, v78, v31
	v_div_fmas_f32 v18, v18, v30, v78
	v_div_fixup_f32 v23, v18, v27, v23
	v_div_scale_f32 v18, s[0:1], v26, v26, v22
	v_rcp_f32_e32 v27, v18
	s_nop 0
	v_fma_f32 v30, -v18, v27, 1.0
	v_fmac_f32_e32 v27, v30, v27
	v_div_scale_f32 v30, vcc, v22, v26, v22
	v_mul_f32_e32 v31, v30, v27
	v_fma_f32 v78, -v18, v31, v30
	v_fmac_f32_e32 v31, v78, v27
	v_fma_f32 v18, -v18, v31, v30
	v_div_fmas_f32 v18, v18, v27, v31
	v_div_fixup_f32 v22, v18, v26, v22
	v_pk_mul_f32 v[22:23], v[22:23], s[26:27] op_sel_hi:[1,0]
	v_lshlrev_b32_e32 v18, 16, v19
	v_cvt_pk_bf16_f32 v78, v22, v23
	v_pk_fma_f32 v[22:23], v[72:73], v[34:35], 0 op_sel_hi:[1,1,0]
	v_and_b32_e32 v19, 0xffff0000, v19
	v_pk_fma_f32 v[22:23], v[76:77], v[42:43], v[22:23]
	v_lshlrev_b32_e32 v76, 16, v24
	v_pk_fma_f32 v[22:23], v[80:81], v[38:39], v[22:23]
	v_and_b32_e32 v77, 0xffff0000, v24
	v_pk_fma_f32 v[22:23], v[84:85], v[46:47], v[22:23]
	v_lshlrev_b32_e32 v46, 16, v28
	v_pk_fma_f32 v[18:19], v[88:89], v[18:19], v[22:23]
	v_and_b32_e32 v47, 0xffff0000, v28
	v_mul_f32_e32 v22, 0xbfb8aa3b, v18
	v_mul_f32_e32 v23, 0xbfb8aa3b, v19
	v_exp_f32_e32 v22, v22
	v_exp_f32_e32 v23, v23
	v_pk_fma_f32 v[76:77], v[50:51], v[76:77], 0 op_sel_hi:[1,1,0]
	v_lshlrev_b32_e32 v42, 16, v32
	v_and_b32_e32 v43, 0xffff0000, v32
	v_pk_add_f32 v[22:23], v[22:23], 1.0 op_sel_hi:[1,0]
	v_pk_fma_f32 v[72:73], v[50:51], v[46:47], 0 op_sel_hi:[1,1,0]
	v_div_scale_f32 v26, s[0:1], v23, v23, v19
	v_rcp_f32_e32 v27, v26
	v_pk_fma_f32 v[46:47], v[54:55], v[46:47], v[76:77]
	v_pk_fma_f32 v[38:39], v[50:51], v[42:43], 0 op_sel_hi:[1,1,0]
	v_pk_fma_f32 v[72:73], v[54:55], v[42:43], v[72:73]
	v_fma_f32 v30, -v26, v27, 1.0
	v_fmac_f32_e32 v27, v30, v27
	v_div_scale_f32 v30, vcc, v19, v23, v19
	v_mul_f32_e32 v31, v30, v27
	v_fma_f32 v34, -v26, v31, v30
	v_fmac_f32_e32 v31, v34, v27
	v_fma_f32 v26, -v26, v31, v30
	v_div_fmas_f32 v26, v26, v27, v31
	v_div_fixup_f32 v19, v26, v23, v19
	v_div_scale_f32 v23, s[0:1], v22, v22, v18
	v_rcp_f32_e32 v26, v23
	v_pk_fma_f32 v[42:43], v[58:59], v[42:43], v[46:47]
	v_lshlrev_b32_e32 v34, 16, v48
	v_and_b32_e32 v35, 0xffff0000, v48
	v_fma_f32 v27, -v23, v26, 1.0
	v_fmac_f32_e32 v26, v27, v26
	v_div_scale_f32 v27, vcc, v18, v22, v18
	v_mul_f32_e32 v30, v27, v26
	v_fma_f32 v31, -v23, v30, v27
	v_fmac_f32_e32 v30, v31, v26
	v_fma_f32 v23, -v23, v30, v27
	v_div_fmas_f32 v23, v23, v26, v30
	v_div_fixup_f32 v18, v23, v22, v18
	v_lshlrev_b32_e32 v22, 16, v36
	v_and_b32_e32 v23, 0xffff0000, v36
	v_lshlrev_b32_e32 v26, 16, v44
	v_and_b32_e32 v27, 0xffff0000, v44
	v_pk_fma_f32 v[42:43], v[62:63], v[22:23], v[42:43]
	v_lshlrev_b32_e32 v30, 16, v40
	s_waitcnt vmcnt(0)
	v_pk_fma_f32 v[42:43], v[66:67], v[26:27], v[42:43]
	v_and_b32_e32 v31, 0xffff0000, v40
	v_mul_f32_e32 v24, 0xbfb8aa3b, v42
	v_exp_f32_e32 v46, v24
	v_mul_f32_e32 v24, 0xbfb8aa3b, v43
	v_exp_f32_e32 v47, v24
	v_pk_fma_f32 v[38:39], v[54:55], v[22:23], v[38:39]
	v_pk_mul_f32 v[18:19], v[18:19], s[26:27] op_sel_hi:[1,0]
	v_pk_fma_f32 v[38:39], v[58:59], v[26:27], v[38:39]
	v_pk_add_f32 v[46:47], v[46:47], 1.0 op_sel_hi:[1,0]
	v_pk_fma_f32 v[38:39], v[62:63], v[30:31], v[38:39]
	v_div_scale_f32 v24, s[0:1], v47, v47, v43
	v_rcp_f32_e32 v28, v24
	v_pk_fma_f32 v[38:39], v[66:67], v[34:35], v[38:39]
	v_fma_f32 v32, -v24, v28, 1.0
	v_fmac_f32_e32 v28, v32, v28
	v_div_scale_f32 v32, vcc, v43, v47, v43
	v_mul_f32_e32 v36, v32, v28
	v_fma_f32 v40, -v24, v36, v32
	v_fmac_f32_e32 v36, v40, v28
	v_fma_f32 v24, -v24, v36, v32
	v_div_fmas_f32 v24, v24, v28, v36
	v_div_fixup_f32 v43, v24, v47, v43
	v_div_scale_f32 v24, s[0:1], v46, v46, v42
	v_rcp_f32_e32 v28, v24
	s_nop 0
	v_fma_f32 v32, -v24, v28, 1.0
	v_fmac_f32_e32 v28, v32, v28
	v_div_scale_f32 v32, vcc, v42, v46, v42
	v_mul_f32_e32 v36, v32, v28
	v_fma_f32 v40, -v24, v36, v32
	v_fmac_f32_e32 v36, v40, v28
	v_fma_f32 v24, -v24, v36, v32
	v_div_fmas_f32 v24, v24, v28, v36
	v_div_fixup_f32 v42, v24, v46, v42
	v_pk_mul_f32 v[42:43], v[42:43], s[26:27] op_sel_hi:[1,0]
	s_nop 0
	v_cvt_pk_bf16_f32 v24, v42, v43
	v_pk_fma_f32 v[42:43], v[58:59], v[22:23], v[72:73]
	v_pk_fma_f32 v[22:23], v[50:51], v[22:23], 0 op_sel_hi:[1,1,0]
	v_pk_fma_f32 v[42:43], v[62:63], v[26:27], v[42:43]
	v_pk_fma_f32 v[22:23], v[54:55], v[26:27], v[22:23]
	v_pk_fma_f32 v[42:43], v[66:67], v[30:31], v[42:43]
	v_pk_fma_f32 v[22:23], v[58:59], v[30:31], v[22:23]
	v_mul_f32_e32 v28, 0xbfb8aa3b, v42
	v_exp_f32_e32 v46, v28
	v_mul_f32_e32 v28, 0xbfb8aa3b, v43
	v_exp_f32_e32 v47, v28
	v_pk_fma_f32 v[22:23], v[62:63], v[34:35], v[22:23]
	v_lshlrev_b32_e32 v26, 16, v20
	v_and_b32_e32 v27, 0xffff0000, v20
	v_pk_add_f32 v[46:47], v[46:47], 1.0 op_sel_hi:[1,0]
	v_pk_fma_f32 v[22:23], v[66:67], v[26:27], v[22:23]
	v_div_scale_f32 v28, s[0:1], v47, v47, v43
	v_rcp_f32_e32 v32, v28
	v_mul_f32_e32 v20, 0xbfb8aa3b, v22
	v_exp_f32_e32 v26, v20
	v_mul_f32_e32 v20, 0xbfb8aa3b, v23
	v_fma_f32 v36, -v28, v32, 1.0
	v_fmac_f32_e32 v32, v36, v32
	v_div_scale_f32 v36, vcc, v43, v47, v43
	v_mul_f32_e32 v40, v36, v32
	v_fma_f32 v44, -v28, v40, v36
	v_fmac_f32_e32 v40, v44, v32
	v_fma_f32 v28, -v28, v40, v36
	v_div_fmas_f32 v28, v28, v32, v40
	v_div_fixup_f32 v43, v28, v47, v43
	v_div_scale_f32 v28, s[0:1], v46, v46, v42
	v_rcp_f32_e32 v32, v28
	v_exp_f32_e32 v27, v20
	v_and_b32_e32 v47, 0xffff0000, v25
	v_and_b32_e32 v35, 0xffff0000, v41
	v_fma_f32 v36, -v28, v32, 1.0
	v_fmac_f32_e32 v32, v36, v32
	v_div_scale_f32 v36, vcc, v42, v46, v42
	v_mul_f32_e32 v40, v36, v32
	v_fma_f32 v44, -v28, v40, v36
	v_fmac_f32_e32 v40, v44, v32
	v_fma_f32 v28, -v28, v40, v36
	v_div_fmas_f32 v28, v28, v32, v40
	v_div_fixup_f32 v42, v28, v46, v42
	v_pk_mul_f32 v[42:43], v[42:43], s[26:27] op_sel_hi:[1,0]
	v_mul_f32_e32 v32, 0xbfb8aa3b, v38
	v_cvt_pk_bf16_f32 v28, v42, v43
	v_exp_f32_e32 v42, v32
	v_mul_f32_e32 v32, 0xbfb8aa3b, v39
	v_exp_f32_e32 v43, v32
	v_pk_add_f32 v[26:27], v[26:27], 1.0 op_sel_hi:[1,0]
	v_pk_add_f32 v[42:43], v[42:43], 1.0 op_sel_hi:[1,0]
	s_nop 0
	v_div_scale_f32 v32, s[0:1], v43, v43, v39
	v_rcp_f32_e32 v36, v32
	v_div_scale_f32 v20, s[0:1], v27, v27, v23
	v_rcp_f32_e32 v30, v20
	v_fma_f32 v40, -v32, v36, 1.0
	v_fmac_f32_e32 v36, v40, v36
	v_div_scale_f32 v40, vcc, v39, v43, v39
	v_mul_f32_e32 v44, v40, v36
	v_fma_f32 v46, -v32, v44, v40
	v_fmac_f32_e32 v44, v46, v36
	v_fma_f32 v32, -v32, v44, v40
	v_div_fmas_f32 v32, v32, v36, v44
	v_div_fixup_f32 v39, v32, v43, v39
	v_div_scale_f32 v32, s[0:1], v42, v42, v38
	v_rcp_f32_e32 v36, v32
	v_fma_f32 v31, -v20, v30, 1.0
	v_fmac_f32_e32 v30, v31, v30
	v_lshlrev_b32_e32 v46, 16, v25
	v_fma_f32 v40, -v32, v36, 1.0
	v_fmac_f32_e32 v36, v40, v36
	v_div_scale_f32 v40, vcc, v38, v42, v38
	v_mul_f32_e32 v43, v40, v36
	v_fma_f32 v44, -v32, v43, v40
	v_fmac_f32_e32 v43, v44, v36
	v_fma_f32 v32, -v32, v43, v40
	v_div_fmas_f32 v32, v32, v36, v43
	v_div_scale_f32 v31, vcc, v23, v27, v23
	v_div_fixup_f32 v38, v32, v42, v38
	v_mul_f32_e32 v32, v31, v30
	v_fma_f32 v34, -v20, v32, v31
	v_fmac_f32_e32 v32, v34, v30
	v_fma_f32 v20, -v20, v32, v31
	v_div_fmas_f32 v20, v20, v30, v32
	v_div_fixup_f32 v23, v20, v27, v23
	v_div_scale_f32 v20, s[0:1], v26, v26, v22
	v_rcp_f32_e32 v27, v20
	v_lshlrev_b32_e32 v42, 16, v29
	v_and_b32_e32 v43, 0xffff0000, v29
	v_pk_fma_f32 v[46:47], v[52:53], v[46:47], 0 op_sel_hi:[1,1,0]
	v_fma_f32 v30, -v20, v27, 1.0
	v_fmac_f32_e32 v27, v30, v27
	v_div_scale_f32 v30, vcc, v22, v26, v22
	v_mul_f32_e32 v31, v30, v27
	v_fma_f32 v32, -v20, v31, v30
	v_fmac_f32_e32 v31, v32, v27
	v_fma_f32 v20, -v20, v31, v30
	v_div_fmas_f32 v20, v20, v27, v31
	v_lshlrev_b32_e32 v30, 16, v45
	v_and_b32_e32 v31, 0xffff0000, v45
	v_lshlrev_b32_e32 v34, 16, v41
	v_lshlrev_b32_e32 v40, 16, v33
	v_and_b32_e32 v41, 0xffff0000, v33
	v_pk_fma_f32 v[44:45], v[52:53], v[42:43], 0 op_sel_hi:[1,1,0]
	v_pk_fma_f32 v[42:43], v[56:57], v[42:43], v[46:47]
	v_div_fixup_f32 v22, v20, v26, v22
	v_lshlrev_b32_e32 v26, 16, v37
	v_and_b32_e32 v27, 0xffff0000, v37
	v_pk_fma_f32 v[32:33], v[52:53], v[40:41], 0 op_sel_hi:[1,1,0]
	v_pk_fma_f32 v[44:45], v[56:57], v[40:41], v[44:45]
	v_pk_fma_f32 v[40:41], v[60:61], v[40:41], v[42:43]
	v_pk_mul_f32 v[38:39], v[38:39], s[26:27] op_sel_hi:[1,0]
	v_pk_fma_f32 v[40:41], v[64:65], v[26:27], v[40:41]
	v_cvt_pk_bf16_f32 v38, v38, v39
	v_pk_fma_f32 v[40:41], v[68:69], v[30:31], v[40:41]
	v_pk_fma_f32 v[32:33], v[56:57], v[26:27], v[32:33]
	v_mul_f32_e32 v20, 0xbfb8aa3b, v40
	v_exp_f32_e32 v42, v20
	v_mul_f32_e32 v20, 0xbfb8aa3b, v41
	v_exp_f32_e32 v43, v20
	v_pk_fma_f32 v[32:33], v[60:61], v[30:31], v[32:33]
	v_lshlrev_b32_e32 v36, 16, v49
	v_and_b32_e32 v37, 0xffff0000, v49
	v_pk_add_f32 v[42:43], v[42:43], 1.0 op_sel_hi:[1,0]
	v_pk_fma_f32 v[32:33], v[64:65], v[34:35], v[32:33]
	v_div_scale_f32 v20, s[0:1], v43, v43, v41
	v_rcp_f32_e32 v25, v20
	v_pk_fma_f32 v[32:33], v[68:69], v[36:37], v[32:33]
	v_pk_mul_f32 v[22:23], v[22:23], s[26:27] op_sel_hi:[1,0]
	v_fma_f32 v29, -v20, v25, 1.0
	v_fmac_f32_e32 v25, v29, v25
	v_div_scale_f32 v29, vcc, v41, v43, v41
	v_mul_f32_e32 v39, v29, v25
	v_fma_f32 v46, -v20, v39, v29
	v_fmac_f32_e32 v39, v46, v25
	v_fma_f32 v20, -v20, v39, v29
	v_div_fmas_f32 v20, v20, v25, v39
	v_div_fixup_f32 v41, v20, v43, v41
	v_div_scale_f32 v20, s[0:1], v42, v42, v40
	v_rcp_f32_e32 v25, v20
	s_nop 0
	v_fma_f32 v29, -v20, v25, 1.0
	v_fmac_f32_e32 v25, v29, v25
	v_div_scale_f32 v29, vcc, v40, v42, v40
	v_mul_f32_e32 v39, v29, v25
	v_fma_f32 v43, -v20, v39, v29
	v_fmac_f32_e32 v39, v43, v25
	v_fma_f32 v20, -v20, v39, v29
	v_div_fmas_f32 v20, v20, v25, v39
	v_div_fixup_f32 v40, v20, v42, v40
	v_pk_mul_f32 v[40:41], v[40:41], s[26:27] op_sel_hi:[1,0]
	s_nop 0
	v_cvt_pk_bf16_f32 v25, v40, v41
	v_pk_fma_f32 v[40:41], v[60:61], v[26:27], v[44:45]
	v_pk_fma_f32 v[26:27], v[52:53], v[26:27], 0 op_sel_hi:[1,1,0]
	v_pk_fma_f32 v[40:41], v[64:65], v[30:31], v[40:41]
	v_pk_fma_f32 v[26:27], v[56:57], v[30:31], v[26:27]
	v_pk_fma_f32 v[40:41], v[68:69], v[34:35], v[40:41]
	v_pk_fma_f32 v[26:27], v[60:61], v[34:35], v[26:27]
	v_mul_f32_e32 v20, 0xbfb8aa3b, v40
	v_exp_f32_e32 v42, v20
	v_mul_f32_e32 v20, 0xbfb8aa3b, v41
	v_exp_f32_e32 v43, v20
	v_pk_fma_f32 v[26:27], v[64:65], v[36:37], v[26:27]
	v_pk_add_f32 v[42:43], v[42:43], 1.0 op_sel_hi:[1,0]
	s_nop 0
	v_div_scale_f32 v20, s[0:1], v43, v43, v41
	v_rcp_f32_e32 v29, v20
	s_nop 0
	v_fma_f32 v39, -v20, v29, 1.0
	v_fmac_f32_e32 v29, v39, v29
	v_div_scale_f32 v39, vcc, v41, v43, v41
	v_mul_f32_e32 v44, v39, v29
	v_fma_f32 v45, -v20, v44, v39
	v_fmac_f32_e32 v44, v45, v29
	v_fma_f32 v20, -v20, v44, v39
	v_div_fmas_f32 v20, v20, v29, v44
	v_div_fixup_f32 v41, v20, v43, v41
	v_div_scale_f32 v20, s[0:1], v42, v42, v40
	v_rcp_f32_e32 v29, v20
	s_nop 0
	v_fma_f32 v39, -v20, v29, 1.0
	v_fmac_f32_e32 v29, v39, v29
	v_div_scale_f32 v39, vcc, v40, v42, v40
	v_mul_f32_e32 v43, v39, v29
	v_fma_f32 v44, -v20, v43, v39
	v_fmac_f32_e32 v43, v44, v29
	v_fma_f32 v20, -v20, v43, v39
	v_div_fmas_f32 v20, v20, v29, v43
	v_div_fixup_f32 v40, v20, v42, v40
	v_pk_mul_f32 v[40:41], v[40:41], s[26:27] op_sel_hi:[1,0]
	v_mul_f32_e32 v20, 0xbfb8aa3b, v32
	v_cvt_pk_bf16_f32 v29, v40, v41
	v_exp_f32_e32 v40, v20
	v_mul_f32_e32 v20, 0xbfb8aa3b, v33
	v_exp_f32_e32 v41, v20
	s_nop 0
	v_pk_add_f32 v[40:41], v[40:41], 1.0 op_sel_hi:[1,0]
	s_nop 0
	v_div_scale_f32 v20, s[0:1], v41, v41, v33
	v_rcp_f32_e32 v39, v20
	s_nop 0
	v_fma_f32 v42, -v20, v39, 1.0
	v_fmac_f32_e32 v39, v42, v39
	v_div_scale_f32 v42, vcc, v33, v41, v33
	v_mul_f32_e32 v43, v42, v39
	v_fma_f32 v44, -v20, v43, v42
	v_fmac_f32_e32 v43, v44, v39
	v_fma_f32 v20, -v20, v43, v42
	v_div_fmas_f32 v20, v20, v39, v43
	v_div_fixup_f32 v33, v20, v41, v33
	v_div_scale_f32 v20, s[0:1], v40, v40, v32
	v_rcp_f32_e32 v39, v20
	s_nop 0
	v_fma_f32 v41, -v20, v39, 1.0
	v_fmac_f32_e32 v39, v41, v39
	v_div_scale_f32 v41, vcc, v32, v40, v32
	v_mul_f32_e32 v42, v41, v39
	v_fma_f32 v43, -v20, v42, v41
	v_fmac_f32_e32 v42, v43, v39
	v_fma_f32 v20, -v20, v42, v41
	v_div_fmas_f32 v20, v20, v39, v42
	v_div_fixup_f32 v32, v20, v40, v32
	v_lshlrev_b32_e32 v20, 16, v21
	v_and_b32_e32 v21, 0xffff0000, v21
	v_pk_fma_f32 v[20:21], v[68:69], v[20:21], v[26:27]
	v_pk_mul_f32 v[32:33], v[32:33], s[26:27] op_sel_hi:[1,0]
	v_mul_f32_e32 v26, 0xbfb8aa3b, v20
	v_mul_f32_e32 v27, 0xbfb8aa3b, v21
	v_exp_f32_e32 v26, v26
	v_exp_f32_e32 v27, v27
	v_cvt_pk_bf16_f32 v32, v32, v33
	v_lshlrev_b32_e32 v40, 2, v102
	v_pk_add_f32 v[26:27], v[26:27], 1.0 op_sel_hi:[1,0]
	s_nop 0
	v_div_scale_f32 v30, s[0:1], v27, v27, v21
	v_rcp_f32_e32 v31, v30
	s_nop 0
	v_fma_f32 v33, -v30, v31, 1.0
	v_fmac_f32_e32 v31, v33, v31
	v_div_scale_f32 v33, vcc, v21, v27, v21
	v_mul_f32_e32 v34, v33, v31
	v_fma_f32 v35, -v30, v34, v33
	v_fmac_f32_e32 v34, v35, v31
	v_fma_f32 v30, -v30, v34, v33
	v_div_fmas_f32 v30, v30, v31, v34
	v_div_fixup_f32 v21, v30, v27, v21
	v_div_scale_f32 v27, s[0:1], v26, v26, v20
	v_rcp_f32_e32 v30, v27
	s_add_i32 s0, 0, 0x10000
	s_add_i32 s1, 0, 0x18800
	v_fma_f32 v31, -v27, v30, 1.0
	v_fmac_f32_e32 v30, v31, v30
	v_div_scale_f32 v31, vcc, v20, v26, v20
	v_mul_f32_e32 v33, v31, v30
	v_fma_f32 v34, -v27, v33, v31
	v_fmac_f32_e32 v33, v34, v30
	v_fma_f32 v27, -v27, v33, v31
	v_div_fmas_f32 v27, v27, v30, v33
	v_div_fixup_f32 v20, v27, v26, v20
	v_cvt_pk_bf16_f32 v33, v18, v19
	v_and_b32_e32 v18, 48, v101
	v_lshlrev_b32_e32 v19, 1, v101
	v_pk_mul_f32 v[20:21], v[20:21], s[26:27] op_sel_hi:[1,0]
	v_and_or_b32 v18, v19, 8, v18
	v_cvt_pk_bf16_f32 v35, v20, v21
	v_lshrrev_b32_e32 v18, 1, v18
	v_lshrrev_b32_e32 v19, 5, v103
	v_lshlrev_b32_e32 v20, 6, v100
	v_or_b32_e32 v18, v18, v19
	v_and_b32_e32 v36, 0xffffc000, v20
	v_lshlrev_b32_e32 v20, 5, v101
	v_lshlrev_b32_e32 v18, 9, v18
	v_and_b32_e32 v19, 48, v178
	v_and_b32_e32 v20, 0x100, v20
	v_or3_b32 v37, v18, v19, v20
	v_add3_u32 v39, s0, v36, v37
	ds_write_b128 v39, v[14:17]
	v_add_u32_e32 v14, s1, v40
	v_cvt_pk_bf16_f32 v34, v22, v23
	ds_read_b32 v22, v14
	v_add_u32_e32 v14, s8, v40
	ds_read_b32 v26, v14
	v_cvt_pk_bf16_f32 v27, v70, v71
	v_lshlrev_b32_e32 v16, 16, v105
	v_and_b32_e32 v17, 0xffff0000, v105
	v_lshlrev_b32_e32 v20, 16, v74
	v_and_b32_e32 v21, 0xffff0000, v74
	s_waitcnt lgkmcnt(1)
	v_pk_mul_f32 v[14:15], v[22:23], v[16:17] op_sel_hi:[0,1]
	s_waitcnt lgkmcnt(0)
	v_pk_mul_f32 v[16:17], v[26:27], v[16:17] op_sel_hi:[0,1]
	v_cvt_pk_bf16_f32 v18, v16, v17
	v_pk_mul_f32 v[16:17], v[22:23], v[20:21] op_sel_hi:[0,1]
	v_lshlrev_b32_e32 v30, 16, v24
	v_and_b32_e32 v31, 0xffff0000, v24
	v_lshlrev_b32_e32 v24, 16, v25
	v_and_b32_e32 v25, 0xffff0000, v25
	v_cvt_pk_bf16_f32 v14, v14, v15
	v_cvt_pk_bf16_f32 v15, v16, v17
	v_pk_mul_f32 v[16:17], v[26:27], v[20:21] op_sel_hi:[0,1]
	v_cvt_pk_bf16_f32 v19, v16, v17
	v_pk_mul_f32 v[16:17], v[22:23], v[30:31] op_sel_hi:[0,1]
	v_pk_mul_f32 v[22:23], v[22:23], v[24:25] op_sel_hi:[0,1]
	v_cvt_pk_bf16_f32 v16, v16, v17
	v_pk_mul_f32 v[20:21], v[26:27], v[30:31] op_sel_hi:[0,1]
	v_cvt_pk_bf16_f32 v17, v22, v23
	v_pk_mul_f32 v[22:23], v[26:27], v[24:25] op_sel_hi:[0,1]
	v_add3_u32 v26, 0, v36, v37
	v_cvt_pk_bf16_f32 v20, v20, v21
	v_cvt_pk_bf16_f32 v21, v22, v23
	ds_write_b128 v26, v[14:17]
	ds_write_b128 v26, v[18:21] offset:32768
	ds_write_b128 v39, v[10:13] offset:64
	v_or_b32_e32 v10, 4, v40
	v_add_u32_e32 v11, s1, v10
	v_add_u32_e32 v10, s8, v10
	ds_read_b32 v18, v11
	ds_read_b32 v20, v10
	v_lshlrev_b32_e32 v12, 16, v106
	v_and_b32_e32 v13, 0xffff0000, v106
	v_lshlrev_b32_e32 v16, 16, v75
	v_and_b32_e32 v17, 0xffff0000, v75
	s_waitcnt lgkmcnt(1)
	v_pk_mul_f32 v[10:11], v[18:19], v[12:13] op_sel_hi:[0,1]
	s_waitcnt lgkmcnt(0)
	v_pk_mul_f32 v[12:13], v[20:21], v[12:13] op_sel_hi:[0,1]
	v_cvt_pk_bf16_f32 v14, v12, v13
	v_pk_mul_f32 v[12:13], v[18:19], v[16:17] op_sel_hi:[0,1]
	v_lshlrev_b32_e32 v22, 16, v28
	v_and_b32_e32 v23, 0xffff0000, v28
	v_lshlrev_b32_e32 v24, 16, v29
	v_and_b32_e32 v25, 0xffff0000, v29
	v_cvt_pk_bf16_f32 v10, v10, v11
	v_cvt_pk_bf16_f32 v11, v12, v13
	v_pk_mul_f32 v[12:13], v[20:21], v[16:17] op_sel_hi:[0,1]
	v_cvt_pk_bf16_f32 v15, v12, v13
	v_pk_mul_f32 v[12:13], v[18:19], v[22:23] op_sel_hi:[0,1]
	v_pk_mul_f32 v[18:19], v[18:19], v[24:25] op_sel_hi:[0,1]
	v_cvt_pk_bf16_f32 v12, v12, v13
	v_pk_mul_f32 v[16:17], v[20:21], v[22:23] op_sel_hi:[0,1]
	v_cvt_pk_bf16_f32 v13, v18, v19
	v_pk_mul_f32 v[18:19], v[20:21], v[24:25] op_sel_hi:[0,1]
	v_cvt_pk_bf16_f32 v16, v16, v17
	v_cvt_pk_bf16_f32 v17, v18, v19
	ds_write_b128 v26, v[10:13] offset:64
	ds_write_b128 v26, v[14:17] offset:32832
	ds_write_b128 v39, v[6:9] offset:128
	v_or_b32_e32 v6, 8, v40
	v_add_u32_e32 v7, s1, v6
	v_add_u32_e32 v6, s8, v6
	ds_read_b32 v14, v7
	ds_read_b32 v16, v6
	v_lshlrev_b32_e32 v8, 16, v98
	v_and_b32_e32 v9, 0xffff0000, v98
	v_lshlrev_b32_e32 v12, 16, v78
	v_and_b32_e32 v13, 0xffff0000, v78
	s_waitcnt lgkmcnt(1)
	v_pk_mul_f32 v[6:7], v[14:15], v[8:9] op_sel_hi:[0,1]
	s_waitcnt lgkmcnt(0)
	v_pk_mul_f32 v[8:9], v[16:17], v[8:9] op_sel_hi:[0,1]
	v_cvt_pk_bf16_f32 v10, v8, v9
	v_pk_mul_f32 v[8:9], v[14:15], v[12:13] op_sel_hi:[0,1]
	v_lshlrev_b32_e32 v18, 16, v38
	v_and_b32_e32 v19, 0xffff0000, v38
	v_lshlrev_b32_e32 v20, 16, v32
	v_and_b32_e32 v21, 0xffff0000, v32
	v_cvt_pk_bf16_f32 v6, v6, v7
	v_cvt_pk_bf16_f32 v7, v8, v9
	v_pk_mul_f32 v[8:9], v[16:17], v[12:13] op_sel_hi:[0,1]
	v_cvt_pk_bf16_f32 v11, v8, v9
	v_pk_mul_f32 v[8:9], v[14:15], v[18:19] op_sel_hi:[0,1]
	v_pk_mul_f32 v[14:15], v[14:15], v[20:21] op_sel_hi:[0,1]
	v_cvt_pk_bf16_f32 v8, v8, v9
	v_pk_mul_f32 v[12:13], v[16:17], v[18:19] op_sel_hi:[0,1]
	v_cvt_pk_bf16_f32 v9, v14, v15
	v_pk_mul_f32 v[14:15], v[16:17], v[20:21] op_sel_hi:[0,1]
	v_cvt_pk_bf16_f32 v12, v12, v13
	v_cvt_pk_bf16_f32 v13, v14, v15
	ds_write_b128 v26, v[6:9] offset:128
	ds_write_b128 v26, v[10:13] offset:32896
	ds_write_b128 v39, v[2:5] offset:192
	v_lshl_or_b32 v2, v101, 2, 12
	v_add_u32_e32 v3, s1, v2
	v_add_u32_e32 v2, s8, v2
	ds_read_b32 v10, v3
	ds_read_b32 v12, v2
	v_lshlrev_b32_e32 v4, 16, v27
	v_and_b32_e32 v5, 0xffff0000, v27
	v_lshlrev_b32_e32 v8, 16, v33
	v_and_b32_e32 v9, 0xffff0000, v33
	s_waitcnt lgkmcnt(1)
	v_pk_mul_f32 v[2:3], v[10:11], v[4:5] op_sel_hi:[0,1]
	s_waitcnt lgkmcnt(0)
	v_pk_mul_f32 v[4:5], v[12:13], v[4:5] op_sel_hi:[0,1]
	v_cvt_pk_bf16_f32 v6, v4, v5
	v_pk_mul_f32 v[4:5], v[10:11], v[8:9] op_sel_hi:[0,1]
	v_lshlrev_b32_e32 v14, 16, v34
	v_and_b32_e32 v15, 0xffff0000, v34
	v_lshlrev_b32_e32 v16, 16, v35
	v_and_b32_e32 v17, 0xffff0000, v35
	v_cvt_pk_bf16_f32 v2, v2, v3
	v_cvt_pk_bf16_f32 v3, v4, v5
	v_pk_mul_f32 v[4:5], v[12:13], v[8:9] op_sel_hi:[0,1]
	v_cvt_pk_bf16_f32 v7, v4, v5
	v_pk_mul_f32 v[4:5], v[10:11], v[14:15] op_sel_hi:[0,1]
	v_pk_mul_f32 v[10:11], v[10:11], v[16:17] op_sel_hi:[0,1]
	v_cvt_pk_bf16_f32 v4, v4, v5
	v_pk_mul_f32 v[8:9], v[12:13], v[14:15] op_sel_hi:[0,1]
	v_cvt_pk_bf16_f32 v5, v10, v11
	v_pk_mul_f32 v[10:11], v[12:13], v[16:17] op_sel_hi:[0,1]
	v_cvt_pk_bf16_f32 v8, v8, v9
	v_cvt_pk_bf16_f32 v9, v10, v11
	ds_write_b128 v26, v[2:5] offset:192
	ds_write_b128 v26, v[6:9] offset:32960
	v_lshlrev_b32_e32 v2, 4, v104
	s_lshl_b32 s1, s5, 15
	v_lshlrev_b32_e32 v78, 3, v104
	v_and_b32_e32 v2, 0xc0, v2
	v_lshlrev_b32_e32 v3, 1, v104
	s_add_i32 s1, s1, 0
	s_lshl_b32 s8, s4, 9
	v_and_or_b32 v2, v78, 24, v2
	v_and_b32_e32 v3, 32, v3
	v_and_b32_e32 v4, 0x100, v78
	s_add_i32 s1, s1, s8
	v_or3_b32 v79, v2, v3, v4
	s_waitcnt lgkmcnt(0)
	s_barrier
	v_add_u32_e32 v92, s1, v79
	ds_read_b64_tr_b16 v[2:3], v92 offset:0
	ds_read_b64_tr_b16 v[4:5], v92 offset:0x800
	ds_read_b64_tr_b16 v[66:67], v92 offset:0x1000
	ds_read_b64_tr_b16 v[68:69], v92 offset:0x1800
	ds_read_b64_tr_b16 v[70:71], v92 offset:0x2000
	ds_read_b64_tr_b16 v[72:73], v92 offset:0x2800
	ds_read_b64_tr_b16 v[74:75], v92 offset:0x3000
	ds_read_b64_tr_b16 v[76:77], v92 offset:0x3800
	v_add_u32_e32 v93, s0, v79
	s_waitcnt lgkmcnt(0)
	ds_read_b64_tr_b16 v[6:7], v93 offset:0
	ds_read_b64_tr_b16 v[8:9], v93 offset:0x800
	ds_read_b64_tr_b16 v[10:11], v93 offset:0x1000
	ds_read_b64_tr_b16 v[12:13], v93 offset:0x1800
	ds_read_b64_tr_b16 v[14:15], v93 offset:0x2000
	ds_read_b64_tr_b16 v[16:17], v93 offset:0x2800
	ds_read_b64_tr_b16 v[18:19], v93 offset:0x3000
	ds_read_b64_tr_b16 v[20:21], v93 offset:0x3800
	s_nop 0
	s_waitcnt lgkmcnt(6)
	s_add_i32 s0, 0, 0x14000
	v_mfma_f32_32x32x16_bf16 v[50:65], v[2:5], v[6:9], 0
	ds_read_b64_tr_b16 v[6:7], v93 offset:0x200
	ds_read_b64_tr_b16 v[8:9], v93 offset:0xa00
	s_waitcnt lgkmcnt(6)
	v_add_u32_e32 v79, s0, v79
	s_movk_i32 s0, 0xff
	v_cmp_lt_i32_e32 vcc, s0, v100
	v_mfma_f32_32x32x16_bf16 v[50:65], v[66:69], v[10:13], v[50:65]
	ds_read_b64_tr_b16 v[10:11], v93 offset:0x1200
	ds_read_b64_tr_b16 v[12:13], v93 offset:0x1a00
	s_waitcnt lgkmcnt(6)
	s_nop 0
	v_mfma_f32_32x32x16_bf16 v[50:65], v[70:73], v[14:17], v[50:65]
	ds_read_b64_tr_b16 v[14:15], v93 offset:0x2200
	ds_read_b64_tr_b16 v[16:17], v93 offset:0x2a00
	s_waitcnt lgkmcnt(6)
	s_nop 0
	v_mfma_f32_32x32x16_bf16 v[50:65], v[74:77], v[18:21], v[50:65]
	ds_read_b64_tr_b16 v[18:19], v93 offset:0x3200
	ds_read_b64_tr_b16 v[20:21], v93 offset:0x3a00
	s_waitcnt lgkmcnt(6)
	s_nop 0
	v_mfma_f32_32x32x16_bf16 v[34:49], v[2:5], v[6:9], 0
	ds_read_b64_tr_b16 v[6:7], v93 offset:0x400
	ds_read_b64_tr_b16 v[8:9], v93 offset:0xc00
	s_waitcnt lgkmcnt(6)
	s_nop 0
	v_mfma_f32_32x32x16_bf16 v[34:49], v[66:69], v[10:13], v[34:49]
	ds_read_b64_tr_b16 v[10:11], v93 offset:0x1400
	ds_read_b64_tr_b16 v[12:13], v93 offset:0x1c00
	s_waitcnt lgkmcnt(6)
	s_nop 0
	v_mfma_f32_32x32x16_bf16 v[34:49], v[70:73], v[14:17], v[34:49]
	ds_read_b64_tr_b16 v[14:15], v93 offset:0x2400
	ds_read_b64_tr_b16 v[16:17], v93 offset:0x2c00
	s_waitcnt lgkmcnt(6)
	ds_read_b64_tr_b16 v[80:81], v93 offset:0x3400
	ds_read_b64_tr_b16 v[82:83], v93 offset:0x3c00
	s_waitcnt lgkmcnt(6)
	s_nop 0
	v_mfma_f32_32x32x16_bf16 v[34:49], v[74:77], v[18:21], v[34:49]
	v_mfma_f32_32x32x16_bf16 v[18:33], v[2:5], v[6:9], 0
	ds_read_b64_tr_b16 v[6:7], v93 offset:0x600
	ds_read_b64_tr_b16 v[8:9], v93 offset:0xe00
	s_waitcnt lgkmcnt(6)
	ds_read_b64_tr_b16 v[84:85], v93 offset:0x1600
	ds_read_b64_tr_b16 v[86:87], v93 offset:0x1e00
	s_waitcnt lgkmcnt(6)
	ds_read_b64_tr_b16 v[88:89], v93 offset:0x2600
	ds_read_b64_tr_b16 v[90:91], v93 offset:0x2e00
	s_nop 0
	v_mfma_f32_32x32x16_bf16 v[18:33], v[66:69], v[10:13], v[18:33]
	s_waitcnt lgkmcnt(6)
	v_mfma_f32_32x32x16_bf16 v[18:33], v[70:73], v[14:17], v[18:33]
	v_mfma_f32_32x32x16_bf16 v[18:33], v[74:77], v[80:83], v[18:33]
	ds_read_b64_tr_b16 v[80:81], v93 offset:0x3600
	ds_read_b64_tr_b16 v[82:83], v93 offset:0x3e00
	s_waitcnt lgkmcnt(6)
	s_waitcnt lgkmcnt(4)
	s_waitcnt lgkmcnt(2)
	s_nop 0
	s_waitcnt lgkmcnt(0)
	v_mfma_f32_32x32x16_bf16 v[2:17], v[2:5], v[6:9], 0
	v_mfma_f32_32x32x16_bf16 v[2:17], v[66:69], v[84:87], v[2:17]
	v_add_u32_e32 v84, 0x4000, v92
	ds_read_b64_tr_b16 v[66:67], v84 offset:0
	ds_read_b64_tr_b16 v[68:69], v84 offset:0x800
	v_mfma_f32_32x32x16_bf16 v[2:17], v[70:73], v[88:91], v[2:17]
	ds_read_b64_tr_b16 v[70:71], v84 offset:0x1000
	ds_read_b64_tr_b16 v[72:73], v84 offset:0x1800
	v_mfma_f32_32x32x16_bf16 v[2:17], v[74:77], v[80:83], v[2:17]
	ds_read_b64_tr_b16 v[74:75], v84 offset:0x2000
	ds_read_b64_tr_b16 v[76:77], v84 offset:0x2800
	ds_read_b64_tr_b16 v[80:81], v84 offset:0x3000
	ds_read_b64_tr_b16 v[82:83], v84 offset:0x3800
	s_nop 0
	s_waitcnt lgkmcnt(0)
	ds_read_b64_tr_b16 v[84:85], v79 offset:0
	ds_read_b64_tr_b16 v[86:87], v79 offset:0x800
	ds_read_b64_tr_b16 v[88:89], v79 offset:0x1000
	ds_read_b64_tr_b16 v[90:91], v79 offset:0x1800
	ds_read_b64_tr_b16 v[92:93], v79 offset:0x2000
	ds_read_b64_tr_b16 v[94:95], v79 offset:0x2800
	ds_read_b64_tr_b16 v[96:97], v79 offset:0x3000
	ds_read_b64_tr_b16 v[98:99], v79 offset:0x3800
	s_nop 0
	s_waitcnt lgkmcnt(6)
	s_nop 0
	v_mfma_f32_32x32x16_bf16 v[50:65], v[66:69], v[84:87], v[50:65]
	ds_read_b64_tr_b16 v[84:85], v79 offset:0x200
	ds_read_b64_tr_b16 v[86:87], v79 offset:0xa00
	s_waitcnt lgkmcnt(6)
	s_nop 0
	v_mfma_f32_32x32x16_bf16 v[50:65], v[70:73], v[88:91], v[50:65]
	ds_read_b64_tr_b16 v[88:89], v79 offset:0x1200
	ds_read_b64_tr_b16 v[90:91], v79 offset:0x1a00
	s_waitcnt lgkmcnt(6)
	s_nop 0
	v_mfma_f32_32x32x16_bf16 v[50:65], v[74:77], v[92:95], v[50:65]
	ds_read_b64_tr_b16 v[92:93], v79 offset:0x2200
	ds_read_b64_tr_b16 v[94:95], v79 offset:0x2a00
	s_waitcnt lgkmcnt(6)
	s_nop 0
	v_mfma_f32_32x32x16_bf16 v[50:65], v[80:83], v[96:99], v[50:65]
	ds_read_b64_tr_b16 v[96:97], v79 offset:0x3200
	ds_read_b64_tr_b16 v[98:99], v79 offset:0x3a00
	s_waitcnt lgkmcnt(6)
	s_nop 0
	v_mfma_f32_32x32x16_bf16 v[34:49], v[66:69], v[84:87], v[34:49]
	ds_read_b64_tr_b16 v[84:85], v79 offset:0x400
	ds_read_b64_tr_b16 v[86:87], v79 offset:0xc00
	s_waitcnt lgkmcnt(6)
	s_nop 0
	v_mfma_f32_32x32x16_bf16 v[34:49], v[70:73], v[88:91], v[34:49]
	ds_read_b64_tr_b16 v[88:89], v79 offset:0x1400
	ds_read_b64_tr_b16 v[90:91], v79 offset:0x1c00
	s_waitcnt lgkmcnt(6)
	s_nop 0
	v_mfma_f32_32x32x16_bf16 v[34:49], v[74:77], v[92:95], v[34:49]
	ds_read_b64_tr_b16 v[92:93], v79 offset:0x2400
	ds_read_b64_tr_b16 v[94:95], v79 offset:0x2c00
	s_waitcnt lgkmcnt(6)
	s_nop 0
	v_mfma_f32_32x32x16_bf16 v[34:49], v[80:83], v[96:99], v[34:49]
	ds_read_b64_tr_b16 v[96:97], v79 offset:0x3400
	ds_read_b64_tr_b16 v[98:99], v79 offset:0x3c00
	s_waitcnt lgkmcnt(6)
	s_nop 0
	v_mfma_f32_32x32x16_bf16 v[18:33], v[66:69], v[84:87], v[18:33]
	ds_read_b64_tr_b16 v[84:85], v79 offset:0x600
	ds_read_b64_tr_b16 v[86:87], v79 offset:0xe00
	s_waitcnt lgkmcnt(6)
	s_nop 0
	v_mfma_f32_32x32x16_bf16 v[18:33], v[70:73], v[88:91], v[18:33]
	ds_read_b64_tr_b16 v[88:89], v79 offset:0x1600
	ds_read_b64_tr_b16 v[90:91], v79 offset:0x1e00
	s_waitcnt lgkmcnt(6)
	s_nop 0
	v_mfma_f32_32x32x16_bf16 v[18:33], v[74:77], v[92:95], v[18:33]
	ds_read_b64_tr_b16 v[92:93], v79 offset:0x2600
	ds_read_b64_tr_b16 v[94:95], v79 offset:0x2e00
	s_waitcnt lgkmcnt(6)
	s_nop 0
	v_mfma_f32_32x32x16_bf16 v[18:33], v[80:83], v[96:99], v[18:33]
	ds_read_b64_tr_b16 v[96:97], v79 offset:0x3600
	ds_read_b64_tr_b16 v[98:99], v79 offset:0x3e00
	s_waitcnt lgkmcnt(6)
	s_waitcnt lgkmcnt(4)
	s_waitcnt lgkmcnt(2)
	v_ashrrev_i32_e32 v79, 7, v100
	s_waitcnt lgkmcnt(0)
	v_mfma_f32_32x32x16_bf16 v[2:17], v[66:69], v[84:87], v[2:17]
	v_lshlrev_b32_e32 v66, 7, v100
	v_lshlrev_b32_e32 v67, 14, v79
	v_and_b32_e32 v66, 0xffff8000, v66
	v_and_b32_e32 v67, 0x4000, v67
	v_add3_u32 v66, 0, v66, v67
	v_lshlrev_b32_e32 v67, 1, v100
	v_lshlrev_b32_e32 v68, 4, v100
	v_mfma_f32_32x32x16_bf16 v[2:17], v[70:73], v[88:91], v[2:17]
	v_and_b32_e32 v67, 62, v67
	v_and_b32_e32 v68, 0x600, v68
	v_mfma_f32_32x32x16_bf16 v[2:17], v[74:77], v[92:95], v[2:17]
	v_mfma_f32_32x32x16_bf16 v[2:17], v[80:83], v[96:99], v[2:17]
	v_add3_u32 v80, v66, v68, v67
	ds_read_u16 v66, v80 offset:6144
	ds_read_u16 v67, v80 offset:6272
	ds_read_u16 v68, v80 offset:6208
	ds_read_u16 v69, v80 offset:6336
	ds_read_u16 v70, v80 offset:4352
	ds_read_u16 v71, v80 offset:4416
	ds_read_u16 v73, v80 offset:4544
	s_waitcnt lgkmcnt(5)
	v_lshlrev_b32_e32 v67, 16, v67
	v_lshlrev_b32_e32 v66, 16, v66
	s_waitcnt lgkmcnt(3)
	v_lshlrev_b32_e32 v69, 16, v69
	s_waitcnt lgkmcnt(1)
	v_lshlrev_b32_e32 v72, 16, v71
	ds_read_u16 v71, v80 offset:4480
	ds_read_u16 v81, v80 offset:6400
	ds_read_u16 v88, v80 offset:6464
	ds_read_u16 v89, v80 offset:6528
	ds_read_u16 v90, v80 offset:6592
	ds_read_u16 v74, v80
	ds_read_u16 v75, v80 offset:128
	ds_read_u16 v76, v80 offset:2048
	ds_read_u16 v77, v80 offset:2176
	ds_read_u16 v82, v80 offset:256
	ds_read_u16 v83, v80 offset:384
	ds_read_u16 v84, v80 offset:2304
	ds_read_u16 v85, v80 offset:2432
	s_waitcnt lgkmcnt(7)
	v_lshlrev_b32_e32 v74, 16, v74
	s_waitcnt lgkmcnt(6)
	v_lshlrev_b32_e32 v75, 16, v75
	s_waitcnt lgkmcnt(4)
	v_lshlrev_b32_e32 v77, 16, v77
	v_lshlrev_b32_e32 v76, 16, v76
	v_pk_add_f32 v[74:75], v[74:75], 0 op_sel_hi:[1,0]
	s_waitcnt lgkmcnt(2)
	v_lshlrev_b32_e32 v83, 16, v83
	v_pk_add_f32 v[74:75], v[74:75], v[76:77]
	ds_read_u16 v76, v80 offset:4096
	ds_read_u16 v77, v80 offset:4224
	v_lshlrev_b32_e32 v82, 16, v82
	s_waitcnt lgkmcnt(2)
	v_lshlrev_b32_e32 v85, 16, v85
	v_lshlrev_b32_e32 v84, 16, v84
	v_pk_add_f32 v[74:75], v[74:75], v[82:83]
	s_waitcnt lgkmcnt(0)
	v_lshlrev_b32_e32 v77, 16, v77
	v_pk_add_f32 v[74:75], v[74:75], v[84:85]
	v_lshlrev_b32_e32 v76, 16, v76
	v_pk_add_f32 v[74:75], v[74:75], v[76:77]
	ds_read_u16 v76, v80 offset:64
	ds_read_u16 v77, v80 offset:192
	ds_read_u16 v82, v80 offset:2112
	ds_read_u16 v83, v80 offset:2240
	ds_read_u16 v84, v80 offset:320
	ds_read_u16 v85, v80 offset:448
	ds_read_u16 v86, v80 offset:2368
	ds_read_u16 v87, v80 offset:2496
	s_waitcnt lgkmcnt(7)
	v_lshlrev_b32_e32 v76, 16, v76
	s_waitcnt lgkmcnt(6)
	v_lshlrev_b32_e32 v77, 16, v77
	s_waitcnt lgkmcnt(4)
	v_lshlrev_b32_e32 v83, 16, v83
	v_lshlrev_b32_e32 v82, 16, v82
	v_pk_add_f32 v[76:77], v[76:77], 0 op_sel_hi:[1,0]
	s_waitcnt lgkmcnt(2)
	v_lshlrev_b32_e32 v85, 16, v85
	v_pk_add_f32 v[76:77], v[76:77], v[82:83]
	ds_read_u16 v82, v80 offset:4160
	ds_read_u16 v83, v80 offset:4288
	v_lshlrev_b32_e32 v84, 16, v84
	s_waitcnt lgkmcnt(2)
	v_lshlrev_b32_e32 v87, 16, v87
	v_lshlrev_b32_e32 v86, 16, v86
	v_pk_add_f32 v[76:77], v[76:77], v[84:85]
	s_waitcnt lgkmcnt(0)
	v_lshlrev_b32_e32 v83, 16, v83
	v_pk_add_f32 v[76:77], v[76:77], v[86:87]
	v_lshlrev_b32_e32 v82, 16, v82
	v_lshlrev_b32_e32 v68, 16, v68
	v_lshlrev_b32_e32 v70, 16, v70
	v_lshlrev_b32_e32 v71, 16, v71
	v_pk_add_f32 v[76:77], v[76:77], v[82:83]
	v_pk_add_f32 v[66:67], v[74:75], v[66:67]
	v_lshlrev_b32_e32 v73, 16, v73
	v_lshlrev_b32_e32 v83, 16, v89
	v_lshlrev_b32_e32 v82, 16, v81
	v_pk_add_f32 v[68:69], v[76:77], v[68:69]
	v_pk_add_f32 v[66:67], v[66:67], v[70:71]
	v_pk_add_f32 v[68:69], v[68:69], v[72:73]
	v_pk_add_f32 v[66:67], v[66:67], v[82:83]
	ds_read_u16 v70, v80 offset:8192
	ds_read_u16 v71, v80 offset:8320
	ds_read_u16 v72, v80 offset:8256
	ds_read_u16 v73, v80 offset:8384
	ds_read_u16 v74, v80 offset:10240
	ds_read_u16 v75, v80 offset:10368
	ds_read_u16 v76, v80 offset:10304
	ds_read_u16 v77, v80 offset:10432
	ds_read_u16 v81, v80 offset:8448
	ds_read_u16 v82, v80 offset:8576
	v_lshlrev_b32_e32 v85, 16, v90
	v_lshlrev_b32_e32 v84, 16, v88
	v_pk_add_f32 v[68:69], v[68:69], v[84:85]
	s_waitcnt lgkmcnt(8)
	v_lshlrev_b32_e32 v71, 16, v71
	s_waitcnt lgkmcnt(0)
	v_lshlrev_b32_e32 v83, 16, v82
	v_lshlrev_b32_e32 v82, 16, v81
	ds_read_u16 v81, v80 offset:8512
	ds_read_u16 v84, v80 offset:8640
	v_lshlrev_b32_e32 v70, 16, v70
	v_lshlrev_b32_e32 v73, 16, v73
	v_lshlrev_b32_e32 v72, 16, v72
	v_lshlrev_b32_e32 v75, 16, v75
	s_waitcnt lgkmcnt(0)
	v_lshlrev_b32_e32 v85, 16, v84
	v_lshlrev_b32_e32 v84, 16, v81
	ds_read_u16 v81, v80 offset:10496
	ds_read_u16 v86, v80 offset:10624
	v_lshlrev_b32_e32 v74, 16, v74
	v_pk_add_f32 v[66:67], v[66:67], v[70:71]
	v_lshlrev_b32_e32 v77, 16, v77
	v_lshlrev_b32_e32 v76, 16, v76
	s_waitcnt lgkmcnt(0)
	v_lshlrev_b32_e32 v87, 16, v86
	v_lshlrev_b32_e32 v86, 16, v81
	ds_read_u16 v81, v80 offset:10560
	ds_read_u16 v88, v80 offset:10688
	v_pk_add_f32 v[68:69], v[68:69], v[72:73]
	v_pk_add_f32 v[66:67], v[66:67], v[74:75]
	v_pk_add_f32 v[68:69], v[68:69], v[76:77]
	v_pk_add_f32 v[66:67], v[66:67], v[82:83]
	s_waitcnt lgkmcnt(0)
	v_lshlrev_b32_e32 v89, 16, v88
	v_lshlrev_b32_e32 v88, 16, v81
	ds_read_u16 v70, v80 offset:12288
	ds_read_u16 v71, v80 offset:12416
	ds_read_u16 v72, v80 offset:12352
	ds_read_u16 v73, v80 offset:12480
	ds_read_u16 v74, v80 offset:14336
	ds_read_u16 v75, v80 offset:14464
	ds_read_u16 v76, v80 offset:14400
	ds_read_u16 v77, v80 offset:14528
	ds_read_u16 v81, v80 offset:12544
	ds_read_u16 v82, v80 offset:12672
	v_pk_add_f32 v[68:69], v[68:69], v[84:85]
	v_pk_add_f32 v[66:67], v[66:67], v[86:87]
	v_pk_add_f32 v[68:69], v[68:69], v[88:89]
	s_waitcnt lgkmcnt(8)
	v_lshlrev_b32_e32 v71, 16, v71
	s_waitcnt lgkmcnt(0)
	v_lshlrev_b32_e32 v83, 16, v82
	v_lshlrev_b32_e32 v82, 16, v81
	ds_read_u16 v81, v80 offset:12608
	ds_read_u16 v84, v80 offset:12736
	v_lshlrev_b32_e32 v70, 16, v70
	v_lshlrev_b32_e32 v73, 16, v73
	v_lshlrev_b32_e32 v72, 16, v72
	v_lshlrev_b32_e32 v75, 16, v75
	s_waitcnt lgkmcnt(0)
	v_lshlrev_b32_e32 v85, 16, v84
	v_lshlrev_b32_e32 v84, 16, v81
	ds_read_u16 v81, v80 offset:14592
	ds_read_u16 v86, v80 offset:14720
	ds_read_u16 v88, v80 offset:14656
	ds_read_u16 v80, v80 offset:14784
	v_lshlrev_b32_e32 v74, 16, v74
	v_lshlrev_b32_e32 v77, 16, v77
	v_lshlrev_b32_e32 v76, 16, v76
	v_pk_add_f32 v[66:67], v[66:67], v[70:71]
	v_pk_add_f32 v[68:69], v[68:69], v[72:73]
	v_pk_add_f32 v[66:67], v[66:67], v[74:75]
	v_pk_add_f32 v[68:69], v[68:69], v[76:77]
	s_waitcnt lgkmcnt(2)
	v_lshlrev_b32_e32 v87, 16, v86
	v_lshlrev_b32_e32 v86, 16, v81
	s_waitcnt lgkmcnt(0)
	v_lshlrev_b32_e32 v81, 16, v80
	v_lshlrev_b32_e32 v80, 16, v88
	v_pk_add_f32 v[66:67], v[66:67], v[82:83]
	v_pk_add_f32 v[68:69], v[68:69], v[84:85]
	v_pk_add_f32 v[66:67], v[66:67], v[86:87]
	v_pk_add_f32 v[68:69], v[68:69], v[80:81]
	s_nop 0
	v_pk_add_f32 v[66:67], v[66:67], v[68:69]
	s_nop 0
	v_add_f32_e32 v66, v66, v67
	v_lshl_add_u32 v67, v100, 2, 0
	v_add_u32_e32 v67, 0x18c00, v67
	ds_write_b32 v67, v66
	s_waitcnt lgkmcnt(0)
	s_barrier
	s_and_saveexec_b64 s[0:1], vcc
	s_xor_b64 s[0:1], exec, s[0:1]
	s_lshl_b32 s8, s61, 2
	s_xor_b32 s9, s21, 15
	s_or_saveexec_b64 s[0:1], s[0:1]
	v_mov_b32_e32 v66, s9
	v_mov_b32_e32 v67, s8
	s_xor_b64 exec, exec, s[0:1]
	s_cbranch_execz .LBB0_446
	v_and_b32_e32 v66, 0x7f, v100
	v_lshlrev_b32_e32 v67, 10, v79
	s_add_i32 s8, 0, 0x18c00
	v_lshlrev_b32_e32 v68, 2, v66
	v_add3_u32 v66, s8, v67, v68
	ds_read2st64_b32 v[70:71], v66 offset1:2
	s_lshl_b32 s8, s61, 2
	v_mov_b32_e32 v67, s8
	v_lshl_add_u32 v66, v79, 5, s8
	s_xor_b32 s8, s21, 15
	s_waitcnt lgkmcnt(0)
	v_add_f32_e32 v72, v70, v71
	v_or_b32_e32 v69, s31, v66
	v_mov_b32_e32 v66, s8
	v_mov_b32_e32 v70, s21
	v_cmp_gt_u32_e32 vcc, s96, v100
	s_nop 1
	v_cndmask_b32_e32 v70, v66, v70, vcc
	v_lshl_or_b32 v70, v69, 4, v70
	v_ashrrev_i32_e32 v71, 31, v70
	v_lshlrev_b64 v[70:71], 9, v[70:71]
	v_lshl_add_u64 v[70:71], s[38:39], 0, v[70:71]
	v_mov_b32_e32 v69, v179
	v_lshl_add_u64 v[68:69], v[70:71], 0, v[68:69]
	global_store_dword v[68:69], v72, off sc1
	s_branch .LBB0_446

.LBB0_512:
	s_andn2_saveexec_b64 s[4:5], s[4:5]
	s_cbranch_execz .LBB0_532
	s_mov_b64 s[4:5], exec
	s_waitcnt lgkmcnt(0)
	s_waitcnt vmcnt(0)
	v_mbcnt_lo_u32_b32 v3, s4, 0
	v_mbcnt_hi_u32_b32 v3, s5, v3
	v_cmp_eq_u32_e32 vcc, 0, v3
	s_and_saveexec_b64 s[8:9], vcc
	s_cbranch_execz .LBB0_515
	s_bcnt1_i32_b64 s4, s[4:5]
	v_mov_b32_e32 v4, s4
	v_readlane_b32 s4, v253, 60
	v_readlane_b32 s5, v253, 61
	s_nop 4
	global_atomic_add v4, v179, v4, s[4:5] sc0

.LBB0_535:
	v_add_u32_e32 v2, 0xfffe0000, v53
	s_mov_b32 s4, 0x20000
	v_lshrrev_b32_e32 v2, 7, v2
	v_ashrrev_i32_e32 v3, 11, v53
	v_cmp_gt_i32_e64 s[4:5], s4, v53
	s_mov_b32 s8, 0x1ffff
	v_cmp_lt_i32_e32 vcc, s8, v53
	v_cndmask_b32_e64 v6, v2, v3, s[4:5]
	v_lshlrev_b32_e32 v2, 5, v6
	v_ashrrev_i32_e32 v3, 31, v2
	v_lshl_add_u64 v[2:3], v[2:3], 2, s[12:13]
	global_load_dwordx2 v[4:5], v[2:3], off
	v_and_b32_e32 v3, 0x7ff, v53
	v_lshlrev_b32_e32 v2, 4, v6
	v_cmp_eq_u32_e64 s[8:9], 0, v3
	s_and_b64 s[4:5], s[4:5], s[8:9]
	v_ashrrev_i32_e32 v3, 31, v2
	s_and_saveexec_b64 s[8:9], s[4:5]
	s_cbranch_execz .LBB0_537
	v_lshl_add_u64 v[6:7], v[2:3], 2, s[14:15]
	v_mov_b32_e32 v8, 0xf149f2ca
	global_store_dword v[6:7], v8, off sc1
.LBB0_537:
	s_or_b64 exec, exec, s[8:9]
	v_or_b32_e32 v8, 1, v2
	v_lshlrev_b32_e32 v6, 1, v8
	v_ashrrev_i32_e32 v7, 31, v6
	v_lshl_add_u64 v[6:7], v[6:7], 2, s[12:13]
	global_load_dwordx2 v[6:7], v[6:7], off
	s_waitcnt vmcnt(1)
	v_add_f32_e32 v38, 0xf149f2ca, v4
	v_max_f32_e32 v4, v5, v5
	v_max_f32_e32 v4, v38, v4
	s_and_saveexec_b64 s[8:9], s[4:5]
	s_cbranch_execz .LBB0_539
	v_ashrrev_i32_e32 v9, 31, v8
	v_lshl_add_u64 v[8:9], v[8:9], 2, s[14:15]
	global_store_dword v[8:9], v4, off sc1
.LBB0_539:
	s_or_b64 exec, exec, s[8:9]
	v_or_b32_e32 v10, 2, v2
	v_lshlrev_b32_e32 v8, 1, v10
	v_ashrrev_i32_e32 v9, 31, v8
	v_lshl_add_u64 v[8:9], v[8:9], 2, s[12:13]
	global_load_dwordx2 v[8:9], v[8:9], off
	s_waitcnt vmcnt(1)
	v_add_f32_e32 v39, v4, v6
	v_max_f32_e32 v6, v7, v7
	v_max_f32_e32 v6, v39, v6
	s_and_saveexec_b64 s[8:9], s[4:5]
	s_cbranch_execz .LBB0_541
	v_ashrrev_i32_e32 v11, 31, v10
	v_lshl_add_u64 v[10:11], v[10:11], 2, s[14:15]
	global_store_dword v[10:11], v6, off sc1
.LBB0_541:
	s_or_b64 exec, exec, s[8:9]
	v_or_b32_e32 v12, 3, v2
	v_lshlrev_b32_e32 v10, 1, v12
	v_ashrrev_i32_e32 v11, 31, v10
	v_lshl_add_u64 v[10:11], v[10:11], 2, s[12:13]
	global_load_dwordx2 v[10:11], v[10:11], off
	s_waitcnt vmcnt(1)
	v_add_f32_e32 v40, v6, v8
	v_max_f32_e32 v8, v9, v9
	v_max_f32_e32 v8, v40, v8
	s_and_saveexec_b64 s[8:9], s[4:5]
	s_cbranch_execz .LBB0_543
	v_ashrrev_i32_e32 v13, 31, v12
	v_lshl_add_u64 v[12:13], v[12:13], 2, s[14:15]
	global_store_dword v[12:13], v8, off sc1
.LBB0_543:
	s_or_b64 exec, exec, s[8:9]
	v_or_b32_e32 v14, 4, v2
	v_lshlrev_b32_e32 v12, 1, v14
	v_ashrrev_i32_e32 v13, 31, v12
	v_lshl_add_u64 v[12:13], v[12:13], 2, s[12:13]
	global_load_dwordx2 v[12:13], v[12:13], off
	s_waitcnt vmcnt(1)
	v_add_f32_e32 v41, v8, v10
	v_max_f32_e32 v10, v11, v11
	v_max_f32_e32 v10, v41, v10
	s_and_saveexec_b64 s[8:9], s[4:5]
	s_cbranch_execz .LBB0_545
	v_ashrrev_i32_e32 v15, 31, v14
	v_lshl_add_u64 v[14:15], v[14:15], 2, s[14:15]
	global_store_dword v[14:15], v10, off sc1
.LBB0_545:
	s_or_b64 exec, exec, s[8:9]
	v_or_b32_e32 v16, 5, v2
	v_lshlrev_b32_e32 v14, 1, v16
	v_ashrrev_i32_e32 v15, 31, v14
	v_lshl_add_u64 v[14:15], v[14:15], 2, s[12:13]
	global_load_dwordx2 v[14:15], v[14:15], off
	s_waitcnt vmcnt(1)
	v_add_f32_e32 v42, v10, v12
	v_max_f32_e32 v12, v13, v13
	v_max_f32_e32 v12, v42, v12
	s_and_saveexec_b64 s[8:9], s[4:5]
	s_cbranch_execz .LBB0_547
	v_ashrrev_i32_e32 v17, 31, v16
	v_lshl_add_u64 v[16:17], v[16:17], 2, s[14:15]
	global_store_dword v[16:17], v12, off sc1
.LBB0_547:
	s_or_b64 exec, exec, s[8:9]
	v_or_b32_e32 v18, 6, v2
	v_lshlrev_b32_e32 v16, 1, v18
	v_ashrrev_i32_e32 v17, 31, v16
	v_lshl_add_u64 v[16:17], v[16:17], 2, s[12:13]
	global_load_dwordx2 v[16:17], v[16:17], off
	s_waitcnt vmcnt(1)
	v_add_f32_e32 v43, v12, v14
	v_max_f32_e32 v14, v15, v15
	v_max_f32_e32 v14, v43, v14
	s_and_saveexec_b64 s[8:9], s[4:5]
	s_cbranch_execz .LBB0_549
	v_ashrrev_i32_e32 v19, 31, v18
	v_lshl_add_u64 v[18:19], v[18:19], 2, s[14:15]
	global_store_dword v[18:19], v14, off sc1
.LBB0_549:
	s_or_b64 exec, exec, s[8:9]
	v_or_b32_e32 v20, 7, v2
	v_lshlrev_b32_e32 v18, 1, v20
	v_ashrrev_i32_e32 v19, 31, v18
	v_lshl_add_u64 v[18:19], v[18:19], 2, s[12:13]
	global_load_dwordx2 v[18:19], v[18:19], off
	s_waitcnt vmcnt(1)
	v_add_f32_e32 v44, v14, v16
	v_max_f32_e32 v16, v17, v17
	v_max_f32_e32 v16, v44, v16
	s_and_saveexec_b64 s[8:9], s[4:5]
	s_cbranch_execz .LBB0_551
	v_ashrrev_i32_e32 v21, 31, v20
	v_lshl_add_u64 v[20:21], v[20:21], 2, s[14:15]
	global_store_dword v[20:21], v16, off sc1
.LBB0_551:
	s_or_b64 exec, exec, s[8:9]
	v_or_b32_e32 v22, 8, v2
	v_lshlrev_b32_e32 v20, 1, v22
	v_ashrrev_i32_e32 v21, 31, v20
	v_lshl_add_u64 v[20:21], v[20:21], 2, s[12:13]
	global_load_dwordx2 v[20:21], v[20:21], off
	s_waitcnt vmcnt(1)
	v_add_f32_e32 v45, v16, v18
	v_max_f32_e32 v18, v19, v19
	v_max_f32_e32 v18, v45, v18
	s_and_saveexec_b64 s[8:9], s[4:5]
	s_cbranch_execz .LBB0_553
	v_ashrrev_i32_e32 v23, 31, v22
	v_lshl_add_u64 v[22:23], v[22:23], 2, s[14:15]
	global_store_dword v[22:23], v18, off sc1
.LBB0_553:
	s_or_b64 exec, exec, s[8:9]
	v_or_b32_e32 v24, 9, v2
	v_lshlrev_b32_e32 v22, 1, v24
	v_ashrrev_i32_e32 v23, 31, v22
	v_lshl_add_u64 v[22:23], v[22:23], 2, s[12:13]
	global_load_dwordx2 v[22:23], v[22:23], off
	s_waitcnt vmcnt(1)
	v_add_f32_e32 v46, v18, v20
	v_max_f32_e32 v20, v21, v21
	v_max_f32_e32 v20, v46, v20
	s_and_saveexec_b64 s[8:9], s[4:5]
	s_cbranch_execz .LBB0_555
	v_ashrrev_i32_e32 v25, 31, v24
	v_lshl_add_u64 v[24:25], v[24:25], 2, s[14:15]
	global_store_dword v[24:25], v20, off sc1
.LBB0_555:
	s_or_b64 exec, exec, s[8:9]
	v_or_b32_e32 v26, 10, v2
	v_lshlrev_b32_e32 v24, 1, v26
	v_ashrrev_i32_e32 v25, 31, v24
	v_lshl_add_u64 v[24:25], v[24:25], 2, s[12:13]
	global_load_dwordx2 v[24:25], v[24:25], off
	s_waitcnt vmcnt(1)
	v_add_f32_e32 v47, v20, v22
	v_max_f32_e32 v22, v23, v23
	v_max_f32_e32 v22, v47, v22
	s_and_saveexec_b64 s[8:9], s[4:5]
	s_cbranch_execz .LBB0_557
	v_ashrrev_i32_e32 v27, 31, v26
	v_lshl_add_u64 v[26:27], v[26:27], 2, s[14:15]
	global_store_dword v[26:27], v22, off sc1
.LBB0_557:
	s_or_b64 exec, exec, s[8:9]
	v_or_b32_e32 v28, 11, v2
	v_lshlrev_b32_e32 v26, 1, v28
	v_ashrrev_i32_e32 v27, 31, v26
	v_lshl_add_u64 v[26:27], v[26:27], 2, s[12:13]
	global_load_dwordx2 v[26:27], v[26:27], off
	s_waitcnt vmcnt(1)
	v_add_f32_e32 v48, v22, v24
	v_max_f32_e32 v24, v25, v25
	v_max_f32_e32 v24, v48, v24
	s_and_saveexec_b64 s[8:9], s[4:5]
	s_cbranch_execz .LBB0_559
	v_ashrrev_i32_e32 v29, 31, v28
	v_lshl_add_u64 v[28:29], v[28:29], 2, s[14:15]
	global_store_dword v[28:29], v24, off sc1
.LBB0_559:
	s_or_b64 exec, exec, s[8:9]
	v_or_b32_e32 v30, 12, v2
	v_lshlrev_b32_e32 v28, 1, v30
	v_ashrrev_i32_e32 v29, 31, v28
	v_lshl_add_u64 v[28:29], v[28:29], 2, s[12:13]
	global_load_dwordx2 v[28:29], v[28:29], off
	s_waitcnt vmcnt(1)
	v_add_f32_e32 v49, v24, v26
	v_max_f32_e32 v26, v27, v27
	v_max_f32_e32 v26, v49, v26
	s_and_saveexec_b64 s[8:9], s[4:5]
	s_cbranch_execz .LBB0_561
	v_ashrrev_i32_e32 v31, 31, v30
	v_lshl_add_u64 v[30:31], v[30:31], 2, s[14:15]
	global_store_dword v[30:31], v26, off sc1
.LBB0_561:
	s_or_b64 exec, exec, s[8:9]
	v_or_b32_e32 v32, 13, v2
	v_lshlrev_b32_e32 v30, 1, v32
	v_ashrrev_i32_e32 v31, 31, v30
	v_lshl_add_u64 v[30:31], v[30:31], 2, s[12:13]
	global_load_dwordx2 v[30:31], v[30:31], off
	s_waitcnt vmcnt(1)
	v_add_f32_e32 v57, v26, v28
	v_max_f32_e32 v28, v29, v29
	v_max_f32_e32 v28, v57, v28
	s_and_saveexec_b64 s[8:9], s[4:5]
	s_cbranch_execz .LBB0_563
	v_ashrrev_i32_e32 v33, 31, v32
	v_lshl_add_u64 v[32:33], v[32:33], 2, s[14:15]
	global_store_dword v[32:33], v28, off sc1
.LBB0_563:
	s_or_b64 exec, exec, s[8:9]
	v_or_b32_e32 v36, 14, v2
	v_lshlrev_b32_e32 v32, 1, v36
	v_ashrrev_i32_e32 v33, 31, v32
	v_lshl_add_u64 v[32:33], v[32:33], 2, s[12:13]
	global_load_dwordx2 v[34:35], v[32:33], off
	s_waitcnt vmcnt(1)
	v_add_f32_e32 v30, v28, v30
	v_max_f32_e32 v32, v31, v31
	v_max_f32_e32 v32, v30, v32
	s_waitcnt vmcnt(0)
	v_add_f32_e32 v34, v32, v34
	v_max_f32_e32 v33, v35, v35
	v_max_f32_e32 v33, v34, v33
	s_and_saveexec_b64 s[8:9], s[4:5]
	s_cbranch_execz .LBB0_565
	v_ashrrev_i32_e32 v37, 31, v36
	v_lshl_add_u64 v[36:37], v[36:37], 2, s[14:15]
	global_store_dwordx2 v[36:37], v[32:33], off sc1
.LBB0_565:
	s_or_b64 exec, exec, s[8:9]
	v_sub_f32_e32 v30, v30, v32
	v_mul_f32_e32 v30, 0x3fb8aa3b, v30
	v_exp_f32_e32 v58, v30
	v_sub_f32_e32 v30, v31, v32
	v_mul_f32_e32 v30, 0x3fb8aa3b, v30
	v_exp_f32_e32 v56, v30
	v_sub_f32_e32 v30, v57, v28
	v_sub_f32_e32 v28, v29, v28
	v_mul_f32_e32 v28, 0x3fb8aa3b, v28
	v_exp_f32_e32 v60, v28
	v_sub_f32_e32 v28, v49, v26
	v_sub_f32_e32 v26, v27, v26
	v_mul_f32_e32 v26, 0x3fb8aa3b, v26
	v_exp_f32_e32 v64, v26
	v_sub_f32_e32 v26, v48, v24
	v_sub_f32_e32 v24, v25, v24
	v_mul_f32_e32 v24, 0x3fb8aa3b, v24
	v_exp_f32_e32 v70, v24
	v_sub_f32_e32 v24, v47, v22
	v_sub_f32_e32 v22, v23, v22
	v_mul_f32_e32 v22, 0x3fb8aa3b, v22
	v_exp_f32_e32 v74, v22
	v_sub_f32_e32 v22, v46, v20
	v_sub_f32_e32 v20, v21, v20
	v_mul_f32_e32 v20, 0x3fb8aa3b, v20
	v_exp_f32_e32 v78, v20
	v_sub_f32_e32 v20, v45, v18
	v_sub_f32_e32 v18, v19, v18
	v_mul_f32_e32 v18, 0x3fb8aa3b, v18
	v_exp_f32_e32 v84, v18
	v_sub_f32_e32 v18, v44, v16
	v_sub_f32_e32 v16, v17, v16
	v_mul_f32_e32 v16, 0x3fb8aa3b, v16
	v_exp_f32_e32 v92, v16
	v_sub_f32_e32 v16, v43, v14
	v_sub_f32_e32 v14, v15, v14
	v_mul_f32_e32 v14, 0x3fb8aa3b, v14
	v_exp_f32_e32 v98, v14
	v_sub_f32_e32 v14, v42, v12
	v_sub_f32_e32 v12, v13, v12
	v_mul_f32_e32 v12, 0x3fb8aa3b, v12
	v_exp_f32_e32 v106, v12
	v_sub_f32_e32 v12, v41, v10
	v_sub_f32_e32 v10, v11, v10
	v_mul_f32_e32 v10, 0x3fb8aa3b, v10
	v_exp_f32_e32 v112, v10
	v_sub_f32_e32 v10, v40, v8
	v_sub_f32_e32 v8, v9, v8
	v_mul_f32_e32 v8, 0x3fb8aa3b, v8
	v_exp_f32_e32 v120, v8
	v_sub_f32_e32 v8, v39, v6
	v_sub_f32_e32 v6, v7, v6
	v_mul_f32_e32 v6, 0x3fb8aa3b, v6
	v_sub_f32_e32 v34, v34, v33
	v_sub_f32_e32 v33, v35, v33
	v_exp_f32_e32 v126, v6
	v_sub_f32_e32 v6, v38, v4
	v_sub_f32_e32 v4, v5, v4
	v_mul_f32_e32 v34, 0x3fb8aa3b, v34
	v_mul_f32_e32 v33, 0x3fb8aa3b, v33
	v_mul_f32_e32 v30, 0x3fb8aa3b, v30
	v_mul_f32_e32 v28, 0x3fb8aa3b, v28
	v_mul_f32_e32 v26, 0x3fb8aa3b, v26
	v_mul_f32_e32 v24, 0x3fb8aa3b, v24
	v_mul_f32_e32 v22, 0x3fb8aa3b, v22
	v_mul_f32_e32 v20, 0x3fb8aa3b, v20
	v_mul_f32_e32 v18, 0x3fb8aa3b, v18
	v_mul_f32_e32 v16, 0x3fb8aa3b, v16
	v_mul_f32_e32 v14, 0x3fb8aa3b, v14
	v_mul_f32_e32 v12, 0x3fb8aa3b, v12
	v_mul_f32_e32 v10, 0x3fb8aa3b, v10
	v_mul_f32_e32 v8, 0x3fb8aa3b, v8
	v_mul_f32_e32 v6, 0x3fb8aa3b, v6
	v_mul_f32_e32 v4, 0x3fb8aa3b, v4
	v_exp_f32_e32 v54, v34
	v_exp_f32_e32 v52, v33
	v_exp_f32_e32 v62, v30
	v_exp_f32_e32 v66, v28
	v_exp_f32_e32 v72, v26
	v_exp_f32_e32 v76, v24
	v_exp_f32_e32 v80, v22
	v_exp_f32_e32 v88, v20
	v_exp_f32_e32 v94, v18
	v_exp_f32_e32 v100, v16
	v_exp_f32_e32 v108, v14
	v_exp_f32_e32 v114, v12
	v_exp_f32_e32 v122, v10
	v_exp_f32_e32 v128, v8
	v_exp_f32_e32 v57, v6
	v_exp_f32_e32 v134, v4
	s_and_saveexec_b64 s[4:5], vcc
	s_xor_b64 s[4:5], exec, s[4:5]
	s_cbranch_execz .LBB0_567
	v_mov_b32_e32 v3, v179
	v_lshlrev_b64 v[2:3], 9, v[2:3]
	v_lshl_add_u64 v[2:3], v[50:51], 0, v[2:3]
	global_load_dword v6, v[2:3], off
	global_load_dword v7, v[2:3], off offset:512
	global_load_dword v8, v[2:3], off offset:1024
	global_load_dword v9, v[2:3], off offset:1536
	global_load_dword v10, v[2:3], off offset:2048
	global_load_dword v11, v[2:3], off offset:2560
	global_load_dword v12, v[2:3], off offset:3072
	global_load_dword v13, v[2:3], off offset:3584
	v_add_co_u32_e32 v4, vcc, 0x1000, v2
	s_waitcnt vmcnt(7)
	v_mul_f32_e32 v6, v134, v6
	v_addc_co_u32_e32 v5, vcc, 0, v3, vcc
	global_load_dword v14, v[4:5], off
	global_load_dword v15, v[4:5], off offset:512
	global_load_dword v16, v[4:5], off offset:1024
	global_load_dword v17, v[4:5], off offset:1536
	global_load_dword v18, v[4:5], off offset:2048
	global_load_dword v19, v[4:5], off offset:2560
	global_load_dword v20, v[4:5], off offset:3072
	v_fmac_f32_e32 v6, 0, v57
	global_store_dword v[2:3], v6, off offset:512 sc1
	v_mul_f32_e32 v6, v128, v6
	s_waitcnt vmcnt(14)
	v_fmac_f32_e32 v6, v126, v7
	global_store_dword v[2:3], v6, off offset:1024 sc1
	v_mul_f32_e32 v6, v122, v6
	s_waitcnt vmcnt(14)
	v_fmac_f32_e32 v6, v120, v8
	global_store_dword v[2:3], v6, off offset:1536 sc1
	v_mul_f32_e32 v6, v114, v6
	s_waitcnt vmcnt(14)
	v_fmac_f32_e32 v6, v112, v9
	global_store_dword v[2:3], v6, off offset:2048 sc1
	v_mul_f32_e32 v6, v108, v6
	s_waitcnt vmcnt(14)
	v_fmac_f32_e32 v6, v106, v10
	global_store_dword v[2:3], v6, off offset:2560 sc1
	v_mul_f32_e32 v6, v100, v6
	s_waitcnt vmcnt(14)
	v_fmac_f32_e32 v6, v98, v11
	global_store_dword v[2:3], v6, off offset:3072 sc1
	v_mul_f32_e32 v6, v94, v6
	s_waitcnt vmcnt(14)
	v_fmac_f32_e32 v6, v92, v12
	global_store_dword v[2:3], v179, off sc1
	global_store_dword v[2:3], v6, off offset:3584 sc1
	v_mul_f32_e32 v2, v88, v6
	s_waitcnt vmcnt(15)
	v_fmac_f32_e32 v2, v84, v13
	global_store_dword v[4:5], v2, off sc1
	v_mul_f32_e32 v2, v80, v2
	s_waitcnt vmcnt(15)
	v_fmac_f32_e32 v2, v78, v14
	global_store_dword v[4:5], v2, off offset:512 sc1
	v_mul_f32_e32 v2, v76, v2
	s_waitcnt vmcnt(15)
	v_fmac_f32_e32 v2, v74, v15
	global_store_dword v[4:5], v2, off offset:1024 sc1
	v_mul_f32_e32 v2, v72, v2
	s_waitcnt vmcnt(15)
	v_fmac_f32_e32 v2, v70, v16
	global_store_dword v[4:5], v2, off offset:1536 sc1
	v_mul_f32_e32 v2, v66, v2
	s_waitcnt vmcnt(15)
	v_fmac_f32_e32 v2, v64, v17
	global_store_dword v[4:5], v2, off offset:2048 sc1
	v_mul_f32_e32 v2, v62, v2
	s_waitcnt vmcnt(15)
	v_fmac_f32_e32 v2, v60, v18
	global_store_dword v[4:5], v2, off offset:2560 sc1
	v_mul_f32_e32 v2, v58, v2
	s_waitcnt vmcnt(15)
	v_fmac_f32_e32 v2, v56, v19
	global_store_dword v[4:5], v2, off offset:3072 sc1
	v_mul_f32_e32 v2, v54, v2
	s_waitcnt vmcnt(15)
	v_fmac_f32_e32 v2, v52, v20
	global_store_dword v[4:5], v2, off offset:3584 sc1
.LBB0_567:
	s_andn2_saveexec_b64 s[4:5], s[4:5]
	s_cbranch_execz .LBB0_534
	v_lshlrev_b64 v[2:3], 15, v[2:3]
	v_and_b32_e32 v4, 0x3ff8, v55
	v_lshl_add_u64 v[2:3], s[10:11], 0, v[2:3]
	v_lshlrev_b32_e32 v178, 1, v4
	v_lshl_add_u64 v[68:69], v[2:3], 0, v[178:179]
	v_add_co_u32_e32 v152, vcc, 0x8000, v68
	s_mov_b32 s8, 0x10000
	s_nop 0
	v_addc_co_u32_e32 v153, vcc, 0, v69, vcc
	global_load_dwordx4 v[136:139], v[68:69], off
	global_load_dwordx4 v[140:143], v[152:153], off
	v_add_co_u32_e32 v154, vcc, s8, v68
	s_mov_b32 s8, 0x18000
	s_nop 0
	v_addc_co_u32_e32 v155, vcc, 0, v69, vcc
	v_add_co_u32_e32 v132, vcc, s8, v68
	s_mov_b32 s8, 0x20000
	s_nop 0
	v_addc_co_u32_e32 v133, vcc, 0, v69, vcc
	global_load_dwordx4 v[144:147], v[154:155], off
	global_load_dwordx4 v[46:49], v[132:133], off
	v_add_co_u32_e32 v130, vcc, s8, v68
	s_mov_b32 s8, 0x28000
	s_nop 0
	v_addc_co_u32_e32 v131, vcc, 0, v69, vcc
	v_add_co_u32_e32 v124, vcc, s8, v68
	s_mov_b32 s8, 0x30000
	s_nop 0
	v_addc_co_u32_e32 v125, vcc, 0, v69, vcc
	global_load_dwordx4 v[42:45], v[130:131], off
	global_load_dwordx4 v[38:41], v[124:125], off
	v_add_co_u32_e32 v118, vcc, s8, v68
	s_mov_b32 s8, 0x38000
	s_nop 0
	v_addc_co_u32_e32 v119, vcc, 0, v69, vcc
	v_add_co_u32_e32 v116, vcc, s8, v68
	s_mov_b32 s8, 0x40000
	s_nop 0
	v_addc_co_u32_e32 v117, vcc, 0, v69, vcc
	global_load_dwordx4 v[34:37], v[118:119], off
	global_load_dwordx4 v[30:33], v[116:117], off
	v_add_co_u32_e32 v110, vcc, s8, v68
	s_mov_b32 s8, 0x48000
	s_nop 0
	v_addc_co_u32_e32 v111, vcc, 0, v69, vcc
	v_add_co_u32_e32 v104, vcc, s8, v68
	s_mov_b32 s8, 0x50000
	s_nop 0
	v_addc_co_u32_e32 v105, vcc, 0, v69, vcc
	v_add_co_u32_e32 v102, vcc, s8, v68
	s_mov_b32 s8, 0x58000
	s_nop 0
	v_addc_co_u32_e32 v103, vcc, 0, v69, vcc
	v_add_co_u32_e32 v96, vcc, s8, v68
	s_mov_b32 s8, 0x60000
	s_nop 0
	v_addc_co_u32_e32 v97, vcc, 0, v69, vcc
	global_load_dwordx4 v[26:29], v[110:111], off
	global_load_dwordx4 v[22:25], v[104:105], off
	v_add_co_u32_e32 v90, vcc, s8, v68
	s_mov_b32 s8, 0x68000
	s_nop 0
	v_addc_co_u32_e32 v91, vcc, 0, v69, vcc
	v_add_co_u32_e32 v86, vcc, s8, v68
	s_mov_b32 s8, 0x70000
	s_nop 0
	v_addc_co_u32_e32 v87, vcc, 0, v69, vcc
	v_add_co_u32_e32 v82, vcc, s8, v68
	v_mov_b32_e32 v59, v179
	s_nop 0
	v_addc_co_u32_e32 v83, vcc, 0, v69, vcc
	global_load_dwordx4 v[18:21], v[102:103], off
	global_load_dwordx4 v[14:17], v[96:97], off
	global_load_dwordx4 v[10:13], v[90:91], off
	global_load_dwordx4 v[6:9], v[86:87], off
	global_load_dwordx4 v[2:5], v[82:83], off
	s_nop 0
	v_bfe_u32 v61, v59, 16, 1
	v_add3_u32 v61, v59, v61, s97
	v_lshrrev_b32_e32 v63, 16, v61
	v_and_or_b32 v148, v61, s27, v63
	v_mov_b32_e32 v149, v148
	v_mov_b32_e32 v150, v148
	v_mov_b32_e32 v151, v148
	global_store_dwordx4 v[68:69], v[148:151], off sc1
	s_nop 1
	v_mul_f32_e32 v148, v57, v59
	s_waitcnt vmcnt(15)
	v_lshlrev_b32_e32 v151, 16, v137
	v_lshlrev_b32_e32 v150, 16, v136
	v_and_b32_e32 v137, 0xffff0000, v137
	v_and_b32_e32 v136, 0xffff0000, v136
	v_pk_fma_f32 v[156:157], v[134:135], v[136:137], v[148:149] op_sel_hi:[0,1,0]
	v_lshlrev_b32_e32 v137, 16, v139
	v_lshlrev_b32_e32 v136, 16, v138
	v_pk_fma_f32 v[150:151], v[134:135], v[150:151], v[148:149] op_sel_hi:[0,1,0]
	v_pk_fma_f32 v[158:159], v[134:135], v[136:137], v[148:149] op_sel_hi:[0,1,0]
	v_and_b32_e32 v137, 0xffff0000, v139
	v_and_b32_e32 v136, 0xffff0000, v138
	v_pk_fma_f32 v[138:139], v[134:135], v[136:137], v[148:149] op_sel_hi:[0,1,0]
	v_bfe_u32 v65, v150, 16, 1
	v_bfe_u32 v67, v151, 16, 1
	v_bfe_u32 v71, v158, 16, 1
	v_bfe_u32 v73, v159, 16, 1
	v_bfe_u32 v57, v139, 16, 1
	v_bfe_u32 v59, v138, 16, 1
	v_bfe_u32 v61, v157, 16, 1
	v_bfe_u32 v63, v156, 16, 1
	v_add3_u32 v73, v159, v73, s97
	v_add3_u32 v71, v158, v71, s97
	v_add3_u32 v67, v151, v67, s97
	v_add3_u32 v65, v150, v65, s97
	v_add3_u32 v63, v156, v63, s97
	v_add3_u32 v61, v157, v61, s97
	v_add3_u32 v59, v138, v59, s97
	v_add3_u32 v57, v139, v57, s97
	v_lshrrev_b32_e32 v65, 16, v65
	v_lshrrev_b32_e32 v67, 16, v67
	v_lshrrev_b32_e32 v71, 16, v71
	v_lshrrev_b32_e32 v73, 16, v73
	v_and_or_b32 v137, v57, s27, v73
	v_and_or_b32 v136, v59, s27, v71
	v_and_or_b32 v135, v61, s27, v67
	v_and_or_b32 v134, v63, s27, v65
	global_store_dwordx4 v[152:153], v[134:137], off sc1
	s_waitcnt vmcnt(15)
	v_lshlrev_b32_e32 v149, 16, v143
	v_lshlrev_b32_e32 v148, 16, v142
	v_pk_mul_f32 v[134:135], v[128:129], v[150:151] op_sel_hi:[0,1]
	v_lshlrev_b32_e32 v137, 16, v141
	v_lshlrev_b32_e32 v136, 16, v140
	v_pk_fma_f32 v[134:135], v[126:127], v[136:137], v[134:135] op_sel_hi:[0,1,1]
	v_pk_mul_f32 v[136:137], v[128:129], v[156:157] op_sel_hi:[0,1]
	v_and_b32_e32 v141, 0xffff0000, v141
	v_and_b32_e32 v140, 0xffff0000, v140
	v_pk_fma_f32 v[136:137], v[126:127], v[140:141], v[136:137] op_sel_hi:[0,1,1]
	v_pk_mul_f32 v[140:141], v[128:129], v[158:159] op_sel_hi:[0,1]
	v_pk_fma_f32 v[140:141], v[126:127], v[148:149], v[140:141] op_sel_hi:[0,1,1]
	v_pk_mul_f32 v[128:129], v[128:129], v[138:139] op_sel_hi:[0,1]
	v_and_b32_e32 v139, 0xffff0000, v143
	v_and_b32_e32 v138, 0xffff0000, v142
	v_pk_fma_f32 v[138:139], v[126:127], v[138:139], v[128:129] op_sel_hi:[0,1,1]
	v_bfe_u32 v65, v134, 16, 1
	v_bfe_u32 v67, v135, 16, 1
	v_bfe_u32 v71, v140, 16, 1
	v_bfe_u32 v73, v141, 16, 1
	v_bfe_u32 v57, v139, 16, 1
	v_bfe_u32 v59, v138, 16, 1
	v_bfe_u32 v61, v137, 16, 1
	v_bfe_u32 v63, v136, 16, 1
	v_add3_u32 v73, v141, v73, s97
	v_add3_u32 v71, v140, v71, s97
	v_add3_u32 v67, v135, v67, s97
	v_add3_u32 v65, v134, v65, s97
	v_add3_u32 v63, v136, v63, s97
	v_add3_u32 v61, v137, v61, s97
	v_add3_u32 v59, v138, v59, s97
	v_add3_u32 v57, v139, v57, s97
	v_lshrrev_b32_e32 v65, 16, v65
	v_lshrrev_b32_e32 v67, 16, v67
	v_lshrrev_b32_e32 v71, 16, v71
	v_lshrrev_b32_e32 v73, 16, v73
	v_and_or_b32 v129, v57, s27, v73
	v_and_or_b32 v128, v59, s27, v71
	v_and_or_b32 v127, v61, s27, v67
	v_and_or_b32 v126, v63, s27, v65
	global_store_dwordx4 v[154:155], v[126:129], off sc1
	s_nop 1
	v_pk_mul_f32 v[126:127], v[122:123], v[134:135] op_sel_hi:[0,1]
	s_waitcnt vmcnt(15)
	v_lshlrev_b32_e32 v129, 16, v145
	v_lshlrev_b32_e32 v128, 16, v144
	v_pk_fma_f32 v[126:127], v[120:121], v[128:129], v[126:127] op_sel_hi:[0,1,1]
	v_pk_mul_f32 v[128:129], v[122:123], v[136:137] op_sel_hi:[0,1]
	v_and_b32_e32 v135, 0xffff0000, v145
	v_and_b32_e32 v134, 0xffff0000, v144
	v_pk_fma_f32 v[128:129], v[120:121], v[134:135], v[128:129] op_sel_hi:[0,1,1]
	v_pk_mul_f32 v[134:135], v[122:123], v[140:141] op_sel_hi:[0,1]
	v_lshlrev_b32_e32 v137, 16, v147
	v_lshlrev_b32_e32 v136, 16, v146
	v_pk_fma_f32 v[134:135], v[120:121], v[136:137], v[134:135] op_sel_hi:[0,1,1]
	v_pk_mul_f32 v[122:123], v[122:123], v[138:139] op_sel_hi:[0,1]
	v_and_b32_e32 v137, 0xffff0000, v147
	v_and_b32_e32 v136, 0xffff0000, v146
	v_pk_fma_f32 v[136:137], v[120:121], v[136:137], v[122:123] op_sel_hi:[0,1,1]
	v_bfe_u32 v65, v126, 16, 1
	v_bfe_u32 v67, v127, 16, 1
	v_bfe_u32 v71, v134, 16, 1
	v_bfe_u32 v73, v135, 16, 1
	v_bfe_u32 v57, v137, 16, 1
	v_bfe_u32 v59, v136, 16, 1
	v_bfe_u32 v61, v129, 16, 1
	v_bfe_u32 v63, v128, 16, 1
	v_add3_u32 v73, v135, v73, s97
	v_add3_u32 v71, v134, v71, s97
	v_add3_u32 v67, v127, v67, s97
	v_add3_u32 v65, v126, v65, s97
	v_add3_u32 v63, v128, v63, s97
	v_add3_u32 v61, v129, v61, s97
	v_add3_u32 v59, v136, v59, s97
	v_add3_u32 v57, v137, v57, s97
	v_lshrrev_b32_e32 v65, 16, v65
	v_lshrrev_b32_e32 v67, 16, v67
	v_lshrrev_b32_e32 v71, 16, v71
	v_lshrrev_b32_e32 v73, 16, v73
	v_and_or_b32 v123, v57, s27, v73
	v_and_or_b32 v122, v59, s27, v71
	v_and_or_b32 v121, v61, s27, v67
	v_and_or_b32 v120, v63, s27, v65
	global_store_dwordx4 v[132:133], v[120:123], off sc1
	s_nop 1
	v_pk_mul_f32 v[120:121], v[114:115], v[126:127] op_sel_hi:[0,1]
	s_waitcnt vmcnt(15)
	v_lshlrev_b32_e32 v123, 16, v47
	v_lshlrev_b32_e32 v122, 16, v46
	v_pk_fma_f32 v[120:121], v[112:113], v[122:123], v[120:121] op_sel_hi:[0,1,1]
	v_pk_mul_f32 v[122:123], v[114:115], v[128:129] op_sel_hi:[0,1]
	v_and_b32_e32 v47, 0xffff0000, v47
	v_and_b32_e32 v46, 0xffff0000, v46
	v_pk_fma_f32 v[122:123], v[112:113], v[46:47], v[122:123] op_sel_hi:[0,1,1]
	v_pk_mul_f32 v[46:47], v[114:115], v[134:135] op_sel_hi:[0,1]
	v_lshlrev_b32_e32 v127, 16, v49
	v_lshlrev_b32_e32 v126, 16, v48
	v_pk_fma_f32 v[126:127], v[112:113], v[126:127], v[46:47] op_sel_hi:[0,1,1]
	v_pk_mul_f32 v[46:47], v[114:115], v[136:137] op_sel_hi:[0,1]
	v_and_b32_e32 v49, 0xffff0000, v49
	v_and_b32_e32 v48, 0xffff0000, v48
	v_pk_fma_f32 v[112:113], v[112:113], v[48:49], v[46:47] op_sel_hi:[0,1,1]
	v_bfe_u32 v48, v123, 16, 1
	v_bfe_u32 v49, v122, 16, 1
	v_add3_u32 v57, v122, v49, s97
	v_add3_u32 v59, v123, v48, s97
	v_bfe_u32 v48, v120, 16, 1
	v_bfe_u32 v49, v121, 16, 1
	v_bfe_u32 v61, v126, 16, 1
	v_bfe_u32 v63, v127, 16, 1
	v_bfe_u32 v46, v113, 16, 1
	v_bfe_u32 v47, v112, 16, 1
	v_add3_u32 v63, v127, v63, s97
	v_add3_u32 v61, v126, v61, s97
	v_add3_u32 v49, v121, v49, s97
	v_add3_u32 v48, v120, v48, s97
	v_add3_u32 v47, v112, v47, s97
	v_add3_u32 v46, v113, v46, s97
	v_lshrrev_b32_e32 v65, 16, v48
	v_lshrrev_b32_e32 v67, 16, v49
	v_lshrrev_b32_e32 v48, 16, v61
	v_lshrrev_b32_e32 v49, 16, v63
	v_and_or_b32 v49, v46, s27, v49
	v_and_or_b32 v48, v47, s27, v48
	v_and_or_b32 v47, v59, s27, v67
	v_and_or_b32 v46, v57, s27, v65
	global_store_dwordx4 v[130:131], v[46:49], off sc1
	s_waitcnt vmcnt(15)
	v_lshlrev_b32_e32 v115, 16, v45
	v_lshlrev_b32_e32 v114, 16, v44
	v_pk_mul_f32 v[46:47], v[108:109], v[120:121] op_sel_hi:[0,1]
	v_lshlrev_b32_e32 v49, 16, v43
	v_lshlrev_b32_e32 v48, 16, v42
	v_pk_fma_f32 v[46:47], v[106:107], v[48:49], v[46:47] op_sel_hi:[0,1,1]
	v_pk_mul_f32 v[48:49], v[108:109], v[122:123] op_sel_hi:[0,1]
	v_and_b32_e32 v43, 0xffff0000, v43
	v_and_b32_e32 v42, 0xffff0000, v42
	v_pk_fma_f32 v[48:49], v[106:107], v[42:43], v[48:49] op_sel_hi:[0,1,1]
	v_pk_mul_f32 v[42:43], v[108:109], v[126:127] op_sel_hi:[0,1]
	v_pk_fma_f32 v[114:115], v[106:107], v[114:115], v[42:43] op_sel_hi:[0,1,1]
	v_pk_mul_f32 v[42:43], v[108:109], v[112:113] op_sel_hi:[0,1]
	v_and_b32_e32 v45, 0xffff0000, v45
	v_and_b32_e32 v44, 0xffff0000, v44
	v_pk_fma_f32 v[106:107], v[106:107], v[44:45], v[42:43] op_sel_hi:[0,1,1]
	v_bfe_u32 v44, v49, 16, 1
	v_bfe_u32 v45, v48, 16, 1
	v_add3_u32 v57, v48, v45, s97
	v_add3_u32 v59, v49, v44, s97
	v_bfe_u32 v44, v46, 16, 1
	v_bfe_u32 v45, v47, 16, 1
	v_bfe_u32 v61, v114, 16, 1
	v_bfe_u32 v63, v115, 16, 1
	v_bfe_u32 v42, v107, 16, 1
	v_bfe_u32 v43, v106, 16, 1
	v_add3_u32 v63, v115, v63, s97
	v_add3_u32 v61, v114, v61, s97
	v_add3_u32 v45, v47, v45, s97
	v_add3_u32 v44, v46, v44, s97
	v_add3_u32 v43, v106, v43, s97
	v_add3_u32 v42, v107, v42, s97
	v_lshrrev_b32_e32 v65, 16, v44
	v_lshrrev_b32_e32 v67, 16, v45
	v_lshrrev_b32_e32 v44, 16, v61
	v_lshrrev_b32_e32 v45, 16, v63
	v_and_or_b32 v45, v42, s27, v45
	v_and_or_b32 v44, v43, s27, v44
	v_and_or_b32 v43, v59, s27, v67
	v_and_or_b32 v42, v57, s27, v65
	global_store_dwordx4 v[124:125], v[42:45], off sc1
	s_nop 1
	v_pk_mul_f32 v[42:43], v[100:101], v[46:47] op_sel_hi:[0,1]
	s_waitcnt vmcnt(15)
	v_lshlrev_b32_e32 v45, 16, v39
	v_lshlrev_b32_e32 v44, 16, v38
	v_pk_fma_f32 v[42:43], v[98:99], v[44:45], v[42:43] op_sel_hi:[0,1,1]
	v_pk_mul_f32 v[44:45], v[100:101], v[48:49] op_sel_hi:[0,1]
	v_and_b32_e32 v39, 0xffff0000, v39
	v_and_b32_e32 v38, 0xffff0000, v38
	v_pk_fma_f32 v[44:45], v[98:99], v[38:39], v[44:45] op_sel_hi:[0,1,1]
	v_pk_mul_f32 v[38:39], v[100:101], v[114:115] op_sel_hi:[0,1]
	v_lshlrev_b32_e32 v47, 16, v41
	v_lshlrev_b32_e32 v46, 16, v40
	v_pk_fma_f32 v[46:47], v[98:99], v[46:47], v[38:39] op_sel_hi:[0,1,1]
	v_pk_mul_f32 v[38:39], v[100:101], v[106:107] op_sel_hi:[0,1]
	v_and_b32_e32 v41, 0xffff0000, v41
	v_and_b32_e32 v40, 0xffff0000, v40
	v_pk_fma_f32 v[48:49], v[98:99], v[40:41], v[38:39] op_sel_hi:[0,1,1]
	v_bfe_u32 v40, v45, 16, 1
	v_bfe_u32 v41, v44, 16, 1
	v_add3_u32 v57, v44, v41, s97
	v_add3_u32 v59, v45, v40, s97
	v_bfe_u32 v40, v42, 16, 1
	v_bfe_u32 v41, v43, 16, 1
	v_bfe_u32 v61, v46, 16, 1
	v_bfe_u32 v63, v47, 16, 1
	v_bfe_u32 v38, v49, 16, 1
	v_bfe_u32 v39, v48, 16, 1
	v_add3_u32 v63, v47, v63, s97
	v_add3_u32 v61, v46, v61, s97
	v_add3_u32 v41, v43, v41, s97
	v_add3_u32 v40, v42, v40, s97
	v_add3_u32 v39, v48, v39, s97
	v_add3_u32 v38, v49, v38, s97
	v_lshrrev_b32_e32 v65, 16, v40
	v_lshrrev_b32_e32 v67, 16, v41
	v_lshrrev_b32_e32 v40, 16, v61
	v_lshrrev_b32_e32 v41, 16, v63
	v_and_or_b32 v41, v38, s27, v41
	v_and_or_b32 v40, v39, s27, v40
	v_and_or_b32 v39, v59, s27, v67
	v_and_or_b32 v38, v57, s27, v65
	global_store_dwordx4 v[118:119], v[38:41], off sc1
	s_nop 1
	v_pk_mul_f32 v[38:39], v[94:95], v[42:43] op_sel_hi:[0,1]
	s_waitcnt vmcnt(15)
	v_lshlrev_b32_e32 v41, 16, v35
	v_lshlrev_b32_e32 v40, 16, v34
	v_pk_fma_f32 v[38:39], v[92:93], v[40:41], v[38:39] op_sel_hi:[0,1,1]
	v_pk_mul_f32 v[40:41], v[94:95], v[44:45] op_sel_hi:[0,1]
	v_and_b32_e32 v35, 0xffff0000, v35
	v_and_b32_e32 v34, 0xffff0000, v34
	v_pk_fma_f32 v[40:41], v[92:93], v[34:35], v[40:41] op_sel_hi:[0,1,1]
	v_pk_mul_f32 v[34:35], v[94:95], v[46:47] op_sel_hi:[0,1]
	v_lshlrev_b32_e32 v43, 16, v37
	v_lshlrev_b32_e32 v42, 16, v36
	v_pk_fma_f32 v[42:43], v[92:93], v[42:43], v[34:35] op_sel_hi:[0,1,1]
	v_pk_mul_f32 v[34:35], v[94:95], v[48:49] op_sel_hi:[0,1]
	v_and_b32_e32 v37, 0xffff0000, v37
	v_and_b32_e32 v36, 0xffff0000, v36
	v_pk_fma_f32 v[44:45], v[92:93], v[36:37], v[34:35] op_sel_hi:[0,1,1]
	v_bfe_u32 v36, v41, 16, 1
	v_bfe_u32 v37, v40, 16, 1
	v_add3_u32 v46, v40, v37, s97
	v_add3_u32 v47, v41, v36, s97
	v_bfe_u32 v36, v38, 16, 1
	v_bfe_u32 v37, v39, 16, 1
	v_bfe_u32 v48, v42, 16, 1
	v_bfe_u32 v49, v43, 16, 1
	v_bfe_u32 v34, v45, 16, 1
	v_bfe_u32 v35, v44, 16, 1
	v_add3_u32 v49, v43, v49, s97
	v_add3_u32 v48, v42, v48, s97
	v_add3_u32 v37, v39, v37, s97
	v_add3_u32 v36, v38, v36, s97
	v_add3_u32 v35, v44, v35, s97
	v_add3_u32 v34, v45, v34, s97
	v_lshrrev_b32_e32 v57, 16, v36
	v_lshrrev_b32_e32 v59, 16, v37
	v_lshrrev_b32_e32 v36, 16, v48
	v_lshrrev_b32_e32 v37, 16, v49
	v_and_or_b32 v37, v34, s27, v37
	v_and_or_b32 v36, v35, s27, v36
	v_and_or_b32 v35, v47, s27, v59
	v_and_or_b32 v34, v46, s27, v57
	global_store_dwordx4 v[116:117], v[34:37], off sc1
	s_nop 1
	v_pk_mul_f32 v[34:35], v[88:89], v[38:39] op_sel_hi:[0,1]
	s_waitcnt vmcnt(15)
	v_lshlrev_b32_e32 v37, 16, v31
	v_lshlrev_b32_e32 v36, 16, v30
	v_pk_fma_f32 v[34:35], v[84:85], v[36:37], v[34:35] op_sel_hi:[0,1,1]
	v_pk_mul_f32 v[36:37], v[88:89], v[40:41] op_sel_hi:[0,1]
	v_and_b32_e32 v31, 0xffff0000, v31
	v_and_b32_e32 v30, 0xffff0000, v30
	v_pk_fma_f32 v[36:37], v[84:85], v[30:31], v[36:37] op_sel_hi:[0,1,1]
	v_pk_mul_f32 v[30:31], v[88:89], v[42:43] op_sel_hi:[0,1]
	v_lshlrev_b32_e32 v39, 16, v33
	v_lshlrev_b32_e32 v38, 16, v32
	v_pk_fma_f32 v[38:39], v[84:85], v[38:39], v[30:31] op_sel_hi:[0,1,1]
	v_pk_mul_f32 v[30:31], v[88:89], v[44:45] op_sel_hi:[0,1]
	v_and_b32_e32 v33, 0xffff0000, v33
	v_and_b32_e32 v32, 0xffff0000, v32
	v_pk_fma_f32 v[40:41], v[84:85], v[32:33], v[30:31] op_sel_hi:[0,1,1]
	v_bfe_u32 v32, v37, 16, 1
	v_bfe_u32 v33, v36, 16, 1
	v_add3_u32 v42, v36, v33, s97
	v_add3_u32 v43, v37, v32, s97
	v_bfe_u32 v32, v34, 16, 1
	v_bfe_u32 v33, v35, 16, 1
	v_bfe_u32 v44, v38, 16, 1
	v_bfe_u32 v45, v39, 16, 1
	v_bfe_u32 v30, v41, 16, 1
	v_bfe_u32 v31, v40, 16, 1
	v_add3_u32 v45, v39, v45, s97
	v_add3_u32 v44, v38, v44, s97
	v_add3_u32 v33, v35, v33, s97
	v_add3_u32 v32, v34, v32, s97
	v_add3_u32 v31, v40, v31, s97
	v_add3_u32 v30, v41, v30, s97
	v_lshrrev_b32_e32 v46, 16, v32
	v_lshrrev_b32_e32 v47, 16, v33
	v_lshrrev_b32_e32 v32, 16, v44
	v_lshrrev_b32_e32 v33, 16, v45
	v_and_or_b32 v33, v30, s27, v33
	v_and_or_b32 v32, v31, s27, v32
	v_and_or_b32 v31, v43, s27, v47
	v_and_or_b32 v30, v42, s27, v46
	global_store_dwordx4 v[110:111], v[30:33], off sc1
	s_nop 1
	v_pk_mul_f32 v[30:31], v[80:81], v[34:35] op_sel_hi:[0,1]
	s_waitcnt vmcnt(15)
	v_lshlrev_b32_e32 v33, 16, v27
	v_lshlrev_b32_e32 v32, 16, v26
	v_pk_fma_f32 v[30:31], v[78:79], v[32:33], v[30:31] op_sel_hi:[0,1,1]
	v_pk_mul_f32 v[32:33], v[80:81], v[36:37] op_sel_hi:[0,1]
	v_and_b32_e32 v27, 0xffff0000, v27
	v_and_b32_e32 v26, 0xffff0000, v26
	v_pk_fma_f32 v[32:33], v[78:79], v[26:27], v[32:33] op_sel_hi:[0,1,1]
	v_pk_mul_f32 v[26:27], v[80:81], v[38:39] op_sel_hi:[0,1]
	v_lshlrev_b32_e32 v35, 16, v29
	v_lshlrev_b32_e32 v34, 16, v28
	v_pk_fma_f32 v[34:35], v[78:79], v[34:35], v[26:27] op_sel_hi:[0,1,1]
	v_pk_mul_f32 v[26:27], v[80:81], v[40:41] op_sel_hi:[0,1]
	v_and_b32_e32 v29, 0xffff0000, v29
	v_and_b32_e32 v28, 0xffff0000, v28
	v_pk_fma_f32 v[36:37], v[78:79], v[28:29], v[26:27] op_sel_hi:[0,1,1]
	v_bfe_u32 v28, v33, 16, 1
	v_bfe_u32 v29, v32, 16, 1
	v_add3_u32 v38, v32, v29, s97
	v_add3_u32 v39, v33, v28, s97
	v_bfe_u32 v28, v30, 16, 1
	v_bfe_u32 v29, v31, 16, 1
	v_bfe_u32 v40, v34, 16, 1
	v_bfe_u32 v41, v35, 16, 1
	v_bfe_u32 v26, v37, 16, 1
	v_bfe_u32 v27, v36, 16, 1
	v_add3_u32 v41, v35, v41, s97
	v_add3_u32 v40, v34, v40, s97
	v_add3_u32 v29, v31, v29, s97
	v_add3_u32 v28, v30, v28, s97
	v_add3_u32 v27, v36, v27, s97
	v_add3_u32 v26, v37, v26, s97
	v_lshrrev_b32_e32 v42, 16, v28
	v_lshrrev_b32_e32 v43, 16, v29
	v_lshrrev_b32_e32 v28, 16, v40
	v_lshrrev_b32_e32 v29, 16, v41
	v_and_or_b32 v29, v26, s27, v29
	v_and_or_b32 v28, v27, s27, v28
	v_and_or_b32 v27, v39, s27, v43
	v_and_or_b32 v26, v38, s27, v42
	global_store_dwordx4 v[104:105], v[26:29], off sc1
	s_nop 1
	v_pk_mul_f32 v[26:27], v[76:77], v[30:31] op_sel_hi:[0,1]
	s_waitcnt vmcnt(15)
	v_lshlrev_b32_e32 v29, 16, v23
	v_lshlrev_b32_e32 v28, 16, v22
	v_pk_fma_f32 v[26:27], v[74:75], v[28:29], v[26:27] op_sel_hi:[0,1,1]
	v_pk_mul_f32 v[28:29], v[76:77], v[32:33] op_sel_hi:[0,1]
	v_and_b32_e32 v23, 0xffff0000, v23
	v_and_b32_e32 v22, 0xffff0000, v22
	v_pk_fma_f32 v[28:29], v[74:75], v[22:23], v[28:29] op_sel_hi:[0,1,1]
	v_pk_mul_f32 v[22:23], v[76:77], v[34:35] op_sel_hi:[0,1]
	v_lshlrev_b32_e32 v31, 16, v25
	v_lshlrev_b32_e32 v30, 16, v24
	v_pk_fma_f32 v[30:31], v[74:75], v[30:31], v[22:23] op_sel_hi:[0,1,1]
	v_pk_mul_f32 v[22:23], v[76:77], v[36:37] op_sel_hi:[0,1]
	v_and_b32_e32 v25, 0xffff0000, v25
	v_and_b32_e32 v24, 0xffff0000, v24
	v_pk_fma_f32 v[32:33], v[74:75], v[24:25], v[22:23] op_sel_hi:[0,1,1]
	v_bfe_u32 v24, v29, 16, 1
	v_bfe_u32 v25, v28, 16, 1
	v_add3_u32 v34, v28, v25, s97
	v_add3_u32 v35, v29, v24, s97
	v_bfe_u32 v24, v26, 16, 1
	v_bfe_u32 v25, v27, 16, 1
	v_bfe_u32 v36, v30, 16, 1
	v_bfe_u32 v37, v31, 16, 1
	v_bfe_u32 v22, v33, 16, 1
	v_bfe_u32 v23, v32, 16, 1
	v_add3_u32 v37, v31, v37, s97
	v_add3_u32 v36, v30, v36, s97
	v_add3_u32 v25, v27, v25, s97
	v_add3_u32 v24, v26, v24, s97
	v_add3_u32 v23, v32, v23, s97
	v_add3_u32 v22, v33, v22, s97
	v_lshrrev_b32_e32 v38, 16, v24
	v_lshrrev_b32_e32 v39, 16, v25
	v_lshrrev_b32_e32 v24, 16, v36
	v_lshrrev_b32_e32 v25, 16, v37
	v_and_or_b32 v25, v22, s27, v25
	v_and_or_b32 v24, v23, s27, v24
	v_and_or_b32 v23, v35, s27, v39
	v_and_or_b32 v22, v34, s27, v38
	global_store_dwordx4 v[102:103], v[22:25], off sc1
	s_nop 1
	v_pk_mul_f32 v[22:23], v[72:73], v[26:27] op_sel_hi:[0,1]
	s_waitcnt vmcnt(15)
	v_lshlrev_b32_e32 v25, 16, v19
	v_lshlrev_b32_e32 v24, 16, v18
	v_pk_fma_f32 v[22:23], v[70:71], v[24:25], v[22:23] op_sel_hi:[0,1,1]
	v_pk_mul_f32 v[24:25], v[72:73], v[28:29] op_sel_hi:[0,1]
	v_and_b32_e32 v19, 0xffff0000, v19
	v_and_b32_e32 v18, 0xffff0000, v18
	v_pk_fma_f32 v[24:25], v[70:71], v[18:19], v[24:25] op_sel_hi:[0,1,1]
	v_pk_mul_f32 v[18:19], v[72:73], v[30:31] op_sel_hi:[0,1]
	v_lshlrev_b32_e32 v27, 16, v21
	v_lshlrev_b32_e32 v26, 16, v20
	v_pk_fma_f32 v[26:27], v[70:71], v[26:27], v[18:19] op_sel_hi:[0,1,1]
	v_pk_mul_f32 v[18:19], v[72:73], v[32:33] op_sel_hi:[0,1]
	v_and_b32_e32 v21, 0xffff0000, v21
	v_and_b32_e32 v20, 0xffff0000, v20
	v_pk_fma_f32 v[28:29], v[70:71], v[20:21], v[18:19] op_sel_hi:[0,1,1]
	v_bfe_u32 v20, v25, 16, 1
	v_bfe_u32 v21, v24, 16, 1
	v_add3_u32 v30, v24, v21, s97
	v_add3_u32 v31, v25, v20, s97
	v_bfe_u32 v20, v22, 16, 1
	v_bfe_u32 v21, v23, 16, 1
	v_bfe_u32 v32, v26, 16, 1
	v_bfe_u32 v33, v27, 16, 1
	v_bfe_u32 v18, v29, 16, 1
	v_bfe_u32 v19, v28, 16, 1
	v_add3_u32 v33, v27, v33, s97
	v_add3_u32 v32, v26, v32, s97
	v_add3_u32 v21, v23, v21, s97
	v_add3_u32 v20, v22, v20, s97
	v_add3_u32 v19, v28, v19, s97
	v_add3_u32 v18, v29, v18, s97
	v_lshrrev_b32_e32 v34, 16, v20
	v_lshrrev_b32_e32 v35, 16, v21
	v_lshrrev_b32_e32 v20, 16, v32
	v_lshrrev_b32_e32 v21, 16, v33
	v_and_or_b32 v21, v18, s27, v21
	v_and_or_b32 v20, v19, s27, v20
	v_and_or_b32 v19, v31, s27, v35
	v_and_or_b32 v18, v30, s27, v34
	global_store_dwordx4 v[96:97], v[18:21], off sc1
	s_nop 1
	v_pk_mul_f32 v[18:19], v[66:67], v[22:23] op_sel_hi:[0,1]
	s_waitcnt vmcnt(15)
	v_lshlrev_b32_e32 v21, 16, v15
	v_lshlrev_b32_e32 v20, 16, v14
	v_pk_fma_f32 v[18:19], v[64:65], v[20:21], v[18:19] op_sel_hi:[0,1,1]
	v_pk_mul_f32 v[20:21], v[66:67], v[24:25] op_sel_hi:[0,1]
	v_and_b32_e32 v15, 0xffff0000, v15
	v_and_b32_e32 v14, 0xffff0000, v14
	v_pk_fma_f32 v[20:21], v[64:65], v[14:15], v[20:21] op_sel_hi:[0,1,1]
	v_pk_mul_f32 v[14:15], v[66:67], v[26:27] op_sel_hi:[0,1]
	v_lshlrev_b32_e32 v23, 16, v17
	v_lshlrev_b32_e32 v22, 16, v16
	v_pk_fma_f32 v[22:23], v[64:65], v[22:23], v[14:15] op_sel_hi:[0,1,1]
	v_pk_mul_f32 v[14:15], v[66:67], v[28:29] op_sel_hi:[0,1]
	v_and_b32_e32 v17, 0xffff0000, v17
	v_and_b32_e32 v16, 0xffff0000, v16
	v_pk_fma_f32 v[24:25], v[64:65], v[16:17], v[14:15] op_sel_hi:[0,1,1]
	v_bfe_u32 v16, v21, 16, 1
	v_bfe_u32 v17, v20, 16, 1
	v_add3_u32 v26, v20, v17, s97
	v_add3_u32 v27, v21, v16, s97
	v_bfe_u32 v16, v18, 16, 1
	v_bfe_u32 v17, v19, 16, 1
	v_bfe_u32 v28, v22, 16, 1
	v_bfe_u32 v29, v23, 16, 1
	v_bfe_u32 v14, v25, 16, 1
	v_bfe_u32 v15, v24, 16, 1
	v_add3_u32 v29, v23, v29, s97
	v_add3_u32 v28, v22, v28, s97
	v_add3_u32 v17, v19, v17, s97
	v_add3_u32 v16, v18, v16, s97
	v_add3_u32 v15, v24, v15, s97
	v_add3_u32 v14, v25, v14, s97
	v_lshrrev_b32_e32 v30, 16, v16
	v_lshrrev_b32_e32 v31, 16, v17
	v_lshrrev_b32_e32 v16, 16, v28
	v_lshrrev_b32_e32 v17, 16, v29
	v_and_or_b32 v17, v14, s27, v17
	v_and_or_b32 v16, v15, s27, v16
	v_and_or_b32 v15, v27, s27, v31
	v_and_or_b32 v14, v26, s27, v30
	global_store_dwordx4 v[90:91], v[14:17], off sc1
	s_nop 1
	v_pk_mul_f32 v[14:15], v[62:63], v[18:19] op_sel_hi:[0,1]
	s_waitcnt vmcnt(15)
	v_lshlrev_b32_e32 v17, 16, v11
	v_lshlrev_b32_e32 v16, 16, v10
	v_pk_fma_f32 v[14:15], v[60:61], v[16:17], v[14:15] op_sel_hi:[0,1,1]
	v_pk_mul_f32 v[16:17], v[62:63], v[20:21] op_sel_hi:[0,1]
	v_and_b32_e32 v11, 0xffff0000, v11
	v_and_b32_e32 v10, 0xffff0000, v10
	v_pk_fma_f32 v[16:17], v[60:61], v[10:11], v[16:17] op_sel_hi:[0,1,1]
	v_pk_mul_f32 v[10:11], v[62:63], v[22:23] op_sel_hi:[0,1]
	v_lshlrev_b32_e32 v19, 16, v13
	v_lshlrev_b32_e32 v18, 16, v12
	v_pk_fma_f32 v[18:19], v[60:61], v[18:19], v[10:11] op_sel_hi:[0,1,1]
	v_pk_mul_f32 v[10:11], v[62:63], v[24:25] op_sel_hi:[0,1]
	v_and_b32_e32 v13, 0xffff0000, v13
	v_and_b32_e32 v12, 0xffff0000, v12
	v_pk_fma_f32 v[20:21], v[60:61], v[12:13], v[10:11] op_sel_hi:[0,1,1]
	v_bfe_u32 v12, v17, 16, 1
	v_bfe_u32 v13, v16, 16, 1
	v_add3_u32 v22, v16, v13, s97
	v_add3_u32 v23, v17, v12, s97
	v_bfe_u32 v12, v14, 16, 1
	v_bfe_u32 v13, v15, 16, 1
	v_bfe_u32 v24, v18, 16, 1
	v_bfe_u32 v25, v19, 16, 1
	v_bfe_u32 v10, v21, 16, 1
	v_bfe_u32 v11, v20, 16, 1
	v_add3_u32 v25, v19, v25, s97
	v_add3_u32 v24, v18, v24, s97
	v_add3_u32 v13, v15, v13, s97
	v_add3_u32 v12, v14, v12, s97
	v_add3_u32 v11, v20, v11, s97
	v_add3_u32 v10, v21, v10, s97
	v_lshrrev_b32_e32 v26, 16, v12
	v_lshrrev_b32_e32 v27, 16, v13
	v_lshrrev_b32_e32 v12, 16, v24
	v_lshrrev_b32_e32 v13, 16, v25
	v_and_or_b32 v13, v10, s27, v13
	v_and_or_b32 v12, v11, s27, v12
	v_and_or_b32 v11, v23, s27, v27
	v_and_or_b32 v10, v22, s27, v26
	global_store_dwordx4 v[86:87], v[10:13], off sc1
	s_nop 1
	v_pk_mul_f32 v[10:11], v[58:59], v[14:15] op_sel_hi:[0,1]
	s_waitcnt vmcnt(15)
	v_lshlrev_b32_e32 v13, 16, v7
	v_lshlrev_b32_e32 v12, 16, v6
	v_pk_fma_f32 v[10:11], v[56:57], v[12:13], v[10:11] op_sel_hi:[0,1,1]
	v_pk_mul_f32 v[12:13], v[58:59], v[16:17] op_sel_hi:[0,1]
	v_and_b32_e32 v7, 0xffff0000, v7
	v_and_b32_e32 v6, 0xffff0000, v6
	v_pk_fma_f32 v[12:13], v[56:57], v[6:7], v[12:13] op_sel_hi:[0,1,1]
	v_pk_mul_f32 v[6:7], v[58:59], v[18:19] op_sel_hi:[0,1]
	v_lshlrev_b32_e32 v15, 16, v9
	v_lshlrev_b32_e32 v14, 16, v8
	v_pk_fma_f32 v[14:15], v[56:57], v[14:15], v[6:7] op_sel_hi:[0,1,1]
	v_pk_mul_f32 v[6:7], v[58:59], v[20:21] op_sel_hi:[0,1]
	v_and_b32_e32 v9, 0xffff0000, v9
	v_and_b32_e32 v8, 0xffff0000, v8
	v_pk_fma_f32 v[16:17], v[56:57], v[8:9], v[6:7] op_sel_hi:[0,1,1]
	v_bfe_u32 v8, v13, 16, 1
	v_bfe_u32 v9, v12, 16, 1
	v_add3_u32 v18, v12, v9, s97
	v_add3_u32 v19, v13, v8, s97
	v_bfe_u32 v8, v10, 16, 1
	v_bfe_u32 v9, v11, 16, 1
	v_bfe_u32 v20, v14, 16, 1
	v_bfe_u32 v21, v15, 16, 1
	v_bfe_u32 v6, v17, 16, 1
	v_bfe_u32 v7, v16, 16, 1
	v_add3_u32 v21, v15, v21, s97
	v_add3_u32 v20, v14, v20, s97
	v_add3_u32 v9, v11, v9, s97
	v_add3_u32 v8, v10, v8, s97
	v_add3_u32 v7, v16, v7, s97
	v_add3_u32 v6, v17, v6, s97
	v_lshrrev_b32_e32 v22, 16, v8
	v_lshrrev_b32_e32 v23, 16, v9
	v_lshrrev_b32_e32 v8, 16, v20
	v_lshrrev_b32_e32 v9, 16, v21
	v_and_or_b32 v9, v6, s27, v9
	v_and_or_b32 v8, v7, s27, v8
	v_and_or_b32 v7, v19, s27, v23
	v_and_or_b32 v6, v18, s27, v22
	global_store_dwordx4 v[82:83], v[6:9], off sc1
	s_nop 1
	v_pk_mul_f32 v[6:7], v[54:55], v[10:11] op_sel_hi:[0,1]
	s_waitcnt vmcnt(15)
	v_lshlrev_b32_e32 v9, 16, v3
	v_lshlrev_b32_e32 v8, 16, v2
	v_pk_fma_f32 v[6:7], v[52:53], v[8:9], v[6:7] op_sel_hi:[0,1,1]
	v_pk_mul_f32 v[8:9], v[54:55], v[12:13] op_sel_hi:[0,1]
	v_and_b32_e32 v3, 0xffff0000, v3
	v_and_b32_e32 v2, 0xffff0000, v2
	v_pk_fma_f32 v[2:3], v[52:53], v[2:3], v[8:9] op_sel_hi:[0,1,1]
	v_pk_mul_f32 v[8:9], v[54:55], v[14:15] op_sel_hi:[0,1]
	v_lshlrev_b32_e32 v11, 16, v5
	v_lshlrev_b32_e32 v10, 16, v4
	v_pk_fma_f32 v[8:9], v[52:53], v[10:11], v[8:9] op_sel_hi:[0,1,1]
	v_pk_mul_f32 v[10:11], v[54:55], v[16:17] op_sel_hi:[0,1]
	v_and_b32_e32 v5, 0xffff0000, v5
	v_and_b32_e32 v4, 0xffff0000, v4
	v_pk_fma_f32 v[4:5], v[52:53], v[4:5], v[10:11] op_sel_hi:[0,1,1]
	v_bfe_u32 v10, v5, 16, 1
	v_bfe_u32 v11, v4, 16, 1
	v_bfe_u32 v12, v3, 16, 1
	v_bfe_u32 v13, v2, 16, 1
	v_add3_u32 v5, v5, v10, s97
	v_bfe_u32 v10, v6, 16, 1
	v_add3_u32 v2, v2, v13, s97
	v_add3_u32 v3, v3, v12, s97
	v_add3_u32 v4, v4, v11, s97
	v_bfe_u32 v11, v7, 16, 1
	v_bfe_u32 v12, v8, 16, 1
	v_bfe_u32 v13, v9, 16, 1
	v_add3_u32 v6, v6, v10, s97
	v_add3_u32 v9, v9, v13, s97
	v_add3_u32 v8, v8, v12, s97
	v_add3_u32 v7, v7, v11, s97
	v_lshrrev_b32_e32 v6, 16, v6
	v_lshrrev_b32_e32 v7, 16, v7
	v_lshrrev_b32_e32 v8, 16, v8
	v_lshrrev_b32_e32 v9, 16, v9
	v_and_or_b32 v2, v2, s27, v6
	v_add_co_u32_e32 v6, vcc, 0x78000, v68
	v_and_or_b32 v5, v5, s27, v9
	v_and_or_b32 v4, v4, s27, v8
	v_and_or_b32 v3, v3, s27, v7
	v_addc_co_u32_e32 v7, vcc, 0, v69, vcc
	global_store_dwordx4 v[6:7], v[2:5], off sc1
	s_branch .LBB0_534

.LBB0_623:
	s_or_b64 exec, exec, s[0:1]
	s_waitcnt lgkmcnt(0)
	ds_read_b128 v[66:69], v144 offset:128
	ds_read_b128 v[70:73], v144 offset:160
	s_lshl_b32 s0, s93, 16
	s_add_i32 s0, s0, 0
	s_lshl_b32 s1, s61, 14
	s_waitcnt lgkmcnt(1)
	v_mul_f32_e32 v74, v2, v66
	v_mul_f32_e32 v18, v18, v66
	v_mul_f32_e32 v34, v34, v66
	v_mul_f32_e32 v50, v50, v66
	v_mul_f32_e32 v66, v3, v67
	v_mul_f32_e32 v19, v19, v67
	v_mul_f32_e32 v35, v35, v67
	v_mul_f32_e32 v51, v51, v67
	v_mul_f32_e32 v67, v4, v68
	v_mul_f32_e32 v20, v20, v68
	v_mul_f32_e32 v36, v36, v68
	v_mul_f32_e32 v52, v52, v68
	v_mul_f32_e32 v68, v5, v69
	ds_read_b128 v[2:5], v144 offset:192
	s_add_i32 s0, s0, s1
	s_waitcnt lgkmcnt(1)
	v_mul_f32_e32 v6, v6, v70
	v_mul_f32_e32 v22, v22, v70
	v_mul_f32_e32 v7, v7, v71
	s_waitcnt lgkmcnt(0)
	v_mul_f32_e32 v10, v10, v2
	v_mul_f32_e32 v26, v26, v2
	v_mul_f32_e32 v42, v42, v2
	v_mul_f32_e32 v58, v58, v2
	v_mul_f32_e32 v11, v11, v3
	v_mul_f32_e32 v27, v27, v3
	v_mul_f32_e32 v43, v43, v3
	v_mul_f32_e32 v59, v59, v3
	v_mul_f32_e32 v12, v12, v4
	v_mul_f32_e32 v28, v28, v4
	v_mul_f32_e32 v44, v44, v4
	v_mul_f32_e32 v60, v60, v4
	v_mul_f32_e32 v13, v13, v5
	v_mul_f32_e32 v29, v29, v5
	v_mul_f32_e32 v45, v45, v5
	v_mul_f32_e32 v61, v61, v5
	ds_read_b128 v[2:5], v144 offset:224
	s_waitcnt lgkmcnt(0)
	s_barrier
	v_mul_f32_e32 v21, v21, v69
	v_mul_f32_e32 v14, v14, v2
	v_mul_f32_e32 v30, v30, v2
	v_mul_f32_e32 v46, v46, v2
	v_mul_f32_e32 v2, v62, v2
	v_mul_f32_e32 v15, v15, v3
	v_mul_f32_e32 v31, v31, v3
	v_mul_f32_e32 v47, v47, v3
	v_mul_f32_e32 v3, v63, v3
	v_lshlrev_b32_e32 v62, 11, v136
	v_lshlrev_b32_e32 v63, 2, v135
	v_add3_u32 v62, s0, v62, v63
	ds_write2_b32 v62, v74, v18 offset1:32
	ds_write2_b32 v62, v66, v19 offset0:128 offset1:160
	v_add_u32_e32 v18, 0x400, v62
	v_add_u32_e32 v19, 0x1000, v62
	v_mul_f32_e32 v23, v23, v71
	v_mul_f32_e32 v8, v8, v72
	v_mul_f32_e32 v24, v24, v72
	v_mul_f32_e32 v9, v9, v73
	ds_write2_b32 v18, v67, v20 offset1:32
	ds_write2_b32 v18, v68, v21 offset0:128 offset1:160
	ds_write2_b32 v19, v6, v22 offset1:32
	ds_write2_b32 v19, v7, v23 offset0:128 offset1:160
	v_add_u32_e32 v6, 0x1400, v62
	v_add_u32_e32 v7, 0x2000, v62
	v_mul_f32_e32 v25, v25, v73
	v_mul_f32_e32 v16, v16, v4
	v_mul_f32_e32 v32, v32, v4
	ds_write2_b32 v6, v8, v24 offset1:32
	ds_write2_b32 v6, v9, v25 offset0:128 offset1:160
	ds_write2_b32 v7, v10, v26 offset1:32
	ds_write2_b32 v7, v11, v27 offset0:128 offset1:160
	v_add_u32_e32 v8, 0x2400, v62
	v_add_u32_e32 v9, 0x3000, v62
	v_add_u32_e32 v10, 0x3400, v62
	v_mul_f32_e32 v37, v37, v69
	v_mul_f32_e32 v53, v53, v69
	v_mul_f32_e32 v38, v38, v70
	v_mul_f32_e32 v54, v54, v70
	v_mul_f32_e32 v39, v39, v71
	v_mul_f32_e32 v55, v55, v71
	v_mul_f32_e32 v40, v40, v72
	v_mul_f32_e32 v56, v56, v72
	v_mul_f32_e32 v41, v41, v73
	v_mul_f32_e32 v57, v57, v73
	v_mul_f32_e32 v48, v48, v4
	v_mul_f32_e32 v4, v64, v4
	v_mul_f32_e32 v17, v17, v5
	v_mul_f32_e32 v33, v33, v5
	v_mul_f32_e32 v49, v49, v5
	v_mul_f32_e32 v5, v65, v5
	ds_write2_b32 v8, v12, v28 offset1:32
	ds_write2_b32 v8, v13, v29 offset0:128 offset1:160
	ds_write2_b32 v9, v14, v30 offset1:32
	ds_write2_b32 v9, v15, v31 offset0:128 offset1:160
	ds_write2_b32 v10, v16, v32 offset1:32
	ds_write2_b32 v10, v17, v33 offset0:128 offset1:160
	ds_write2_b32 v62, v34, v50 offset0:64 offset1:96
	ds_write2_b32 v62, v35, v51 offset0:192 offset1:224
	ds_write2_b32 v18, v36, v52 offset0:64 offset1:96
	ds_write2_b32 v18, v37, v53 offset0:192 offset1:224
	ds_write2_b32 v19, v38, v54 offset0:64 offset1:96
	ds_write2_b32 v19, v39, v55 offset0:192 offset1:224
	ds_write2_b32 v6, v40, v56 offset0:64 offset1:96
	ds_write2_b32 v6, v41, v57 offset0:192 offset1:224
	ds_write2_b32 v7, v42, v58 offset0:64 offset1:96
	ds_write2_b32 v7, v43, v59 offset0:192 offset1:224
	ds_write2_b32 v8, v44, v60 offset0:64 offset1:96
	ds_write2_b32 v8, v45, v61 offset0:192 offset1:224
	ds_write2_b32 v9, v46, v2 offset0:64 offset1:96
	ds_write2_b32 v9, v47, v3 offset0:192 offset1:224
	ds_write2_b32 v10, v48, v4 offset0:64 offset1:96
	ds_write2_b32 v10, v49, v5 offset0:192 offset1:224
	v_add_u32_e32 v34, s60, v170
	v_mov_b64_e32 v[2:3], s[28:29]
	v_mad_i64_i32 v[4:5], s[0:1], v34, s36, v[2:3]
	v_lshl_add_u64 v[4:5], v[4:5], 0, s[82:83]
	v_lshl_add_u64 v[4:5], v[4:5], 0, v[178:179]
	global_load_dwordx4 v[14:17], v[4:5], off offset:3072
	v_add_u32_e32 v4, 0x200, v168
	v_ashrrev_i32_e32 v40, 4, v4
	v_add_u32_e32 v32, s60, v40
	v_mad_i64_i32 v[4:5], s[0:1], v32, s36, v[2:3]
	v_lshl_add_u64 v[4:5], v[4:5], 0, s[82:83]
	v_lshl_add_u64 v[4:5], v[4:5], 0, v[178:179]
	global_load_dwordx4 v[10:13], v[4:5], off offset:3072
	v_add_u32_e32 v4, 0x400, v168
	v_ashrrev_i32_e32 v39, 4, v4
	v_add_u32_e32 v30, s60, v39
	v_mad_i64_i32 v[4:5], s[0:1], v30, s36, v[2:3]
	v_lshl_add_u64 v[4:5], v[4:5], 0, s[82:83]
	v_lshl_add_u64 v[4:5], v[4:5], 0, v[178:179]
	global_load_dwordx4 v[6:9], v[4:5], off offset:3072
	v_add_u32_e32 v4, 0x600, v168
	v_ashrrev_i32_e32 v36, 4, v4
	v_add_u32_e32 v26, s60, v36
	v_mad_i64_i32 v[2:3], s[0:1], v26, s36, v[2:3]
	v_lshlrev_b32_e32 v18, 2, v169
	v_lshl_add_u64 v[2:3], v[2:3], 0, s[82:83]
	v_add_u32_e32 v38, 0, v18
	v_add_u32_e32 v37, s92, v18
	v_lshlrev_b32_e32 v22, 2, v134
	v_lshl_add_u64 v[2:3], v[2:3], 0, v[178:179]
	v_add_u32_e32 v18, v38, v22
	v_add_u32_e32 v22, v37, v22
	global_load_dwordx4 v[2:5], v[2:3], off offset:3072
	s_waitcnt lgkmcnt(0)
	s_barrier
	ds_read_b128 v[42:45], v18
	ds_read_b128 v[18:21], v18 offset:16
	ds_read_b128 v[46:49], v22
	ds_read_b128 v[22:25], v22 offset:16
	v_ashrrev_i32_e32 v35, 31, v34
	v_mov_b32_e32 v155, v179
	v_lshl_add_u64 v[28:29], s[22:23], 0, v[154:155]
	s_waitcnt lgkmcnt(1)
	v_pk_add_f32 v[42:43], v[42:43], v[46:47]
	v_pk_add_f32 v[44:45], v[44:45], v[48:49]
	s_waitcnt lgkmcnt(0)
	v_pk_add_f32 v[18:19], v[18:19], v[22:23]
	v_pk_add_f32 v[20:21], v[20:21], v[24:25]
	v_ashrrev_i32_e32 v33, 31, v32
	v_ashrrev_i32_e32 v31, 31, v30
	v_ashrrev_i32_e32 v27, 31, v26
	s_add_i32 s31, s31, s3
	s_cmpk_lt_i32 s31, 0x200
	s_waitcnt vmcnt(3)
	v_lshlrev_b32_e32 v41, 16, v14
	v_and_b32_e32 v14, 0xffff0000, v14
	v_mul_f32_e32 v41, 0xbfb8aa3b, v41
	v_mul_f32_e32 v14, 0xbfb8aa3b, v14
	v_exp_f32_e32 v50, v41
	v_exp_f32_e32 v51, v14
	s_nop 0
	v_pk_add_f32 v[50:51], v[50:51], 1.0 op_sel_hi:[1,0]
	s_nop 0
	v_div_scale_f32 v14, s[0:1], v51, v51, 1.0
	v_rcp_f32_e32 v41, v14
	s_nop 0
	v_fma_f32 v52, -v14, v41, 1.0
	v_fmac_f32_e32 v41, v52, v41
	v_div_scale_f32 v52, vcc, 1.0, v51, 1.0
	v_mul_f32_e32 v53, v52, v41
	v_fma_f32 v54, -v14, v53, v52
	v_fmac_f32_e32 v53, v54, v41
	v_fma_f32 v14, -v14, v53, v52
	v_div_fmas_f32 v14, v14, v41, v53
	v_div_fixup_f32 v51, v14, v51, 1.0
	v_div_scale_f32 v14, s[0:1], v50, v50, 1.0
	v_rcp_f32_e32 v41, v14
	s_nop 0
	v_fma_f32 v52, -v14, v41, 1.0
	v_fmac_f32_e32 v41, v52, v41
	v_div_scale_f32 v52, vcc, 1.0, v50, 1.0
	v_mul_f32_e32 v53, v52, v41
	v_fma_f32 v54, -v14, v53, v52
	v_fmac_f32_e32 v53, v54, v41
	v_fma_f32 v14, -v14, v53, v52
	v_div_fmas_f32 v14, v14, v41, v53
	v_div_fixup_f32 v50, v14, v50, 1.0
	v_lshlrev_b32_e32 v41, 16, v15
	v_and_b32_e32 v15, 0xffff0000, v15
	v_pk_mul_f32 v[42:43], v[50:51], v[42:43]
	v_mul_f32_e32 v41, 0xbfb8aa3b, v41
	v_mul_f32_e32 v15, 0xbfb8aa3b, v15
	v_cvt_pk_bf16_f32 v14, v42, v43
	v_exp_f32_e32 v42, v41
	v_exp_f32_e32 v43, v15
	s_nop 0
	v_pk_add_f32 v[42:43], v[42:43], 1.0 op_sel_hi:[1,0]
	s_nop 0
	v_div_scale_f32 v15, s[0:1], v43, v43, 1.0
	v_rcp_f32_e32 v41, v15
	s_nop 0
	v_fma_f32 v46, -v15, v41, 1.0
	v_fmac_f32_e32 v41, v46, v41
	v_div_scale_f32 v46, vcc, 1.0, v43, 1.0
	v_mul_f32_e32 v47, v46, v41
	v_fma_f32 v48, -v15, v47, v46
	v_fmac_f32_e32 v47, v48, v41
	v_fma_f32 v15, -v15, v47, v46
	v_div_fmas_f32 v15, v15, v41, v47
	v_div_fixup_f32 v43, v15, v43, 1.0
	v_div_scale_f32 v15, s[0:1], v42, v42, 1.0
	v_rcp_f32_e32 v41, v15
	s_nop 0
	v_fma_f32 v46, -v15, v41, 1.0
	v_fmac_f32_e32 v41, v46, v41
	v_div_scale_f32 v46, vcc, 1.0, v42, 1.0
	v_mul_f32_e32 v47, v46, v41
	v_fma_f32 v48, -v15, v47, v46
	v_fmac_f32_e32 v47, v48, v41
	v_fma_f32 v15, -v15, v47, v46
	v_div_fmas_f32 v15, v15, v41, v47
	v_div_fixup_f32 v42, v15, v42, 1.0
	v_lshlrev_b32_e32 v41, 16, v16
	v_and_b32_e32 v16, 0xffff0000, v16
	v_pk_mul_f32 v[42:43], v[42:43], v[44:45]
	v_mul_f32_e32 v41, 0xbfb8aa3b, v41
	v_mul_f32_e32 v16, 0xbfb8aa3b, v16
	v_cvt_pk_bf16_f32 v15, v42, v43
	v_exp_f32_e32 v42, v41
	v_exp_f32_e32 v43, v16
	s_nop 0
	v_pk_add_f32 v[42:43], v[42:43], 1.0 op_sel_hi:[1,0]
	s_nop 0
	v_div_scale_f32 v16, s[0:1], v43, v43, 1.0
	v_rcp_f32_e32 v41, v16
	s_nop 0
	v_fma_f32 v44, -v16, v41, 1.0
	v_fmac_f32_e32 v41, v44, v41
	v_div_scale_f32 v44, vcc, 1.0, v43, 1.0
	v_mul_f32_e32 v45, v44, v41
	v_fma_f32 v46, -v16, v45, v44
	v_fmac_f32_e32 v45, v46, v41
	v_fma_f32 v16, -v16, v45, v44
	v_div_fmas_f32 v16, v16, v41, v45
	v_div_fixup_f32 v43, v16, v43, 1.0
	v_div_scale_f32 v16, s[0:1], v42, v42, 1.0
	v_rcp_f32_e32 v41, v16
	s_nop 0
	v_fma_f32 v44, -v16, v41, 1.0
	v_fmac_f32_e32 v41, v44, v41
	v_div_scale_f32 v44, vcc, 1.0, v42, 1.0
	v_mul_f32_e32 v45, v44, v41
	v_fma_f32 v46, -v16, v45, v44
	v_fmac_f32_e32 v45, v46, v41
	v_fma_f32 v16, -v16, v45, v44
	v_div_fmas_f32 v16, v16, v41, v45
	v_div_fixup_f32 v42, v16, v42, 1.0
	v_pk_mul_f32 v[18:19], v[42:43], v[18:19]
	s_nop 0
	v_cvt_pk_bf16_f32 v16, v18, v19
	v_lshlrev_b32_e32 v18, 16, v17
	v_and_b32_e32 v17, 0xffff0000, v17
	v_mul_f32_e32 v18, 0xbfb8aa3b, v18
	v_mul_f32_e32 v17, 0xbfb8aa3b, v17
	v_exp_f32_e32 v18, v18
	v_exp_f32_e32 v19, v17
	s_nop 0
	v_pk_add_f32 v[18:19], v[18:19], 1.0 op_sel_hi:[1,0]
	s_nop 0
	v_div_scale_f32 v17, s[0:1], v19, v19, 1.0
	v_rcp_f32_e32 v22, v17
	s_nop 0
	v_fma_f32 v23, -v17, v22, 1.0
	v_fmac_f32_e32 v22, v23, v22
	v_div_scale_f32 v23, vcc, 1.0, v19, 1.0
	v_mul_f32_e32 v24, v23, v22
	v_fma_f32 v25, -v17, v24, v23
	v_fmac_f32_e32 v24, v25, v22
	v_fma_f32 v17, -v17, v24, v23
	v_div_fmas_f32 v17, v17, v22, v24
	v_div_fixup_f32 v19, v17, v19, 1.0
	v_div_scale_f32 v17, s[0:1], v18, v18, 1.0
	v_rcp_f32_e32 v22, v17
	s_nop 0
	v_fma_f32 v23, -v17, v22, 1.0
	v_fmac_f32_e32 v22, v23, v22
	v_div_scale_f32 v23, vcc, 1.0, v18, 1.0
	v_mul_f32_e32 v24, v23, v22
	v_fma_f32 v25, -v17, v24, v23
	v_fmac_f32_e32 v24, v25, v22
	v_fma_f32 v17, -v17, v24, v23
	v_div_fmas_f32 v17, v17, v22, v24
	v_div_fixup_f32 v18, v17, v18, 1.0
	v_pk_mul_f32 v[18:19], v[18:19], v[20:21]
	s_nop 0
	v_cvt_pk_bf16_f32 v17, v18, v19
	v_lshlrev_b64 v[18:19], 11, v[34:35]
	s_waitcnt vmcnt(2)
	v_lshlrev_b32_e32 v34, 16, v10
	v_and_b32_e32 v10, 0xffff0000, v10
	v_mul_f32_e32 v34, 0xbfb8aa3b, v34
	v_mul_f32_e32 v10, 0xbfb8aa3b, v10
	v_exp_f32_e32 v34, v34
	v_exp_f32_e32 v35, v10
	v_lshl_add_u64 v[18:19], v[28:29], 0, v[18:19]
	global_store_dwordx4 v[18:19], v[14:17], off sc1
	v_lshlrev_b32_e32 v18, 9, v40
	v_pk_add_f32 v[34:35], v[34:35], 1.0 op_sel_hi:[1,0]
	v_add_u32_e32 v14, v38, v18
	v_div_scale_f32 v10, s[0:1], v35, v35, 1.0
	v_rcp_f32_e32 v44, v10
	v_add_u32_e32 v18, v37, v18
	ds_read_b128 v[22:25], v14
	ds_read_b128 v[14:17], v14 offset:16
	ds_read_b128 v[40:43], v18
	ds_read_b128 v[18:21], v18 offset:16
	v_fma_f32 v45, -v10, v44, 1.0
	v_fmac_f32_e32 v44, v45, v44
	v_div_scale_f32 v45, vcc, 1.0, v35, 1.0
	v_mul_f32_e32 v46, v45, v44
	v_fma_f32 v47, -v10, v46, v45
	v_fmac_f32_e32 v46, v47, v44
	v_fma_f32 v10, -v10, v46, v45
	v_div_fmas_f32 v10, v10, v44, v46
	v_div_fixup_f32 v35, v10, v35, 1.0
	v_div_scale_f32 v10, s[0:1], v34, v34, 1.0
	v_rcp_f32_e32 v44, v10
	s_waitcnt lgkmcnt(1)
	v_pk_add_f32 v[22:23], v[22:23], v[40:41]
	v_pk_add_f32 v[24:25], v[24:25], v[42:43]
	s_waitcnt lgkmcnt(0)
	v_pk_add_f32 v[14:15], v[14:15], v[18:19]
	v_fma_f32 v45, -v10, v44, 1.0
	v_fmac_f32_e32 v44, v45, v44
	v_div_scale_f32 v45, vcc, 1.0, v34, 1.0
	v_mul_f32_e32 v46, v45, v44
	v_fma_f32 v47, -v10, v46, v45
	v_fmac_f32_e32 v46, v47, v44
	v_fma_f32 v10, -v10, v46, v45
	v_div_fmas_f32 v10, v10, v44, v46
	v_div_fixup_f32 v34, v10, v34, 1.0
	v_pk_mul_f32 v[22:23], v[34:35], v[22:23]
	v_pk_add_f32 v[16:17], v[16:17], v[20:21]
	v_cvt_pk_bf16_f32 v10, v22, v23
	v_lshlrev_b32_e32 v22, 16, v11
	v_and_b32_e32 v11, 0xffff0000, v11
	v_mul_f32_e32 v22, 0xbfb8aa3b, v22
	v_mul_f32_e32 v11, 0xbfb8aa3b, v11
	v_exp_f32_e32 v22, v22
	v_exp_f32_e32 v23, v11
	s_nop 0
	v_pk_add_f32 v[22:23], v[22:23], 1.0 op_sel_hi:[1,0]
	s_nop 0
	v_div_scale_f32 v11, s[0:1], v23, v23, 1.0
	v_rcp_f32_e32 v34, v11
	s_nop 0
	v_fma_f32 v35, -v11, v34, 1.0
	v_fmac_f32_e32 v34, v35, v34
	v_div_scale_f32 v35, vcc, 1.0, v23, 1.0
	v_mul_f32_e32 v40, v35, v34
	v_fma_f32 v41, -v11, v40, v35
	v_fmac_f32_e32 v40, v41, v34
	v_fma_f32 v11, -v11, v40, v35
	v_div_fmas_f32 v11, v11, v34, v40
	v_div_fixup_f32 v23, v11, v23, 1.0
	v_div_scale_f32 v11, s[0:1], v22, v22, 1.0
	v_rcp_f32_e32 v34, v11
	s_nop 0
	v_fma_f32 v35, -v11, v34, 1.0
	v_fmac_f32_e32 v34, v35, v34
	v_div_scale_f32 v35, vcc, 1.0, v22, 1.0
	v_mul_f32_e32 v40, v35, v34
	v_fma_f32 v41, -v11, v40, v35
	v_fmac_f32_e32 v40, v41, v34
	v_fma_f32 v11, -v11, v40, v35
	v_div_fmas_f32 v11, v11, v34, v40
	v_div_fixup_f32 v22, v11, v22, 1.0
	v_pk_mul_f32 v[22:23], v[22:23], v[24:25]
	s_nop 0
	v_cvt_pk_bf16_f32 v11, v22, v23
	v_lshlrev_b32_e32 v22, 16, v12
	v_and_b32_e32 v12, 0xffff0000, v12
	v_mul_f32_e32 v22, 0xbfb8aa3b, v22
	v_mul_f32_e32 v12, 0xbfb8aa3b, v12
	v_exp_f32_e32 v22, v22
	v_exp_f32_e32 v23, v12
	s_nop 0
	v_pk_add_f32 v[22:23], v[22:23], 1.0 op_sel_hi:[1,0]
	s_nop 0
	v_div_scale_f32 v12, s[0:1], v23, v23, 1.0
	v_rcp_f32_e32 v24, v12
	s_nop 0
	v_fma_f32 v25, -v12, v24, 1.0
	v_fmac_f32_e32 v24, v25, v24
	v_div_scale_f32 v25, vcc, 1.0, v23, 1.0
	v_mul_f32_e32 v34, v25, v24
	v_fma_f32 v35, -v12, v34, v25
	v_fmac_f32_e32 v34, v35, v24
	v_fma_f32 v12, -v12, v34, v25
	v_div_fmas_f32 v12, v12, v24, v34
	v_div_fixup_f32 v23, v12, v23, 1.0
	v_div_scale_f32 v12, s[0:1], v22, v22, 1.0
	v_rcp_f32_e32 v24, v12
	s_nop 0
	v_fma_f32 v25, -v12, v24, 1.0
	v_fmac_f32_e32 v24, v25, v24
	v_div_scale_f32 v25, vcc, 1.0, v22, 1.0
	v_mul_f32_e32 v34, v25, v24
	v_fma_f32 v35, -v12, v34, v25
	v_fmac_f32_e32 v34, v35, v24
	v_fma_f32 v12, -v12, v34, v25
	v_div_fmas_f32 v12, v12, v24, v34
	v_div_fixup_f32 v22, v12, v22, 1.0
	v_pk_mul_f32 v[14:15], v[22:23], v[14:15]
	s_nop 0
	v_cvt_pk_bf16_f32 v12, v14, v15
	v_lshlrev_b32_e32 v14, 16, v13
	v_and_b32_e32 v13, 0xffff0000, v13
	v_mul_f32_e32 v14, 0xbfb8aa3b, v14
	v_mul_f32_e32 v13, 0xbfb8aa3b, v13
	v_exp_f32_e32 v14, v14
	v_exp_f32_e32 v15, v13
	s_nop 0
	v_pk_add_f32 v[14:15], v[14:15], 1.0 op_sel_hi:[1,0]
	s_nop 0
	v_div_scale_f32 v13, s[0:1], v15, v15, 1.0
	v_rcp_f32_e32 v18, v13
	s_nop 0
	v_fma_f32 v19, -v13, v18, 1.0
	v_fmac_f32_e32 v18, v19, v18
	v_div_scale_f32 v19, vcc, 1.0, v15, 1.0
	v_mul_f32_e32 v20, v19, v18
	v_fma_f32 v21, -v13, v20, v19
	v_fmac_f32_e32 v20, v21, v18
	v_fma_f32 v13, -v13, v20, v19
	v_div_fmas_f32 v13, v13, v18, v20
	v_div_fixup_f32 v15, v13, v15, 1.0
	v_div_scale_f32 v13, s[0:1], v14, v14, 1.0
	v_rcp_f32_e32 v18, v13
	s_nop 0
	v_fma_f32 v19, -v13, v18, 1.0
	v_fmac_f32_e32 v18, v19, v18
	v_div_scale_f32 v19, vcc, 1.0, v14, 1.0
	v_mul_f32_e32 v20, v19, v18
	v_fma_f32 v21, -v13, v20, v19
	v_fmac_f32_e32 v20, v21, v18
	v_fma_f32 v13, -v13, v20, v19
	v_div_fmas_f32 v13, v13, v18, v20
	v_div_fixup_f32 v14, v13, v14, 1.0
	v_pk_mul_f32 v[14:15], v[14:15], v[16:17]
	s_nop 0
	v_cvt_pk_bf16_f32 v13, v14, v15
	v_lshlrev_b64 v[14:15], 11, v[32:33]
	s_waitcnt vmcnt(2)
	v_lshlrev_b32_e32 v32, 16, v6
	v_and_b32_e32 v6, 0xffff0000, v6
	v_mul_f32_e32 v32, 0xbfb8aa3b, v32
	v_mul_f32_e32 v6, 0xbfb8aa3b, v6
	v_exp_f32_e32 v32, v32
	v_exp_f32_e32 v33, v6
	v_lshl_add_u64 v[14:15], v[28:29], 0, v[14:15]
	global_store_dwordx4 v[14:15], v[10:13], off sc1
	v_lshlrev_b32_e32 v14, 9, v39
	v_pk_add_f32 v[32:33], v[32:33], 1.0 op_sel_hi:[1,0]
	v_add_u32_e32 v10, v38, v14
	v_div_scale_f32 v6, s[0:1], v33, v33, 1.0
	v_rcp_f32_e32 v34, v6
	v_add_u32_e32 v14, v37, v14
	ds_read_b128 v[18:21], v10
	ds_read_b128 v[10:13], v10 offset:16
	ds_read_b128 v[22:25], v14
	ds_read_b128 v[14:17], v14 offset:16
	v_fma_f32 v35, -v6, v34, 1.0
	v_fmac_f32_e32 v34, v35, v34
	v_div_scale_f32 v35, vcc, 1.0, v33, 1.0
	v_mul_f32_e32 v39, v35, v34
	v_fma_f32 v40, -v6, v39, v35
	v_fmac_f32_e32 v39, v40, v34
	v_fma_f32 v6, -v6, v39, v35
	v_div_fmas_f32 v6, v6, v34, v39
	v_div_fixup_f32 v33, v6, v33, 1.0
	v_div_scale_f32 v6, s[0:1], v32, v32, 1.0
	v_rcp_f32_e32 v34, v6
	s_waitcnt lgkmcnt(1)
	v_pk_add_f32 v[18:19], v[18:19], v[22:23]
	v_pk_add_f32 v[20:21], v[20:21], v[24:25]
	s_waitcnt lgkmcnt(0)
	v_pk_add_f32 v[10:11], v[10:11], v[14:15]
	v_fma_f32 v35, -v6, v34, 1.0
	v_fmac_f32_e32 v34, v35, v34
	v_div_scale_f32 v35, vcc, 1.0, v32, 1.0
	v_mul_f32_e32 v39, v35, v34
	v_fma_f32 v40, -v6, v39, v35
	v_fmac_f32_e32 v39, v40, v34
	v_fma_f32 v6, -v6, v39, v35
	v_div_fmas_f32 v6, v6, v34, v39
	v_div_fixup_f32 v32, v6, v32, 1.0
	v_pk_mul_f32 v[18:19], v[32:33], v[18:19]
	v_pk_add_f32 v[12:13], v[12:13], v[16:17]
	v_cvt_pk_bf16_f32 v6, v18, v19
	v_lshlrev_b32_e32 v18, 16, v7
	v_and_b32_e32 v7, 0xffff0000, v7
	v_mul_f32_e32 v18, 0xbfb8aa3b, v18
	v_mul_f32_e32 v7, 0xbfb8aa3b, v7
	v_exp_f32_e32 v18, v18
	v_exp_f32_e32 v19, v7
	s_nop 0
	v_pk_add_f32 v[18:19], v[18:19], 1.0 op_sel_hi:[1,0]
	s_nop 0
	v_div_scale_f32 v7, s[0:1], v19, v19, 1.0
	v_rcp_f32_e32 v22, v7
	s_nop 0
	v_fma_f32 v23, -v7, v22, 1.0
	v_fmac_f32_e32 v22, v23, v22
	v_div_scale_f32 v23, vcc, 1.0, v19, 1.0
	v_mul_f32_e32 v24, v23, v22
	v_fma_f32 v25, -v7, v24, v23
	v_fmac_f32_e32 v24, v25, v22
	v_fma_f32 v7, -v7, v24, v23
	v_div_fmas_f32 v7, v7, v22, v24
	v_div_fixup_f32 v19, v7, v19, 1.0
	v_div_scale_f32 v7, s[0:1], v18, v18, 1.0
	v_rcp_f32_e32 v22, v7
	s_nop 0
	v_fma_f32 v23, -v7, v22, 1.0
	v_fmac_f32_e32 v22, v23, v22
	v_div_scale_f32 v23, vcc, 1.0, v18, 1.0
	v_mul_f32_e32 v24, v23, v22
	v_fma_f32 v25, -v7, v24, v23
	v_fmac_f32_e32 v24, v25, v22
	v_fma_f32 v7, -v7, v24, v23
	v_div_fmas_f32 v7, v7, v22, v24
	v_div_fixup_f32 v18, v7, v18, 1.0
	v_pk_mul_f32 v[18:19], v[18:19], v[20:21]
	s_nop 0
	v_cvt_pk_bf16_f32 v7, v18, v19
	v_lshlrev_b32_e32 v18, 16, v8
	v_and_b32_e32 v8, 0xffff0000, v8
	v_mul_f32_e32 v18, 0xbfb8aa3b, v18
	v_mul_f32_e32 v8, 0xbfb8aa3b, v8
	v_exp_f32_e32 v18, v18
	v_exp_f32_e32 v19, v8
	s_nop 0
	v_pk_add_f32 v[18:19], v[18:19], 1.0 op_sel_hi:[1,0]
	s_nop 0
	v_div_scale_f32 v8, s[0:1], v19, v19, 1.0
	v_rcp_f32_e32 v20, v8
	s_nop 0
	v_fma_f32 v21, -v8, v20, 1.0
	v_fmac_f32_e32 v20, v21, v20
	v_div_scale_f32 v21, vcc, 1.0, v19, 1.0
	v_mul_f32_e32 v22, v21, v20
	v_fma_f32 v23, -v8, v22, v21
	v_fmac_f32_e32 v22, v23, v20
	v_fma_f32 v8, -v8, v22, v21
	v_div_fmas_f32 v8, v8, v20, v22
	v_div_fixup_f32 v19, v8, v19, 1.0
	v_div_scale_f32 v8, s[0:1], v18, v18, 1.0
	v_rcp_f32_e32 v20, v8
	s_nop 0
	v_fma_f32 v21, -v8, v20, 1.0
	v_fmac_f32_e32 v20, v21, v20
	v_div_scale_f32 v21, vcc, 1.0, v18, 1.0
	v_mul_f32_e32 v22, v21, v20
	v_fma_f32 v23, -v8, v22, v21
	v_fmac_f32_e32 v22, v23, v20
	v_fma_f32 v8, -v8, v22, v21
	v_div_fmas_f32 v8, v8, v20, v22
	v_div_fixup_f32 v18, v8, v18, 1.0
	v_pk_mul_f32 v[10:11], v[18:19], v[10:11]
	s_waitcnt vmcnt(2)
	v_lshlrev_b32_e32 v22, 16, v2
	v_cvt_pk_bf16_f32 v8, v10, v11
	v_lshlrev_b32_e32 v10, 16, v9
	v_and_b32_e32 v9, 0xffff0000, v9
	v_mul_f32_e32 v10, 0xbfb8aa3b, v10
	v_mul_f32_e32 v9, 0xbfb8aa3b, v9
	v_exp_f32_e32 v10, v10
	v_exp_f32_e32 v11, v9
	v_and_b32_e32 v2, 0xffff0000, v2
	v_mul_f32_e32 v22, 0xbfb8aa3b, v22
	v_mul_f32_e32 v2, 0xbfb8aa3b, v2
	v_pk_add_f32 v[10:11], v[10:11], 1.0 op_sel_hi:[1,0]
	v_exp_f32_e32 v22, v22
	v_div_scale_f32 v9, s[0:1], v11, v11, 1.0
	v_rcp_f32_e32 v14, v9
	v_exp_f32_e32 v23, v2
	v_fma_f32 v15, -v9, v14, 1.0
	v_fmac_f32_e32 v14, v15, v14
	v_div_scale_f32 v15, vcc, 1.0, v11, 1.0
	v_mul_f32_e32 v16, v15, v14
	v_fma_f32 v17, -v9, v16, v15
	v_fmac_f32_e32 v16, v17, v14
	v_fma_f32 v9, -v9, v16, v15
	v_div_fmas_f32 v9, v9, v14, v16
	v_div_fixup_f32 v11, v9, v11, 1.0
	v_div_scale_f32 v9, s[0:1], v10, v10, 1.0
	v_rcp_f32_e32 v14, v9
	v_pk_add_f32 v[22:23], v[22:23], 1.0 op_sel_hi:[1,0]
	v_fma_f32 v15, -v9, v14, 1.0
	v_fmac_f32_e32 v14, v15, v14
	v_div_scale_f32 v15, vcc, 1.0, v10, 1.0
	v_mul_f32_e32 v16, v15, v14
	v_div_scale_f32 v2, s[0:1], v23, v23, 1.0
	v_fma_f32 v17, -v9, v16, v15
	v_rcp_f32_e32 v24, v2
	v_fmac_f32_e32 v16, v17, v14
	v_fma_f32 v9, -v9, v16, v15
	v_div_fmas_f32 v9, v9, v14, v16
	v_div_fixup_f32 v10, v9, v10, 1.0
	v_fma_f32 v25, -v2, v24, 1.0
	v_pk_mul_f32 v[10:11], v[10:11], v[12:13]
	v_fmac_f32_e32 v24, v25, v24
	v_div_scale_f32 v25, vcc, 1.0, v23, 1.0
	v_cvt_pk_bf16_f32 v9, v10, v11
	v_lshlrev_b64 v[10:11], 11, v[30:31]
	v_mul_f32_e32 v30, v25, v24
	v_fma_f32 v31, -v2, v30, v25
	v_fmac_f32_e32 v30, v31, v24
	v_fma_f32 v2, -v2, v30, v25
	v_div_fmas_f32 v2, v2, v24, v30
	v_div_fixup_f32 v23, v2, v23, 1.0
	v_div_scale_f32 v2, s[0:1], v22, v22, 1.0
	v_rcp_f32_e32 v24, v2
	v_lshl_add_u64 v[10:11], v[28:29], 0, v[10:11]
	global_store_dwordx4 v[10:11], v[6:9], off sc1
	v_lshlrev_b32_e32 v10, 9, v36
	v_fma_f32 v25, -v2, v24, 1.0
	v_fmac_f32_e32 v24, v25, v24
	v_div_scale_f32 v25, vcc, 1.0, v22, 1.0
	v_add_u32_e32 v6, v38, v10
	v_add_u32_e32 v10, v37, v10
	v_mul_f32_e32 v30, v25, v24
	ds_read_b128 v[14:17], v6
	ds_read_b128 v[6:9], v6 offset:16
	ds_read_b128 v[18:21], v10
	ds_read_b128 v[10:13], v10 offset:16
	v_fma_f32 v31, -v2, v30, v25
	v_fmac_f32_e32 v30, v31, v24
	v_fma_f32 v2, -v2, v30, v25
	v_div_fmas_f32 v2, v2, v24, v30
	v_div_fixup_f32 v22, v2, v22, 1.0
	s_waitcnt lgkmcnt(1)
	v_pk_add_f32 v[14:15], v[14:15], v[18:19]
	v_pk_add_f32 v[16:17], v[16:17], v[20:21]
	v_pk_mul_f32 v[14:15], v[22:23], v[14:15]
	s_waitcnt lgkmcnt(0)
	v_pk_add_f32 v[6:7], v[6:7], v[10:11]
	v_cvt_pk_bf16_f32 v2, v14, v15
	v_lshlrev_b32_e32 v14, 16, v3
	v_and_b32_e32 v3, 0xffff0000, v3
	v_mul_f32_e32 v14, 0xbfb8aa3b, v14
	v_mul_f32_e32 v3, 0xbfb8aa3b, v3
	v_exp_f32_e32 v14, v14
	v_exp_f32_e32 v15, v3
	v_pk_add_f32 v[8:9], v[8:9], v[12:13]
	v_pk_add_f32 v[14:15], v[14:15], 1.0 op_sel_hi:[1,0]
	s_nop 0
	v_div_scale_f32 v3, s[0:1], v15, v15, 1.0
	v_rcp_f32_e32 v18, v3
	s_nop 0
	v_fma_f32 v19, -v3, v18, 1.0
	v_fmac_f32_e32 v18, v19, v18
	v_div_scale_f32 v19, vcc, 1.0, v15, 1.0
	v_mul_f32_e32 v20, v19, v18
	v_fma_f32 v21, -v3, v20, v19
	v_fmac_f32_e32 v20, v21, v18
	v_fma_f32 v3, -v3, v20, v19
	v_div_fmas_f32 v3, v3, v18, v20
	v_div_fixup_f32 v15, v3, v15, 1.0
	v_div_scale_f32 v3, s[0:1], v14, v14, 1.0
	v_rcp_f32_e32 v18, v3
	s_nop 0
	v_fma_f32 v19, -v3, v18, 1.0
	v_fmac_f32_e32 v18, v19, v18
	v_div_scale_f32 v19, vcc, 1.0, v14, 1.0
	v_mul_f32_e32 v20, v19, v18
	v_fma_f32 v21, -v3, v20, v19
	v_fmac_f32_e32 v20, v21, v18
	v_fma_f32 v3, -v3, v20, v19
	v_div_fmas_f32 v3, v3, v18, v20
	v_div_fixup_f32 v14, v3, v14, 1.0
	v_pk_mul_f32 v[14:15], v[14:15], v[16:17]
	s_nop 0
	v_cvt_pk_bf16_f32 v3, v14, v15
	v_lshlrev_b32_e32 v14, 16, v4
	v_and_b32_e32 v4, 0xffff0000, v4
	v_mul_f32_e32 v14, 0xbfb8aa3b, v14
	v_mul_f32_e32 v4, 0xbfb8aa3b, v4
	v_exp_f32_e32 v14, v14
	v_exp_f32_e32 v15, v4
	s_nop 0
	v_pk_add_f32 v[14:15], v[14:15], 1.0 op_sel_hi:[1,0]
	s_nop 0
	v_div_scale_f32 v4, s[0:1], v15, v15, 1.0
	v_rcp_f32_e32 v16, v4
	s_nop 0
	v_fma_f32 v17, -v4, v16, 1.0
	v_fmac_f32_e32 v16, v17, v16
	v_div_scale_f32 v17, vcc, 1.0, v15, 1.0
	v_mul_f32_e32 v18, v17, v16
	v_fma_f32 v19, -v4, v18, v17
	v_fmac_f32_e32 v18, v19, v16
	v_fma_f32 v4, -v4, v18, v17
	v_div_fmas_f32 v4, v4, v16, v18
	v_div_fixup_f32 v15, v4, v15, 1.0
	v_div_scale_f32 v4, s[0:1], v14, v14, 1.0
	v_rcp_f32_e32 v16, v4
	s_nop 0
	v_fma_f32 v17, -v4, v16, 1.0
	v_fmac_f32_e32 v16, v17, v16
	v_div_scale_f32 v17, vcc, 1.0, v14, 1.0
	v_mul_f32_e32 v18, v17, v16
	v_fma_f32 v19, -v4, v18, v17
	v_fmac_f32_e32 v18, v19, v16
	v_fma_f32 v4, -v4, v18, v17
	v_div_fmas_f32 v4, v4, v16, v18
	v_div_fixup_f32 v14, v4, v14, 1.0
	v_pk_mul_f32 v[6:7], v[14:15], v[6:7]
	s_nop 0
	v_cvt_pk_bf16_f32 v4, v6, v7
	v_lshlrev_b32_e32 v6, 16, v5
	v_and_b32_e32 v5, 0xffff0000, v5
	v_mul_f32_e32 v6, 0xbfb8aa3b, v6
	v_mul_f32_e32 v5, 0xbfb8aa3b, v5
	v_exp_f32_e32 v6, v6
	v_exp_f32_e32 v7, v5
	s_nop 0
	v_pk_add_f32 v[6:7], v[6:7], 1.0 op_sel_hi:[1,0]
	s_nop 0
	v_div_scale_f32 v5, s[0:1], v7, v7, 1.0
	v_rcp_f32_e32 v10, v5
	s_nop 0
	v_fma_f32 v11, -v5, v10, 1.0
	v_fmac_f32_e32 v10, v11, v10
	v_div_scale_f32 v11, vcc, 1.0, v7, 1.0
	v_mul_f32_e32 v12, v11, v10
	v_fma_f32 v13, -v5, v12, v11
	v_fmac_f32_e32 v12, v13, v10
	v_fma_f32 v5, -v5, v12, v11
	v_div_fmas_f32 v5, v5, v10, v12
	v_div_fixup_f32 v7, v5, v7, 1.0
	v_div_scale_f32 v5, s[0:1], v6, v6, 1.0
	v_rcp_f32_e32 v10, v5
	s_nop 0
	v_fma_f32 v11, -v5, v10, 1.0
	v_fmac_f32_e32 v10, v11, v10
	v_div_scale_f32 v11, vcc, 1.0, v6, 1.0
	v_mul_f32_e32 v12, v11, v10
	v_fma_f32 v13, -v5, v12, v11
	v_fmac_f32_e32 v12, v13, v10
	v_fma_f32 v5, -v5, v12, v11
	v_div_fmas_f32 v5, v5, v10, v12
	v_div_fixup_f32 v6, v5, v6, 1.0
	v_pk_mul_f32 v[6:7], v[6:7], v[8:9]
	s_nop 0
	v_cvt_pk_bf16_f32 v5, v6, v7
	v_lshlrev_b64 v[6:7], 11, v[26:27]
	v_lshl_add_u64 v[6:7], v[28:29], 0, v[6:7]
	global_store_dwordx4 v[6:7], v[2:5], off sc1
	s_barrier
	s_cbranch_scc0 .LBB0_690

.LBB0_804:
	s_or_b64 exec, exec, s[0:1]
	s_waitcnt lgkmcnt(0)
	s_barrier
	v_lshl_add_u32 v169, v168, 3, 0
	ds_read_b64 v[172:173], v169 offset:8192
	v_add_u32_e32 v166, s34, v168
	v_ashrrev_i32_e32 v167, 31, v166
	v_lshlrev_b64 v[174:175], 11, v[166:167]
	s_waitcnt lgkmcnt(1)
	v_cmp_eq_u32_e32 vcc, 0, v171
	s_waitcnt lgkmcnt(0)
	v_sub_f32_e32 v15, v15, v172
	v_sub_f32_e32 v14, v14, v172
	v_pk_mul_f32 v[14:15], v[172:173], v[14:15] op_sel:[1,0]
	v_sub_f32_e32 v11, v11, v172
	v_sub_f32_e32 v10, v10, v172
	v_sub_f32_e32 v17, v17, v172
	v_sub_f32_e32 v16, v16, v172
	s_waitcnt vmcnt(4)
	v_pk_fma_f32 v[14:15], v[154:155], v[14:15], v[158:159]
	v_sub_f32_e32 v13, v13, v172
	v_sub_f32_e32 v12, v12, v172
	v_pk_mul_f32 v[10:11], v[172:173], v[10:11] op_sel:[1,0]
	v_pk_mul_f32 v[16:17], v[172:173], v[16:17] op_sel:[1,0]
	v_pk_mul_f32 v[12:13], v[172:173], v[12:13] op_sel:[1,0]
	v_pk_fma_f32 v[10:11], v[146:147], v[10:11], v[150:151]
	v_cndmask_b32_e32 v167, v208, v14, vcc
	v_cndmask_b32_e32 v168, v208, v15, vcc
	v_lshl_add_u64 v[14:15], s[24:25], 0, v[174:175]
	v_pk_fma_f32 v[16:17], v[156:157], v[16:17], v[160:161]
	v_pk_fma_f32 v[12:13], v[148:149], v[12:13], v[152:153]
	v_cndmask_b32_e32 v178, v208, v10, vcc
	v_cvt_pk_bf16_f32 v10, v167, v168
	v_lshl_add_u64 v[170:171], v[14:15], 0, v[164:165]
	v_cndmask_b32_e32 v16, v208, v16, vcc
	v_cndmask_b32_e32 v17, v208, v17, vcc
	v_cndmask_b32_e32 v176, v208, v12, vcc
	v_cndmask_b32_e32 v177, v208, v13, vcc
	v_cndmask_b32_e32 v185, v208, v11, vcc
	v_cvt_pk_bf16_f32 v11, v16, v17
	v_cvt_pk_bf16_f32 v12, v178, v185
	v_cvt_pk_bf16_f32 v13, v176, v177
	global_store_dwordx4 v[170:171], v[10:13], off sc1
	v_lshlrev_b32_e32 v14, 16, v10
	v_sub_f32_e32 v14, v167, v14
	v_and_b32_e32 v10, 0xffff0000, v10
	v_sub_f32_e32 v10, v168, v10
	v_mul_f32_e32 v14, 0x45000000, v14
	v_mul_f32_e32 v15, 0x45000000, v10
	v_mov_b32_e32 v10, v179
	v_cvt_pk_fp8_f32 v10, v14, v15
	v_lshlrev_b32_e32 v14, 16, v11
	v_and_b32_e32 v11, 0xffff0000, v11
	v_sub_f32_e32 v14, v16, v14
	v_sub_f32_e32 v11, v17, v11
	v_mul_f32_e32 v14, 0x45000000, v14
	v_mul_f32_e32 v11, 0x45000000, v11
	v_cvt_pk_fp8_f32 v10, v14, v11 op_sel:[0,0,1]
	v_lshlrev_b32_e32 v11, 16, v12
	v_sub_f32_e32 v11, v178, v11
	v_mul_f32_e32 v14, 0x45000000, v11
	v_and_b32_e32 v11, 0xffff0000, v12
	v_sub_f32_e32 v11, v185, v11
	v_mul_f32_e32 v12, 0x45000000, v11
	v_mov_b32_e32 v11, v179
	v_cvt_pk_fp8_f32 v11, v14, v12
	v_lshlrev_b32_e32 v12, 16, v13
	v_and_b32_e32 v13, 0xffff0000, v13
	v_sub_f32_e32 v12, v176, v12
	v_sub_f32_e32 v13, v177, v13
	v_mul_f32_e32 v12, 0x45000000, v12
	v_mul_f32_e32 v13, 0x45000000, v13
	v_cvt_pk_fp8_f32 v11, v12, v13 op_sel:[0,0,1]
	v_sub_f32_e32 v13, v23, v172
	v_sub_f32_e32 v12, v22, v172
	v_sub_f32_e32 v15, v25, v172
	v_sub_f32_e32 v14, v24, v172
	v_pk_mul_f32 v[14:15], v[172:173], v[14:15] op_sel:[1,0]
	v_pk_mul_f32 v[12:13], v[172:173], v[12:13] op_sel:[1,0]
	s_waitcnt vmcnt(1)
	v_pk_fma_f32 v[14:15], v[140:141], v[14:15], v[144:145]
	v_pk_fma_f32 v[12:13], v[138:139], v[12:13], v[142:143]
	v_sub_f32_e32 v16, v18, v172
	v_sub_f32_e32 v18, v20, v172
	v_cndmask_b32_e32 v20, v208, v14, vcc
	v_cndmask_b32_e32 v12, v208, v12, vcc
	v_cndmask_b32_e32 v13, v208, v13, vcc
	v_cvt_pk_bf16_f32 v14, v12, v13
	v_sub_f32_e32 v17, v19, v172
	v_lshlrev_b32_e32 v24, 16, v14
	v_sub_f32_e32 v12, v12, v24
	v_mul_f32_e32 v24, 0x45000000, v12
	v_and_b32_e32 v12, 0xffff0000, v14
	v_sub_f32_e32 v12, v13, v12
	v_mul_f32_e32 v13, 0x45000000, v12
	v_mov_b32_e32 v12, v179
	v_sub_f32_e32 v19, v21, v172
	v_cndmask_b32_e32 v21, v208, v15, vcc
	v_cvt_pk_bf16_f32 v15, v20, v21
	v_cvt_pk_fp8_f32 v12, v24, v13
	v_lshlrev_b32_e32 v13, 16, v15
	v_sub_f32_e32 v13, v20, v13
	v_and_b32_e32 v20, 0xffff0000, v15
	v_pk_mul_f32 v[16:17], v[172:173], v[16:17] op_sel:[1,0]
	v_sub_f32_e32 v20, v21, v20
	v_pk_fma_f32 v[16:17], v[6:7], v[16:17], v[130:131]
	v_mul_f32_e32 v13, 0x45000000, v13
	v_mul_f32_e32 v20, 0x45000000, v20
	v_cndmask_b32_e32 v22, v208, v16, vcc
	v_cndmask_b32_e32 v23, v208, v17, vcc
	v_cvt_pk_bf16_f32 v16, v22, v23
	v_cvt_pk_fp8_f32 v12, v13, v20 op_sel:[0,0,1]
	v_lshlrev_b32_e32 v13, 16, v16
	v_sub_f32_e32 v13, v22, v13
	v_mul_f32_e32 v20, 0x45000000, v13
	v_and_b32_e32 v13, 0xffff0000, v16
	v_pk_mul_f32 v[18:19], v[172:173], v[18:19] op_sel:[1,0]
	v_sub_f32_e32 v13, v23, v13
	v_pk_fma_f32 v[18:19], v[8:9], v[18:19], v[132:133]
	v_mul_f32_e32 v21, 0x45000000, v13
	v_mov_b32_e32 v13, v179
	v_cndmask_b32_e32 v18, v208, v18, vcc
	v_cndmask_b32_e32 v19, v208, v19, vcc
	v_cvt_pk_bf16_f32 v17, v18, v19
	v_cvt_pk_fp8_f32 v13, v20, v21
	v_lshlrev_b32_e32 v20, 16, v17
	v_sub_f32_e32 v18, v18, v20
	v_and_b32_e32 v20, 0xffff0000, v17
	v_sub_f32_e32 v19, v19, v20
	v_mul_f32_e32 v18, 0x45000000, v18
	v_mul_f32_e32 v19, 0x45000000, v19
	v_cvt_pk_fp8_f32 v13, v18, v19 op_sel:[0,0,1]
	global_store_dwordx4 v[170:171], v[14:17], off offset:256 sc1
	s_nop 1
	v_lshl_add_u64 v[14:15], s[18:19], 0, v[174:175]
	v_lshl_add_u64 v[14:15], v[14:15], 0, v[162:163]
	global_store_dwordx4 v[14:15], v[10:13], off sc1
	ds_read_b64 v[14:15], v169 offset:8320
	s_waitcnt lgkmcnt(0)
	v_sub_f32_e32 v17, v35, v14
	v_add_u32_e32 v10, 16, v166
	v_ashrrev_i32_e32 v11, 31, v10
	v_sub_f32_e32 v16, v34, v14
	v_lshlrev_b64 v[18:19], 11, v[10:11]
	v_sub_f32_e32 v11, v39, v14
	v_sub_f32_e32 v10, v38, v14
	v_sub_f32_e32 v21, v37, v14
	v_sub_f32_e32 v20, v36, v14
	v_pk_mul_f32 v[16:17], v[14:15], v[16:17] op_sel:[1,0]
	v_sub_f32_e32 v13, v41, v14
	v_sub_f32_e32 v12, v40, v14
	v_pk_mul_f32 v[10:11], v[14:15], v[10:11] op_sel:[1,0]
	v_pk_mul_f32 v[20:21], v[14:15], v[20:21] op_sel:[1,0]
	v_pk_fma_f32 v[16:17], v[146:147], v[16:17], v[150:151]
	v_pk_mul_f32 v[12:13], v[14:15], v[12:13] op_sel:[1,0]
	v_pk_fma_f32 v[10:11], v[154:155], v[10:11], v[158:159]
	v_pk_fma_f32 v[20:21], v[148:149], v[20:21], v[152:153]
	v_cndmask_b32_e32 v36, v208, v16, vcc
	v_cndmask_b32_e32 v37, v208, v17, vcc
	v_lshl_add_u64 v[16:17], s[24:25], 0, v[18:19]
	v_pk_fma_f32 v[12:13], v[156:157], v[12:13], v[160:161]
	v_cndmask_b32_e32 v24, v208, v10, vcc
	v_cndmask_b32_e32 v25, v208, v11, vcc
	v_cndmask_b32_e32 v34, v208, v20, vcc
	v_cndmask_b32_e32 v35, v208, v21, vcc
	v_cvt_pk_bf16_f32 v10, v24, v25
	v_lshl_add_u64 v[20:21], v[16:17], 0, v[164:165]
	v_cndmask_b32_e32 v22, v208, v12, vcc
	v_cndmask_b32_e32 v23, v208, v13, vcc
	v_cvt_pk_bf16_f32 v11, v22, v23
	v_cvt_pk_bf16_f32 v12, v36, v37
	v_cvt_pk_bf16_f32 v13, v34, v35
	global_store_dwordx4 v[20:21], v[10:13], off sc1
	v_lshlrev_b32_e32 v16, 16, v10
	v_sub_f32_e32 v16, v24, v16
	v_and_b32_e32 v10, 0xffff0000, v10
	v_sub_f32_e32 v10, v25, v10
	v_mul_f32_e32 v16, 0x45000000, v16
	v_mul_f32_e32 v17, 0x45000000, v10
	v_mov_b32_e32 v10, v179
	v_cvt_pk_fp8_f32 v10, v16, v17
	v_lshlrev_b32_e32 v16, 16, v11
	v_and_b32_e32 v11, 0xffff0000, v11
	v_sub_f32_e32 v16, v22, v16
	v_sub_f32_e32 v11, v23, v11
	v_mul_f32_e32 v16, 0x45000000, v16
	v_mul_f32_e32 v11, 0x45000000, v11
	v_cvt_pk_fp8_f32 v10, v16, v11 op_sel:[0,0,1]
	v_lshlrev_b32_e32 v11, 16, v12
	v_sub_f32_e32 v11, v36, v11
	v_mul_f32_e32 v16, 0x45000000, v11
	v_and_b32_e32 v11, 0xffff0000, v12
	v_sub_f32_e32 v11, v37, v11
	v_mul_f32_e32 v12, 0x45000000, v11
	v_mov_b32_e32 v11, v179
	v_cvt_pk_fp8_f32 v11, v16, v12
	v_lshlrev_b32_e32 v12, 16, v13
	v_and_b32_e32 v13, 0xffff0000, v13
	v_sub_f32_e32 v12, v34, v12
	v_sub_f32_e32 v13, v35, v13
	v_mul_f32_e32 v12, 0x45000000, v12
	v_mul_f32_e32 v13, 0x45000000, v13
	v_cvt_pk_fp8_f32 v11, v12, v13 op_sel:[0,0,1]
	v_sub_f32_e32 v13, v47, v14
	v_sub_f32_e32 v12, v46, v14
	v_sub_f32_e32 v17, v49, v14
	v_sub_f32_e32 v16, v48, v14
	v_sub_f32_e32 v23, v43, v14
	v_sub_f32_e32 v22, v42, v14
	v_sub_f32_e32 v25, v45, v14
	v_sub_f32_e32 v24, v44, v14
	v_pk_mul_f32 v[16:17], v[14:15], v[16:17] op_sel:[1,0]
	v_pk_mul_f32 v[12:13], v[14:15], v[12:13] op_sel:[1,0]
	v_pk_mul_f32 v[24:25], v[14:15], v[24:25] op_sel:[1,0]
	v_pk_mul_f32 v[14:15], v[14:15], v[22:23] op_sel:[1,0]
	v_pk_fma_f32 v[12:13], v[138:139], v[12:13], v[142:143]
	v_pk_fma_f32 v[14:15], v[6:7], v[14:15], v[130:131]
	v_cndmask_b32_e32 v12, v208, v12, vcc
	v_cndmask_b32_e32 v13, v208, v13, vcc
	v_cndmask_b32_e32 v34, v208, v14, vcc
	v_cvt_pk_bf16_f32 v14, v12, v13
	v_pk_fma_f32 v[16:17], v[140:141], v[16:17], v[144:145]
	v_lshlrev_b32_e32 v36, 16, v14
	v_sub_f32_e32 v12, v12, v36
	v_mul_f32_e32 v36, 0x45000000, v12
	v_and_b32_e32 v12, 0xffff0000, v14
	v_sub_f32_e32 v12, v13, v12
	v_mul_f32_e32 v13, 0x45000000, v12
	v_mov_b32_e32 v12, v179
	v_pk_fma_f32 v[22:23], v[8:9], v[24:25], v[132:133]
	v_cndmask_b32_e32 v24, v208, v16, vcc
	v_cndmask_b32_e32 v25, v208, v17, vcc
	v_cndmask_b32_e32 v35, v208, v15, vcc
	v_cvt_pk_bf16_f32 v15, v24, v25
	v_cvt_pk_fp8_f32 v12, v36, v13
	v_lshlrev_b32_e32 v13, 16, v15
	v_sub_f32_e32 v13, v24, v13
	v_and_b32_e32 v24, 0xffff0000, v15
	v_sub_f32_e32 v24, v25, v24
	v_mul_f32_e32 v13, 0x45000000, v13
	v_mul_f32_e32 v24, 0x45000000, v24
	v_cvt_pk_bf16_f32 v16, v34, v35
	v_cvt_pk_fp8_f32 v12, v13, v24 op_sel:[0,0,1]
	v_lshlrev_b32_e32 v13, 16, v16
	v_sub_f32_e32 v13, v34, v13
	v_mul_f32_e32 v24, 0x45000000, v13
	v_and_b32_e32 v13, 0xffff0000, v16
	v_sub_f32_e32 v13, v35, v13
	v_mul_f32_e32 v25, 0x45000000, v13
	v_mov_b32_e32 v13, v179
	v_cndmask_b32_e32 v22, v208, v22, vcc
	v_cndmask_b32_e32 v23, v208, v23, vcc
	v_cvt_pk_bf16_f32 v17, v22, v23
	v_cvt_pk_fp8_f32 v13, v24, v25
	v_lshlrev_b32_e32 v24, 16, v17
	v_sub_f32_e32 v22, v22, v24
	v_and_b32_e32 v24, 0xffff0000, v17
	v_sub_f32_e32 v23, v23, v24
	v_mul_f32_e32 v22, 0x45000000, v22
	v_mul_f32_e32 v23, 0x45000000, v23
	v_cvt_pk_fp8_f32 v13, v22, v23 op_sel:[0,0,1]
	global_store_dwordx4 v[20:21], v[14:17], off offset:256 sc1
	s_nop 1
	v_lshl_add_u64 v[14:15], s[18:19], 0, v[18:19]
	v_lshl_add_u64 v[14:15], v[14:15], 0, v[162:163]
	global_store_dwordx4 v[14:15], v[10:13], off sc1
	ds_read_b64 v[14:15], v169 offset:8448
	s_waitcnt lgkmcnt(0)
	v_sub_f32_e32 v17, v59, v14
	v_add_u32_e32 v10, 32, v166
	v_ashrrev_i32_e32 v11, 31, v10
	v_sub_f32_e32 v16, v58, v14
	v_lshlrev_b64 v[18:19], 11, v[10:11]
	v_sub_f32_e32 v11, v63, v14
	v_sub_f32_e32 v10, v62, v14
	v_sub_f32_e32 v21, v61, v14
	v_sub_f32_e32 v20, v60, v14
	v_pk_mul_f32 v[16:17], v[14:15], v[16:17] op_sel:[1,0]
	v_sub_f32_e32 v13, v65, v14
	v_sub_f32_e32 v12, v64, v14
	v_pk_mul_f32 v[10:11], v[14:15], v[10:11] op_sel:[1,0]
	v_pk_mul_f32 v[20:21], v[14:15], v[20:21] op_sel:[1,0]
	v_pk_fma_f32 v[16:17], v[146:147], v[16:17], v[150:151]
	v_pk_mul_f32 v[12:13], v[14:15], v[12:13] op_sel:[1,0]
	v_pk_fma_f32 v[10:11], v[154:155], v[10:11], v[158:159]
	v_pk_fma_f32 v[20:21], v[148:149], v[20:21], v[152:153]
	v_cndmask_b32_e32 v36, v208, v16, vcc
	v_cndmask_b32_e32 v37, v208, v17, vcc
	v_lshl_add_u64 v[16:17], s[24:25], 0, v[18:19]
	v_pk_fma_f32 v[12:13], v[156:157], v[12:13], v[160:161]
	v_cndmask_b32_e32 v24, v208, v10, vcc
	v_cndmask_b32_e32 v25, v208, v11, vcc
	v_cndmask_b32_e32 v34, v208, v20, vcc
	v_cndmask_b32_e32 v35, v208, v21, vcc
	v_cvt_pk_bf16_f32 v10, v24, v25
	v_lshl_add_u64 v[20:21], v[16:17], 0, v[164:165]
	v_cndmask_b32_e32 v22, v208, v12, vcc
	v_cndmask_b32_e32 v23, v208, v13, vcc
	v_cvt_pk_bf16_f32 v11, v22, v23
	v_cvt_pk_bf16_f32 v12, v36, v37
	v_cvt_pk_bf16_f32 v13, v34, v35
	global_store_dwordx4 v[20:21], v[10:13], off sc1
	v_lshlrev_b32_e32 v16, 16, v10
	v_sub_f32_e32 v16, v24, v16
	v_and_b32_e32 v10, 0xffff0000, v10
	v_sub_f32_e32 v10, v25, v10
	v_mul_f32_e32 v16, 0x45000000, v16
	v_mul_f32_e32 v17, 0x45000000, v10
	v_mov_b32_e32 v10, v179
	v_cvt_pk_fp8_f32 v10, v16, v17
	v_lshlrev_b32_e32 v16, 16, v11
	v_and_b32_e32 v11, 0xffff0000, v11
	v_sub_f32_e32 v16, v22, v16
	v_sub_f32_e32 v11, v23, v11
	v_mul_f32_e32 v16, 0x45000000, v16
	v_mul_f32_e32 v11, 0x45000000, v11
	v_cvt_pk_fp8_f32 v10, v16, v11 op_sel:[0,0,1]
	v_lshlrev_b32_e32 v11, 16, v12
	v_sub_f32_e32 v11, v36, v11
	v_mul_f32_e32 v16, 0x45000000, v11
	v_and_b32_e32 v11, 0xffff0000, v12
	v_sub_f32_e32 v11, v37, v11
	v_mul_f32_e32 v12, 0x45000000, v11
	v_mov_b32_e32 v11, v179
	v_cvt_pk_fp8_f32 v11, v16, v12
	v_lshlrev_b32_e32 v12, 16, v13
	v_and_b32_e32 v13, 0xffff0000, v13
	v_sub_f32_e32 v12, v34, v12
	v_sub_f32_e32 v13, v35, v13
	v_mul_f32_e32 v12, 0x45000000, v12
	v_mul_f32_e32 v13, 0x45000000, v13
	v_cvt_pk_fp8_f32 v11, v12, v13 op_sel:[0,0,1]
	v_sub_f32_e32 v13, v71, v14
	v_sub_f32_e32 v12, v70, v14
	v_sub_f32_e32 v17, v73, v14
	v_sub_f32_e32 v16, v72, v14
	v_sub_f32_e32 v23, v67, v14
	v_sub_f32_e32 v22, v66, v14
	v_sub_f32_e32 v25, v69, v14
	v_sub_f32_e32 v24, v68, v14
	v_pk_mul_f32 v[16:17], v[14:15], v[16:17] op_sel:[1,0]
	v_pk_mul_f32 v[12:13], v[14:15], v[12:13] op_sel:[1,0]
	v_pk_mul_f32 v[24:25], v[14:15], v[24:25] op_sel:[1,0]
	v_pk_mul_f32 v[14:15], v[14:15], v[22:23] op_sel:[1,0]
	v_pk_fma_f32 v[12:13], v[138:139], v[12:13], v[142:143]
	v_pk_fma_f32 v[14:15], v[6:7], v[14:15], v[130:131]
	v_cndmask_b32_e32 v12, v208, v12, vcc
	v_cndmask_b32_e32 v13, v208, v13, vcc
	v_cndmask_b32_e32 v34, v208, v14, vcc
	v_cvt_pk_bf16_f32 v14, v12, v13
	v_pk_fma_f32 v[16:17], v[140:141], v[16:17], v[144:145]
	v_lshlrev_b32_e32 v36, 16, v14
	v_sub_f32_e32 v12, v12, v36
	v_mul_f32_e32 v36, 0x45000000, v12
	v_and_b32_e32 v12, 0xffff0000, v14
	v_sub_f32_e32 v12, v13, v12
	v_mul_f32_e32 v13, 0x45000000, v12
	v_mov_b32_e32 v12, v179
	v_pk_fma_f32 v[22:23], v[8:9], v[24:25], v[132:133]
	v_cndmask_b32_e32 v24, v208, v16, vcc
	v_cndmask_b32_e32 v25, v208, v17, vcc
	v_cndmask_b32_e32 v35, v208, v15, vcc
	v_cvt_pk_bf16_f32 v15, v24, v25
	v_cvt_pk_fp8_f32 v12, v36, v13
	v_lshlrev_b32_e32 v13, 16, v15
	v_sub_f32_e32 v13, v24, v13
	v_and_b32_e32 v24, 0xffff0000, v15
	v_sub_f32_e32 v24, v25, v24
	v_mul_f32_e32 v13, 0x45000000, v13
	v_mul_f32_e32 v24, 0x45000000, v24
	v_cvt_pk_bf16_f32 v16, v34, v35
	v_cvt_pk_fp8_f32 v12, v13, v24 op_sel:[0,0,1]
	v_lshlrev_b32_e32 v13, 16, v16
	v_sub_f32_e32 v13, v34, v13
	v_mul_f32_e32 v24, 0x45000000, v13
	v_and_b32_e32 v13, 0xffff0000, v16
	v_sub_f32_e32 v13, v35, v13
	v_mul_f32_e32 v25, 0x45000000, v13
	v_mov_b32_e32 v13, v179
	v_cndmask_b32_e32 v22, v208, v22, vcc
	v_cndmask_b32_e32 v23, v208, v23, vcc
	v_cvt_pk_bf16_f32 v17, v22, v23
	v_cvt_pk_fp8_f32 v13, v24, v25
	v_lshlrev_b32_e32 v24, 16, v17
	v_sub_f32_e32 v22, v22, v24
	v_and_b32_e32 v24, 0xffff0000, v17
	v_sub_f32_e32 v23, v23, v24
	v_mul_f32_e32 v22, 0x45000000, v22
	v_mul_f32_e32 v23, 0x45000000, v23
	v_cvt_pk_fp8_f32 v13, v22, v23 op_sel:[0,0,1]
	global_store_dwordx4 v[20:21], v[14:17], off offset:256 sc1
	s_nop 1
	v_lshl_add_u64 v[14:15], s[18:19], 0, v[18:19]
	v_lshl_add_u64 v[14:15], v[14:15], 0, v[162:163]
	global_store_dwordx4 v[14:15], v[10:13], off sc1
	ds_read_b64 v[14:15], v169 offset:8576
	s_waitcnt lgkmcnt(0)
	v_sub_f32_e32 v17, v83, v14
	v_add_u32_e32 v10, 48, v166
	v_ashrrev_i32_e32 v11, 31, v10
	v_sub_f32_e32 v16, v82, v14
	v_lshlrev_b64 v[18:19], 11, v[10:11]
	v_sub_f32_e32 v11, v87, v14
	v_sub_f32_e32 v10, v86, v14
	v_sub_f32_e32 v21, v85, v14
	v_sub_f32_e32 v20, v84, v14
	v_pk_mul_f32 v[16:17], v[14:15], v[16:17] op_sel:[1,0]
	v_sub_f32_e32 v13, v89, v14
	v_sub_f32_e32 v12, v88, v14
	v_pk_mul_f32 v[10:11], v[14:15], v[10:11] op_sel:[1,0]
	v_pk_mul_f32 v[20:21], v[14:15], v[20:21] op_sel:[1,0]
	v_pk_fma_f32 v[16:17], v[146:147], v[16:17], v[150:151]
	v_pk_mul_f32 v[12:13], v[14:15], v[12:13] op_sel:[1,0]
	v_pk_fma_f32 v[10:11], v[154:155], v[10:11], v[158:159]
	v_pk_fma_f32 v[20:21], v[148:149], v[20:21], v[152:153]
	v_cndmask_b32_e32 v36, v208, v16, vcc
	v_cndmask_b32_e32 v37, v208, v17, vcc
	v_lshl_add_u64 v[16:17], s[24:25], 0, v[18:19]
	v_pk_fma_f32 v[12:13], v[156:157], v[12:13], v[160:161]
	v_cndmask_b32_e32 v24, v208, v10, vcc
	v_cndmask_b32_e32 v25, v208, v11, vcc
	v_cndmask_b32_e32 v34, v208, v20, vcc
	v_cndmask_b32_e32 v35, v208, v21, vcc
	v_cvt_pk_bf16_f32 v10, v24, v25
	v_lshl_add_u64 v[20:21], v[16:17], 0, v[164:165]
	v_cndmask_b32_e32 v22, v208, v12, vcc
	v_cndmask_b32_e32 v23, v208, v13, vcc
	v_cvt_pk_bf16_f32 v11, v22, v23
	v_cvt_pk_bf16_f32 v12, v36, v37
	v_cvt_pk_bf16_f32 v13, v34, v35
	global_store_dwordx4 v[20:21], v[10:13], off sc1
	v_lshlrev_b32_e32 v16, 16, v10
	v_sub_f32_e32 v16, v24, v16
	v_and_b32_e32 v10, 0xffff0000, v10
	v_sub_f32_e32 v10, v25, v10
	v_mul_f32_e32 v16, 0x45000000, v16
	v_mul_f32_e32 v17, 0x45000000, v10
	v_mov_b32_e32 v10, v179
	v_cvt_pk_fp8_f32 v10, v16, v17
	v_lshlrev_b32_e32 v16, 16, v11
	v_and_b32_e32 v11, 0xffff0000, v11
	v_sub_f32_e32 v16, v22, v16
	v_sub_f32_e32 v11, v23, v11
	v_mul_f32_e32 v16, 0x45000000, v16
	v_mul_f32_e32 v11, 0x45000000, v11
	v_cvt_pk_fp8_f32 v10, v16, v11 op_sel:[0,0,1]
	v_lshlrev_b32_e32 v11, 16, v12
	v_sub_f32_e32 v11, v36, v11
	v_mul_f32_e32 v16, 0x45000000, v11
	v_and_b32_e32 v11, 0xffff0000, v12
	v_sub_f32_e32 v11, v37, v11
	v_mul_f32_e32 v12, 0x45000000, v11
	v_mov_b32_e32 v11, v179
	v_cvt_pk_fp8_f32 v11, v16, v12
	v_lshlrev_b32_e32 v12, 16, v13
	v_and_b32_e32 v13, 0xffff0000, v13
	v_sub_f32_e32 v12, v34, v12
	v_sub_f32_e32 v13, v35, v13
	v_mul_f32_e32 v12, 0x45000000, v12
	v_mul_f32_e32 v13, 0x45000000, v13
	v_cvt_pk_fp8_f32 v11, v12, v13 op_sel:[0,0,1]
	v_sub_f32_e32 v13, v95, v14
	v_sub_f32_e32 v12, v94, v14
	v_sub_f32_e32 v17, v97, v14
	v_sub_f32_e32 v16, v96, v14
	v_sub_f32_e32 v23, v91, v14
	v_sub_f32_e32 v22, v90, v14
	v_sub_f32_e32 v25, v93, v14
	v_sub_f32_e32 v24, v92, v14
	v_pk_mul_f32 v[16:17], v[14:15], v[16:17] op_sel:[1,0]
	v_pk_mul_f32 v[12:13], v[14:15], v[12:13] op_sel:[1,0]
	v_pk_mul_f32 v[24:25], v[14:15], v[24:25] op_sel:[1,0]
	v_pk_mul_f32 v[14:15], v[14:15], v[22:23] op_sel:[1,0]
	v_pk_fma_f32 v[12:13], v[138:139], v[12:13], v[142:143]
	v_pk_fma_f32 v[14:15], v[6:7], v[14:15], v[130:131]
	v_cndmask_b32_e32 v12, v208, v12, vcc
	v_cndmask_b32_e32 v13, v208, v13, vcc
	v_cndmask_b32_e32 v34, v208, v14, vcc
	v_cvt_pk_bf16_f32 v14, v12, v13
	v_pk_fma_f32 v[16:17], v[140:141], v[16:17], v[144:145]
	v_lshlrev_b32_e32 v36, 16, v14
	v_sub_f32_e32 v12, v12, v36
	v_mul_f32_e32 v36, 0x45000000, v12
	v_and_b32_e32 v12, 0xffff0000, v14
	v_sub_f32_e32 v12, v13, v12
	v_mul_f32_e32 v13, 0x45000000, v12
	v_mov_b32_e32 v12, v179
	v_pk_fma_f32 v[22:23], v[8:9], v[24:25], v[132:133]
	v_cndmask_b32_e32 v24, v208, v16, vcc
	v_cndmask_b32_e32 v25, v208, v17, vcc
	v_cndmask_b32_e32 v35, v208, v15, vcc
	v_cvt_pk_bf16_f32 v15, v24, v25
	v_cvt_pk_fp8_f32 v12, v36, v13
	v_lshlrev_b32_e32 v13, 16, v15
	v_sub_f32_e32 v13, v24, v13
	v_and_b32_e32 v24, 0xffff0000, v15
	v_sub_f32_e32 v24, v25, v24
	v_mul_f32_e32 v13, 0x45000000, v13
	v_mul_f32_e32 v24, 0x45000000, v24
	v_cvt_pk_bf16_f32 v16, v34, v35
	v_cvt_pk_fp8_f32 v12, v13, v24 op_sel:[0,0,1]
	v_lshlrev_b32_e32 v13, 16, v16
	v_sub_f32_e32 v13, v34, v13
	v_mul_f32_e32 v24, 0x45000000, v13
	v_and_b32_e32 v13, 0xffff0000, v16
	v_sub_f32_e32 v13, v35, v13
	v_mul_f32_e32 v25, 0x45000000, v13
	v_mov_b32_e32 v13, v179
	v_cndmask_b32_e32 v22, v208, v22, vcc
	v_cndmask_b32_e32 v23, v208, v23, vcc
	v_cvt_pk_bf16_f32 v17, v22, v23
	v_cvt_pk_fp8_f32 v13, v24, v25
	v_lshlrev_b32_e32 v24, 16, v17
	v_sub_f32_e32 v22, v22, v24
	v_and_b32_e32 v24, 0xffff0000, v17
	v_sub_f32_e32 v23, v23, v24
	v_mul_f32_e32 v22, 0x45000000, v22
	v_mul_f32_e32 v23, 0x45000000, v23
	v_cvt_pk_fp8_f32 v13, v22, v23 op_sel:[0,0,1]
	global_store_dwordx4 v[20:21], v[14:17], off offset:256 sc1
	s_nop 1
	v_lshl_add_u64 v[14:15], s[18:19], 0, v[18:19]
	v_lshl_add_u64 v[14:15], v[14:15], 0, v[162:163]
	global_store_dwordx4 v[14:15], v[10:13], off sc1
	ds_read_b64 v[14:15], v169 offset:9216
	s_waitcnt lgkmcnt(0)
	v_sub_f32_e32 v17, v115, v14
	v_add_u32_e32 v10, 0x80, v166
	v_ashrrev_i32_e32 v11, 31, v10
	v_sub_f32_e32 v16, v114, v14
	v_lshlrev_b64 v[18:19], 11, v[10:11]
	v_sub_f32_e32 v11, v119, v14
	v_sub_f32_e32 v10, v118, v14
	v_sub_f32_e32 v21, v117, v14
	v_sub_f32_e32 v20, v116, v14
	v_pk_mul_f32 v[16:17], v[14:15], v[16:17] op_sel:[1,0]
	v_sub_f32_e32 v13, v121, v14
	v_sub_f32_e32 v12, v120, v14
	v_pk_mul_f32 v[10:11], v[14:15], v[10:11] op_sel:[1,0]
	v_pk_mul_f32 v[20:21], v[14:15], v[20:21] op_sel:[1,0]
	v_pk_fma_f32 v[16:17], v[146:147], v[16:17], v[150:151]
	v_pk_mul_f32 v[12:13], v[14:15], v[12:13] op_sel:[1,0]
	v_pk_fma_f32 v[10:11], v[154:155], v[10:11], v[158:159]
	v_pk_fma_f32 v[20:21], v[148:149], v[20:21], v[152:153]
	v_cndmask_b32_e32 v36, v208, v16, vcc
	v_cndmask_b32_e32 v37, v208, v17, vcc
	v_lshl_add_u64 v[16:17], s[24:25], 0, v[18:19]
	v_pk_fma_f32 v[12:13], v[156:157], v[12:13], v[160:161]
	v_cndmask_b32_e32 v24, v208, v10, vcc
	v_cndmask_b32_e32 v25, v208, v11, vcc
	v_cndmask_b32_e32 v34, v208, v20, vcc
	v_cndmask_b32_e32 v35, v208, v21, vcc
	v_cvt_pk_bf16_f32 v10, v24, v25
	v_lshl_add_u64 v[20:21], v[16:17], 0, v[164:165]
	v_cndmask_b32_e32 v22, v208, v12, vcc
	v_cndmask_b32_e32 v23, v208, v13, vcc
	v_cvt_pk_bf16_f32 v11, v22, v23
	v_cvt_pk_bf16_f32 v12, v36, v37
	v_cvt_pk_bf16_f32 v13, v34, v35
	global_store_dwordx4 v[20:21], v[10:13], off sc1
	v_lshlrev_b32_e32 v16, 16, v10
	v_sub_f32_e32 v16, v24, v16
	v_and_b32_e32 v10, 0xffff0000, v10
	v_sub_f32_e32 v10, v25, v10
	v_mul_f32_e32 v16, 0x45000000, v16
	v_mul_f32_e32 v17, 0x45000000, v10
	v_mov_b32_e32 v10, v179
	v_cvt_pk_fp8_f32 v10, v16, v17
	v_lshlrev_b32_e32 v16, 16, v11
	v_and_b32_e32 v11, 0xffff0000, v11
	v_sub_f32_e32 v16, v22, v16
	v_sub_f32_e32 v11, v23, v11
	v_mul_f32_e32 v16, 0x45000000, v16
	v_mul_f32_e32 v11, 0x45000000, v11
	v_cvt_pk_fp8_f32 v10, v16, v11 op_sel:[0,0,1]
	v_lshlrev_b32_e32 v11, 16, v12
	v_sub_f32_e32 v11, v36, v11
	v_mul_f32_e32 v16, 0x45000000, v11
	v_and_b32_e32 v11, 0xffff0000, v12
	v_sub_f32_e32 v11, v37, v11
	v_mul_f32_e32 v12, 0x45000000, v11
	v_mov_b32_e32 v11, v179
	v_cvt_pk_fp8_f32 v11, v16, v12
	v_lshlrev_b32_e32 v12, 16, v13
	v_and_b32_e32 v13, 0xffff0000, v13
	v_sub_f32_e32 v12, v34, v12
	v_sub_f32_e32 v13, v35, v13
	v_mul_f32_e32 v12, 0x45000000, v12
	v_mul_f32_e32 v13, 0x45000000, v13
	v_cvt_pk_fp8_f32 v11, v12, v13 op_sel:[0,0,1]
	v_sub_f32_e32 v13, v127, v14
	v_sub_f32_e32 v12, v126, v14
	v_sub_f32_e32 v17, v129, v14
	v_sub_f32_e32 v16, v128, v14
	v_sub_f32_e32 v23, v123, v14
	v_sub_f32_e32 v22, v122, v14
	v_sub_f32_e32 v25, v125, v14
	v_sub_f32_e32 v24, v124, v14
	v_pk_mul_f32 v[16:17], v[14:15], v[16:17] op_sel:[1,0]
	v_pk_mul_f32 v[12:13], v[14:15], v[12:13] op_sel:[1,0]
	v_pk_mul_f32 v[24:25], v[14:15], v[24:25] op_sel:[1,0]
	v_pk_mul_f32 v[14:15], v[14:15], v[22:23] op_sel:[1,0]
	v_pk_fma_f32 v[12:13], v[138:139], v[12:13], v[142:143]
	v_pk_fma_f32 v[14:15], v[6:7], v[14:15], v[130:131]
	v_cndmask_b32_e32 v12, v208, v12, vcc
	v_cndmask_b32_e32 v13, v208, v13, vcc
	v_cndmask_b32_e32 v34, v208, v14, vcc
	v_cvt_pk_bf16_f32 v14, v12, v13
	v_pk_fma_f32 v[16:17], v[140:141], v[16:17], v[144:145]
	v_lshlrev_b32_e32 v36, 16, v14
	v_sub_f32_e32 v12, v12, v36
	v_mul_f32_e32 v36, 0x45000000, v12
	v_and_b32_e32 v12, 0xffff0000, v14
	v_sub_f32_e32 v12, v13, v12
	v_mul_f32_e32 v13, 0x45000000, v12
	v_mov_b32_e32 v12, v179
	v_pk_fma_f32 v[22:23], v[8:9], v[24:25], v[132:133]
	v_cndmask_b32_e32 v24, v208, v16, vcc
	v_cndmask_b32_e32 v25, v208, v17, vcc
	v_cndmask_b32_e32 v35, v208, v15, vcc
	v_cvt_pk_bf16_f32 v15, v24, v25
	v_cvt_pk_fp8_f32 v12, v36, v13
	v_lshlrev_b32_e32 v13, 16, v15
	v_sub_f32_e32 v13, v24, v13
	v_and_b32_e32 v24, 0xffff0000, v15
	v_sub_f32_e32 v24, v25, v24
	v_mul_f32_e32 v13, 0x45000000, v13
	v_mul_f32_e32 v24, 0x45000000, v24
	v_cvt_pk_bf16_f32 v16, v34, v35
	v_cvt_pk_fp8_f32 v12, v13, v24 op_sel:[0,0,1]
	v_lshlrev_b32_e32 v13, 16, v16
	v_sub_f32_e32 v13, v34, v13
	v_mul_f32_e32 v24, 0x45000000, v13
	v_and_b32_e32 v13, 0xffff0000, v16
	v_sub_f32_e32 v13, v35, v13
	v_mul_f32_e32 v25, 0x45000000, v13
	v_mov_b32_e32 v13, v179
	v_cndmask_b32_e32 v22, v208, v22, vcc
	v_cndmask_b32_e32 v23, v208, v23, vcc
	v_cvt_pk_bf16_f32 v17, v22, v23
	v_cvt_pk_fp8_f32 v13, v24, v25
	v_lshlrev_b32_e32 v24, 16, v17
	v_sub_f32_e32 v22, v22, v24
	v_and_b32_e32 v24, 0xffff0000, v17
	v_sub_f32_e32 v23, v23, v24
	v_mul_f32_e32 v22, 0x45000000, v22
	v_mul_f32_e32 v23, 0x45000000, v23
	v_cvt_pk_fp8_f32 v13, v22, v23 op_sel:[0,0,1]
	global_store_dwordx4 v[20:21], v[14:17], off offset:256 sc1
	s_nop 1
	v_lshl_add_u64 v[14:15], s[18:19], 0, v[18:19]
	v_lshl_add_u64 v[14:15], v[14:15], 0, v[162:163]
	global_store_dwordx4 v[14:15], v[10:13], off sc1
	ds_read_b64 v[14:15], v169 offset:9344
	s_waitcnt lgkmcnt(0)
	v_sub_f32_e32 v17, v107, v14
	v_add_u32_e32 v10, 0x90, v166
	v_ashrrev_i32_e32 v11, 31, v10
	v_sub_f32_e32 v16, v106, v14
	v_lshlrev_b64 v[18:19], 11, v[10:11]
	v_sub_f32_e32 v11, v111, v14
	v_sub_f32_e32 v10, v110, v14
	v_sub_f32_e32 v21, v109, v14
	v_sub_f32_e32 v20, v108, v14
	v_pk_mul_f32 v[16:17], v[14:15], v[16:17] op_sel:[1,0]
	v_sub_f32_e32 v13, v113, v14
	v_sub_f32_e32 v12, v112, v14
	v_pk_mul_f32 v[10:11], v[14:15], v[10:11] op_sel:[1,0]
	v_pk_mul_f32 v[20:21], v[14:15], v[20:21] op_sel:[1,0]
	v_pk_fma_f32 v[16:17], v[146:147], v[16:17], v[150:151]
	v_pk_mul_f32 v[12:13], v[14:15], v[12:13] op_sel:[1,0]
	v_pk_fma_f32 v[10:11], v[154:155], v[10:11], v[158:159]
	v_pk_fma_f32 v[20:21], v[148:149], v[20:21], v[152:153]
	v_cndmask_b32_e32 v36, v208, v16, vcc
	v_cndmask_b32_e32 v37, v208, v17, vcc
	v_lshl_add_u64 v[16:17], s[24:25], 0, v[18:19]
	v_pk_fma_f32 v[12:13], v[156:157], v[12:13], v[160:161]
	v_cndmask_b32_e32 v24, v208, v10, vcc
	v_cndmask_b32_e32 v25, v208, v11, vcc
	v_cndmask_b32_e32 v34, v208, v20, vcc
	v_cndmask_b32_e32 v35, v208, v21, vcc
	v_cvt_pk_bf16_f32 v10, v24, v25
	v_lshl_add_u64 v[20:21], v[16:17], 0, v[164:165]
	v_cndmask_b32_e32 v22, v208, v12, vcc
	v_cndmask_b32_e32 v23, v208, v13, vcc
	v_cvt_pk_bf16_f32 v11, v22, v23
	v_cvt_pk_bf16_f32 v12, v36, v37
	v_cvt_pk_bf16_f32 v13, v34, v35
	global_store_dwordx4 v[20:21], v[10:13], off sc1
	v_lshlrev_b32_e32 v16, 16, v10
	v_sub_f32_e32 v16, v24, v16
	v_and_b32_e32 v10, 0xffff0000, v10
	v_sub_f32_e32 v10, v25, v10
	v_mul_f32_e32 v16, 0x45000000, v16
	v_mul_f32_e32 v17, 0x45000000, v10
	v_mov_b32_e32 v10, v179
	v_cvt_pk_fp8_f32 v10, v16, v17
	v_lshlrev_b32_e32 v16, 16, v11
	v_and_b32_e32 v11, 0xffff0000, v11
	v_sub_f32_e32 v16, v22, v16
	v_sub_f32_e32 v11, v23, v11
	v_mul_f32_e32 v16, 0x45000000, v16
	v_mul_f32_e32 v11, 0x45000000, v11
	v_cvt_pk_fp8_f32 v10, v16, v11 op_sel:[0,0,1]
	v_lshlrev_b32_e32 v11, 16, v12
	v_sub_f32_e32 v11, v36, v11
	v_mul_f32_e32 v16, 0x45000000, v11
	v_and_b32_e32 v11, 0xffff0000, v12
	v_sub_f32_e32 v11, v37, v11
	v_mul_f32_e32 v12, 0x45000000, v11
	v_mov_b32_e32 v11, v179
	v_cvt_pk_fp8_f32 v11, v16, v12
	v_lshlrev_b32_e32 v12, 16, v13
	v_and_b32_e32 v13, 0xffff0000, v13
	v_sub_f32_e32 v12, v34, v12
	v_sub_f32_e32 v13, v35, v13
	v_mul_f32_e32 v12, 0x45000000, v12
	v_mul_f32_e32 v13, 0x45000000, v13
	v_cvt_pk_fp8_f32 v11, v12, v13 op_sel:[0,0,1]
	v_sub_f32_e32 v13, v103, v14
	v_sub_f32_e32 v12, v102, v14
	v_sub_f32_e32 v17, v105, v14
	v_sub_f32_e32 v16, v104, v14
	v_sub_f32_e32 v23, v99, v14
	v_sub_f32_e32 v22, v98, v14
	v_sub_f32_e32 v25, v101, v14
	v_sub_f32_e32 v24, v100, v14
	v_pk_mul_f32 v[16:17], v[14:15], v[16:17] op_sel:[1,0]
	v_pk_mul_f32 v[12:13], v[14:15], v[12:13] op_sel:[1,0]
	v_pk_mul_f32 v[24:25], v[14:15], v[24:25] op_sel:[1,0]
	v_pk_mul_f32 v[14:15], v[14:15], v[22:23] op_sel:[1,0]
	v_pk_fma_f32 v[12:13], v[138:139], v[12:13], v[142:143]
	v_pk_fma_f32 v[14:15], v[6:7], v[14:15], v[130:131]
	v_cndmask_b32_e32 v12, v208, v12, vcc
	v_cndmask_b32_e32 v13, v208, v13, vcc
	v_cndmask_b32_e32 v34, v208, v14, vcc
	v_cvt_pk_bf16_f32 v14, v12, v13
	v_pk_fma_f32 v[16:17], v[140:141], v[16:17], v[144:145]
	v_lshlrev_b32_e32 v36, 16, v14
	v_sub_f32_e32 v12, v12, v36
	v_mul_f32_e32 v36, 0x45000000, v12
	v_and_b32_e32 v12, 0xffff0000, v14
	v_sub_f32_e32 v12, v13, v12
	v_mul_f32_e32 v13, 0x45000000, v12
	v_mov_b32_e32 v12, v179
	v_pk_fma_f32 v[22:23], v[8:9], v[24:25], v[132:133]
	v_cndmask_b32_e32 v24, v208, v16, vcc
	v_cndmask_b32_e32 v25, v208, v17, vcc
	v_cndmask_b32_e32 v35, v208, v15, vcc
	v_cvt_pk_bf16_f32 v15, v24, v25
	v_cvt_pk_fp8_f32 v12, v36, v13
	v_lshlrev_b32_e32 v13, 16, v15
	v_sub_f32_e32 v13, v24, v13
	v_and_b32_e32 v24, 0xffff0000, v15
	v_sub_f32_e32 v24, v25, v24
	v_mul_f32_e32 v13, 0x45000000, v13
	v_mul_f32_e32 v24, 0x45000000, v24
	v_cvt_pk_bf16_f32 v16, v34, v35
	v_cvt_pk_fp8_f32 v12, v13, v24 op_sel:[0,0,1]
	v_lshlrev_b32_e32 v13, 16, v16
	v_sub_f32_e32 v13, v34, v13
	v_mul_f32_e32 v24, 0x45000000, v13
	v_and_b32_e32 v13, 0xffff0000, v16
	v_sub_f32_e32 v13, v35, v13
	v_mul_f32_e32 v25, 0x45000000, v13
	v_mov_b32_e32 v13, v179
	v_cndmask_b32_e32 v22, v208, v22, vcc
	v_cndmask_b32_e32 v23, v208, v23, vcc
	v_cvt_pk_bf16_f32 v17, v22, v23
	v_cvt_pk_fp8_f32 v13, v24, v25
	v_lshlrev_b32_e32 v24, 16, v17
	v_sub_f32_e32 v22, v22, v24
	v_and_b32_e32 v24, 0xffff0000, v17
	v_sub_f32_e32 v23, v23, v24
	v_mul_f32_e32 v22, 0x45000000, v22
	v_mul_f32_e32 v23, 0x45000000, v23
	v_cvt_pk_fp8_f32 v13, v22, v23 op_sel:[0,0,1]
	global_store_dwordx4 v[20:21], v[14:17], off offset:256 sc1
	s_nop 1
	v_lshl_add_u64 v[14:15], s[18:19], 0, v[18:19]
	v_lshl_add_u64 v[14:15], v[14:15], 0, v[162:163]
	global_store_dwordx4 v[14:15], v[10:13], off sc1
	ds_read_b64 v[14:15], v169 offset:9472
	s_waitcnt lgkmcnt(0)
	v_sub_f32_e32 v17, v75, v14
	v_add_u32_e32 v10, 0xa0, v166
	v_ashrrev_i32_e32 v11, 31, v10
	v_sub_f32_e32 v16, v74, v14
	v_lshlrev_b64 v[18:19], 11, v[10:11]
	v_sub_f32_e32 v11, v79, v14
	v_sub_f32_e32 v10, v78, v14
	v_sub_f32_e32 v21, v77, v14
	v_sub_f32_e32 v20, v76, v14
	v_pk_mul_f32 v[16:17], v[14:15], v[16:17] op_sel:[1,0]
	v_sub_f32_e32 v13, v81, v14
	v_sub_f32_e32 v12, v80, v14
	v_pk_mul_f32 v[10:11], v[14:15], v[10:11] op_sel:[1,0]
	v_pk_mul_f32 v[20:21], v[14:15], v[20:21] op_sel:[1,0]
	v_pk_fma_f32 v[16:17], v[146:147], v[16:17], v[150:151]
	v_pk_mul_f32 v[12:13], v[14:15], v[12:13] op_sel:[1,0]
	v_pk_fma_f32 v[10:11], v[154:155], v[10:11], v[158:159]
	v_pk_fma_f32 v[20:21], v[148:149], v[20:21], v[152:153]
	v_cndmask_b32_e32 v36, v208, v16, vcc
	v_cndmask_b32_e32 v37, v208, v17, vcc
	v_lshl_add_u64 v[16:17], s[24:25], 0, v[18:19]
	v_pk_fma_f32 v[12:13], v[156:157], v[12:13], v[160:161]
	v_cndmask_b32_e32 v24, v208, v10, vcc
	v_cndmask_b32_e32 v25, v208, v11, vcc
	v_cndmask_b32_e32 v34, v208, v20, vcc
	v_cndmask_b32_e32 v35, v208, v21, vcc
	v_cvt_pk_bf16_f32 v10, v24, v25
	v_lshl_add_u64 v[20:21], v[16:17], 0, v[164:165]
	v_cndmask_b32_e32 v22, v208, v12, vcc
	v_cndmask_b32_e32 v23, v208, v13, vcc
	v_cvt_pk_bf16_f32 v11, v22, v23
	v_cvt_pk_bf16_f32 v12, v36, v37
	v_cvt_pk_bf16_f32 v13, v34, v35
	global_store_dwordx4 v[20:21], v[10:13], off sc1
	v_lshlrev_b32_e32 v16, 16, v10
	v_sub_f32_e32 v16, v24, v16
	v_and_b32_e32 v10, 0xffff0000, v10
	v_sub_f32_e32 v10, v25, v10
	v_mul_f32_e32 v16, 0x45000000, v16
	v_mul_f32_e32 v17, 0x45000000, v10
	v_mov_b32_e32 v10, v179
	v_cvt_pk_fp8_f32 v10, v16, v17
	v_lshlrev_b32_e32 v16, 16, v11
	v_and_b32_e32 v11, 0xffff0000, v11
	v_sub_f32_e32 v16, v22, v16
	v_sub_f32_e32 v11, v23, v11
	v_mul_f32_e32 v16, 0x45000000, v16
	v_mul_f32_e32 v11, 0x45000000, v11
	v_cvt_pk_fp8_f32 v10, v16, v11 op_sel:[0,0,1]
	v_lshlrev_b32_e32 v11, 16, v12
	v_sub_f32_e32 v11, v36, v11
	v_mul_f32_e32 v16, 0x45000000, v11
	v_and_b32_e32 v11, 0xffff0000, v12
	v_sub_f32_e32 v11, v37, v11
	v_mul_f32_e32 v12, 0x45000000, v11
	v_mov_b32_e32 v11, v179
	v_cvt_pk_fp8_f32 v11, v16, v12
	v_lshlrev_b32_e32 v12, 16, v13
	v_and_b32_e32 v13, 0xffff0000, v13
	v_sub_f32_e32 v12, v34, v12
	v_sub_f32_e32 v13, v35, v13
	v_mul_f32_e32 v12, 0x45000000, v12
	v_mul_f32_e32 v13, 0x45000000, v13
	v_cvt_pk_fp8_f32 v11, v12, v13 op_sel:[0,0,1]
	v_sub_f32_e32 v13, v55, v14
	v_sub_f32_e32 v12, v54, v14
	v_sub_f32_e32 v17, v57, v14
	v_sub_f32_e32 v16, v56, v14
	v_sub_f32_e32 v23, v51, v14
	v_sub_f32_e32 v22, v50, v14
	v_sub_f32_e32 v25, v53, v14
	v_sub_f32_e32 v24, v52, v14
	v_pk_mul_f32 v[16:17], v[14:15], v[16:17] op_sel:[1,0]
	v_pk_mul_f32 v[12:13], v[14:15], v[12:13] op_sel:[1,0]
	v_pk_mul_f32 v[24:25], v[14:15], v[24:25] op_sel:[1,0]
	v_pk_mul_f32 v[14:15], v[14:15], v[22:23] op_sel:[1,0]
	v_pk_fma_f32 v[12:13], v[138:139], v[12:13], v[142:143]
	v_pk_fma_f32 v[14:15], v[6:7], v[14:15], v[130:131]
	v_cndmask_b32_e32 v12, v208, v12, vcc
	v_cndmask_b32_e32 v13, v208, v13, vcc
	v_cndmask_b32_e32 v34, v208, v14, vcc
	v_cvt_pk_bf16_f32 v14, v12, v13
	v_pk_fma_f32 v[16:17], v[140:141], v[16:17], v[144:145]
	v_lshlrev_b32_e32 v36, 16, v14
	v_sub_f32_e32 v12, v12, v36
	v_mul_f32_e32 v36, 0x45000000, v12
	v_and_b32_e32 v12, 0xffff0000, v14
	v_sub_f32_e32 v12, v13, v12
	v_mul_f32_e32 v13, 0x45000000, v12
	v_mov_b32_e32 v12, v179
	v_pk_fma_f32 v[22:23], v[8:9], v[24:25], v[132:133]
	v_cndmask_b32_e32 v24, v208, v16, vcc
	v_cndmask_b32_e32 v25, v208, v17, vcc
	v_cndmask_b32_e32 v35, v208, v15, vcc
	v_cvt_pk_bf16_f32 v15, v24, v25
	v_cvt_pk_fp8_f32 v12, v36, v13
	v_lshlrev_b32_e32 v13, 16, v15
	v_sub_f32_e32 v13, v24, v13
	v_and_b32_e32 v24, 0xffff0000, v15
	v_sub_f32_e32 v24, v25, v24
	v_mul_f32_e32 v13, 0x45000000, v13
	v_mul_f32_e32 v24, 0x45000000, v24
	v_cvt_pk_bf16_f32 v16, v34, v35
	v_cvt_pk_fp8_f32 v12, v13, v24 op_sel:[0,0,1]
	v_lshlrev_b32_e32 v13, 16, v16
	v_sub_f32_e32 v13, v34, v13
	v_mul_f32_e32 v24, 0x45000000, v13
	v_and_b32_e32 v13, 0xffff0000, v16
	v_sub_f32_e32 v13, v35, v13
	v_mul_f32_e32 v25, 0x45000000, v13
	v_mov_b32_e32 v13, v179
	v_cndmask_b32_e32 v22, v208, v22, vcc
	v_cndmask_b32_e32 v23, v208, v23, vcc
	v_cvt_pk_bf16_f32 v17, v22, v23
	v_cvt_pk_fp8_f32 v13, v24, v25
	v_lshlrev_b32_e32 v24, 16, v17
	v_sub_f32_e32 v22, v22, v24
	v_and_b32_e32 v24, 0xffff0000, v17
	v_sub_f32_e32 v23, v23, v24
	v_mul_f32_e32 v22, 0x45000000, v22
	v_mul_f32_e32 v23, 0x45000000, v23
	v_cvt_pk_fp8_f32 v13, v22, v23 op_sel:[0,0,1]
	global_store_dwordx4 v[20:21], v[14:17], off offset:256 sc1
	s_nop 1
	v_lshl_add_u64 v[14:15], s[18:19], 0, v[18:19]
	v_lshl_add_u64 v[14:15], v[14:15], 0, v[162:163]
	global_store_dwordx4 v[14:15], v[10:13], off sc1
	ds_read_b64 v[14:15], v169 offset:9600
	s_waitcnt lgkmcnt(0)
	v_sub_f32_e32 v19, v27, v14
	v_add_u32_e32 v10, 0xb0, v166
	v_ashrrev_i32_e32 v11, 31, v10
	v_sub_f32_e32 v18, v26, v14
	v_lshlrev_b64 v[16:17], 11, v[10:11]
	v_sub_f32_e32 v11, v31, v14
	v_sub_f32_e32 v10, v30, v14
	v_pk_mul_f32 v[18:19], v[14:15], v[18:19] op_sel:[1,0]
	v_sub_f32_e32 v13, v33, v14
	v_sub_f32_e32 v12, v32, v14
	v_pk_mul_f32 v[10:11], v[14:15], v[10:11] op_sel:[1,0]
	v_sub_f32_e32 v21, v29, v14
	v_sub_f32_e32 v20, v28, v14
	v_pk_fma_f32 v[18:19], v[146:147], v[18:19], v[150:151]
	v_pk_mul_f32 v[12:13], v[14:15], v[12:13] op_sel:[1,0]
	v_pk_fma_f32 v[10:11], v[154:155], v[10:11], v[158:159]
	v_pk_mul_f32 v[20:21], v[14:15], v[20:21] op_sel:[1,0]
	v_cndmask_b32_e32 v26, v208, v18, vcc
	v_cndmask_b32_e32 v27, v208, v19, vcc
	v_lshl_add_u64 v[18:19], s[24:25], 0, v[16:17]
	v_pk_fma_f32 v[12:13], v[156:157], v[12:13], v[160:161]
	v_pk_fma_f32 v[20:21], v[148:149], v[20:21], v[152:153]
	v_cndmask_b32_e32 v24, v208, v10, vcc
	v_cndmask_b32_e32 v25, v208, v11, vcc
	v_cvt_pk_bf16_f32 v10, v24, v25
	v_lshl_add_u64 v[18:19], v[18:19], 0, v[164:165]
	v_cndmask_b32_e32 v22, v208, v12, vcc
	v_cndmask_b32_e32 v23, v208, v13, vcc
	v_cndmask_b32_e32 v20, v208, v20, vcc
	v_cndmask_b32_e32 v21, v208, v21, vcc
	v_cvt_pk_bf16_f32 v11, v22, v23
	v_cvt_pk_bf16_f32 v12, v26, v27
	v_cvt_pk_bf16_f32 v13, v20, v21
	global_store_dwordx4 v[18:19], v[10:13], off sc1
	v_lshlrev_b32_e32 v28, 16, v10
	v_sub_f32_e32 v24, v24, v28
	v_and_b32_e32 v10, 0xffff0000, v10
	v_sub_f32_e32 v10, v25, v10
	v_mul_f32_e32 v24, 0x45000000, v24
	v_mul_f32_e32 v25, 0x45000000, v10
	v_mov_b32_e32 v10, v179
	v_cvt_pk_fp8_f32 v10, v24, v25
	v_lshlrev_b32_e32 v24, 16, v11
	v_and_b32_e32 v11, 0xffff0000, v11
	v_sub_f32_e32 v22, v22, v24
	v_sub_f32_e32 v11, v23, v11
	v_mul_f32_e32 v22, 0x45000000, v22
	v_mul_f32_e32 v11, 0x45000000, v11
	v_cvt_pk_fp8_f32 v10, v22, v11 op_sel:[0,0,1]
	v_lshlrev_b32_e32 v11, 16, v12
	v_sub_f32_e32 v11, v26, v11
	v_mul_f32_e32 v22, 0x45000000, v11
	v_and_b32_e32 v11, 0xffff0000, v12
	v_sub_f32_e32 v11, v27, v11
	v_mul_f32_e32 v12, 0x45000000, v11
	v_mov_b32_e32 v11, v179
	v_cvt_pk_fp8_f32 v11, v22, v12
	v_lshlrev_b32_e32 v12, 16, v13
	v_and_b32_e32 v13, 0xffff0000, v13
	v_sub_f32_e32 v12, v20, v12
	v_sub_f32_e32 v13, v21, v13
	v_mul_f32_e32 v12, 0x45000000, v12
	v_mul_f32_e32 v13, 0x45000000, v13
	v_cvt_pk_fp8_f32 v11, v12, v13 op_sel:[0,0,1]
	v_sub_f32_e32 v13, v135, v14
	v_sub_f32_e32 v12, v134, v14
	v_sub_f32_e32 v3, v3, v14
	v_sub_f32_e32 v2, v2, v14
	v_pk_mul_f32 v[12:13], v[14:15], v[12:13] op_sel:[1,0]
	v_sub_f32_e32 v5, v5, v14
	v_sub_f32_e32 v4, v4, v14
	v_pk_mul_f32 v[2:3], v[14:15], v[2:3] op_sel:[1,0]
	v_pk_fma_f32 v[12:13], v[138:139], v[12:13], v[142:143]
	v_pk_mul_f32 v[4:5], v[14:15], v[4:5] op_sel:[1,0]
	v_pk_fma_f32 v[2:3], v[6:7], v[2:3], v[130:131]
	v_pk_fma_f32 v[4:5], v[8:9], v[4:5], v[132:133]
	v_cndmask_b32_e32 v8, v208, v12, vcc
	v_cndmask_b32_e32 v9, v208, v13, vcc
	v_cndmask_b32_e32 v13, v208, v2, vcc
	v_cvt_pk_bf16_f32 v2, v8, v9
	v_sub_f32_e32 v21, v137, v14
	v_lshlrev_b32_e32 v12, 16, v2
	v_sub_f32_e32 v20, v136, v14
	v_sub_f32_e32 v8, v8, v12
	v_and_b32_e32 v12, 0xffff0000, v2
	v_pk_mul_f32 v[20:21], v[14:15], v[20:21] op_sel:[1,0]
	v_sub_f32_e32 v9, v9, v12
	v_pk_fma_f32 v[20:21], v[140:141], v[20:21], v[144:145]
	v_mul_f32_e32 v8, 0x45000000, v8
	v_mul_f32_e32 v9, 0x45000000, v9
	v_mov_b32_e32 v12, v179
	v_cndmask_b32_e32 v6, v208, v20, vcc
	v_cndmask_b32_e32 v7, v208, v21, vcc
	v_cndmask_b32_e32 v20, v208, v3, vcc
	v_cvt_pk_bf16_f32 v3, v6, v7
	v_cvt_pk_fp8_f32 v12, v8, v9
	v_lshlrev_b32_e32 v8, 16, v3
	v_sub_f32_e32 v6, v6, v8
	v_and_b32_e32 v8, 0xffff0000, v3
	v_sub_f32_e32 v7, v7, v8
	v_mul_f32_e32 v6, 0x45000000, v6
	v_mul_f32_e32 v7, 0x45000000, v7
	v_cndmask_b32_e32 v14, v208, v4, vcc
	v_cvt_pk_bf16_f32 v4, v13, v20
	v_cvt_pk_fp8_f32 v12, v6, v7 op_sel:[0,0,1]
	v_lshlrev_b32_e32 v6, 16, v4
	v_and_b32_e32 v7, 0xffff0000, v4
	v_sub_f32_e32 v6, v13, v6
	v_sub_f32_e32 v7, v20, v7
	v_mul_f32_e32 v6, 0x45000000, v6
	v_mul_f32_e32 v7, 0x45000000, v7
	v_mov_b32_e32 v13, v179
	v_cvt_pk_fp8_f32 v13, v6, v7
	v_cndmask_b32_e32 v15, v208, v5, vcc
	v_cvt_pk_bf16_f32 v5, v14, v15
	global_store_dwordx4 v[18:19], v[2:5], off offset:256 sc1
	v_lshlrev_b32_e32 v6, 16, v5
	v_and_b32_e32 v7, 0xffff0000, v5
	v_sub_f32_e32 v6, v14, v6
	v_sub_f32_e32 v7, v15, v7
	v_mul_f32_e32 v6, 0x45000000, v6
	v_mul_f32_e32 v7, 0x45000000, v7
	v_cvt_pk_fp8_f32 v13, v6, v7 op_sel:[0,0,1]
	v_lshl_add_u64 v[2:3], s[18:19], 0, v[16:17]
	v_lshl_add_u64 v[2:3], v[2:3], 0, v[162:163]
	global_store_dwordx4 v[2:3], v[10:13], off sc1

.LBB0_865:
	s_or_b64 exec, exec, s[0:1]
	v_lshl_or_b32 v164, s10, 6, v169
	s_waitcnt lgkmcnt(0)
	s_barrier
	v_lshl_add_u32 v169, v168, 3, 0
	ds_read_b64 v[172:173], v169 offset:8192
	s_add_u32 s0, s74, s24
	s_addc_u32 s1, s75, s25
	v_add_u32_e32 v166, s12, v168
	s_add_u32 s0, s0, 0x9c00000
	s_waitcnt lgkmcnt(0)
	v_sub_f32_e32 v161, v161, v172
	v_sub_f32_e32 v160, v160, v172
	v_sub_f32_e32 v155, v155, v172
	v_sub_f32_e32 v154, v154, v172
	v_ashrrev_i32_e32 v167, 31, v166
	v_sub_f32_e32 v159, v159, v172
	v_sub_f32_e32 v158, v158, v172
	v_pk_mul_f32 v[160:161], v[172:173], v[160:161] op_sel:[1,0]
	v_sub_f32_e32 v157, v157, v172
	v_sub_f32_e32 v156, v156, v172
	v_pk_mul_f32 v[154:155], v[172:173], v[154:155] op_sel:[1,0]
	s_addc_u32 s1, s1, 0
	v_lshlrev_b64 v[174:175], 11, v[166:167]
	v_pk_mul_f32 v[158:159], v[172:173], v[158:159] op_sel:[1,0]
	s_waitcnt vmcnt(4)
	v_pk_fma_f32 v[160:161], v[52:53], v[160:161], v[56:57]
	v_pk_mul_f32 v[156:157], v[172:173], v[156:157] op_sel:[1,0]
	v_pk_fma_f32 v[154:155], v[34:35], v[154:155], v[42:43]
	v_cmp_eq_u32_e32 vcc, 0, v170
	v_pk_fma_f32 v[158:159], v[50:51], v[158:159], v[54:55]
	v_pk_fma_f32 v[156:157], v[36:37], v[156:157], v[44:45]
	v_cndmask_b32_e32 v167, v208, v160, vcc
	v_cndmask_b32_e32 v168, v208, v161, vcc
	v_cndmask_b32_e32 v178, v208, v154, vcc
	v_cndmask_b32_e32 v185, v208, v155, vcc
	v_lshl_add_u64 v[160:161], s[0:1], 0, v[174:175]
	v_lshlrev_b64 v[154:155], 1, v[162:163]
	v_cndmask_b32_e32 v170, v208, v158, vcc
	v_cndmask_b32_e32 v171, v208, v159, vcc
	v_cndmask_b32_e32 v176, v208, v156, vcc
	v_cvt_pk_bf16_f32 v156, v170, v171
	v_lshl_add_u64 v[160:161], v[160:161], 0, v[154:155]
	v_cndmask_b32_e32 v177, v208, v157, vcc
	v_cvt_pk_bf16_f32 v157, v167, v168
	v_cvt_pk_bf16_f32 v158, v178, v185
	v_cvt_pk_bf16_f32 v159, v176, v177
	global_store_dwordx4 v[160:161], v[156:159], off sc1
	v_lshlrev_b32_e32 v162, 16, v156
	v_sub_f32_e32 v162, v170, v162
	v_and_b32_e32 v156, 0xffff0000, v156
	v_sub_f32_e32 v156, v171, v156
	v_mul_f32_e32 v162, 0x45000000, v162
	v_mul_f32_e32 v163, 0x45000000, v156
	v_mov_b32_e32 v156, v179
	v_cvt_pk_fp8_f32 v156, v162, v163
	v_lshlrev_b32_e32 v162, 16, v157
	v_and_b32_e32 v157, 0xffff0000, v157
	v_sub_f32_e32 v162, v167, v162
	v_sub_f32_e32 v157, v168, v157
	v_mul_f32_e32 v162, 0x45000000, v162
	v_mul_f32_e32 v157, 0x45000000, v157
	v_cvt_pk_fp8_f32 v156, v162, v157 op_sel:[0,0,1]
	v_lshlrev_b32_e32 v157, 16, v158
	v_sub_f32_e32 v157, v178, v157
	v_mul_f32_e32 v162, 0x45000000, v157
	v_and_b32_e32 v157, 0xffff0000, v158
	v_sub_f32_e32 v157, v185, v157
	v_mul_f32_e32 v158, 0x45000000, v157
	v_mov_b32_e32 v157, v179
	v_cvt_pk_fp8_f32 v157, v162, v158
	v_lshlrev_b32_e32 v158, 16, v159
	v_and_b32_e32 v159, 0xffff0000, v159
	v_sub_f32_e32 v151, v151, v172
	v_sub_f32_e32 v150, v150, v172
	v_sub_f32_e32 v147, v147, v172
	v_sub_f32_e32 v146, v146, v172
	v_sub_f32_e32 v158, v176, v158
	v_sub_f32_e32 v159, v177, v159
	v_pk_mul_f32 v[150:151], v[172:173], v[150:151] op_sel:[1,0]
	v_pk_mul_f32 v[146:147], v[172:173], v[146:147] op_sel:[1,0]
	v_mul_f32_e32 v158, 0x45000000, v158
	v_mul_f32_e32 v159, 0x45000000, v159
	s_waitcnt vmcnt(1)
	v_pk_fma_f32 v[150:151], v[18:19], v[150:151], v[22:23]
	v_pk_fma_f32 v[146:147], v[2:3], v[146:147], v[10:11]
	v_cvt_pk_fp8_f32 v157, v158, v159 op_sel:[0,0,1]
	v_cndmask_b32_e32 v150, v208, v150, vcc
	v_cndmask_b32_e32 v151, v208, v151, vcc
	v_cndmask_b32_e32 v159, v208, v146, vcc
	v_cvt_pk_bf16_f32 v146, v150, v151
	v_sub_f32_e32 v153, v153, v172
	v_lshlrev_b32_e32 v158, 16, v146
	v_sub_f32_e32 v150, v150, v158
	v_and_b32_e32 v158, 0xffff0000, v146
	v_sub_f32_e32 v152, v152, v172
	v_sub_f32_e32 v151, v151, v158
	v_pk_mul_f32 v[152:153], v[172:173], v[152:153] op_sel:[1,0]
	v_mul_f32_e32 v150, 0x45000000, v150
	v_mul_f32_e32 v151, 0x45000000, v151
	v_mov_b32_e32 v158, v179
	v_pk_fma_f32 v[152:153], v[20:21], v[152:153], v[24:25]
	v_cvt_pk_fp8_f32 v158, v150, v151
	v_sub_f32_e32 v149, v149, v172
	v_sub_f32_e32 v148, v148, v172
	v_cndmask_b32_e32 v152, v208, v152, vcc
	v_cndmask_b32_e32 v153, v208, v153, vcc
	v_cndmask_b32_e32 v167, v208, v147, vcc
	v_cvt_pk_bf16_f32 v147, v152, v153
	v_pk_mul_f32 v[148:149], v[172:173], v[148:149] op_sel:[1,0]
	v_lshlrev_b32_e32 v150, 16, v147
	v_and_b32_e32 v151, 0xffff0000, v147
	v_sub_f32_e32 v150, v152, v150
	v_sub_f32_e32 v151, v153, v151
	v_pk_fma_f32 v[148:149], v[4:5], v[148:149], v[12:13]
	v_mul_f32_e32 v150, 0x45000000, v150
	v_mul_f32_e32 v151, 0x45000000, v151
	v_cndmask_b32_e32 v162, v208, v148, vcc
	v_cvt_pk_bf16_f32 v148, v159, v167
	v_cvt_pk_fp8_f32 v158, v150, v151 op_sel:[0,0,1]
	v_lshlrev_b32_e32 v150, 16, v148
	v_and_b32_e32 v151, 0xffff0000, v148
	v_sub_f32_e32 v150, v159, v150
	v_sub_f32_e32 v151, v167, v151
	v_mul_f32_e32 v150, 0x45000000, v150
	v_mul_f32_e32 v151, 0x45000000, v151
	v_mov_b32_e32 v159, v179
	v_cvt_pk_fp8_f32 v159, v150, v151
	v_cndmask_b32_e32 v163, v208, v149, vcc
	v_cvt_pk_bf16_f32 v149, v162, v163
	v_or_b32_e32 v164, s28, v164
	v_lshlrev_b32_e32 v150, 16, v149
	v_and_b32_e32 v151, 0xffff0000, v149
	v_sub_f32_e32 v150, v162, v150
	v_sub_f32_e32 v151, v163, v151
	v_mul_f32_e32 v150, 0x45000000, v150
	v_mul_f32_e32 v151, 0x45000000, v151
	v_cvt_pk_fp8_f32 v159, v150, v151 op_sel:[0,0,1]
	v_ashrrev_i32_e32 v165, 31, v164
	global_store_dwordx4 v[160:161], v[146:149], off offset:256 sc1
	s_nop 1
	v_lshl_add_u64 v[146:147], s[18:19], 0, v[174:175]
	v_lshl_add_u64 v[146:147], v[146:147], 0, v[164:165]
	global_store_dwordx4 v[146:147], v[156:159], off sc1
	ds_read_b64 v[146:147], v169 offset:8320
	v_add_u32_e32 v148, 16, v166
	v_ashrrev_i32_e32 v149, 31, v148
	v_lshlrev_b64 v[148:149], 11, v[148:149]
	s_waitcnt lgkmcnt(0)
	v_sub_f32_e32 v143, v143, v146
	v_sub_f32_e32 v142, v142, v146
	v_pk_mul_f32 v[142:143], v[146:147], v[142:143] op_sel:[1,0]
	v_sub_f32_e32 v139, v139, v146
	v_sub_f32_e32 v138, v138, v146
	v_sub_f32_e32 v145, v145, v146
	v_sub_f32_e32 v144, v144, v146
	v_pk_fma_f32 v[142:143], v[50:51], v[142:143], v[54:55]
	v_sub_f32_e32 v141, v141, v146
	v_sub_f32_e32 v140, v140, v146
	v_pk_mul_f32 v[138:139], v[146:147], v[138:139] op_sel:[1,0]
	v_pk_mul_f32 v[144:145], v[146:147], v[144:145] op_sel:[1,0]
	v_pk_mul_f32 v[140:141], v[146:147], v[140:141] op_sel:[1,0]
	v_pk_fma_f32 v[138:139], v[34:35], v[138:139], v[42:43]
	v_cndmask_b32_e32 v150, v208, v142, vcc
	v_cndmask_b32_e32 v151, v208, v143, vcc
	v_lshl_add_u64 v[142:143], s[0:1], 0, v[148:149]
	v_pk_fma_f32 v[144:145], v[52:53], v[144:145], v[56:57]
	v_pk_fma_f32 v[140:141], v[36:37], v[140:141], v[44:45]
	v_cndmask_b32_e32 v156, v208, v138, vcc
	v_cvt_pk_bf16_f32 v138, v150, v151
	v_lshl_add_u64 v[142:143], v[142:143], 0, v[154:155]
	v_cndmask_b32_e32 v144, v208, v144, vcc
	v_cndmask_b32_e32 v145, v208, v145, vcc
	v_cndmask_b32_e32 v152, v208, v140, vcc
	v_cndmask_b32_e32 v153, v208, v141, vcc
	v_cndmask_b32_e32 v157, v208, v139, vcc
	v_cvt_pk_bf16_f32 v139, v144, v145
	v_cvt_pk_bf16_f32 v140, v156, v157
	v_cvt_pk_bf16_f32 v141, v152, v153
	global_store_dwordx4 v[142:143], v[138:141], off sc1
	v_lshlrev_b32_e32 v158, 16, v138
	v_sub_f32_e32 v150, v150, v158
	v_and_b32_e32 v138, 0xffff0000, v138
	v_sub_f32_e32 v138, v151, v138
	v_mul_f32_e32 v150, 0x45000000, v150
	v_mul_f32_e32 v151, 0x45000000, v138
	v_mov_b32_e32 v138, v179
	v_cvt_pk_fp8_f32 v138, v150, v151
	v_lshlrev_b32_e32 v150, 16, v139
	v_and_b32_e32 v139, 0xffff0000, v139
	v_sub_f32_e32 v144, v144, v150
	v_sub_f32_e32 v139, v145, v139
	v_mul_f32_e32 v144, 0x45000000, v144
	v_mul_f32_e32 v139, 0x45000000, v139
	v_cvt_pk_fp8_f32 v138, v144, v139 op_sel:[0,0,1]
	v_lshlrev_b32_e32 v139, 16, v140
	v_sub_f32_e32 v139, v156, v139
	v_mul_f32_e32 v144, 0x45000000, v139
	v_and_b32_e32 v139, 0xffff0000, v140
	v_sub_f32_e32 v139, v157, v139
	v_mul_f32_e32 v140, 0x45000000, v139
	v_mov_b32_e32 v139, v179
	v_cvt_pk_fp8_f32 v139, v144, v140
	v_lshlrev_b32_e32 v140, 16, v141
	v_and_b32_e32 v141, 0xffff0000, v141
	v_sub_f32_e32 v135, v135, v146
	v_sub_f32_e32 v134, v134, v146
	v_sub_f32_e32 v131, v131, v146
	v_sub_f32_e32 v130, v130, v146
	v_sub_f32_e32 v140, v152, v140
	v_sub_f32_e32 v141, v153, v141
	v_pk_mul_f32 v[134:135], v[146:147], v[134:135] op_sel:[1,0]
	v_pk_mul_f32 v[130:131], v[146:147], v[130:131] op_sel:[1,0]
	v_mul_f32_e32 v140, 0x45000000, v140
	v_mul_f32_e32 v141, 0x45000000, v141
	v_pk_fma_f32 v[134:135], v[18:19], v[134:135], v[22:23]
	v_pk_fma_f32 v[130:131], v[2:3], v[130:131], v[10:11]
	v_cvt_pk_fp8_f32 v139, v140, v141 op_sel:[0,0,1]
	v_cndmask_b32_e32 v134, v208, v134, vcc
	v_cndmask_b32_e32 v135, v208, v135, vcc
	v_cndmask_b32_e32 v141, v208, v130, vcc
	v_cvt_pk_bf16_f32 v130, v134, v135
	v_sub_f32_e32 v137, v137, v146
	v_lshlrev_b32_e32 v140, 16, v130
	v_sub_f32_e32 v134, v134, v140
	v_and_b32_e32 v140, 0xffff0000, v130
	v_sub_f32_e32 v136, v136, v146
	v_sub_f32_e32 v135, v135, v140
	v_pk_mul_f32 v[136:137], v[146:147], v[136:137] op_sel:[1,0]
	v_mul_f32_e32 v134, 0x45000000, v134
	v_mul_f32_e32 v135, 0x45000000, v135
	v_mov_b32_e32 v140, v179
	v_pk_fma_f32 v[136:137], v[20:21], v[136:137], v[24:25]
	v_sub_f32_e32 v133, v133, v146
	v_sub_f32_e32 v132, v132, v146
	v_cvt_pk_fp8_f32 v140, v134, v135
	v_pk_mul_f32 v[132:133], v[146:147], v[132:133] op_sel:[1,0]
	v_cndmask_b32_e32 v136, v208, v136, vcc
	v_cndmask_b32_e32 v137, v208, v137, vcc
	v_cndmask_b32_e32 v146, v208, v131, vcc
	v_cvt_pk_bf16_f32 v131, v136, v137
	v_pk_fma_f32 v[132:133], v[4:5], v[132:133], v[12:13]
	v_lshlrev_b32_e32 v134, 16, v131
	v_and_b32_e32 v135, 0xffff0000, v131
	v_sub_f32_e32 v134, v136, v134
	v_sub_f32_e32 v135, v137, v135
	v_mul_f32_e32 v134, 0x45000000, v134
	v_mul_f32_e32 v135, 0x45000000, v135
	v_cndmask_b32_e32 v144, v208, v132, vcc
	v_cvt_pk_bf16_f32 v132, v141, v146
	v_cvt_pk_fp8_f32 v140, v134, v135 op_sel:[0,0,1]
	v_lshlrev_b32_e32 v134, 16, v132
	v_and_b32_e32 v135, 0xffff0000, v132
	v_sub_f32_e32 v134, v141, v134
	v_sub_f32_e32 v135, v146, v135
	v_mul_f32_e32 v134, 0x45000000, v134
	v_mul_f32_e32 v135, 0x45000000, v135
	v_mov_b32_e32 v141, v179
	v_cvt_pk_fp8_f32 v141, v134, v135
	v_cndmask_b32_e32 v145, v208, v133, vcc
	v_cvt_pk_bf16_f32 v133, v144, v145
	global_store_dwordx4 v[142:143], v[130:133], off offset:256 sc1
	v_lshlrev_b32_e32 v134, 16, v133
	v_and_b32_e32 v135, 0xffff0000, v133
	v_sub_f32_e32 v134, v144, v134
	v_sub_f32_e32 v135, v145, v135
	v_mul_f32_e32 v134, 0x45000000, v134
	v_mul_f32_e32 v135, 0x45000000, v135
	v_cvt_pk_fp8_f32 v141, v134, v135 op_sel:[0,0,1]
	v_lshl_add_u64 v[130:131], s[18:19], 0, v[148:149]
	v_lshl_add_u64 v[130:131], v[130:131], 0, v[164:165]
	v_add_u32_e32 v132, 32, v166
	global_store_dwordx4 v[130:131], v[138:141], off sc1
	ds_read_b64 v[130:131], v169 offset:8448
	v_ashrrev_i32_e32 v133, 31, v132
	v_lshlrev_b64 v[132:133], 11, v[132:133]
	s_waitcnt lgkmcnt(0)
	v_sub_f32_e32 v127, v127, v130
	v_sub_f32_e32 v126, v126, v130
	v_pk_mul_f32 v[126:127], v[130:131], v[126:127] op_sel:[1,0]
	v_sub_f32_e32 v123, v123, v130
	v_sub_f32_e32 v122, v122, v130
	v_sub_f32_e32 v129, v129, v130
	v_sub_f32_e32 v128, v128, v130
	v_pk_fma_f32 v[126:127], v[50:51], v[126:127], v[54:55]
	v_sub_f32_e32 v125, v125, v130
	v_sub_f32_e32 v124, v124, v130
	v_pk_mul_f32 v[122:123], v[130:131], v[122:123] op_sel:[1,0]
	v_pk_mul_f32 v[128:129], v[130:131], v[128:129] op_sel:[1,0]
	v_pk_mul_f32 v[124:125], v[130:131], v[124:125] op_sel:[1,0]
	v_pk_fma_f32 v[122:123], v[34:35], v[122:123], v[42:43]
	v_cndmask_b32_e32 v134, v208, v126, vcc
	v_cndmask_b32_e32 v135, v208, v127, vcc
	v_lshl_add_u64 v[126:127], s[0:1], 0, v[132:133]
	v_pk_fma_f32 v[128:129], v[52:53], v[128:129], v[56:57]
	v_pk_fma_f32 v[124:125], v[36:37], v[124:125], v[44:45]
	v_cndmask_b32_e32 v138, v208, v122, vcc
	v_cvt_pk_bf16_f32 v122, v134, v135
	v_lshl_add_u64 v[126:127], v[126:127], 0, v[154:155]
	v_cndmask_b32_e32 v128, v208, v128, vcc
	v_cndmask_b32_e32 v129, v208, v129, vcc
	v_cndmask_b32_e32 v136, v208, v124, vcc
	v_cndmask_b32_e32 v137, v208, v125, vcc
	v_cndmask_b32_e32 v139, v208, v123, vcc
	v_cvt_pk_bf16_f32 v123, v128, v129
	v_cvt_pk_bf16_f32 v124, v138, v139
	v_cvt_pk_bf16_f32 v125, v136, v137
	global_store_dwordx4 v[126:127], v[122:125], off sc1
	v_lshlrev_b32_e32 v140, 16, v122
	v_sub_f32_e32 v134, v134, v140
	v_and_b32_e32 v122, 0xffff0000, v122
	v_sub_f32_e32 v122, v135, v122
	v_mul_f32_e32 v134, 0x45000000, v134
	v_mul_f32_e32 v135, 0x45000000, v122
	v_mov_b32_e32 v122, v179
	v_cvt_pk_fp8_f32 v122, v134, v135
	v_lshlrev_b32_e32 v134, 16, v123
	v_and_b32_e32 v123, 0xffff0000, v123
	v_sub_f32_e32 v128, v128, v134
	v_sub_f32_e32 v123, v129, v123
	v_mul_f32_e32 v128, 0x45000000, v128
	v_mul_f32_e32 v123, 0x45000000, v123
	v_cvt_pk_fp8_f32 v122, v128, v123 op_sel:[0,0,1]
	v_lshlrev_b32_e32 v123, 16, v124
	v_sub_f32_e32 v123, v138, v123
	v_mul_f32_e32 v128, 0x45000000, v123
	v_and_b32_e32 v123, 0xffff0000, v124
	v_sub_f32_e32 v123, v139, v123
	v_mul_f32_e32 v124, 0x45000000, v123
	v_mov_b32_e32 v123, v179
	v_cvt_pk_fp8_f32 v123, v128, v124
	v_lshlrev_b32_e32 v124, 16, v125
	v_and_b32_e32 v125, 0xffff0000, v125
	v_sub_f32_e32 v119, v119, v130
	v_sub_f32_e32 v118, v118, v130
	v_sub_f32_e32 v115, v115, v130
	v_sub_f32_e32 v114, v114, v130
	v_sub_f32_e32 v124, v136, v124
	v_sub_f32_e32 v125, v137, v125
	v_pk_mul_f32 v[118:119], v[130:131], v[118:119] op_sel:[1,0]
	v_pk_mul_f32 v[114:115], v[130:131], v[114:115] op_sel:[1,0]
	v_mul_f32_e32 v124, 0x45000000, v124
	v_mul_f32_e32 v125, 0x45000000, v125
	v_pk_fma_f32 v[118:119], v[18:19], v[118:119], v[22:23]
	v_pk_fma_f32 v[114:115], v[2:3], v[114:115], v[10:11]
	v_cvt_pk_fp8_f32 v123, v124, v125 op_sel:[0,0,1]
	v_cndmask_b32_e32 v118, v208, v118, vcc
	v_cndmask_b32_e32 v119, v208, v119, vcc
	v_cndmask_b32_e32 v125, v208, v114, vcc
	v_cvt_pk_bf16_f32 v114, v118, v119
	v_sub_f32_e32 v121, v121, v130
	v_lshlrev_b32_e32 v124, 16, v114
	v_sub_f32_e32 v118, v118, v124
	v_and_b32_e32 v124, 0xffff0000, v114
	v_sub_f32_e32 v120, v120, v130
	v_sub_f32_e32 v119, v119, v124
	v_pk_mul_f32 v[120:121], v[130:131], v[120:121] op_sel:[1,0]
	v_mul_f32_e32 v118, 0x45000000, v118
	v_mul_f32_e32 v119, 0x45000000, v119
	v_mov_b32_e32 v124, v179
	v_pk_fma_f32 v[120:121], v[20:21], v[120:121], v[24:25]
	v_sub_f32_e32 v117, v117, v130
	v_sub_f32_e32 v116, v116, v130
	v_cvt_pk_fp8_f32 v124, v118, v119
	v_pk_mul_f32 v[116:117], v[130:131], v[116:117] op_sel:[1,0]
	v_cndmask_b32_e32 v120, v208, v120, vcc
	v_cndmask_b32_e32 v121, v208, v121, vcc
	v_cndmask_b32_e32 v130, v208, v115, vcc
	v_cvt_pk_bf16_f32 v115, v120, v121
	v_pk_fma_f32 v[116:117], v[4:5], v[116:117], v[12:13]
	v_lshlrev_b32_e32 v118, 16, v115
	v_and_b32_e32 v119, 0xffff0000, v115
	v_sub_f32_e32 v118, v120, v118
	v_sub_f32_e32 v119, v121, v119
	v_mul_f32_e32 v118, 0x45000000, v118
	v_mul_f32_e32 v119, 0x45000000, v119
	v_cndmask_b32_e32 v128, v208, v116, vcc
	v_cvt_pk_bf16_f32 v116, v125, v130
	v_cvt_pk_fp8_f32 v124, v118, v119 op_sel:[0,0,1]
	v_lshlrev_b32_e32 v118, 16, v116
	v_and_b32_e32 v119, 0xffff0000, v116
	v_sub_f32_e32 v118, v125, v118
	v_sub_f32_e32 v119, v130, v119
	v_mul_f32_e32 v118, 0x45000000, v118
	v_mul_f32_e32 v119, 0x45000000, v119
	v_mov_b32_e32 v125, v179
	v_cvt_pk_fp8_f32 v125, v118, v119
	v_cndmask_b32_e32 v129, v208, v117, vcc
	v_cvt_pk_bf16_f32 v117, v128, v129
	global_store_dwordx4 v[126:127], v[114:117], off offset:256 sc1
	v_lshlrev_b32_e32 v118, 16, v117
	v_and_b32_e32 v119, 0xffff0000, v117
	v_sub_f32_e32 v118, v128, v118
	v_sub_f32_e32 v119, v129, v119
	v_mul_f32_e32 v118, 0x45000000, v118
	v_mul_f32_e32 v119, 0x45000000, v119
	v_cvt_pk_fp8_f32 v125, v118, v119 op_sel:[0,0,1]
	v_lshl_add_u64 v[114:115], s[18:19], 0, v[132:133]
	v_lshl_add_u64 v[114:115], v[114:115], 0, v[164:165]
	v_add_u32_e32 v116, 48, v166
	global_store_dwordx4 v[114:115], v[122:125], off sc1
	ds_read_b64 v[114:115], v169 offset:8576
	v_ashrrev_i32_e32 v117, 31, v116
	v_lshlrev_b64 v[116:117], 11, v[116:117]
	s_waitcnt lgkmcnt(0)
	v_sub_f32_e32 v111, v111, v114
	v_sub_f32_e32 v110, v110, v114
	v_pk_mul_f32 v[110:111], v[114:115], v[110:111] op_sel:[1,0]
	v_sub_f32_e32 v107, v107, v114
	v_sub_f32_e32 v106, v106, v114
	v_sub_f32_e32 v113, v113, v114
	v_sub_f32_e32 v112, v112, v114
	v_pk_fma_f32 v[110:111], v[50:51], v[110:111], v[54:55]
	v_sub_f32_e32 v109, v109, v114
	v_sub_f32_e32 v108, v108, v114
	v_pk_mul_f32 v[106:107], v[114:115], v[106:107] op_sel:[1,0]
	v_pk_mul_f32 v[112:113], v[114:115], v[112:113] op_sel:[1,0]
	v_pk_mul_f32 v[108:109], v[114:115], v[108:109] op_sel:[1,0]
	v_pk_fma_f32 v[106:107], v[34:35], v[106:107], v[42:43]
	v_cndmask_b32_e32 v118, v208, v110, vcc
	v_cndmask_b32_e32 v119, v208, v111, vcc
	v_lshl_add_u64 v[110:111], s[0:1], 0, v[116:117]
	v_pk_fma_f32 v[112:113], v[52:53], v[112:113], v[56:57]
	v_pk_fma_f32 v[108:109], v[36:37], v[108:109], v[44:45]
	v_cndmask_b32_e32 v122, v208, v106, vcc
	v_cvt_pk_bf16_f32 v106, v118, v119
	v_lshl_add_u64 v[110:111], v[110:111], 0, v[154:155]
	v_cndmask_b32_e32 v112, v208, v112, vcc
	v_cndmask_b32_e32 v113, v208, v113, vcc
	v_cndmask_b32_e32 v120, v208, v108, vcc
	v_cndmask_b32_e32 v121, v208, v109, vcc
	v_cndmask_b32_e32 v123, v208, v107, vcc
	v_cvt_pk_bf16_f32 v107, v112, v113
	v_cvt_pk_bf16_f32 v108, v122, v123
	v_cvt_pk_bf16_f32 v109, v120, v121
	global_store_dwordx4 v[110:111], v[106:109], off sc1
	v_lshlrev_b32_e32 v124, 16, v106
	v_sub_f32_e32 v118, v118, v124
	v_and_b32_e32 v106, 0xffff0000, v106
	v_sub_f32_e32 v106, v119, v106
	v_mul_f32_e32 v118, 0x45000000, v118
	v_mul_f32_e32 v119, 0x45000000, v106
	v_mov_b32_e32 v106, v179
	v_cvt_pk_fp8_f32 v106, v118, v119
	v_lshlrev_b32_e32 v118, 16, v107
	v_and_b32_e32 v107, 0xffff0000, v107
	v_sub_f32_e32 v112, v112, v118
	v_sub_f32_e32 v107, v113, v107
	v_mul_f32_e32 v112, 0x45000000, v112
	v_mul_f32_e32 v107, 0x45000000, v107
	v_cvt_pk_fp8_f32 v106, v112, v107 op_sel:[0,0,1]
	v_lshlrev_b32_e32 v107, 16, v108
	v_sub_f32_e32 v107, v122, v107
	v_mul_f32_e32 v112, 0x45000000, v107
	v_and_b32_e32 v107, 0xffff0000, v108
	v_sub_f32_e32 v107, v123, v107
	v_mul_f32_e32 v108, 0x45000000, v107
	v_mov_b32_e32 v107, v179
	v_cvt_pk_fp8_f32 v107, v112, v108
	v_lshlrev_b32_e32 v108, 16, v109
	v_and_b32_e32 v109, 0xffff0000, v109
	v_sub_f32_e32 v103, v103, v114
	v_sub_f32_e32 v102, v102, v114
	v_sub_f32_e32 v99, v99, v114
	v_sub_f32_e32 v98, v98, v114
	v_sub_f32_e32 v108, v120, v108
	v_sub_f32_e32 v109, v121, v109
	v_pk_mul_f32 v[102:103], v[114:115], v[102:103] op_sel:[1,0]
	v_pk_mul_f32 v[98:99], v[114:115], v[98:99] op_sel:[1,0]
	v_mul_f32_e32 v108, 0x45000000, v108
	v_mul_f32_e32 v109, 0x45000000, v109
	v_pk_fma_f32 v[102:103], v[18:19], v[102:103], v[22:23]
	v_pk_fma_f32 v[98:99], v[2:3], v[98:99], v[10:11]
	v_cvt_pk_fp8_f32 v107, v108, v109 op_sel:[0,0,1]
	v_cndmask_b32_e32 v102, v208, v102, vcc
	v_cndmask_b32_e32 v103, v208, v103, vcc
	v_cndmask_b32_e32 v109, v208, v98, vcc
	v_cvt_pk_bf16_f32 v98, v102, v103
	v_sub_f32_e32 v105, v105, v114
	v_lshlrev_b32_e32 v108, 16, v98
	v_sub_f32_e32 v102, v102, v108
	v_and_b32_e32 v108, 0xffff0000, v98
	v_sub_f32_e32 v104, v104, v114
	v_sub_f32_e32 v103, v103, v108
	v_pk_mul_f32 v[104:105], v[114:115], v[104:105] op_sel:[1,0]
	v_mul_f32_e32 v102, 0x45000000, v102
	v_mul_f32_e32 v103, 0x45000000, v103
	v_mov_b32_e32 v108, v179
	v_pk_fma_f32 v[104:105], v[20:21], v[104:105], v[24:25]
	v_sub_f32_e32 v101, v101, v114
	v_sub_f32_e32 v100, v100, v114
	v_cvt_pk_fp8_f32 v108, v102, v103
	v_pk_mul_f32 v[100:101], v[114:115], v[100:101] op_sel:[1,0]
	v_cndmask_b32_e32 v104, v208, v104, vcc
	v_cndmask_b32_e32 v105, v208, v105, vcc
	v_cndmask_b32_e32 v114, v208, v99, vcc
	v_cvt_pk_bf16_f32 v99, v104, v105
	v_pk_fma_f32 v[100:101], v[4:5], v[100:101], v[12:13]
	v_lshlrev_b32_e32 v102, 16, v99
	v_and_b32_e32 v103, 0xffff0000, v99
	v_sub_f32_e32 v102, v104, v102
	v_sub_f32_e32 v103, v105, v103
	v_mul_f32_e32 v102, 0x45000000, v102
	v_mul_f32_e32 v103, 0x45000000, v103
	v_cndmask_b32_e32 v112, v208, v100, vcc
	v_cvt_pk_bf16_f32 v100, v109, v114
	v_cvt_pk_fp8_f32 v108, v102, v103 op_sel:[0,0,1]
	v_lshlrev_b32_e32 v102, 16, v100
	v_and_b32_e32 v103, 0xffff0000, v100
	v_sub_f32_e32 v102, v109, v102
	v_sub_f32_e32 v103, v114, v103
	v_mul_f32_e32 v102, 0x45000000, v102
	v_mul_f32_e32 v103, 0x45000000, v103
	v_mov_b32_e32 v109, v179
	v_cvt_pk_fp8_f32 v109, v102, v103
	v_cndmask_b32_e32 v113, v208, v101, vcc
	v_cvt_pk_bf16_f32 v101, v112, v113
	global_store_dwordx4 v[110:111], v[98:101], off offset:256 sc1
	v_lshlrev_b32_e32 v102, 16, v101
	v_and_b32_e32 v103, 0xffff0000, v101
	v_sub_f32_e32 v102, v112, v102
	v_sub_f32_e32 v103, v113, v103
	v_mul_f32_e32 v102, 0x45000000, v102
	v_mul_f32_e32 v103, 0x45000000, v103
	v_cvt_pk_fp8_f32 v109, v102, v103 op_sel:[0,0,1]
	v_lshl_add_u64 v[98:99], s[18:19], 0, v[116:117]
	v_lshl_add_u64 v[98:99], v[98:99], 0, v[164:165]
	v_add_u32_e32 v100, 0x80, v166
	global_store_dwordx4 v[98:99], v[106:109], off sc1
	ds_read_b64 v[98:99], v169 offset:9216
	v_ashrrev_i32_e32 v101, 31, v100
	v_lshlrev_b64 v[100:101], 11, v[100:101]
	s_waitcnt lgkmcnt(0)
	v_sub_f32_e32 v95, v95, v98
	v_sub_f32_e32 v94, v94, v98
	v_pk_mul_f32 v[94:95], v[98:99], v[94:95] op_sel:[1,0]
	v_sub_f32_e32 v91, v91, v98
	v_sub_f32_e32 v90, v90, v98
	v_sub_f32_e32 v97, v97, v98
	v_sub_f32_e32 v96, v96, v98
	v_pk_fma_f32 v[94:95], v[50:51], v[94:95], v[54:55]
	v_sub_f32_e32 v93, v93, v98
	v_sub_f32_e32 v92, v92, v98
	v_pk_mul_f32 v[90:91], v[98:99], v[90:91] op_sel:[1,0]
	v_pk_mul_f32 v[96:97], v[98:99], v[96:97] op_sel:[1,0]
	v_pk_mul_f32 v[92:93], v[98:99], v[92:93] op_sel:[1,0]
	v_pk_fma_f32 v[90:91], v[34:35], v[90:91], v[42:43]
	v_cndmask_b32_e32 v102, v208, v94, vcc
	v_cndmask_b32_e32 v103, v208, v95, vcc
	v_lshl_add_u64 v[94:95], s[0:1], 0, v[100:101]
	v_pk_fma_f32 v[96:97], v[52:53], v[96:97], v[56:57]
	v_pk_fma_f32 v[92:93], v[36:37], v[92:93], v[44:45]
	v_cndmask_b32_e32 v106, v208, v90, vcc
	v_cvt_pk_bf16_f32 v90, v102, v103
	v_lshl_add_u64 v[94:95], v[94:95], 0, v[154:155]
	v_cndmask_b32_e32 v96, v208, v96, vcc
	v_cndmask_b32_e32 v97, v208, v97, vcc
	v_cndmask_b32_e32 v104, v208, v92, vcc
	v_cndmask_b32_e32 v105, v208, v93, vcc
	v_cndmask_b32_e32 v107, v208, v91, vcc
	v_cvt_pk_bf16_f32 v91, v96, v97
	v_cvt_pk_bf16_f32 v92, v106, v107
	v_cvt_pk_bf16_f32 v93, v104, v105
	global_store_dwordx4 v[94:95], v[90:93], off sc1
	v_lshlrev_b32_e32 v108, 16, v90
	v_sub_f32_e32 v102, v102, v108
	v_and_b32_e32 v90, 0xffff0000, v90
	v_sub_f32_e32 v90, v103, v90
	v_mul_f32_e32 v102, 0x45000000, v102
	v_mul_f32_e32 v103, 0x45000000, v90
	v_mov_b32_e32 v90, v179
	v_cvt_pk_fp8_f32 v90, v102, v103
	v_lshlrev_b32_e32 v102, 16, v91
	v_and_b32_e32 v91, 0xffff0000, v91
	v_sub_f32_e32 v96, v96, v102
	v_sub_f32_e32 v91, v97, v91
	v_mul_f32_e32 v96, 0x45000000, v96
	v_mul_f32_e32 v91, 0x45000000, v91
	v_cvt_pk_fp8_f32 v90, v96, v91 op_sel:[0,0,1]
	v_lshlrev_b32_e32 v91, 16, v92
	v_sub_f32_e32 v91, v106, v91
	v_mul_f32_e32 v96, 0x45000000, v91
	v_and_b32_e32 v91, 0xffff0000, v92
	v_sub_f32_e32 v91, v107, v91
	v_mul_f32_e32 v92, 0x45000000, v91
	v_mov_b32_e32 v91, v179
	v_cvt_pk_fp8_f32 v91, v96, v92
	v_lshlrev_b32_e32 v92, 16, v93
	v_and_b32_e32 v93, 0xffff0000, v93
	v_sub_f32_e32 v87, v87, v98
	v_sub_f32_e32 v86, v86, v98
	v_sub_f32_e32 v83, v83, v98
	v_sub_f32_e32 v82, v82, v98
	v_sub_f32_e32 v92, v104, v92
	v_sub_f32_e32 v93, v105, v93
	v_pk_mul_f32 v[86:87], v[98:99], v[86:87] op_sel:[1,0]
	v_pk_mul_f32 v[82:83], v[98:99], v[82:83] op_sel:[1,0]
	v_mul_f32_e32 v92, 0x45000000, v92
	v_mul_f32_e32 v93, 0x45000000, v93
	v_pk_fma_f32 v[86:87], v[18:19], v[86:87], v[22:23]
	v_pk_fma_f32 v[82:83], v[2:3], v[82:83], v[10:11]
	v_cvt_pk_fp8_f32 v91, v92, v93 op_sel:[0,0,1]
	v_cndmask_b32_e32 v86, v208, v86, vcc
	v_cndmask_b32_e32 v87, v208, v87, vcc
	v_cndmask_b32_e32 v93, v208, v82, vcc
	v_cvt_pk_bf16_f32 v82, v86, v87
	v_sub_f32_e32 v89, v89, v98
	v_lshlrev_b32_e32 v92, 16, v82
	v_sub_f32_e32 v86, v86, v92
	v_and_b32_e32 v92, 0xffff0000, v82
	v_sub_f32_e32 v88, v88, v98
	v_sub_f32_e32 v87, v87, v92
	v_pk_mul_f32 v[88:89], v[98:99], v[88:89] op_sel:[1,0]
	v_mul_f32_e32 v86, 0x45000000, v86
	v_mul_f32_e32 v87, 0x45000000, v87
	v_mov_b32_e32 v92, v179
	v_pk_fma_f32 v[88:89], v[20:21], v[88:89], v[24:25]
	v_sub_f32_e32 v85, v85, v98
	v_sub_f32_e32 v84, v84, v98
	v_cvt_pk_fp8_f32 v92, v86, v87
	v_pk_mul_f32 v[84:85], v[98:99], v[84:85] op_sel:[1,0]
	v_cndmask_b32_e32 v88, v208, v88, vcc
	v_cndmask_b32_e32 v89, v208, v89, vcc
	v_cndmask_b32_e32 v98, v208, v83, vcc
	v_cvt_pk_bf16_f32 v83, v88, v89
	v_pk_fma_f32 v[84:85], v[4:5], v[84:85], v[12:13]
	v_lshlrev_b32_e32 v86, 16, v83
	v_and_b32_e32 v87, 0xffff0000, v83
	v_sub_f32_e32 v86, v88, v86
	v_sub_f32_e32 v87, v89, v87
	v_mul_f32_e32 v86, 0x45000000, v86
	v_mul_f32_e32 v87, 0x45000000, v87
	v_cndmask_b32_e32 v96, v208, v84, vcc
	v_cvt_pk_bf16_f32 v84, v93, v98
	v_cvt_pk_fp8_f32 v92, v86, v87 op_sel:[0,0,1]
	v_lshlrev_b32_e32 v86, 16, v84
	v_and_b32_e32 v87, 0xffff0000, v84
	v_sub_f32_e32 v86, v93, v86
	v_sub_f32_e32 v87, v98, v87
	v_mul_f32_e32 v86, 0x45000000, v86
	v_mul_f32_e32 v87, 0x45000000, v87
	v_mov_b32_e32 v93, v179
	v_cvt_pk_fp8_f32 v93, v86, v87
	v_cndmask_b32_e32 v97, v208, v85, vcc
	v_cvt_pk_bf16_f32 v85, v96, v97
	global_store_dwordx4 v[94:95], v[82:85], off offset:256 sc1
	v_lshlrev_b32_e32 v86, 16, v85
	v_and_b32_e32 v87, 0xffff0000, v85
	v_sub_f32_e32 v86, v96, v86
	v_sub_f32_e32 v87, v97, v87
	v_mul_f32_e32 v86, 0x45000000, v86
	v_mul_f32_e32 v87, 0x45000000, v87
	v_cvt_pk_fp8_f32 v93, v86, v87 op_sel:[0,0,1]
	v_lshl_add_u64 v[82:83], s[18:19], 0, v[100:101]
	v_lshl_add_u64 v[82:83], v[82:83], 0, v[164:165]
	v_add_u32_e32 v84, 0x90, v166
	global_store_dwordx4 v[82:83], v[90:93], off sc1
	ds_read_b64 v[82:83], v169 offset:9344
	v_ashrrev_i32_e32 v85, 31, v84
	v_lshlrev_b64 v[84:85], 11, v[84:85]
	s_waitcnt lgkmcnt(0)
	v_sub_f32_e32 v79, v79, v82
	v_sub_f32_e32 v78, v78, v82
	v_pk_mul_f32 v[78:79], v[82:83], v[78:79] op_sel:[1,0]
	v_sub_f32_e32 v75, v75, v82
	v_sub_f32_e32 v74, v74, v82
	v_sub_f32_e32 v81, v81, v82
	v_sub_f32_e32 v80, v80, v82
	v_pk_fma_f32 v[78:79], v[50:51], v[78:79], v[54:55]
	v_sub_f32_e32 v77, v77, v82
	v_sub_f32_e32 v76, v76, v82
	v_pk_mul_f32 v[74:75], v[82:83], v[74:75] op_sel:[1,0]
	v_pk_mul_f32 v[80:81], v[82:83], v[80:81] op_sel:[1,0]
	v_pk_mul_f32 v[76:77], v[82:83], v[76:77] op_sel:[1,0]
	v_pk_fma_f32 v[74:75], v[34:35], v[74:75], v[42:43]
	v_cndmask_b32_e32 v86, v208, v78, vcc
	v_cndmask_b32_e32 v87, v208, v79, vcc
	v_lshl_add_u64 v[78:79], s[0:1], 0, v[84:85]
	v_pk_fma_f32 v[80:81], v[52:53], v[80:81], v[56:57]
	v_pk_fma_f32 v[76:77], v[36:37], v[76:77], v[44:45]
	v_cndmask_b32_e32 v90, v208, v74, vcc
	v_cvt_pk_bf16_f32 v74, v86, v87
	v_lshl_add_u64 v[78:79], v[78:79], 0, v[154:155]
	v_cndmask_b32_e32 v80, v208, v80, vcc
	v_cndmask_b32_e32 v81, v208, v81, vcc
	v_cndmask_b32_e32 v88, v208, v76, vcc
	v_cndmask_b32_e32 v89, v208, v77, vcc
	v_cndmask_b32_e32 v91, v208, v75, vcc
	v_cvt_pk_bf16_f32 v75, v80, v81
	v_cvt_pk_bf16_f32 v76, v90, v91
	v_cvt_pk_bf16_f32 v77, v88, v89
	global_store_dwordx4 v[78:79], v[74:77], off sc1
	v_lshlrev_b32_e32 v92, 16, v74
	v_sub_f32_e32 v86, v86, v92
	v_and_b32_e32 v74, 0xffff0000, v74
	v_sub_f32_e32 v74, v87, v74
	v_mul_f32_e32 v86, 0x45000000, v86
	v_mul_f32_e32 v87, 0x45000000, v74
	v_mov_b32_e32 v74, v179
	v_cvt_pk_fp8_f32 v74, v86, v87
	v_lshlrev_b32_e32 v86, 16, v75
	v_and_b32_e32 v75, 0xffff0000, v75
	v_sub_f32_e32 v80, v80, v86
	v_sub_f32_e32 v75, v81, v75
	v_mul_f32_e32 v80, 0x45000000, v80
	v_mul_f32_e32 v75, 0x45000000, v75
	v_cvt_pk_fp8_f32 v74, v80, v75 op_sel:[0,0,1]
	v_lshlrev_b32_e32 v75, 16, v76
	v_sub_f32_e32 v75, v90, v75
	v_mul_f32_e32 v80, 0x45000000, v75
	v_and_b32_e32 v75, 0xffff0000, v76
	v_sub_f32_e32 v75, v91, v75
	v_mul_f32_e32 v76, 0x45000000, v75
	v_mov_b32_e32 v75, v179
	v_cvt_pk_fp8_f32 v75, v80, v76
	v_lshlrev_b32_e32 v76, 16, v77
	v_and_b32_e32 v77, 0xffff0000, v77
	v_sub_f32_e32 v71, v71, v82
	v_sub_f32_e32 v70, v70, v82
	v_sub_f32_e32 v67, v67, v82
	v_sub_f32_e32 v66, v66, v82
	v_sub_f32_e32 v76, v88, v76
	v_sub_f32_e32 v77, v89, v77
	v_pk_mul_f32 v[70:71], v[82:83], v[70:71] op_sel:[1,0]
	v_pk_mul_f32 v[66:67], v[82:83], v[66:67] op_sel:[1,0]
	v_mul_f32_e32 v76, 0x45000000, v76
	v_mul_f32_e32 v77, 0x45000000, v77
	v_pk_fma_f32 v[70:71], v[18:19], v[70:71], v[22:23]
	v_pk_fma_f32 v[66:67], v[2:3], v[66:67], v[10:11]
	v_cvt_pk_fp8_f32 v75, v76, v77 op_sel:[0,0,1]
	v_cndmask_b32_e32 v70, v208, v70, vcc
	v_cndmask_b32_e32 v71, v208, v71, vcc
	v_cndmask_b32_e32 v77, v208, v66, vcc
	v_cvt_pk_bf16_f32 v66, v70, v71
	v_sub_f32_e32 v73, v73, v82
	v_lshlrev_b32_e32 v76, 16, v66
	v_sub_f32_e32 v70, v70, v76
	v_and_b32_e32 v76, 0xffff0000, v66
	v_sub_f32_e32 v72, v72, v82
	v_sub_f32_e32 v71, v71, v76
	v_pk_mul_f32 v[72:73], v[82:83], v[72:73] op_sel:[1,0]
	v_mul_f32_e32 v70, 0x45000000, v70
	v_mul_f32_e32 v71, 0x45000000, v71
	v_mov_b32_e32 v76, v179
	v_pk_fma_f32 v[72:73], v[20:21], v[72:73], v[24:25]
	v_sub_f32_e32 v69, v69, v82
	v_sub_f32_e32 v68, v68, v82
	v_cvt_pk_fp8_f32 v76, v70, v71
	v_pk_mul_f32 v[68:69], v[82:83], v[68:69] op_sel:[1,0]
	v_cndmask_b32_e32 v72, v208, v72, vcc
	v_cndmask_b32_e32 v73, v208, v73, vcc
	v_cndmask_b32_e32 v82, v208, v67, vcc
	v_cvt_pk_bf16_f32 v67, v72, v73
	v_pk_fma_f32 v[68:69], v[4:5], v[68:69], v[12:13]
	v_lshlrev_b32_e32 v70, 16, v67
	v_and_b32_e32 v71, 0xffff0000, v67
	v_sub_f32_e32 v70, v72, v70
	v_sub_f32_e32 v71, v73, v71
	v_mul_f32_e32 v70, 0x45000000, v70
	v_mul_f32_e32 v71, 0x45000000, v71
	v_cndmask_b32_e32 v80, v208, v68, vcc
	v_cvt_pk_bf16_f32 v68, v77, v82
	v_cvt_pk_fp8_f32 v76, v70, v71 op_sel:[0,0,1]
	v_lshlrev_b32_e32 v70, 16, v68
	v_and_b32_e32 v71, 0xffff0000, v68
	v_sub_f32_e32 v70, v77, v70
	v_sub_f32_e32 v71, v82, v71
	v_mul_f32_e32 v70, 0x45000000, v70
	v_mul_f32_e32 v71, 0x45000000, v71
	v_mov_b32_e32 v77, v179
	v_cvt_pk_fp8_f32 v77, v70, v71
	v_cndmask_b32_e32 v81, v208, v69, vcc
	v_cvt_pk_bf16_f32 v69, v80, v81
	global_store_dwordx4 v[78:79], v[66:69], off offset:256 sc1
	v_lshlrev_b32_e32 v70, 16, v69
	v_and_b32_e32 v71, 0xffff0000, v69
	v_sub_f32_e32 v70, v80, v70
	v_sub_f32_e32 v71, v81, v71
	v_mul_f32_e32 v70, 0x45000000, v70
	v_mul_f32_e32 v71, 0x45000000, v71
	v_cvt_pk_fp8_f32 v77, v70, v71 op_sel:[0,0,1]
	v_lshl_add_u64 v[66:67], s[18:19], 0, v[84:85]
	v_lshl_add_u64 v[66:67], v[66:67], 0, v[164:165]
	v_add_u32_e32 v68, 0xa0, v166
	global_store_dwordx4 v[66:67], v[74:77], off sc1
	ds_read_b64 v[66:67], v169 offset:9472
	v_ashrrev_i32_e32 v69, 31, v68
	v_lshlrev_b64 v[68:69], 11, v[68:69]
	s_waitcnt lgkmcnt(0)
	v_sub_f32_e32 v63, v63, v66
	v_sub_f32_e32 v62, v62, v66
	v_pk_mul_f32 v[62:63], v[66:67], v[62:63] op_sel:[1,0]
	v_sub_f32_e32 v59, v59, v66
	v_sub_f32_e32 v58, v58, v66
	v_sub_f32_e32 v65, v65, v66
	v_sub_f32_e32 v64, v64, v66
	v_pk_fma_f32 v[62:63], v[50:51], v[62:63], v[54:55]
	v_sub_f32_e32 v61, v61, v66
	v_sub_f32_e32 v60, v60, v66
	v_pk_mul_f32 v[58:59], v[66:67], v[58:59] op_sel:[1,0]
	v_pk_mul_f32 v[64:65], v[66:67], v[64:65] op_sel:[1,0]
	v_pk_mul_f32 v[60:61], v[66:67], v[60:61] op_sel:[1,0]
	v_pk_fma_f32 v[58:59], v[34:35], v[58:59], v[42:43]
	v_cndmask_b32_e32 v70, v208, v62, vcc
	v_cndmask_b32_e32 v71, v208, v63, vcc
	v_lshl_add_u64 v[62:63], s[0:1], 0, v[68:69]
	v_pk_fma_f32 v[64:65], v[52:53], v[64:65], v[56:57]
	v_pk_fma_f32 v[60:61], v[36:37], v[60:61], v[44:45]
	v_cndmask_b32_e32 v74, v208, v58, vcc
	v_cvt_pk_bf16_f32 v58, v70, v71
	v_lshl_add_u64 v[62:63], v[62:63], 0, v[154:155]
	v_cndmask_b32_e32 v64, v208, v64, vcc
	v_cndmask_b32_e32 v65, v208, v65, vcc
	v_cndmask_b32_e32 v72, v208, v60, vcc
	v_cndmask_b32_e32 v73, v208, v61, vcc
	v_cndmask_b32_e32 v75, v208, v59, vcc
	v_cvt_pk_bf16_f32 v59, v64, v65
	v_cvt_pk_bf16_f32 v60, v74, v75
	v_cvt_pk_bf16_f32 v61, v72, v73
	global_store_dwordx4 v[62:63], v[58:61], off sc1
	v_lshlrev_b32_e32 v76, 16, v58
	v_sub_f32_e32 v70, v70, v76
	v_and_b32_e32 v58, 0xffff0000, v58
	v_sub_f32_e32 v58, v71, v58
	v_mul_f32_e32 v70, 0x45000000, v70
	v_mul_f32_e32 v71, 0x45000000, v58
	v_mov_b32_e32 v58, v179
	v_cvt_pk_fp8_f32 v58, v70, v71
	v_lshlrev_b32_e32 v70, 16, v59
	v_and_b32_e32 v59, 0xffff0000, v59
	v_sub_f32_e32 v64, v64, v70
	v_sub_f32_e32 v59, v65, v59
	v_mul_f32_e32 v64, 0x45000000, v64
	v_mul_f32_e32 v59, 0x45000000, v59
	v_cvt_pk_fp8_f32 v58, v64, v59 op_sel:[0,0,1]
	v_lshlrev_b32_e32 v59, 16, v60
	v_sub_f32_e32 v59, v74, v59
	v_mul_f32_e32 v64, 0x45000000, v59
	v_and_b32_e32 v59, 0xffff0000, v60
	v_sub_f32_e32 v59, v75, v59
	v_mul_f32_e32 v60, 0x45000000, v59
	v_mov_b32_e32 v59, v179
	v_cvt_pk_fp8_f32 v59, v64, v60
	v_lshlrev_b32_e32 v60, 16, v61
	v_and_b32_e32 v61, 0xffff0000, v61
	v_sub_f32_e32 v31, v31, v66
	v_sub_f32_e32 v30, v30, v66
	v_sub_f32_e32 v27, v27, v66
	v_sub_f32_e32 v26, v26, v66
	v_sub_f32_e32 v60, v72, v60
	v_sub_f32_e32 v61, v73, v61
	v_pk_mul_f32 v[30:31], v[66:67], v[30:31] op_sel:[1,0]
	v_pk_mul_f32 v[26:27], v[66:67], v[26:27] op_sel:[1,0]
	v_mul_f32_e32 v60, 0x45000000, v60
	v_mul_f32_e32 v61, 0x45000000, v61
	v_pk_fma_f32 v[30:31], v[18:19], v[30:31], v[22:23]
	v_pk_fma_f32 v[26:27], v[2:3], v[26:27], v[10:11]
	v_cvt_pk_fp8_f32 v59, v60, v61 op_sel:[0,0,1]
	v_cndmask_b32_e32 v30, v208, v30, vcc
	v_cndmask_b32_e32 v31, v208, v31, vcc
	v_cndmask_b32_e32 v61, v208, v26, vcc
	v_cvt_pk_bf16_f32 v26, v30, v31
	v_sub_f32_e32 v33, v33, v66
	v_lshlrev_b32_e32 v60, 16, v26
	v_sub_f32_e32 v30, v30, v60
	v_and_b32_e32 v60, 0xffff0000, v26
	v_sub_f32_e32 v32, v32, v66
	v_sub_f32_e32 v31, v31, v60
	v_pk_mul_f32 v[32:33], v[66:67], v[32:33] op_sel:[1,0]
	v_mul_f32_e32 v30, 0x45000000, v30
	v_mul_f32_e32 v31, 0x45000000, v31
	v_mov_b32_e32 v60, v179
	v_pk_fma_f32 v[32:33], v[20:21], v[32:33], v[24:25]
	v_sub_f32_e32 v29, v29, v66
	v_sub_f32_e32 v28, v28, v66
	v_cvt_pk_fp8_f32 v60, v30, v31
	v_pk_mul_f32 v[28:29], v[66:67], v[28:29] op_sel:[1,0]
	v_cndmask_b32_e32 v32, v208, v32, vcc
	v_cndmask_b32_e32 v33, v208, v33, vcc
	v_cndmask_b32_e32 v66, v208, v27, vcc
	v_cvt_pk_bf16_f32 v27, v32, v33
	v_pk_fma_f32 v[28:29], v[4:5], v[28:29], v[12:13]
	v_lshlrev_b32_e32 v30, 16, v27
	v_and_b32_e32 v31, 0xffff0000, v27
	v_sub_f32_e32 v30, v32, v30
	v_sub_f32_e32 v31, v33, v31
	v_mul_f32_e32 v30, 0x45000000, v30
	v_mul_f32_e32 v31, 0x45000000, v31
	v_cndmask_b32_e32 v64, v208, v28, vcc
	v_cvt_pk_bf16_f32 v28, v61, v66
	v_cvt_pk_fp8_f32 v60, v30, v31 op_sel:[0,0,1]
	v_lshlrev_b32_e32 v30, 16, v28
	v_and_b32_e32 v31, 0xffff0000, v28
	v_sub_f32_e32 v30, v61, v30
	v_sub_f32_e32 v31, v66, v31
	v_mul_f32_e32 v30, 0x45000000, v30
	v_mul_f32_e32 v31, 0x45000000, v31
	v_mov_b32_e32 v61, v179
	v_cvt_pk_fp8_f32 v61, v30, v31
	v_cndmask_b32_e32 v65, v208, v29, vcc
	v_cvt_pk_bf16_f32 v29, v64, v65
	global_store_dwordx4 v[62:63], v[26:29], off offset:256 sc1
	v_lshlrev_b32_e32 v30, 16, v29
	v_and_b32_e32 v31, 0xffff0000, v29
	v_sub_f32_e32 v30, v64, v30
	v_sub_f32_e32 v31, v65, v31
	v_mul_f32_e32 v30, 0x45000000, v30
	v_mul_f32_e32 v31, 0x45000000, v31
	v_cvt_pk_fp8_f32 v61, v30, v31 op_sel:[0,0,1]
	v_lshl_add_u64 v[26:27], s[18:19], 0, v[68:69]
	v_lshl_add_u64 v[26:27], v[26:27], 0, v[164:165]
	global_store_dwordx4 v[26:27], v[58:61], off sc1
	ds_read_b64 v[30:31], v169 offset:9600
	v_add_u32_e32 v26, 0xb0, v166
	v_ashrrev_i32_e32 v27, 31, v26
	v_lshlrev_b64 v[32:33], 11, v[26:27]
	s_waitcnt lgkmcnt(0)
	v_sub_f32_e32 v39, v39, v30
	v_sub_f32_e32 v38, v38, v30
	v_sub_f32_e32 v27, v47, v30
	v_sub_f32_e32 v26, v46, v30
	v_pk_mul_f32 v[38:39], v[30:31], v[38:39] op_sel:[1,0]
	v_sub_f32_e32 v29, v49, v30
	v_sub_f32_e32 v28, v48, v30
	v_pk_mul_f32 v[26:27], v[30:31], v[26:27] op_sel:[1,0]
	v_sub_f32_e32 v41, v41, v30
	v_sub_f32_e32 v40, v40, v30
	v_pk_fma_f32 v[34:35], v[34:35], v[38:39], v[42:43]
	v_pk_mul_f32 v[28:29], v[30:31], v[28:29] op_sel:[1,0]
	v_pk_fma_f32 v[26:27], v[50:51], v[26:27], v[54:55]
	v_pk_mul_f32 v[40:41], v[30:31], v[40:41] op_sel:[1,0]
	v_cndmask_b32_e32 v42, v208, v34, vcc
	v_cndmask_b32_e32 v43, v208, v35, vcc
	v_lshl_add_u64 v[34:35], s[0:1], 0, v[32:33]
	v_pk_fma_f32 v[28:29], v[52:53], v[28:29], v[56:57]
	v_pk_fma_f32 v[36:37], v[36:37], v[40:41], v[44:45]
	v_cndmask_b32_e32 v40, v208, v26, vcc
	v_cndmask_b32_e32 v41, v208, v27, vcc
	v_cvt_pk_bf16_f32 v26, v40, v41
	v_lshl_add_u64 v[34:35], v[34:35], 0, v[154:155]
	v_cndmask_b32_e32 v38, v208, v28, vcc
	v_cndmask_b32_e32 v39, v208, v29, vcc
	v_cndmask_b32_e32 v36, v208, v36, vcc
	v_cndmask_b32_e32 v37, v208, v37, vcc
	v_cvt_pk_bf16_f32 v27, v38, v39
	v_cvt_pk_bf16_f32 v28, v42, v43
	v_cvt_pk_bf16_f32 v29, v36, v37
	global_store_dwordx4 v[34:35], v[26:29], off sc1
	v_lshlrev_b32_e32 v44, 16, v26
	v_sub_f32_e32 v40, v40, v44
	v_and_b32_e32 v26, 0xffff0000, v26
	v_sub_f32_e32 v26, v41, v26
	v_mul_f32_e32 v40, 0x45000000, v40
	v_mul_f32_e32 v41, 0x45000000, v26
	v_mov_b32_e32 v26, v179
	v_cvt_pk_fp8_f32 v26, v40, v41
	v_lshlrev_b32_e32 v40, 16, v27
	v_and_b32_e32 v27, 0xffff0000, v27
	v_sub_f32_e32 v38, v38, v40
	v_sub_f32_e32 v27, v39, v27
	v_mul_f32_e32 v38, 0x45000000, v38
	v_mul_f32_e32 v27, 0x45000000, v27
	v_cvt_pk_fp8_f32 v26, v38, v27 op_sel:[0,0,1]
	v_lshlrev_b32_e32 v27, 16, v28
	v_sub_f32_e32 v27, v42, v27
	v_mul_f32_e32 v38, 0x45000000, v27
	v_and_b32_e32 v27, 0xffff0000, v28
	v_sub_f32_e32 v27, v43, v27
	v_sub_f32_e32 v15, v15, v30
	v_sub_f32_e32 v14, v14, v30
	v_sub_f32_e32 v7, v7, v30
	v_sub_f32_e32 v6, v6, v30
	v_mul_f32_e32 v28, 0x45000000, v27
	v_mov_b32_e32 v27, v179
	v_pk_mul_f32 v[14:15], v[30:31], v[14:15] op_sel:[1,0]
	v_sub_f32_e32 v9, v9, v30
	v_sub_f32_e32 v8, v8, v30
	v_pk_mul_f32 v[6:7], v[30:31], v[6:7] op_sel:[1,0]
	v_cvt_pk_fp8_f32 v27, v38, v28
	v_pk_fma_f32 v[14:15], v[18:19], v[14:15], v[22:23]
	v_pk_mul_f32 v[8:9], v[30:31], v[8:9] op_sel:[1,0]
	v_pk_fma_f32 v[2:3], v[2:3], v[6:7], v[10:11]
	v_lshlrev_b32_e32 v28, 16, v29
	v_and_b32_e32 v29, 0xffff0000, v29
	v_pk_fma_f32 v[4:5], v[4:5], v[8:9], v[12:13]
	v_cndmask_b32_e32 v8, v208, v14, vcc
	v_cndmask_b32_e32 v9, v208, v15, vcc
	v_cndmask_b32_e32 v12, v208, v2, vcc
	v_cvt_pk_bf16_f32 v2, v8, v9
	v_sub_f32_e32 v28, v36, v28
	v_lshlrev_b32_e32 v14, 16, v2
	v_sub_f32_e32 v29, v37, v29
	v_sub_f32_e32 v17, v17, v30
	v_sub_f32_e32 v16, v16, v30
	v_sub_f32_e32 v8, v8, v14
	v_and_b32_e32 v14, 0xffff0000, v2
	v_mul_f32_e32 v28, 0x45000000, v28
	v_mul_f32_e32 v29, 0x45000000, v29
	v_pk_mul_f32 v[16:17], v[30:31], v[16:17] op_sel:[1,0]
	v_sub_f32_e32 v9, v9, v14
	v_cvt_pk_fp8_f32 v27, v28, v29 op_sel:[0,0,1]
	v_pk_fma_f32 v[16:17], v[20:21], v[16:17], v[24:25]
	v_mul_f32_e32 v8, 0x45000000, v8
	v_mul_f32_e32 v9, 0x45000000, v9
	v_mov_b32_e32 v28, v179
	v_cndmask_b32_e32 v6, v208, v16, vcc
	v_cndmask_b32_e32 v7, v208, v17, vcc
	v_cndmask_b32_e32 v13, v208, v3, vcc
	v_cvt_pk_bf16_f32 v3, v6, v7
	v_cvt_pk_fp8_f32 v28, v8, v9
	v_lshlrev_b32_e32 v8, 16, v3
	v_sub_f32_e32 v6, v6, v8
	v_and_b32_e32 v8, 0xffff0000, v3
	v_sub_f32_e32 v7, v7, v8
	v_mul_f32_e32 v6, 0x45000000, v6
	v_mul_f32_e32 v7, 0x45000000, v7
	v_cndmask_b32_e32 v10, v208, v4, vcc
	v_cvt_pk_bf16_f32 v4, v12, v13
	v_cvt_pk_fp8_f32 v28, v6, v7 op_sel:[0,0,1]
	v_lshlrev_b32_e32 v6, 16, v4
	v_and_b32_e32 v7, 0xffff0000, v4
	v_sub_f32_e32 v6, v12, v6
	v_sub_f32_e32 v7, v13, v7
	v_mul_f32_e32 v6, 0x45000000, v6
	v_mul_f32_e32 v7, 0x45000000, v7
	v_mov_b32_e32 v29, v179
	v_cvt_pk_fp8_f32 v29, v6, v7
	v_cndmask_b32_e32 v11, v208, v5, vcc
	v_cvt_pk_bf16_f32 v5, v10, v11
	global_store_dwordx4 v[34:35], v[2:5], off offset:256 sc1
	v_lshlrev_b32_e32 v6, 16, v5
	v_and_b32_e32 v7, 0xffff0000, v5
	v_sub_f32_e32 v6, v10, v6
	v_sub_f32_e32 v7, v11, v7
	v_mul_f32_e32 v6, 0x45000000, v6
	v_mul_f32_e32 v7, 0x45000000, v7
	v_cvt_pk_fp8_f32 v29, v6, v7 op_sel:[0,0,1]
	v_lshl_add_u64 v[2:3], s[18:19], 0, v[32:33]
	v_lshl_add_u64 v[2:3], v[2:3], 0, v[164:165]
	global_store_dwordx4 v[2:3], v[26:29], off sc1

.LBB0_934:
	s_ashr_i32 s15, s43, 31
	s_lshr_b32 s15, s15, 30
	s_add_i32 s15, s43, s15
	s_lshl_b32 s15, s15, 8
	s_lshl_b32 s14, s43, 8
	s_and_b32 s15, s15, 0xfffffc00
	s_sub_i32 s14, s14, s15
	s_add_i32 s15, s43, 3
	s_cmp_lt_u32 s15, 7
	v_lshl_add_u32 v148, s42, 8, v141
	v_or_b32_e32 v142, s14, v145
	s_cselect_b64 vcc, -1, 0
	v_ashrrev_i32_e32 v143, 31, v142
	v_ashrrev_i32_e32 v149, 31, v148
	v_cndmask_b32_e32 v140, 1.0, v211, vcc
	v_lshl_add_u64 v[150:151], v[142:143], 1, s[6:7]
	v_lshlrev_b64 v[142:143], 11, v[148:149]
	v_pk_add_f32 v[128:129], v[128:129], 0 op_sel_hi:[1,0]
	v_pk_add_f32 v[126:127], v[126:127], 0 op_sel_hi:[1,0]
	v_pk_add_f32 v[124:125], v[124:125], 0 op_sel_hi:[1,0]
	v_pk_add_f32 v[122:123], v[122:123], 0 op_sel_hi:[1,0]
	v_lshl_add_u64 v[142:143], v[150:151], 0, v[142:143]
	v_pk_mul_f32 v[128:129], v[140:141], v[128:129] op_sel_hi:[0,1]
	v_pk_mul_f32 v[126:127], v[140:141], v[126:127] op_sel_hi:[0,1]
	v_pk_mul_f32 v[152:153], v[140:141], v[124:125] op_sel_hi:[0,1]
	v_pk_mul_f32 v[124:125], v[140:141], v[122:123] op_sel_hi:[0,1]
	v_cvt_pk_bf16_f32 v122, v126, v127
	v_cvt_pk_bf16_f32 v123, v128, v129
	v_pk_add_f32 v[118:119], v[118:119], 0 op_sel_hi:[1,0]
	v_pk_add_f32 v[116:117], v[116:117], 0 op_sel_hi:[1,0]
	v_pk_add_f32 v[114:115], v[114:115], 0 op_sel_hi:[1,0]
	v_cvt_pk_bf16_f32 v124, v124, v125
	v_cvt_pk_bf16_f32 v125, v152, v153
	global_store_dwordx4 v[142:143], v[122:125], off sc1
	v_pk_add_f32 v[120:121], v[120:121], 0 op_sel_hi:[1,0]
	v_pk_mul_f32 v[118:119], v[140:141], v[118:119] op_sel_hi:[0,1]
	v_pk_mul_f32 v[122:123], v[140:141], v[116:117] op_sel_hi:[0,1]
	v_pk_mul_f32 v[116:117], v[140:141], v[114:115] op_sel_hi:[0,1]
	v_cvt_pk_bf16_f32 v114, v118, v119
	v_pk_mul_f32 v[120:121], v[140:141], v[120:121] op_sel_hi:[0,1]
	v_cvt_pk_bf16_f32 v115, v120, v121
	v_cvt_pk_bf16_f32 v116, v116, v117
	v_cvt_pk_bf16_f32 v117, v122, v123
	global_store_dwordx4 v[142:143], v[114:117], off offset:256 sc1
	v_pk_add_f32 v[112:113], v[112:113], 0 op_sel_hi:[1,0]
	v_pk_add_f32 v[110:111], v[110:111], 0 op_sel_hi:[1,0]
	v_or_b32_e32 v114, 16, v148
	v_ashrrev_i32_e32 v115, 31, v114
	v_lshlrev_b64 v[114:115], 11, v[114:115]
	v_pk_add_f32 v[108:109], v[108:109], 0 op_sel_hi:[1,0]
	v_pk_add_f32 v[106:107], v[106:107], 0 op_sel_hi:[1,0]
	v_lshl_add_u64 v[114:115], v[150:151], 0, v[114:115]
	v_pk_mul_f32 v[112:113], v[140:141], v[112:113] op_sel_hi:[0,1]
	v_pk_mul_f32 v[110:111], v[140:141], v[110:111] op_sel_hi:[0,1]
	v_pk_mul_f32 v[116:117], v[140:141], v[108:109] op_sel_hi:[0,1]
	v_pk_mul_f32 v[108:109], v[140:141], v[106:107] op_sel_hi:[0,1]
	v_cvt_pk_bf16_f32 v106, v110, v111
	v_cvt_pk_bf16_f32 v107, v112, v113
	v_pk_add_f32 v[102:103], v[102:103], 0 op_sel_hi:[1,0]
	v_pk_add_f32 v[100:101], v[100:101], 0 op_sel_hi:[1,0]
	v_pk_add_f32 v[98:99], v[98:99], 0 op_sel_hi:[1,0]
	v_cvt_pk_bf16_f32 v108, v108, v109
	v_cvt_pk_bf16_f32 v109, v116, v117
	global_store_dwordx4 v[114:115], v[106:109], off sc1
	v_pk_add_f32 v[104:105], v[104:105], 0 op_sel_hi:[1,0]
	v_pk_mul_f32 v[102:103], v[140:141], v[102:103] op_sel_hi:[0,1]
	v_pk_mul_f32 v[106:107], v[140:141], v[100:101] op_sel_hi:[0,1]
	v_pk_mul_f32 v[100:101], v[140:141], v[98:99] op_sel_hi:[0,1]
	v_cvt_pk_bf16_f32 v98, v102, v103
	v_pk_mul_f32 v[104:105], v[140:141], v[104:105] op_sel_hi:[0,1]
	v_cvt_pk_bf16_f32 v99, v104, v105
	v_cvt_pk_bf16_f32 v100, v100, v101
	v_cvt_pk_bf16_f32 v101, v106, v107
	global_store_dwordx4 v[114:115], v[98:101], off offset:256 sc1
	v_pk_add_f32 v[96:97], v[96:97], 0 op_sel_hi:[1,0]
	v_pk_add_f32 v[94:95], v[94:95], 0 op_sel_hi:[1,0]
	v_or_b32_e32 v98, 32, v148
	v_ashrrev_i32_e32 v99, 31, v98
	v_lshlrev_b64 v[98:99], 11, v[98:99]
	v_pk_add_f32 v[92:93], v[92:93], 0 op_sel_hi:[1,0]
	v_pk_add_f32 v[90:91], v[90:91], 0 op_sel_hi:[1,0]
	v_lshl_add_u64 v[98:99], v[150:151], 0, v[98:99]
	v_pk_mul_f32 v[96:97], v[140:141], v[96:97] op_sel_hi:[0,1]
	v_pk_mul_f32 v[94:95], v[140:141], v[94:95] op_sel_hi:[0,1]
	v_pk_mul_f32 v[100:101], v[140:141], v[92:93] op_sel_hi:[0,1]
	v_pk_mul_f32 v[92:93], v[140:141], v[90:91] op_sel_hi:[0,1]
	v_cvt_pk_bf16_f32 v90, v94, v95
	v_cvt_pk_bf16_f32 v91, v96, v97
	v_pk_add_f32 v[86:87], v[86:87], 0 op_sel_hi:[1,0]
	v_pk_add_f32 v[84:85], v[84:85], 0 op_sel_hi:[1,0]
	v_pk_add_f32 v[82:83], v[82:83], 0 op_sel_hi:[1,0]
	v_cvt_pk_bf16_f32 v92, v92, v93
	v_cvt_pk_bf16_f32 v93, v100, v101
	global_store_dwordx4 v[98:99], v[90:93], off sc1
	v_pk_add_f32 v[88:89], v[88:89], 0 op_sel_hi:[1,0]
	v_pk_mul_f32 v[86:87], v[140:141], v[86:87] op_sel_hi:[0,1]
	v_pk_mul_f32 v[90:91], v[140:141], v[84:85] op_sel_hi:[0,1]
	v_pk_mul_f32 v[84:85], v[140:141], v[82:83] op_sel_hi:[0,1]
	v_cvt_pk_bf16_f32 v82, v86, v87
	v_pk_mul_f32 v[88:89], v[140:141], v[88:89] op_sel_hi:[0,1]
	v_cvt_pk_bf16_f32 v83, v88, v89
	v_cvt_pk_bf16_f32 v84, v84, v85
	v_cvt_pk_bf16_f32 v85, v90, v91
	global_store_dwordx4 v[98:99], v[82:85], off offset:256 sc1
	v_pk_add_f32 v[80:81], v[80:81], 0 op_sel_hi:[1,0]
	v_pk_add_f32 v[78:79], v[78:79], 0 op_sel_hi:[1,0]
	v_or_b32_e32 v82, 48, v148
	v_ashrrev_i32_e32 v83, 31, v82
	v_lshlrev_b64 v[82:83], 11, v[82:83]
	v_pk_add_f32 v[76:77], v[76:77], 0 op_sel_hi:[1,0]
	v_pk_add_f32 v[74:75], v[74:75], 0 op_sel_hi:[1,0]
	v_lshl_add_u64 v[82:83], v[150:151], 0, v[82:83]
	v_pk_mul_f32 v[80:81], v[140:141], v[80:81] op_sel_hi:[0,1]
	v_pk_mul_f32 v[78:79], v[140:141], v[78:79] op_sel_hi:[0,1]
	v_pk_mul_f32 v[84:85], v[140:141], v[76:77] op_sel_hi:[0,1]
	v_pk_mul_f32 v[76:77], v[140:141], v[74:75] op_sel_hi:[0,1]
	v_cvt_pk_bf16_f32 v74, v78, v79
	v_cvt_pk_bf16_f32 v75, v80, v81
	v_pk_add_f32 v[72:73], v[72:73], 0 op_sel_hi:[1,0]
	v_pk_add_f32 v[70:71], v[70:71], 0 op_sel_hi:[1,0]
	v_pk_add_f32 v[68:69], v[68:69], 0 op_sel_hi:[1,0]
	v_pk_add_f32 v[66:67], v[66:67], 0 op_sel_hi:[1,0]
	v_cvt_pk_bf16_f32 v76, v76, v77
	v_cvt_pk_bf16_f32 v77, v84, v85
	global_store_dwordx4 v[82:83], v[74:77], off sc1
	v_pk_mul_f32 v[72:73], v[140:141], v[72:73] op_sel_hi:[0,1]
	v_pk_mul_f32 v[70:71], v[140:141], v[70:71] op_sel_hi:[0,1]
	v_pk_mul_f32 v[74:75], v[140:141], v[68:69] op_sel_hi:[0,1]
	v_pk_mul_f32 v[68:69], v[140:141], v[66:67] op_sel_hi:[0,1]
	v_cvt_pk_bf16_f32 v66, v70, v71
	v_cvt_pk_bf16_f32 v67, v72, v73
	s_mov_b64 s[14:15], 0x40000
	v_pk_add_f32 v[62:63], v[62:63], 0 op_sel_hi:[1,0]
	v_cvt_pk_bf16_f32 v68, v68, v69
	v_cvt_pk_bf16_f32 v69, v74, v75
	global_store_dwordx4 v[82:83], v[66:69], off offset:256 sc1
	v_pk_add_f32 v[60:61], v[60:61], 0 op_sel_hi:[1,0]
	v_pk_add_f32 v[58:59], v[58:59], 0 op_sel_hi:[1,0]
	v_lshl_add_u64 v[66:67], v[142:143], 0, s[14:15]
	v_pk_mul_f32 v[62:63], v[140:141], v[62:63] op_sel_hi:[0,1]
	s_mov_b32 s14, 0x40000
	v_pk_add_f32 v[64:65], v[64:65], 0 op_sel_hi:[1,0]
	v_pk_mul_f32 v[68:69], v[140:141], v[60:61] op_sel_hi:[0,1]
	v_pk_mul_f32 v[60:61], v[140:141], v[58:59] op_sel_hi:[0,1]
	v_cvt_pk_bf16_f32 v58, v62, v63
	v_add_co_u32_e32 v62, vcc, s14, v142
	v_pk_mul_f32 v[64:65], v[140:141], v[64:65] op_sel_hi:[0,1]
	v_cvt_pk_bf16_f32 v59, v64, v65
	s_nop 0
	v_addc_co_u32_e32 v63, vcc, 0, v143, vcc
	v_pk_add_f32 v[48:49], v[48:49], 0 op_sel_hi:[1,0]
	v_pk_add_f32 v[46:47], v[46:47], 0 op_sel_hi:[1,0]
	v_cvt_pk_bf16_f32 v60, v60, v61
	v_cvt_pk_bf16_f32 v61, v68, v69
	global_store_dwordx4 v[62:63], v[58:61], off sc1
	v_pk_add_f32 v[56:57], v[56:57], 0 op_sel_hi:[1,0]
	v_pk_add_f32 v[54:55], v[54:55], 0 op_sel_hi:[1,0]
	v_pk_mul_f32 v[58:59], v[140:141], v[48:49] op_sel_hi:[0,1]
	v_pk_mul_f32 v[48:49], v[140:141], v[46:47] op_sel_hi:[0,1]
	v_pk_mul_f32 v[56:57], v[140:141], v[56:57] op_sel_hi:[0,1]
	v_pk_mul_f32 v[54:55], v[140:141], v[54:55] op_sel_hi:[0,1]
	v_cvt_pk_bf16_f32 v46, v54, v55
	v_cvt_pk_bf16_f32 v47, v56, v57
	v_cvt_pk_bf16_f32 v48, v48, v49
	v_cvt_pk_bf16_f32 v49, v58, v59
	global_store_dwordx4 v[66:67], v[46:49], off offset:256 sc1
	s_mov_b64 s[14:15], 0x48000
	v_pk_add_f32 v[50:51], v[50:51], 0 op_sel_hi:[1,0]
	v_pk_add_f32 v[48:49], v[52:53], 0 op_sel_hi:[1,0]
	v_lshl_add_u64 v[46:47], v[142:143], 0, s[14:15]
	v_pk_add_f32 v[44:45], v[44:45], 0 op_sel_hi:[1,0]
	v_pk_add_f32 v[42:43], v[42:43], 0 op_sel_hi:[1,0]
	v_pk_mul_f32 v[48:49], v[140:141], v[48:49] op_sel_hi:[0,1]
	s_mov_b32 s14, 0x48000
	v_pk_mul_f32 v[50:51], v[140:141], v[50:51] op_sel_hi:[0,1]
	v_pk_mul_f32 v[52:53], v[140:141], v[44:45] op_sel_hi:[0,1]
	v_pk_mul_f32 v[44:45], v[140:141], v[42:43] op_sel_hi:[0,1]
	v_cvt_pk_bf16_f32 v42, v50, v51
	v_cvt_pk_bf16_f32 v43, v48, v49
	v_add_co_u32_e32 v48, vcc, s14, v142
	v_pk_add_f32 v[32:33], v[32:33], 0 op_sel_hi:[1,0]
	s_nop 0
	v_addc_co_u32_e32 v49, vcc, 0, v143, vcc
	v_pk_add_f32 v[30:31], v[30:31], 0 op_sel_hi:[1,0]
	v_cvt_pk_bf16_f32 v44, v44, v45
	v_cvt_pk_bf16_f32 v45, v52, v53
	global_store_dwordx4 v[48:49], v[42:45], off sc1
	v_pk_add_f32 v[40:41], v[40:41], 0 op_sel_hi:[1,0]
	v_pk_add_f32 v[38:39], v[38:39], 0 op_sel_hi:[1,0]
	v_pk_mul_f32 v[42:43], v[140:141], v[32:33] op_sel_hi:[0,1]
	v_pk_mul_f32 v[32:33], v[140:141], v[30:31] op_sel_hi:[0,1]
	v_pk_mul_f32 v[40:41], v[140:141], v[40:41] op_sel_hi:[0,1]
	v_pk_mul_f32 v[38:39], v[140:141], v[38:39] op_sel_hi:[0,1]
	v_cvt_pk_bf16_f32 v30, v38, v39
	v_cvt_pk_bf16_f32 v31, v40, v41
	v_cvt_pk_bf16_f32 v32, v32, v33
	v_cvt_pk_bf16_f32 v33, v42, v43
	global_store_dwordx4 v[46:47], v[30:33], off offset:256 sc1
	s_mov_b64 s[14:15], 0x50000
	v_pk_add_f32 v[34:35], v[34:35], 0 op_sel_hi:[1,0]
	v_pk_add_f32 v[32:33], v[36:37], 0 op_sel_hi:[1,0]
	v_lshl_add_u64 v[30:31], v[142:143], 0, s[14:15]
	v_pk_add_f32 v[28:29], v[28:29], 0 op_sel_hi:[1,0]
	v_pk_add_f32 v[26:27], v[26:27], 0 op_sel_hi:[1,0]
	v_pk_mul_f32 v[32:33], v[140:141], v[32:33] op_sel_hi:[0,1]
	s_mov_b32 s14, 0x50000
	v_pk_mul_f32 v[34:35], v[140:141], v[34:35] op_sel_hi:[0,1]
	v_pk_mul_f32 v[36:37], v[140:141], v[28:29] op_sel_hi:[0,1]
	v_pk_mul_f32 v[28:29], v[140:141], v[26:27] op_sel_hi:[0,1]
	v_cvt_pk_bf16_f32 v26, v34, v35
	v_cvt_pk_bf16_f32 v27, v32, v33
	v_add_co_u32_e32 v32, vcc, s14, v142
	v_pk_add_f32 v[16:17], v[16:17], 0 op_sel_hi:[1,0]
	s_nop 0
	v_addc_co_u32_e32 v33, vcc, 0, v143, vcc
	v_pk_add_f32 v[14:15], v[14:15], 0 op_sel_hi:[1,0]
	v_cvt_pk_bf16_f32 v28, v28, v29
	v_cvt_pk_bf16_f32 v29, v36, v37
	global_store_dwordx4 v[32:33], v[26:29], off sc1
	v_pk_add_f32 v[24:25], v[24:25], 0 op_sel_hi:[1,0]
	v_pk_add_f32 v[22:23], v[22:23], 0 op_sel_hi:[1,0]
	v_pk_mul_f32 v[26:27], v[140:141], v[16:17] op_sel_hi:[0,1]
	v_pk_mul_f32 v[16:17], v[140:141], v[14:15] op_sel_hi:[0,1]
	v_pk_mul_f32 v[24:25], v[140:141], v[24:25] op_sel_hi:[0,1]
	v_pk_mul_f32 v[22:23], v[140:141], v[22:23] op_sel_hi:[0,1]
	v_cvt_pk_bf16_f32 v14, v22, v23
	v_cvt_pk_bf16_f32 v15, v24, v25
	v_cvt_pk_bf16_f32 v16, v16, v17
	v_cvt_pk_bf16_f32 v17, v26, v27
	global_store_dwordx4 v[30:31], v[14:17], off offset:256 sc1
	s_mov_b64 s[14:15], 0x58000
	v_pk_add_f32 v[18:19], v[18:19], 0 op_sel_hi:[1,0]
	v_pk_add_f32 v[16:17], v[20:21], 0 op_sel_hi:[1,0]
	v_lshl_add_u64 v[14:15], v[142:143], 0, s[14:15]
	v_pk_add_f32 v[12:13], v[12:13], 0 op_sel_hi:[1,0]
	v_pk_add_f32 v[10:11], v[10:11], 0 op_sel_hi:[1,0]
	v_pk_mul_f32 v[16:17], v[140:141], v[16:17] op_sel_hi:[0,1]
	s_mov_b32 s14, 0x58000
	v_pk_mul_f32 v[18:19], v[140:141], v[18:19] op_sel_hi:[0,1]
	v_pk_mul_f32 v[20:21], v[140:141], v[12:13] op_sel_hi:[0,1]
	v_pk_mul_f32 v[12:13], v[140:141], v[10:11] op_sel_hi:[0,1]
	v_cvt_pk_bf16_f32 v10, v18, v19
	v_cvt_pk_bf16_f32 v11, v16, v17
	v_add_co_u32_e32 v16, vcc, s14, v142
	v_pk_add_f32 v[4:5], v[4:5], 0 op_sel_hi:[1,0]
	s_nop 0
	v_addc_co_u32_e32 v17, vcc, 0, v143, vcc
	v_pk_add_f32 v[2:3], v[2:3], 0 op_sel_hi:[1,0]
	v_cvt_pk_bf16_f32 v12, v12, v13
	v_cvt_pk_bf16_f32 v13, v20, v21
	global_store_dwordx4 v[16:17], v[10:13], off sc1
	v_pk_add_f32 v[8:9], v[8:9], 0 op_sel_hi:[1,0]
	v_pk_add_f32 v[6:7], v[6:7], 0 op_sel_hi:[1,0]
	v_pk_mul_f32 v[10:11], v[140:141], v[4:5] op_sel_hi:[0,1]
	v_pk_mul_f32 v[4:5], v[140:141], v[2:3] op_sel_hi:[0,1]
	s_andn2_b64 vcc, exec, s[4:5]
	s_mov_b64 s[4:5], -1
	v_pk_mul_f32 v[8:9], v[140:141], v[8:9] op_sel_hi:[0,1]
	v_pk_mul_f32 v[6:7], v[140:141], v[6:7] op_sel_hi:[0,1]
	v_cvt_pk_bf16_f32 v2, v6, v7
	v_cvt_pk_bf16_f32 v3, v8, v9
	v_cvt_pk_bf16_f32 v4, v4, v5
	v_cvt_pk_bf16_f32 v5, v10, v11
	global_store_dwordx4 v[14:15], v[2:5], off offset:256 sc1
	s_cbranch_vccnz .LBB0_923
	s_andn2_b64 vcc, exec, s[0:1]
	s_cbranch_vccnz .LBB0_922
	s_barrier
	s_branch .LBB0_922

.LBB0_941:
	v_add_u32_e32 v67, s12, v198
	v_add_u32_e32 v68, s34, v198
	ds_read_b128 v[70:73], v67
	ds_read_b128 v[74:77], v68
	v_lshlrev_b32_e32 v66, 1, v197
	s_lshl_b64 s[0:1], s[0:1], 11
	s_add_u32 s0, s61, s0
	s_addc_u32 s1, s82, s1
	s_waitcnt lgkmcnt(0)
	v_add_f32_e32 v69, v70, v74
	v_rcp_f32_e32 v69, v69
	v_lshlrev_b32_e32 v70, 10, v212
	v_add3_u32 v66, s60, v66, v70
	v_mov_b32_e32 v197, v179
	v_mul_f32_e32 v50, v50, v69
	v_bfe_u32 v70, v50, 16, 1
	v_add3_u32 v50, v50, v70, s97
	v_mul_f32_e32 v34, v34, v69
	ds_write_b16_d16_hi v66, v50
	v_bfe_u32 v50, v34, 16, 1
	v_add3_u32 v34, v34, v50, s97
	v_mul_f32_e32 v18, v18, v69
	ds_write_b16_d16_hi v66, v34 offset:64
	v_bfe_u32 v34, v18, 16, 1
	v_add3_u32 v18, v18, v34, s97
	v_mul_f32_e32 v2, v2, v69
	ds_write_b16_d16_hi v66, v18 offset:128
	v_bfe_u32 v18, v2, 16, 1
	v_add3_u32 v2, v2, v18, s97
	ds_write_b16_d16_hi v66, v2 offset:192
	v_add_f32_e32 v2, v71, v75
	v_rcp_f32_e32 v2, v2
	s_mov_b32 s88, 1
	s_mov_b64 s[28:29], 0
	s_andn2_b64 vcc, exec, s[24:25]
	v_mul_f32_e32 v18, v51, v2
	v_bfe_u32 v34, v18, 16, 1
	v_add3_u32 v18, v18, v34, s97
	ds_write_b16_d16_hi v66, v18 offset:256
	v_mul_f32_e32 v18, v35, v2
	v_bfe_u32 v34, v18, 16, 1
	v_add3_u32 v18, v18, v34, s97
	ds_write_b16_d16_hi v66, v18 offset:320
	v_mul_f32_e32 v18, v19, v2
	v_mul_f32_e32 v2, v3, v2
	v_bfe_u32 v3, v2, 16, 1
	v_add3_u32 v2, v2, v3, s97
	ds_write_b16_d16_hi v66, v2 offset:448
	v_add_f32_e32 v2, v72, v76
	v_rcp_f32_e32 v2, v2
	v_bfe_u32 v19, v18, 16, 1
	v_add3_u32 v18, v18, v19, s97
	ds_write_b16_d16_hi v66, v18 offset:384
	v_mul_f32_e32 v3, v52, v2
	v_bfe_u32 v18, v3, 16, 1
	v_add3_u32 v3, v3, v18, s97
	ds_write_b16_d16_hi v66, v3 offset:512
	v_mul_f32_e32 v3, v36, v2
	v_bfe_u32 v18, v3, 16, 1
	v_add3_u32 v3, v3, v18, s97
	ds_write_b16_d16_hi v66, v3 offset:576
	v_mul_f32_e32 v3, v20, v2
	v_bfe_u32 v18, v3, 16, 1
	v_add3_u32 v3, v3, v18, s97
	v_mul_f32_e32 v2, v4, v2
	ds_write_b16_d16_hi v66, v3 offset:640
	v_bfe_u32 v3, v2, 16, 1
	v_add3_u32 v2, v2, v3, s97
	ds_write_b16_d16_hi v66, v2 offset:704
	v_add_f32_e32 v2, v73, v77
	v_rcp_f32_e32 v2, v2
	s_nop 0
	v_mul_f32_e32 v3, v53, v2
	v_bfe_u32 v4, v3, 16, 1
	v_add3_u32 v3, v3, v4, s97
	ds_write_b16_d16_hi v66, v3 offset:768
	v_mul_f32_e32 v3, v37, v2
	v_bfe_u32 v4, v3, 16, 1
	v_add3_u32 v3, v3, v4, s97
	ds_write_b16_d16_hi v66, v3 offset:832
	v_mul_f32_e32 v3, v21, v2
	v_bfe_u32 v4, v3, 16, 1
	v_add3_u32 v3, v3, v4, s97
	v_mul_f32_e32 v2, v5, v2
	ds_write_b16_d16_hi v66, v3 offset:896
	v_bfe_u32 v3, v2, 16, 1
	v_add3_u32 v2, v2, v3, s97
	ds_write_b16_d16_hi v66, v2 offset:960
	ds_read_b128 v[2:5], v67 offset:32
	ds_read_b128 v[18:21], v68 offset:32
	s_waitcnt lgkmcnt(0)
	v_add_f32_e32 v2, v2, v18
	v_rcp_f32_e32 v2, v2
	s_nop 0
	v_mul_f32_e32 v18, v54, v2
	v_bfe_u32 v34, v18, 16, 1
	v_add3_u32 v18, v18, v34, s97
	ds_write_b16_d16_hi v66, v18 offset:2048
	v_mul_f32_e32 v18, v38, v2
	v_bfe_u32 v34, v18, 16, 1
	v_add3_u32 v18, v18, v34, s97
	ds_write_b16_d16_hi v66, v18 offset:2112
	v_mul_f32_e32 v18, v22, v2
	v_mul_f32_e32 v2, v6, v2
	v_bfe_u32 v6, v2, 16, 1
	v_add3_u32 v2, v2, v6, s97
	ds_write_b16_d16_hi v66, v2 offset:2240
	v_add_f32_e32 v2, v3, v19
	v_rcp_f32_e32 v2, v2
	v_bfe_u32 v22, v18, 16, 1
	v_add3_u32 v18, v18, v22, s97
	ds_write_b16_d16_hi v66, v18 offset:2176
	v_mul_f32_e32 v3, v55, v2
	v_bfe_u32 v6, v3, 16, 1
	v_add3_u32 v3, v3, v6, s97
	ds_write_b16_d16_hi v66, v3 offset:2304
	v_mul_f32_e32 v3, v39, v2
	v_bfe_u32 v6, v3, 16, 1
	v_add3_u32 v3, v3, v6, s97
	ds_write_b16_d16_hi v66, v3 offset:2368
	v_mul_f32_e32 v3, v23, v2
	v_bfe_u32 v6, v3, 16, 1
	v_add3_u32 v3, v3, v6, s97
	v_mul_f32_e32 v2, v7, v2
	ds_write_b16_d16_hi v66, v3 offset:2432
	v_bfe_u32 v3, v2, 16, 1
	v_add3_u32 v2, v2, v3, s97
	ds_write_b16_d16_hi v66, v2 offset:2496
	v_add_f32_e32 v2, v4, v20
	v_rcp_f32_e32 v2, v2
	s_nop 0
	v_mul_f32_e32 v3, v56, v2
	v_bfe_u32 v4, v3, 16, 1
	v_add3_u32 v3, v3, v4, s97
	ds_write_b16_d16_hi v66, v3 offset:2560
	v_mul_f32_e32 v3, v40, v2
	v_bfe_u32 v4, v3, 16, 1
	v_add3_u32 v3, v3, v4, s97
	ds_write_b16_d16_hi v66, v3 offset:2624
	v_mul_f32_e32 v3, v24, v2
	v_bfe_u32 v4, v3, 16, 1
	v_add3_u32 v3, v3, v4, s97
	v_mul_f32_e32 v2, v8, v2
	ds_write_b16_d16_hi v66, v3 offset:2688
	v_bfe_u32 v3, v2, 16, 1
	v_add3_u32 v2, v2, v3, s97
	ds_write_b16_d16_hi v66, v2 offset:2752
	v_add_f32_e32 v2, v5, v21
	v_rcp_f32_e32 v2, v2
	s_nop 0
	v_mul_f32_e32 v3, v57, v2
	v_bfe_u32 v4, v3, 16, 1
	v_add3_u32 v3, v3, v4, s97
	ds_write_b16_d16_hi v66, v3 offset:2816
	v_mul_f32_e32 v3, v41, v2
	v_bfe_u32 v4, v3, 16, 1
	v_add3_u32 v3, v3, v4, s97
	ds_write_b16_d16_hi v66, v3 offset:2880
	v_mul_f32_e32 v3, v25, v2
	v_bfe_u32 v4, v3, 16, 1
	v_add3_u32 v3, v3, v4, s97
	v_mul_f32_e32 v2, v9, v2
	ds_write_b16_d16_hi v66, v3 offset:2944
	v_bfe_u32 v3, v2, 16, 1
	v_add3_u32 v2, v2, v3, s97
	ds_write_b16_d16_hi v66, v2 offset:3008
	ds_read_b128 v[2:5], v67 offset:64
	ds_read_b128 v[6:9], v68 offset:64
	s_waitcnt lgkmcnt(0)
	v_add_f32_e32 v2, v2, v6
	v_rcp_f32_e32 v2, v2
	s_nop 0
	v_mul_f32_e32 v6, v58, v2
	v_bfe_u32 v18, v6, 16, 1
	v_add3_u32 v6, v6, v18, s97
	ds_write_b16_d16_hi v66, v6 offset:4096
	v_mul_f32_e32 v6, v42, v2
	v_bfe_u32 v18, v6, 16, 1
	v_add3_u32 v6, v6, v18, s97
	ds_write_b16_d16_hi v66, v6 offset:4160
	v_mul_f32_e32 v6, v26, v2
	v_bfe_u32 v18, v6, 16, 1
	v_add3_u32 v6, v6, v18, s97
	v_mul_f32_e32 v2, v10, v2
	ds_write_b16_d16_hi v66, v6 offset:4224
	v_bfe_u32 v6, v2, 16, 1
	v_add3_u32 v2, v2, v6, s97
	ds_write_b16_d16_hi v66, v2 offset:4288
	v_add_f32_e32 v2, v3, v7
	v_rcp_f32_e32 v2, v2
	s_nop 0
	v_mul_f32_e32 v3, v59, v2
	v_bfe_u32 v6, v3, 16, 1
	v_add3_u32 v3, v3, v6, s97
	ds_write_b16_d16_hi v66, v3 offset:4352
	v_mul_f32_e32 v3, v43, v2
	v_bfe_u32 v6, v3, 16, 1
	v_add3_u32 v3, v3, v6, s97
	ds_write_b16_d16_hi v66, v3 offset:4416
	v_mul_f32_e32 v3, v27, v2
	v_bfe_u32 v6, v3, 16, 1
	v_add3_u32 v3, v3, v6, s97
	v_mul_f32_e32 v2, v11, v2
	ds_write_b16_d16_hi v66, v3 offset:4480
	v_bfe_u32 v3, v2, 16, 1
	v_add3_u32 v2, v2, v3, s97
	ds_write_b16_d16_hi v66, v2 offset:4544
	v_add_f32_e32 v2, v4, v8
	v_rcp_f32_e32 v2, v2
	v_add_u32_e32 v11, s60, v196
	v_mul_f32_e32 v3, v60, v2
	v_bfe_u32 v4, v3, 16, 1
	v_add3_u32 v3, v3, v4, s97
	ds_write_b16_d16_hi v66, v3 offset:4608
	v_mul_f32_e32 v3, v44, v2
	v_bfe_u32 v4, v3, 16, 1
	v_add3_u32 v3, v3, v4, s97
	ds_write_b16_d16_hi v66, v3 offset:4672
	v_mul_f32_e32 v3, v28, v2
	v_bfe_u32 v4, v3, 16, 1
	v_add3_u32 v3, v3, v4, s97
	v_mul_f32_e32 v2, v12, v2
	ds_write_b16_d16_hi v66, v3 offset:4736
	v_bfe_u32 v3, v2, 16, 1
	v_add3_u32 v2, v2, v3, s97
	ds_write_b16_d16_hi v66, v2 offset:4800
	v_add_f32_e32 v2, v5, v9
	v_rcp_f32_e32 v2, v2
	s_nop 0
	v_mul_f32_e32 v3, v61, v2
	v_bfe_u32 v4, v3, 16, 1
	v_add3_u32 v3, v3, v4, s97
	ds_write_b16_d16_hi v66, v3 offset:4864
	v_mul_f32_e32 v3, v45, v2
	v_bfe_u32 v4, v3, 16, 1
	v_add3_u32 v3, v3, v4, s97
	ds_write_b16_d16_hi v66, v3 offset:4928
	v_mul_f32_e32 v3, v29, v2
	v_bfe_u32 v4, v3, 16, 1
	v_add3_u32 v3, v3, v4, s97
	v_mul_f32_e32 v2, v13, v2
	ds_write_b16_d16_hi v66, v3 offset:4992
	v_bfe_u32 v3, v2, 16, 1
	v_add3_u32 v2, v2, v3, s97
	ds_write_b16_d16_hi v66, v2 offset:5056
	ds_read_b128 v[2:5], v67 offset:96
	ds_read_b128 v[6:9], v68 offset:96
	s_waitcnt lgkmcnt(0)
	v_add_f32_e32 v2, v2, v6
	v_rcp_f32_e32 v2, v2
	s_nop 0
	v_mul_f32_e32 v6, v62, v2
	v_bfe_u32 v10, v6, 16, 1
	v_add3_u32 v6, v6, v10, s97
	ds_write_b16_d16_hi v66, v6 offset:6144
	v_mul_f32_e32 v6, v46, v2
	v_bfe_u32 v10, v6, 16, 1
	v_add3_u32 v6, v6, v10, s97
	ds_write_b16_d16_hi v66, v6 offset:6208
	v_mul_f32_e32 v6, v30, v2
	v_bfe_u32 v10, v6, 16, 1
	v_add3_u32 v6, v6, v10, s97
	v_mul_f32_e32 v2, v14, v2
	ds_write_b16_d16_hi v66, v6 offset:6272
	v_bfe_u32 v6, v2, 16, 1
	v_add3_u32 v2, v2, v6, s97
	ds_write_b16_d16_hi v66, v2 offset:6336
	v_add_f32_e32 v2, v3, v7
	v_rcp_f32_e32 v2, v2
	v_lshrrev_b32_e32 v10, 4, v185
	v_lshlrev_b32_e32 v178, 11, v10
	v_mul_f32_e32 v3, v63, v2
	v_bfe_u32 v6, v3, 16, 1
	v_add3_u32 v3, v3, v6, s97
	ds_write_b16_d16_hi v66, v3 offset:6400
	v_mul_f32_e32 v3, v47, v2
	v_bfe_u32 v6, v3, 16, 1
	v_add3_u32 v3, v3, v6, s97
	ds_write_b16_d16_hi v66, v3 offset:6464
	v_mul_f32_e32 v3, v31, v2
	v_bfe_u32 v6, v3, 16, 1
	v_add3_u32 v3, v3, v6, s97
	v_mul_f32_e32 v2, v15, v2
	ds_write_b16_d16_hi v66, v3 offset:6528
	v_bfe_u32 v3, v2, 16, 1
	v_add3_u32 v2, v2, v3, s97
	ds_write_b16_d16_hi v66, v2 offset:6592
	v_add_f32_e32 v2, v4, v8
	v_rcp_f32_e32 v2, v2
	v_lshl_add_u64 v[6:7], s[0:1], 0, v[196:197]
	v_mul_f32_e32 v3, v64, v2
	v_bfe_u32 v4, v3, 16, 1
	v_add3_u32 v3, v3, v4, s97
	ds_write_b16_d16_hi v66, v3 offset:6656
	v_mul_f32_e32 v3, v48, v2
	v_bfe_u32 v4, v3, 16, 1
	v_add3_u32 v3, v3, v4, s97
	ds_write_b16_d16_hi v66, v3 offset:6720
	v_mul_f32_e32 v3, v32, v2
	v_bfe_u32 v4, v3, 16, 1
	v_add3_u32 v3, v3, v4, s97
	v_mul_f32_e32 v2, v16, v2
	ds_write_b16_d16_hi v66, v3 offset:6784
	v_bfe_u32 v3, v2, 16, 1
	v_add3_u32 v2, v2, v3, s97
	ds_write_b16_d16_hi v66, v2 offset:6848
	v_add_f32_e32 v2, v5, v9
	v_rcp_f32_e32 v2, v2
	v_lshl_add_u64 v[8:9], v[6:7], 0, v[178:179]
	v_mul_f32_e32 v3, v65, v2
	v_bfe_u32 v4, v3, 16, 1
	v_add3_u32 v3, v3, v4, s97
	ds_write_b16_d16_hi v66, v3 offset:6912
	v_mul_f32_e32 v3, v49, v2
	v_bfe_u32 v4, v3, 16, 1
	v_add3_u32 v3, v3, v4, s97
	ds_write_b16_d16_hi v66, v3 offset:6976
	v_mul_f32_e32 v3, v33, v2
	v_bfe_u32 v4, v3, 16, 1
	v_add3_u32 v3, v3, v4, s97
	v_mul_f32_e32 v2, v17, v2
	ds_write_b16_d16_hi v66, v3 offset:7040
	v_bfe_u32 v3, v2, 16, 1
	v_add3_u32 v2, v2, v3, s97
	ds_write_b16_d16_hi v66, v2 offset:7104
	s_waitcnt lgkmcnt(0)
	v_lshl_add_u32 v2, v10, 8, v11
	ds_read_b128 v[2:5], v2
	s_waitcnt lgkmcnt(0)
	global_store_dwordx4 v[8:9], v[2:5], off sc1
	v_or_b32_e32 v8, 4, v10
	s_nop 0
	v_lshl_add_u32 v2, v8, 8, v11
	ds_read_b128 v[2:5], v2
	v_lshlrev_b32_e32 v178, 11, v8
	v_lshl_add_u64 v[8:9], v[6:7], 0, v[178:179]
	s_waitcnt lgkmcnt(0)
	global_store_dwordx4 v[8:9], v[2:5], off sc1
	v_or_b32_e32 v8, 8, v10
	s_nop 0
	v_lshl_add_u32 v2, v8, 8, v11
	ds_read_b128 v[2:5], v2
	v_lshlrev_b32_e32 v178, 11, v8
	v_lshl_add_u64 v[8:9], v[6:7], 0, v[178:179]
	s_waitcnt lgkmcnt(0)
	global_store_dwordx4 v[8:9], v[2:5], off sc1
	v_or_b32_e32 v8, 12, v10
	s_nop 0
	v_lshl_add_u32 v2, v8, 8, v11
	ds_read_b128 v[2:5], v2
	v_lshlrev_b32_e32 v178, 11, v8
	v_lshl_add_u64 v[8:9], v[6:7], 0, v[178:179]
	s_waitcnt lgkmcnt(0)
	global_store_dwordx4 v[8:9], v[2:5], off sc1
	v_or_b32_e32 v8, 16, v10
	s_nop 0
	v_lshl_add_u32 v2, v8, 8, v11
	ds_read_b128 v[2:5], v2
	v_lshlrev_b32_e32 v178, 11, v8
	v_lshl_add_u64 v[8:9], v[6:7], 0, v[178:179]
	s_waitcnt lgkmcnt(0)
	global_store_dwordx4 v[8:9], v[2:5], off sc1
	v_or_b32_e32 v8, 20, v10
	s_nop 0
	v_lshl_add_u32 v2, v8, 8, v11
	ds_read_b128 v[2:5], v2
	v_lshlrev_b32_e32 v178, 11, v8
	v_lshl_add_u64 v[8:9], v[6:7], 0, v[178:179]
	s_waitcnt lgkmcnt(0)
	global_store_dwordx4 v[8:9], v[2:5], off sc1
	v_or_b32_e32 v8, 24, v10
	s_nop 0
	v_lshl_add_u32 v2, v8, 8, v11
	ds_read_b128 v[2:5], v2
	v_lshlrev_b32_e32 v178, 11, v8
	v_lshl_add_u64 v[8:9], v[6:7], 0, v[178:179]
	s_waitcnt lgkmcnt(0)
	global_store_dwordx4 v[8:9], v[2:5], off sc1
	v_or_b32_e32 v8, 28, v10
	s_nop 0
	v_lshl_add_u32 v2, v8, 8, v11
	ds_read_b128 v[2:5], v2
	v_lshlrev_b32_e32 v178, 11, v8
	v_lshl_add_u64 v[6:7], v[6:7], 0, v[178:179]
	s_waitcnt lgkmcnt(0)
	global_store_dwordx4 v[6:7], v[2:5], off sc1
	s_barrier
	s_cbranch_vccz .LBB0_954

.LBB0_1066:
	s_or_b64 exec, exec, s[0:1]
	s_waitcnt lgkmcnt(0)
	s_barrier
	v_lshl_add_u32 v169, v168, 3, 0
	ds_read_b64 v[172:173], v169 offset:8192
	v_add_u32_e32 v166, s11, v168
	v_ashrrev_i32_e32 v167, 31, v166
	v_lshlrev_b64 v[174:175], 11, v[166:167]
	s_waitcnt lgkmcnt(1)
	v_cmp_eq_u32_e32 vcc, 0, v171
	s_waitcnt lgkmcnt(0)
	v_sub_f32_e32 v7, v7, v172
	v_sub_f32_e32 v6, v6, v172
	v_pk_mul_f32 v[6:7], v[172:173], v[6:7] op_sel:[1,0]
	v_sub_f32_e32 v3, v3, v172
	v_sub_f32_e32 v2, v2, v172
	v_sub_f32_e32 v9, v9, v172
	v_sub_f32_e32 v8, v8, v172
	s_waitcnt vmcnt(5)
	v_pk_fma_f32 v[6:7], v[154:155], v[6:7], v[158:159]
	v_sub_f32_e32 v5, v5, v172
	v_sub_f32_e32 v4, v4, v172
	v_pk_mul_f32 v[2:3], v[172:173], v[2:3] op_sel:[1,0]
	v_pk_mul_f32 v[8:9], v[172:173], v[8:9] op_sel:[1,0]
	v_pk_mul_f32 v[4:5], v[172:173], v[4:5] op_sel:[1,0]
	s_waitcnt vmcnt(4)
	v_pk_fma_f32 v[2:3], v[146:147], v[2:3], v[150:151]
	v_cndmask_b32_e32 v167, v208, v6, vcc
	v_cndmask_b32_e32 v168, v208, v7, vcc
	v_lshl_add_u64 v[6:7], s[88:89], 0, v[174:175]
	v_pk_fma_f32 v[8:9], v[156:157], v[8:9], v[160:161]
	v_pk_fma_f32 v[4:5], v[148:149], v[4:5], v[152:153]
	v_cndmask_b32_e32 v178, v208, v2, vcc
	v_cvt_pk_bf16_f32 v2, v167, v168
	v_lshl_add_u64 v[170:171], v[6:7], 0, v[164:165]
	v_cndmask_b32_e32 v8, v208, v8, vcc
	v_cndmask_b32_e32 v9, v208, v9, vcc
	v_cndmask_b32_e32 v176, v208, v4, vcc
	v_cndmask_b32_e32 v177, v208, v5, vcc
	v_cndmask_b32_e32 v185, v208, v3, vcc
	v_cvt_pk_bf16_f32 v3, v8, v9
	v_cvt_pk_bf16_f32 v4, v178, v185
	v_cvt_pk_bf16_f32 v5, v176, v177
	global_store_dwordx4 v[170:171], v[2:5], off sc1
	v_lshlrev_b32_e32 v6, 16, v2
	v_sub_f32_e32 v6, v167, v6
	v_and_b32_e32 v2, 0xffff0000, v2
	v_sub_f32_e32 v2, v168, v2
	v_mul_f32_e32 v6, 0x45000000, v6
	v_mul_f32_e32 v7, 0x45000000, v2
	v_mov_b32_e32 v2, v179
	v_cvt_pk_fp8_f32 v2, v6, v7
	v_lshlrev_b32_e32 v6, 16, v3
	v_and_b32_e32 v3, 0xffff0000, v3
	v_sub_f32_e32 v6, v8, v6
	v_sub_f32_e32 v3, v9, v3
	v_mul_f32_e32 v6, 0x45000000, v6
	v_mul_f32_e32 v3, 0x45000000, v3
	v_cvt_pk_fp8_f32 v2, v6, v3 op_sel:[0,0,1]
	v_lshlrev_b32_e32 v3, 16, v4
	v_sub_f32_e32 v3, v178, v3
	v_mul_f32_e32 v6, 0x45000000, v3
	v_and_b32_e32 v3, 0xffff0000, v4
	v_sub_f32_e32 v3, v185, v3
	v_mul_f32_e32 v4, 0x45000000, v3
	v_mov_b32_e32 v3, v179
	v_cvt_pk_fp8_f32 v3, v6, v4
	v_lshlrev_b32_e32 v4, 16, v5
	v_and_b32_e32 v5, 0xffff0000, v5
	v_sub_f32_e32 v4, v176, v4
	v_sub_f32_e32 v5, v177, v5
	v_mul_f32_e32 v4, 0x45000000, v4
	v_mul_f32_e32 v5, 0x45000000, v5
	v_cvt_pk_fp8_f32 v3, v4, v5 op_sel:[0,0,1]
	v_sub_f32_e32 v5, v15, v172
	v_sub_f32_e32 v4, v14, v172
	v_sub_f32_e32 v7, v17, v172
	v_sub_f32_e32 v6, v16, v172
	v_pk_mul_f32 v[6:7], v[172:173], v[6:7] op_sel:[1,0]
	v_pk_mul_f32 v[4:5], v[172:173], v[4:5] op_sel:[1,0]
	s_waitcnt vmcnt(1)
	v_pk_fma_f32 v[6:7], v[140:141], v[6:7], v[144:145]
	v_pk_fma_f32 v[4:5], v[138:139], v[4:5], v[142:143]
	v_sub_f32_e32 v8, v10, v172
	v_sub_f32_e32 v10, v12, v172
	v_cndmask_b32_e32 v12, v208, v6, vcc
	v_cndmask_b32_e32 v4, v208, v4, vcc
	v_cndmask_b32_e32 v5, v208, v5, vcc
	v_cvt_pk_bf16_f32 v6, v4, v5
	v_sub_f32_e32 v9, v11, v172
	v_lshlrev_b32_e32 v16, 16, v6
	v_sub_f32_e32 v4, v4, v16
	v_mul_f32_e32 v16, 0x45000000, v4
	v_and_b32_e32 v4, 0xffff0000, v6
	v_sub_f32_e32 v4, v5, v4
	v_mul_f32_e32 v5, 0x45000000, v4
	v_mov_b32_e32 v4, v179
	v_sub_f32_e32 v11, v13, v172
	v_cndmask_b32_e32 v13, v208, v7, vcc
	v_cvt_pk_bf16_f32 v7, v12, v13
	v_cvt_pk_fp8_f32 v4, v16, v5
	v_lshlrev_b32_e32 v5, 16, v7
	v_sub_f32_e32 v5, v12, v5
	v_and_b32_e32 v12, 0xffff0000, v7
	v_pk_mul_f32 v[8:9], v[172:173], v[8:9] op_sel:[1,0]
	v_sub_f32_e32 v12, v13, v12
	v_pk_fma_f32 v[8:9], v[130:131], v[8:9], v[134:135]
	v_mul_f32_e32 v5, 0x45000000, v5
	v_mul_f32_e32 v12, 0x45000000, v12
	v_cndmask_b32_e32 v14, v208, v8, vcc
	v_cndmask_b32_e32 v15, v208, v9, vcc
	v_cvt_pk_bf16_f32 v8, v14, v15
	v_cvt_pk_fp8_f32 v4, v5, v12 op_sel:[0,0,1]
	v_lshlrev_b32_e32 v5, 16, v8
	v_sub_f32_e32 v5, v14, v5
	v_mul_f32_e32 v12, 0x45000000, v5
	v_and_b32_e32 v5, 0xffff0000, v8
	v_pk_mul_f32 v[10:11], v[172:173], v[10:11] op_sel:[1,0]
	v_sub_f32_e32 v5, v15, v5
	v_pk_fma_f32 v[10:11], v[132:133], v[10:11], v[136:137]
	v_mul_f32_e32 v13, 0x45000000, v5
	v_mov_b32_e32 v5, v179
	v_cndmask_b32_e32 v10, v208, v10, vcc
	v_cndmask_b32_e32 v11, v208, v11, vcc
	v_cvt_pk_bf16_f32 v9, v10, v11
	v_cvt_pk_fp8_f32 v5, v12, v13
	v_lshlrev_b32_e32 v12, 16, v9
	v_sub_f32_e32 v10, v10, v12
	v_and_b32_e32 v12, 0xffff0000, v9
	v_sub_f32_e32 v11, v11, v12
	v_mul_f32_e32 v10, 0x45000000, v10
	v_mul_f32_e32 v11, 0x45000000, v11
	v_cvt_pk_fp8_f32 v5, v10, v11 op_sel:[0,0,1]
	global_store_dwordx4 v[170:171], v[6:9], off offset:256 sc1
	s_nop 1
	v_lshl_add_u64 v[6:7], s[18:19], 0, v[174:175]
	v_lshl_add_u64 v[6:7], v[6:7], 0, v[162:163]
	global_store_dwordx4 v[6:7], v[2:5], off sc1
	ds_read_b64 v[6:7], v169 offset:8320
	s_waitcnt lgkmcnt(0)
	v_sub_f32_e32 v9, v27, v6
	v_add_u32_e32 v2, 16, v166
	v_ashrrev_i32_e32 v3, 31, v2
	v_sub_f32_e32 v8, v26, v6
	v_lshlrev_b64 v[10:11], 11, v[2:3]
	v_sub_f32_e32 v3, v31, v6
	v_sub_f32_e32 v2, v30, v6
	v_sub_f32_e32 v13, v29, v6
	v_sub_f32_e32 v12, v28, v6
	v_pk_mul_f32 v[8:9], v[6:7], v[8:9] op_sel:[1,0]
	v_sub_f32_e32 v5, v33, v6
	v_sub_f32_e32 v4, v32, v6
	v_pk_mul_f32 v[2:3], v[6:7], v[2:3] op_sel:[1,0]
	v_pk_mul_f32 v[12:13], v[6:7], v[12:13] op_sel:[1,0]
	v_pk_fma_f32 v[8:9], v[146:147], v[8:9], v[150:151]
	v_pk_mul_f32 v[4:5], v[6:7], v[4:5] op_sel:[1,0]
	v_pk_fma_f32 v[2:3], v[154:155], v[2:3], v[158:159]
	v_pk_fma_f32 v[12:13], v[148:149], v[12:13], v[152:153]
	v_cndmask_b32_e32 v28, v208, v8, vcc
	v_cndmask_b32_e32 v29, v208, v9, vcc
	v_lshl_add_u64 v[8:9], s[88:89], 0, v[10:11]
	v_pk_fma_f32 v[4:5], v[156:157], v[4:5], v[160:161]
	v_cndmask_b32_e32 v16, v208, v2, vcc
	v_cndmask_b32_e32 v17, v208, v3, vcc
	v_cndmask_b32_e32 v26, v208, v12, vcc
	v_cndmask_b32_e32 v27, v208, v13, vcc
	v_cvt_pk_bf16_f32 v2, v16, v17
	v_lshl_add_u64 v[12:13], v[8:9], 0, v[164:165]
	v_cndmask_b32_e32 v14, v208, v4, vcc
	v_cndmask_b32_e32 v15, v208, v5, vcc
	v_cvt_pk_bf16_f32 v3, v14, v15
	v_cvt_pk_bf16_f32 v4, v28, v29
	v_cvt_pk_bf16_f32 v5, v26, v27
	global_store_dwordx4 v[12:13], v[2:5], off sc1
	v_lshlrev_b32_e32 v8, 16, v2
	v_sub_f32_e32 v8, v16, v8
	v_and_b32_e32 v2, 0xffff0000, v2
	v_sub_f32_e32 v2, v17, v2
	v_mul_f32_e32 v8, 0x45000000, v8
	v_mul_f32_e32 v9, 0x45000000, v2
	v_mov_b32_e32 v2, v179
	v_cvt_pk_fp8_f32 v2, v8, v9
	v_lshlrev_b32_e32 v8, 16, v3
	v_and_b32_e32 v3, 0xffff0000, v3
	v_sub_f32_e32 v8, v14, v8
	v_sub_f32_e32 v3, v15, v3
	v_mul_f32_e32 v8, 0x45000000, v8
	v_mul_f32_e32 v3, 0x45000000, v3
	v_cvt_pk_fp8_f32 v2, v8, v3 op_sel:[0,0,1]
	v_lshlrev_b32_e32 v3, 16, v4
	v_sub_f32_e32 v3, v28, v3
	v_mul_f32_e32 v8, 0x45000000, v3
	v_and_b32_e32 v3, 0xffff0000, v4
	v_sub_f32_e32 v3, v29, v3
	v_mul_f32_e32 v4, 0x45000000, v3
	v_mov_b32_e32 v3, v179
	v_cvt_pk_fp8_f32 v3, v8, v4
	v_lshlrev_b32_e32 v4, 16, v5
	v_and_b32_e32 v5, 0xffff0000, v5
	v_sub_f32_e32 v4, v26, v4
	v_sub_f32_e32 v5, v27, v5
	v_mul_f32_e32 v4, 0x45000000, v4
	v_mul_f32_e32 v5, 0x45000000, v5
	v_cvt_pk_fp8_f32 v3, v4, v5 op_sel:[0,0,1]
	v_sub_f32_e32 v5, v47, v6
	v_sub_f32_e32 v4, v46, v6
	v_sub_f32_e32 v9, v49, v6
	v_sub_f32_e32 v8, v48, v6
	v_sub_f32_e32 v15, v43, v6
	v_sub_f32_e32 v14, v42, v6
	v_sub_f32_e32 v17, v45, v6
	v_sub_f32_e32 v16, v44, v6
	v_pk_mul_f32 v[8:9], v[6:7], v[8:9] op_sel:[1,0]
	v_pk_mul_f32 v[4:5], v[6:7], v[4:5] op_sel:[1,0]
	v_pk_mul_f32 v[16:17], v[6:7], v[16:17] op_sel:[1,0]
	v_pk_mul_f32 v[6:7], v[6:7], v[14:15] op_sel:[1,0]
	v_pk_fma_f32 v[4:5], v[138:139], v[4:5], v[142:143]
	v_pk_fma_f32 v[6:7], v[130:131], v[6:7], v[134:135]
	v_cndmask_b32_e32 v4, v208, v4, vcc
	v_cndmask_b32_e32 v5, v208, v5, vcc
	v_cndmask_b32_e32 v26, v208, v6, vcc
	v_cvt_pk_bf16_f32 v6, v4, v5
	v_pk_fma_f32 v[8:9], v[140:141], v[8:9], v[144:145]
	v_lshlrev_b32_e32 v28, 16, v6
	v_sub_f32_e32 v4, v4, v28
	v_mul_f32_e32 v28, 0x45000000, v4
	v_and_b32_e32 v4, 0xffff0000, v6
	v_sub_f32_e32 v4, v5, v4
	v_mul_f32_e32 v5, 0x45000000, v4
	v_mov_b32_e32 v4, v179
	v_pk_fma_f32 v[14:15], v[132:133], v[16:17], v[136:137]
	v_cndmask_b32_e32 v16, v208, v8, vcc
	v_cndmask_b32_e32 v17, v208, v9, vcc
	v_cndmask_b32_e32 v27, v208, v7, vcc
	v_cvt_pk_bf16_f32 v7, v16, v17
	v_cvt_pk_fp8_f32 v4, v28, v5
	v_lshlrev_b32_e32 v5, 16, v7
	v_sub_f32_e32 v5, v16, v5
	v_and_b32_e32 v16, 0xffff0000, v7
	v_sub_f32_e32 v16, v17, v16
	v_mul_f32_e32 v5, 0x45000000, v5
	v_mul_f32_e32 v16, 0x45000000, v16
	v_cvt_pk_bf16_f32 v8, v26, v27
	v_cvt_pk_fp8_f32 v4, v5, v16 op_sel:[0,0,1]
	v_lshlrev_b32_e32 v5, 16, v8
	v_sub_f32_e32 v5, v26, v5
	v_mul_f32_e32 v16, 0x45000000, v5
	v_and_b32_e32 v5, 0xffff0000, v8
	v_sub_f32_e32 v5, v27, v5
	v_mul_f32_e32 v17, 0x45000000, v5
	v_mov_b32_e32 v5, v179
	v_cndmask_b32_e32 v14, v208, v14, vcc
	v_cndmask_b32_e32 v15, v208, v15, vcc
	v_cvt_pk_bf16_f32 v9, v14, v15
	v_cvt_pk_fp8_f32 v5, v16, v17
	v_lshlrev_b32_e32 v16, 16, v9
	v_sub_f32_e32 v14, v14, v16
	v_and_b32_e32 v16, 0xffff0000, v9
	v_sub_f32_e32 v15, v15, v16
	v_mul_f32_e32 v14, 0x45000000, v14
	v_mul_f32_e32 v15, 0x45000000, v15
	v_cvt_pk_fp8_f32 v5, v14, v15 op_sel:[0,0,1]
	global_store_dwordx4 v[12:13], v[6:9], off offset:256 sc1
	s_nop 1
	v_lshl_add_u64 v[6:7], s[18:19], 0, v[10:11]
	v_lshl_add_u64 v[6:7], v[6:7], 0, v[162:163]
	global_store_dwordx4 v[6:7], v[2:5], off sc1
	ds_read_b64 v[6:7], v169 offset:8448
	s_waitcnt lgkmcnt(0)
	v_sub_f32_e32 v9, v51, v6
	v_add_u32_e32 v2, 32, v166
	v_ashrrev_i32_e32 v3, 31, v2
	v_sub_f32_e32 v8, v50, v6
	v_lshlrev_b64 v[10:11], 11, v[2:3]
	v_sub_f32_e32 v3, v59, v6
	v_sub_f32_e32 v2, v58, v6
	v_sub_f32_e32 v13, v53, v6
	v_sub_f32_e32 v12, v52, v6
	v_pk_mul_f32 v[8:9], v[6:7], v[8:9] op_sel:[1,0]
	v_sub_f32_e32 v5, v61, v6
	v_sub_f32_e32 v4, v60, v6
	v_pk_mul_f32 v[2:3], v[6:7], v[2:3] op_sel:[1,0]
	v_pk_mul_f32 v[12:13], v[6:7], v[12:13] op_sel:[1,0]
	v_pk_fma_f32 v[8:9], v[146:147], v[8:9], v[150:151]
	v_pk_mul_f32 v[4:5], v[6:7], v[4:5] op_sel:[1,0]
	v_pk_fma_f32 v[2:3], v[154:155], v[2:3], v[158:159]
	v_pk_fma_f32 v[12:13], v[148:149], v[12:13], v[152:153]
	v_cndmask_b32_e32 v28, v208, v8, vcc
	v_cndmask_b32_e32 v29, v208, v9, vcc
	v_lshl_add_u64 v[8:9], s[88:89], 0, v[10:11]
	v_pk_fma_f32 v[4:5], v[156:157], v[4:5], v[160:161]
	v_cndmask_b32_e32 v16, v208, v2, vcc
	v_cndmask_b32_e32 v17, v208, v3, vcc
	v_cndmask_b32_e32 v26, v208, v12, vcc
	v_cndmask_b32_e32 v27, v208, v13, vcc
	v_cvt_pk_bf16_f32 v2, v16, v17
	v_lshl_add_u64 v[12:13], v[8:9], 0, v[164:165]
	v_cndmask_b32_e32 v14, v208, v4, vcc
	v_cndmask_b32_e32 v15, v208, v5, vcc
	v_cvt_pk_bf16_f32 v3, v14, v15
	v_cvt_pk_bf16_f32 v4, v28, v29
	v_cvt_pk_bf16_f32 v5, v26, v27
	global_store_dwordx4 v[12:13], v[2:5], off sc1
	v_lshlrev_b32_e32 v8, 16, v2
	v_sub_f32_e32 v8, v16, v8
	v_and_b32_e32 v2, 0xffff0000, v2
	v_sub_f32_e32 v2, v17, v2
	v_mul_f32_e32 v8, 0x45000000, v8
	v_mul_f32_e32 v9, 0x45000000, v2
	v_mov_b32_e32 v2, v179
	v_cvt_pk_fp8_f32 v2, v8, v9
	v_lshlrev_b32_e32 v8, 16, v3
	v_and_b32_e32 v3, 0xffff0000, v3
	v_sub_f32_e32 v8, v14, v8
	v_sub_f32_e32 v3, v15, v3
	v_mul_f32_e32 v8, 0x45000000, v8
	v_mul_f32_e32 v3, 0x45000000, v3
	v_cvt_pk_fp8_f32 v2, v8, v3 op_sel:[0,0,1]
	v_lshlrev_b32_e32 v3, 16, v4
	v_sub_f32_e32 v3, v28, v3
	v_mul_f32_e32 v8, 0x45000000, v3
	v_and_b32_e32 v3, 0xffff0000, v4
	v_sub_f32_e32 v3, v29, v3
	v_mul_f32_e32 v4, 0x45000000, v3
	v_mov_b32_e32 v3, v179
	v_cvt_pk_fp8_f32 v3, v8, v4
	v_lshlrev_b32_e32 v4, 16, v5
	v_and_b32_e32 v5, 0xffff0000, v5
	v_sub_f32_e32 v4, v26, v4
	v_sub_f32_e32 v5, v27, v5
	v_mul_f32_e32 v4, 0x45000000, v4
	v_mul_f32_e32 v5, 0x45000000, v5
	v_cvt_pk_fp8_f32 v3, v4, v5 op_sel:[0,0,1]
	v_sub_f32_e32 v5, v71, v6
	v_sub_f32_e32 v4, v70, v6
	v_sub_f32_e32 v9, v73, v6
	v_sub_f32_e32 v8, v72, v6
	v_sub_f32_e32 v15, v67, v6
	v_sub_f32_e32 v14, v66, v6
	v_sub_f32_e32 v17, v69, v6
	v_sub_f32_e32 v16, v68, v6
	v_pk_mul_f32 v[8:9], v[6:7], v[8:9] op_sel:[1,0]
	v_pk_mul_f32 v[4:5], v[6:7], v[4:5] op_sel:[1,0]
	v_pk_mul_f32 v[16:17], v[6:7], v[16:17] op_sel:[1,0]
	v_pk_mul_f32 v[6:7], v[6:7], v[14:15] op_sel:[1,0]
	v_pk_fma_f32 v[4:5], v[138:139], v[4:5], v[142:143]
	v_pk_fma_f32 v[6:7], v[130:131], v[6:7], v[134:135]
	v_cndmask_b32_e32 v4, v208, v4, vcc
	v_cndmask_b32_e32 v5, v208, v5, vcc
	v_cndmask_b32_e32 v26, v208, v6, vcc
	v_cvt_pk_bf16_f32 v6, v4, v5
	v_pk_fma_f32 v[8:9], v[140:141], v[8:9], v[144:145]
	v_lshlrev_b32_e32 v28, 16, v6
	v_sub_f32_e32 v4, v4, v28
	v_mul_f32_e32 v28, 0x45000000, v4
	v_and_b32_e32 v4, 0xffff0000, v6
	v_sub_f32_e32 v4, v5, v4
	v_mul_f32_e32 v5, 0x45000000, v4
	v_mov_b32_e32 v4, v179
	v_pk_fma_f32 v[14:15], v[132:133], v[16:17], v[136:137]
	v_cndmask_b32_e32 v16, v208, v8, vcc
	v_cndmask_b32_e32 v17, v208, v9, vcc
	v_cndmask_b32_e32 v27, v208, v7, vcc
	v_cvt_pk_bf16_f32 v7, v16, v17
	v_cvt_pk_fp8_f32 v4, v28, v5
	v_lshlrev_b32_e32 v5, 16, v7
	v_sub_f32_e32 v5, v16, v5
	v_and_b32_e32 v16, 0xffff0000, v7
	v_sub_f32_e32 v16, v17, v16
	v_mul_f32_e32 v5, 0x45000000, v5
	v_mul_f32_e32 v16, 0x45000000, v16
	v_cvt_pk_bf16_f32 v8, v26, v27
	v_cvt_pk_fp8_f32 v4, v5, v16 op_sel:[0,0,1]
	v_lshlrev_b32_e32 v5, 16, v8
	v_sub_f32_e32 v5, v26, v5
	v_mul_f32_e32 v16, 0x45000000, v5
	v_and_b32_e32 v5, 0xffff0000, v8
	v_sub_f32_e32 v5, v27, v5
	v_mul_f32_e32 v17, 0x45000000, v5
	v_mov_b32_e32 v5, v179
	v_cndmask_b32_e32 v14, v208, v14, vcc
	v_cndmask_b32_e32 v15, v208, v15, vcc
	v_cvt_pk_bf16_f32 v9, v14, v15
	v_cvt_pk_fp8_f32 v5, v16, v17
	v_lshlrev_b32_e32 v16, 16, v9
	v_sub_f32_e32 v14, v14, v16
	v_and_b32_e32 v16, 0xffff0000, v9
	v_sub_f32_e32 v15, v15, v16
	v_mul_f32_e32 v14, 0x45000000, v14
	v_mul_f32_e32 v15, 0x45000000, v15
	v_cvt_pk_fp8_f32 v5, v14, v15 op_sel:[0,0,1]
	global_store_dwordx4 v[12:13], v[6:9], off offset:256 sc1
	s_nop 1
	v_lshl_add_u64 v[6:7], s[18:19], 0, v[10:11]
	v_lshl_add_u64 v[6:7], v[6:7], 0, v[162:163]
	global_store_dwordx4 v[6:7], v[2:5], off sc1
	ds_read_b64 v[6:7], v169 offset:8576
	s_waitcnt lgkmcnt(0)
	v_sub_f32_e32 v9, v83, v6
	v_add_u32_e32 v2, 48, v166
	v_ashrrev_i32_e32 v3, 31, v2
	v_sub_f32_e32 v8, v82, v6
	v_lshlrev_b64 v[10:11], 11, v[2:3]
	v_sub_f32_e32 v3, v87, v6
	v_sub_f32_e32 v2, v86, v6
	v_sub_f32_e32 v13, v85, v6
	v_sub_f32_e32 v12, v84, v6
	v_pk_mul_f32 v[8:9], v[6:7], v[8:9] op_sel:[1,0]
	v_sub_f32_e32 v5, v89, v6
	v_sub_f32_e32 v4, v88, v6
	v_pk_mul_f32 v[2:3], v[6:7], v[2:3] op_sel:[1,0]
	v_pk_mul_f32 v[12:13], v[6:7], v[12:13] op_sel:[1,0]
	v_pk_fma_f32 v[8:9], v[146:147], v[8:9], v[150:151]
	v_pk_mul_f32 v[4:5], v[6:7], v[4:5] op_sel:[1,0]
	v_pk_fma_f32 v[2:3], v[154:155], v[2:3], v[158:159]
	v_pk_fma_f32 v[12:13], v[148:149], v[12:13], v[152:153]
	v_cndmask_b32_e32 v28, v208, v8, vcc
	v_cndmask_b32_e32 v29, v208, v9, vcc
	v_lshl_add_u64 v[8:9], s[88:89], 0, v[10:11]
	v_pk_fma_f32 v[4:5], v[156:157], v[4:5], v[160:161]
	v_cndmask_b32_e32 v16, v208, v2, vcc
	v_cndmask_b32_e32 v17, v208, v3, vcc
	v_cndmask_b32_e32 v26, v208, v12, vcc
	v_cndmask_b32_e32 v27, v208, v13, vcc
	v_cvt_pk_bf16_f32 v2, v16, v17
	v_lshl_add_u64 v[12:13], v[8:9], 0, v[164:165]
	v_cndmask_b32_e32 v14, v208, v4, vcc
	v_cndmask_b32_e32 v15, v208, v5, vcc
	v_cvt_pk_bf16_f32 v3, v14, v15
	v_cvt_pk_bf16_f32 v4, v28, v29
	v_cvt_pk_bf16_f32 v5, v26, v27
	global_store_dwordx4 v[12:13], v[2:5], off sc1
	v_lshlrev_b32_e32 v8, 16, v2
	v_sub_f32_e32 v8, v16, v8
	v_and_b32_e32 v2, 0xffff0000, v2
	v_sub_f32_e32 v2, v17, v2
	v_mul_f32_e32 v8, 0x45000000, v8
	v_mul_f32_e32 v9, 0x45000000, v2
	v_mov_b32_e32 v2, v179
	v_cvt_pk_fp8_f32 v2, v8, v9
	v_lshlrev_b32_e32 v8, 16, v3
	v_and_b32_e32 v3, 0xffff0000, v3
	v_sub_f32_e32 v8, v14, v8
	v_sub_f32_e32 v3, v15, v3
	v_mul_f32_e32 v8, 0x45000000, v8
	v_mul_f32_e32 v3, 0x45000000, v3
	v_cvt_pk_fp8_f32 v2, v8, v3 op_sel:[0,0,1]
	v_lshlrev_b32_e32 v3, 16, v4
	v_sub_f32_e32 v3, v28, v3
	v_mul_f32_e32 v8, 0x45000000, v3
	v_and_b32_e32 v3, 0xffff0000, v4
	v_sub_f32_e32 v3, v29, v3
	v_mul_f32_e32 v4, 0x45000000, v3
	v_mov_b32_e32 v3, v179
	v_cvt_pk_fp8_f32 v3, v8, v4
	v_lshlrev_b32_e32 v4, 16, v5
	v_and_b32_e32 v5, 0xffff0000, v5
	v_sub_f32_e32 v4, v26, v4
	v_sub_f32_e32 v5, v27, v5
	v_mul_f32_e32 v4, 0x45000000, v4
	v_mul_f32_e32 v5, 0x45000000, v5
	v_cvt_pk_fp8_f32 v3, v4, v5 op_sel:[0,0,1]
	v_sub_f32_e32 v5, v95, v6
	v_sub_f32_e32 v4, v94, v6
	v_sub_f32_e32 v9, v97, v6
	v_sub_f32_e32 v8, v96, v6
	v_sub_f32_e32 v15, v91, v6
	v_sub_f32_e32 v14, v90, v6
	v_sub_f32_e32 v17, v93, v6
	v_sub_f32_e32 v16, v92, v6
	v_pk_mul_f32 v[8:9], v[6:7], v[8:9] op_sel:[1,0]
	v_pk_mul_f32 v[4:5], v[6:7], v[4:5] op_sel:[1,0]
	v_pk_mul_f32 v[16:17], v[6:7], v[16:17] op_sel:[1,0]
	v_pk_mul_f32 v[6:7], v[6:7], v[14:15] op_sel:[1,0]
	v_pk_fma_f32 v[4:5], v[138:139], v[4:5], v[142:143]
	v_pk_fma_f32 v[6:7], v[130:131], v[6:7], v[134:135]
	v_cndmask_b32_e32 v4, v208, v4, vcc
	v_cndmask_b32_e32 v5, v208, v5, vcc
	v_cndmask_b32_e32 v26, v208, v6, vcc
	v_cvt_pk_bf16_f32 v6, v4, v5
	v_pk_fma_f32 v[8:9], v[140:141], v[8:9], v[144:145]
	v_lshlrev_b32_e32 v28, 16, v6
	v_sub_f32_e32 v4, v4, v28
	v_mul_f32_e32 v28, 0x45000000, v4
	v_and_b32_e32 v4, 0xffff0000, v6
	v_sub_f32_e32 v4, v5, v4
	v_mul_f32_e32 v5, 0x45000000, v4
	v_mov_b32_e32 v4, v179
	v_pk_fma_f32 v[14:15], v[132:133], v[16:17], v[136:137]
	v_cndmask_b32_e32 v16, v208, v8, vcc
	v_cndmask_b32_e32 v17, v208, v9, vcc
	v_cndmask_b32_e32 v27, v208, v7, vcc
	v_cvt_pk_bf16_f32 v7, v16, v17
	v_cvt_pk_fp8_f32 v4, v28, v5
	v_lshlrev_b32_e32 v5, 16, v7
	v_sub_f32_e32 v5, v16, v5
	v_and_b32_e32 v16, 0xffff0000, v7
	v_sub_f32_e32 v16, v17, v16
	v_mul_f32_e32 v5, 0x45000000, v5
	v_mul_f32_e32 v16, 0x45000000, v16
	v_cvt_pk_bf16_f32 v8, v26, v27
	v_cvt_pk_fp8_f32 v4, v5, v16 op_sel:[0,0,1]
	v_lshlrev_b32_e32 v5, 16, v8
	v_sub_f32_e32 v5, v26, v5
	v_mul_f32_e32 v16, 0x45000000, v5
	v_and_b32_e32 v5, 0xffff0000, v8
	v_sub_f32_e32 v5, v27, v5
	v_mul_f32_e32 v17, 0x45000000, v5
	v_mov_b32_e32 v5, v179
	v_cndmask_b32_e32 v14, v208, v14, vcc
	v_cndmask_b32_e32 v15, v208, v15, vcc
	v_cvt_pk_bf16_f32 v9, v14, v15
	v_cvt_pk_fp8_f32 v5, v16, v17
	v_lshlrev_b32_e32 v16, 16, v9
	v_sub_f32_e32 v14, v14, v16
	v_and_b32_e32 v16, 0xffff0000, v9
	v_sub_f32_e32 v15, v15, v16
	v_mul_f32_e32 v14, 0x45000000, v14
	v_mul_f32_e32 v15, 0x45000000, v15
	v_cvt_pk_fp8_f32 v5, v14, v15 op_sel:[0,0,1]
	global_store_dwordx4 v[12:13], v[6:9], off offset:256 sc1
	s_nop 1
	v_lshl_add_u64 v[6:7], s[18:19], 0, v[10:11]
	v_lshl_add_u64 v[6:7], v[6:7], 0, v[162:163]
	global_store_dwordx4 v[6:7], v[2:5], off sc1
	ds_read_b64 v[6:7], v169 offset:9216
	s_waitcnt lgkmcnt(0)
	v_sub_f32_e32 v9, v107, v6
	v_add_u32_e32 v2, 0x80, v166
	v_ashrrev_i32_e32 v3, 31, v2
	v_sub_f32_e32 v8, v106, v6
	v_lshlrev_b64 v[10:11], 11, v[2:3]
	v_sub_f32_e32 v3, v111, v6
	v_sub_f32_e32 v2, v110, v6
	v_sub_f32_e32 v13, v109, v6
	v_sub_f32_e32 v12, v108, v6
	v_pk_mul_f32 v[8:9], v[6:7], v[8:9] op_sel:[1,0]
	v_sub_f32_e32 v5, v113, v6
	v_sub_f32_e32 v4, v112, v6
	v_pk_mul_f32 v[2:3], v[6:7], v[2:3] op_sel:[1,0]
	v_pk_mul_f32 v[12:13], v[6:7], v[12:13] op_sel:[1,0]
	v_pk_fma_f32 v[8:9], v[146:147], v[8:9], v[150:151]
	v_pk_mul_f32 v[4:5], v[6:7], v[4:5] op_sel:[1,0]
	v_pk_fma_f32 v[2:3], v[154:155], v[2:3], v[158:159]
	v_pk_fma_f32 v[12:13], v[148:149], v[12:13], v[152:153]
	v_cndmask_b32_e32 v28, v208, v8, vcc
	v_cndmask_b32_e32 v29, v208, v9, vcc
	v_lshl_add_u64 v[8:9], s[88:89], 0, v[10:11]
	v_pk_fma_f32 v[4:5], v[156:157], v[4:5], v[160:161]
	v_cndmask_b32_e32 v16, v208, v2, vcc
	v_cndmask_b32_e32 v17, v208, v3, vcc
	v_cndmask_b32_e32 v26, v208, v12, vcc
	v_cndmask_b32_e32 v27, v208, v13, vcc
	v_cvt_pk_bf16_f32 v2, v16, v17
	v_lshl_add_u64 v[12:13], v[8:9], 0, v[164:165]
	v_cndmask_b32_e32 v14, v208, v4, vcc
	v_cndmask_b32_e32 v15, v208, v5, vcc
	v_cvt_pk_bf16_f32 v3, v14, v15
	v_cvt_pk_bf16_f32 v4, v28, v29
	v_cvt_pk_bf16_f32 v5, v26, v27
	global_store_dwordx4 v[12:13], v[2:5], off sc1
	v_lshlrev_b32_e32 v8, 16, v2
	v_sub_f32_e32 v8, v16, v8
	v_and_b32_e32 v2, 0xffff0000, v2
	v_sub_f32_e32 v2, v17, v2
	v_mul_f32_e32 v8, 0x45000000, v8
	v_mul_f32_e32 v9, 0x45000000, v2
	v_mov_b32_e32 v2, v179
	v_cvt_pk_fp8_f32 v2, v8, v9
	v_lshlrev_b32_e32 v8, 16, v3
	v_and_b32_e32 v3, 0xffff0000, v3
	v_sub_f32_e32 v8, v14, v8
	v_sub_f32_e32 v3, v15, v3
	v_mul_f32_e32 v8, 0x45000000, v8
	v_mul_f32_e32 v3, 0x45000000, v3
	v_cvt_pk_fp8_f32 v2, v8, v3 op_sel:[0,0,1]
	v_lshlrev_b32_e32 v3, 16, v4
	v_sub_f32_e32 v3, v28, v3
	v_mul_f32_e32 v8, 0x45000000, v3
	v_and_b32_e32 v3, 0xffff0000, v4
	v_sub_f32_e32 v3, v29, v3
	v_mul_f32_e32 v4, 0x45000000, v3
	v_mov_b32_e32 v3, v179
	v_cvt_pk_fp8_f32 v3, v8, v4
	v_lshlrev_b32_e32 v4, 16, v5
	v_and_b32_e32 v5, 0xffff0000, v5
	v_sub_f32_e32 v4, v26, v4
	v_sub_f32_e32 v5, v27, v5
	v_mul_f32_e32 v4, 0x45000000, v4
	v_mul_f32_e32 v5, 0x45000000, v5
	v_cvt_pk_fp8_f32 v3, v4, v5 op_sel:[0,0,1]
	v_sub_f32_e32 v5, v119, v6
	v_sub_f32_e32 v4, v118, v6
	v_sub_f32_e32 v9, v121, v6
	v_sub_f32_e32 v8, v120, v6
	v_sub_f32_e32 v15, v115, v6
	v_sub_f32_e32 v14, v114, v6
	v_sub_f32_e32 v17, v117, v6
	v_sub_f32_e32 v16, v116, v6
	v_pk_mul_f32 v[8:9], v[6:7], v[8:9] op_sel:[1,0]
	v_pk_mul_f32 v[4:5], v[6:7], v[4:5] op_sel:[1,0]
	v_pk_mul_f32 v[16:17], v[6:7], v[16:17] op_sel:[1,0]
	v_pk_mul_f32 v[6:7], v[6:7], v[14:15] op_sel:[1,0]
	v_pk_fma_f32 v[4:5], v[138:139], v[4:5], v[142:143]
	v_pk_fma_f32 v[6:7], v[130:131], v[6:7], v[134:135]
	v_cndmask_b32_e32 v4, v208, v4, vcc
	v_cndmask_b32_e32 v5, v208, v5, vcc
	v_cndmask_b32_e32 v26, v208, v6, vcc
	v_cvt_pk_bf16_f32 v6, v4, v5
	v_pk_fma_f32 v[8:9], v[140:141], v[8:9], v[144:145]
	v_lshlrev_b32_e32 v28, 16, v6
	v_sub_f32_e32 v4, v4, v28
	v_mul_f32_e32 v28, 0x45000000, v4
	v_and_b32_e32 v4, 0xffff0000, v6
	v_sub_f32_e32 v4, v5, v4
	v_mul_f32_e32 v5, 0x45000000, v4
	v_mov_b32_e32 v4, v179
	v_pk_fma_f32 v[14:15], v[132:133], v[16:17], v[136:137]
	v_cndmask_b32_e32 v16, v208, v8, vcc
	v_cndmask_b32_e32 v17, v208, v9, vcc
	v_cndmask_b32_e32 v27, v208, v7, vcc
	v_cvt_pk_bf16_f32 v7, v16, v17
	v_cvt_pk_fp8_f32 v4, v28, v5
	v_lshlrev_b32_e32 v5, 16, v7
	v_sub_f32_e32 v5, v16, v5
	v_and_b32_e32 v16, 0xffff0000, v7
	v_sub_f32_e32 v16, v17, v16
	v_mul_f32_e32 v5, 0x45000000, v5
	v_mul_f32_e32 v16, 0x45000000, v16
	v_cvt_pk_bf16_f32 v8, v26, v27
	v_cvt_pk_fp8_f32 v4, v5, v16 op_sel:[0,0,1]
	v_lshlrev_b32_e32 v5, 16, v8
	v_sub_f32_e32 v5, v26, v5
	v_mul_f32_e32 v16, 0x45000000, v5
	v_and_b32_e32 v5, 0xffff0000, v8
	v_sub_f32_e32 v5, v27, v5
	v_mul_f32_e32 v17, 0x45000000, v5
	v_mov_b32_e32 v5, v179
	v_cndmask_b32_e32 v14, v208, v14, vcc
	v_cndmask_b32_e32 v15, v208, v15, vcc
	v_cvt_pk_bf16_f32 v9, v14, v15
	v_cvt_pk_fp8_f32 v5, v16, v17
	v_lshlrev_b32_e32 v16, 16, v9
	v_sub_f32_e32 v14, v14, v16
	v_and_b32_e32 v16, 0xffff0000, v9
	v_sub_f32_e32 v15, v15, v16
	v_mul_f32_e32 v14, 0x45000000, v14
	v_mul_f32_e32 v15, 0x45000000, v15
	v_cvt_pk_fp8_f32 v5, v14, v15 op_sel:[0,0,1]
	global_store_dwordx4 v[12:13], v[6:9], off offset:256 sc1
	s_nop 1
	v_lshl_add_u64 v[6:7], s[18:19], 0, v[10:11]
	v_lshl_add_u64 v[6:7], v[6:7], 0, v[162:163]
	global_store_dwordx4 v[6:7], v[2:5], off sc1
	ds_read_b64 v[6:7], v169 offset:9344
	s_waitcnt lgkmcnt(0)
	v_sub_f32_e32 v9, v123, v6
	v_add_u32_e32 v2, 0x90, v166
	v_ashrrev_i32_e32 v3, 31, v2
	v_sub_f32_e32 v8, v122, v6
	v_lshlrev_b64 v[10:11], 11, v[2:3]
	v_sub_f32_e32 v3, v127, v6
	v_sub_f32_e32 v2, v126, v6
	v_sub_f32_e32 v13, v125, v6
	v_sub_f32_e32 v12, v124, v6
	v_pk_mul_f32 v[8:9], v[6:7], v[8:9] op_sel:[1,0]
	v_sub_f32_e32 v5, v129, v6
	v_sub_f32_e32 v4, v128, v6
	v_pk_mul_f32 v[2:3], v[6:7], v[2:3] op_sel:[1,0]
	v_pk_mul_f32 v[12:13], v[6:7], v[12:13] op_sel:[1,0]
	v_pk_fma_f32 v[8:9], v[146:147], v[8:9], v[150:151]
	v_pk_mul_f32 v[4:5], v[6:7], v[4:5] op_sel:[1,0]
	v_pk_fma_f32 v[2:3], v[154:155], v[2:3], v[158:159]
	v_pk_fma_f32 v[12:13], v[148:149], v[12:13], v[152:153]
	v_cndmask_b32_e32 v28, v208, v8, vcc
	v_cndmask_b32_e32 v29, v208, v9, vcc
	v_lshl_add_u64 v[8:9], s[88:89], 0, v[10:11]
	v_pk_fma_f32 v[4:5], v[156:157], v[4:5], v[160:161]
	v_cndmask_b32_e32 v16, v208, v2, vcc
	v_cndmask_b32_e32 v17, v208, v3, vcc
	v_cndmask_b32_e32 v26, v208, v12, vcc
	v_cndmask_b32_e32 v27, v208, v13, vcc
	v_cvt_pk_bf16_f32 v2, v16, v17
	v_lshl_add_u64 v[12:13], v[8:9], 0, v[164:165]
	v_cndmask_b32_e32 v14, v208, v4, vcc
	v_cndmask_b32_e32 v15, v208, v5, vcc
	v_cvt_pk_bf16_f32 v3, v14, v15
	v_cvt_pk_bf16_f32 v4, v28, v29
	v_cvt_pk_bf16_f32 v5, v26, v27
	global_store_dwordx4 v[12:13], v[2:5], off sc1
	v_lshlrev_b32_e32 v8, 16, v2
	v_sub_f32_e32 v8, v16, v8
	v_and_b32_e32 v2, 0xffff0000, v2
	v_sub_f32_e32 v2, v17, v2
	v_mul_f32_e32 v8, 0x45000000, v8
	v_mul_f32_e32 v9, 0x45000000, v2
	v_mov_b32_e32 v2, v179
	v_cvt_pk_fp8_f32 v2, v8, v9
	v_lshlrev_b32_e32 v8, 16, v3
	v_and_b32_e32 v3, 0xffff0000, v3
	v_sub_f32_e32 v8, v14, v8
	v_sub_f32_e32 v3, v15, v3
	v_mul_f32_e32 v8, 0x45000000, v8
	v_mul_f32_e32 v3, 0x45000000, v3
	v_cvt_pk_fp8_f32 v2, v8, v3 op_sel:[0,0,1]
	v_lshlrev_b32_e32 v3, 16, v4
	v_sub_f32_e32 v3, v28, v3
	v_mul_f32_e32 v8, 0x45000000, v3
	v_and_b32_e32 v3, 0xffff0000, v4
	v_sub_f32_e32 v3, v29, v3
	v_mul_f32_e32 v4, 0x45000000, v3
	v_mov_b32_e32 v3, v179
	v_cvt_pk_fp8_f32 v3, v8, v4
	v_lshlrev_b32_e32 v4, 16, v5
	v_and_b32_e32 v5, 0xffff0000, v5
	v_sub_f32_e32 v4, v26, v4
	v_sub_f32_e32 v5, v27, v5
	v_mul_f32_e32 v4, 0x45000000, v4
	v_mul_f32_e32 v5, 0x45000000, v5
	v_cvt_pk_fp8_f32 v3, v4, v5 op_sel:[0,0,1]
	v_sub_f32_e32 v5, v103, v6
	v_sub_f32_e32 v4, v102, v6
	v_sub_f32_e32 v9, v105, v6
	v_sub_f32_e32 v8, v104, v6
	v_sub_f32_e32 v15, v99, v6
	v_sub_f32_e32 v14, v98, v6
	v_sub_f32_e32 v17, v101, v6
	v_sub_f32_e32 v16, v100, v6
	v_pk_mul_f32 v[8:9], v[6:7], v[8:9] op_sel:[1,0]
	v_pk_mul_f32 v[4:5], v[6:7], v[4:5] op_sel:[1,0]
	v_pk_mul_f32 v[16:17], v[6:7], v[16:17] op_sel:[1,0]
	v_pk_mul_f32 v[6:7], v[6:7], v[14:15] op_sel:[1,0]
	v_pk_fma_f32 v[4:5], v[138:139], v[4:5], v[142:143]
	v_pk_fma_f32 v[6:7], v[130:131], v[6:7], v[134:135]
	v_cndmask_b32_e32 v4, v208, v4, vcc
	v_cndmask_b32_e32 v5, v208, v5, vcc
	v_cndmask_b32_e32 v26, v208, v6, vcc
	v_cvt_pk_bf16_f32 v6, v4, v5
	v_pk_fma_f32 v[8:9], v[140:141], v[8:9], v[144:145]
	v_lshlrev_b32_e32 v28, 16, v6
	v_sub_f32_e32 v4, v4, v28
	v_mul_f32_e32 v28, 0x45000000, v4
	v_and_b32_e32 v4, 0xffff0000, v6
	v_sub_f32_e32 v4, v5, v4
	v_mul_f32_e32 v5, 0x45000000, v4
	v_mov_b32_e32 v4, v179
	v_pk_fma_f32 v[14:15], v[132:133], v[16:17], v[136:137]
	v_cndmask_b32_e32 v16, v208, v8, vcc
	v_cndmask_b32_e32 v17, v208, v9, vcc
	v_cndmask_b32_e32 v27, v208, v7, vcc
	v_cvt_pk_bf16_f32 v7, v16, v17
	v_cvt_pk_fp8_f32 v4, v28, v5
	v_lshlrev_b32_e32 v5, 16, v7
	v_sub_f32_e32 v5, v16, v5
	v_and_b32_e32 v16, 0xffff0000, v7
	v_sub_f32_e32 v16, v17, v16
	v_mul_f32_e32 v5, 0x45000000, v5
	v_mul_f32_e32 v16, 0x45000000, v16
	v_cvt_pk_bf16_f32 v8, v26, v27
	v_cvt_pk_fp8_f32 v4, v5, v16 op_sel:[0,0,1]
	v_lshlrev_b32_e32 v5, 16, v8
	v_sub_f32_e32 v5, v26, v5
	v_mul_f32_e32 v16, 0x45000000, v5
	v_and_b32_e32 v5, 0xffff0000, v8
	v_sub_f32_e32 v5, v27, v5
	v_mul_f32_e32 v17, 0x45000000, v5
	v_mov_b32_e32 v5, v179
	v_cndmask_b32_e32 v14, v208, v14, vcc
	v_cndmask_b32_e32 v15, v208, v15, vcc
	v_cvt_pk_bf16_f32 v9, v14, v15
	v_cvt_pk_fp8_f32 v5, v16, v17
	v_lshlrev_b32_e32 v16, 16, v9
	v_sub_f32_e32 v14, v14, v16
	v_and_b32_e32 v16, 0xffff0000, v9
	v_sub_f32_e32 v15, v15, v16
	v_mul_f32_e32 v14, 0x45000000, v14
	v_mul_f32_e32 v15, 0x45000000, v15
	v_cvt_pk_fp8_f32 v5, v14, v15 op_sel:[0,0,1]
	global_store_dwordx4 v[12:13], v[6:9], off offset:256 sc1
	s_nop 1
	v_lshl_add_u64 v[6:7], s[18:19], 0, v[10:11]
	v_lshl_add_u64 v[6:7], v[6:7], 0, v[162:163]
	global_store_dwordx4 v[6:7], v[2:5], off sc1
	ds_read_b64 v[6:7], v169 offset:9472
	s_waitcnt lgkmcnt(0)
	v_sub_f32_e32 v9, v75, v6
	v_add_u32_e32 v2, 0xa0, v166
	v_ashrrev_i32_e32 v3, 31, v2
	v_sub_f32_e32 v8, v74, v6
	v_lshlrev_b64 v[10:11], 11, v[2:3]
	v_sub_f32_e32 v3, v79, v6
	v_sub_f32_e32 v2, v78, v6
	v_sub_f32_e32 v13, v77, v6
	v_sub_f32_e32 v12, v76, v6
	v_pk_mul_f32 v[8:9], v[6:7], v[8:9] op_sel:[1,0]
	v_sub_f32_e32 v5, v81, v6
	v_sub_f32_e32 v4, v80, v6
	v_pk_mul_f32 v[2:3], v[6:7], v[2:3] op_sel:[1,0]
	v_pk_mul_f32 v[12:13], v[6:7], v[12:13] op_sel:[1,0]
	v_pk_fma_f32 v[8:9], v[146:147], v[8:9], v[150:151]
	v_pk_mul_f32 v[4:5], v[6:7], v[4:5] op_sel:[1,0]
	v_pk_fma_f32 v[2:3], v[154:155], v[2:3], v[158:159]
	v_pk_fma_f32 v[12:13], v[148:149], v[12:13], v[152:153]
	v_cndmask_b32_e32 v28, v208, v8, vcc
	v_cndmask_b32_e32 v29, v208, v9, vcc
	v_lshl_add_u64 v[8:9], s[88:89], 0, v[10:11]
	v_pk_fma_f32 v[4:5], v[156:157], v[4:5], v[160:161]
	v_cndmask_b32_e32 v16, v208, v2, vcc
	v_cndmask_b32_e32 v17, v208, v3, vcc
	v_cndmask_b32_e32 v26, v208, v12, vcc
	v_cndmask_b32_e32 v27, v208, v13, vcc
	v_cvt_pk_bf16_f32 v2, v16, v17
	v_lshl_add_u64 v[12:13], v[8:9], 0, v[164:165]
	v_cndmask_b32_e32 v14, v208, v4, vcc
	v_cndmask_b32_e32 v15, v208, v5, vcc
	v_cvt_pk_bf16_f32 v3, v14, v15
	v_cvt_pk_bf16_f32 v4, v28, v29
	v_cvt_pk_bf16_f32 v5, v26, v27
	global_store_dwordx4 v[12:13], v[2:5], off sc1
	v_lshlrev_b32_e32 v8, 16, v2
	v_sub_f32_e32 v8, v16, v8
	v_and_b32_e32 v2, 0xffff0000, v2
	v_sub_f32_e32 v2, v17, v2
	v_mul_f32_e32 v8, 0x45000000, v8
	v_mul_f32_e32 v9, 0x45000000, v2
	v_mov_b32_e32 v2, v179
	v_cvt_pk_fp8_f32 v2, v8, v9
	v_lshlrev_b32_e32 v8, 16, v3
	v_and_b32_e32 v3, 0xffff0000, v3
	v_sub_f32_e32 v8, v14, v8
	v_sub_f32_e32 v3, v15, v3
	v_mul_f32_e32 v8, 0x45000000, v8
	v_mul_f32_e32 v3, 0x45000000, v3
	v_cvt_pk_fp8_f32 v2, v8, v3 op_sel:[0,0,1]
	v_lshlrev_b32_e32 v3, 16, v4
	v_sub_f32_e32 v3, v28, v3
	v_mul_f32_e32 v8, 0x45000000, v3
	v_and_b32_e32 v3, 0xffff0000, v4
	v_sub_f32_e32 v3, v29, v3
	v_mul_f32_e32 v4, 0x45000000, v3
	v_mov_b32_e32 v3, v179
	v_cvt_pk_fp8_f32 v3, v8, v4
	v_lshlrev_b32_e32 v4, 16, v5
	v_and_b32_e32 v5, 0xffff0000, v5
	v_sub_f32_e32 v4, v26, v4
	v_sub_f32_e32 v5, v27, v5
	v_mul_f32_e32 v4, 0x45000000, v4
	v_mul_f32_e32 v5, 0x45000000, v5
	v_cvt_pk_fp8_f32 v3, v4, v5 op_sel:[0,0,1]
	v_sub_f32_e32 v5, v63, v6
	v_sub_f32_e32 v4, v62, v6
	v_sub_f32_e32 v9, v65, v6
	v_sub_f32_e32 v8, v64, v6
	v_sub_f32_e32 v15, v55, v6
	v_sub_f32_e32 v14, v54, v6
	v_sub_f32_e32 v17, v57, v6
	v_sub_f32_e32 v16, v56, v6
	v_pk_mul_f32 v[8:9], v[6:7], v[8:9] op_sel:[1,0]
	v_pk_mul_f32 v[4:5], v[6:7], v[4:5] op_sel:[1,0]
	v_pk_mul_f32 v[16:17], v[6:7], v[16:17] op_sel:[1,0]
	v_pk_mul_f32 v[6:7], v[6:7], v[14:15] op_sel:[1,0]
	v_pk_fma_f32 v[4:5], v[138:139], v[4:5], v[142:143]
	v_pk_fma_f32 v[6:7], v[130:131], v[6:7], v[134:135]
	v_cndmask_b32_e32 v4, v208, v4, vcc
	v_cndmask_b32_e32 v5, v208, v5, vcc
	v_cndmask_b32_e32 v26, v208, v6, vcc
	v_cvt_pk_bf16_f32 v6, v4, v5
	v_pk_fma_f32 v[8:9], v[140:141], v[8:9], v[144:145]
	v_lshlrev_b32_e32 v28, 16, v6
	v_sub_f32_e32 v4, v4, v28
	v_mul_f32_e32 v28, 0x45000000, v4
	v_and_b32_e32 v4, 0xffff0000, v6
	v_sub_f32_e32 v4, v5, v4
	v_mul_f32_e32 v5, 0x45000000, v4
	v_mov_b32_e32 v4, v179
	v_pk_fma_f32 v[14:15], v[132:133], v[16:17], v[136:137]
	v_cndmask_b32_e32 v16, v208, v8, vcc
	v_cndmask_b32_e32 v17, v208, v9, vcc
	v_cndmask_b32_e32 v27, v208, v7, vcc
	v_cvt_pk_bf16_f32 v7, v16, v17
	v_cvt_pk_fp8_f32 v4, v28, v5
	v_lshlrev_b32_e32 v5, 16, v7
	v_sub_f32_e32 v5, v16, v5
	v_and_b32_e32 v16, 0xffff0000, v7
	v_sub_f32_e32 v16, v17, v16
	v_mul_f32_e32 v5, 0x45000000, v5
	v_mul_f32_e32 v16, 0x45000000, v16
	v_cvt_pk_bf16_f32 v8, v26, v27
	v_cvt_pk_fp8_f32 v4, v5, v16 op_sel:[0,0,1]
	v_lshlrev_b32_e32 v5, 16, v8
	v_sub_f32_e32 v5, v26, v5
	v_mul_f32_e32 v16, 0x45000000, v5
	v_and_b32_e32 v5, 0xffff0000, v8
	v_sub_f32_e32 v5, v27, v5
	v_mul_f32_e32 v17, 0x45000000, v5
	v_mov_b32_e32 v5, v179
	v_cndmask_b32_e32 v14, v208, v14, vcc
	v_cndmask_b32_e32 v15, v208, v15, vcc
	v_cvt_pk_bf16_f32 v9, v14, v15
	v_cvt_pk_fp8_f32 v5, v16, v17
	v_lshlrev_b32_e32 v16, 16, v9
	v_sub_f32_e32 v14, v14, v16
	v_and_b32_e32 v16, 0xffff0000, v9
	v_sub_f32_e32 v15, v15, v16
	v_mul_f32_e32 v14, 0x45000000, v14
	v_mul_f32_e32 v15, 0x45000000, v15
	v_cvt_pk_fp8_f32 v5, v14, v15 op_sel:[0,0,1]
	global_store_dwordx4 v[12:13], v[6:9], off offset:256 sc1
	s_nop 1
	v_lshl_add_u64 v[6:7], s[18:19], 0, v[10:11]
	v_lshl_add_u64 v[6:7], v[6:7], 0, v[162:163]
	global_store_dwordx4 v[6:7], v[2:5], off sc1
	ds_read_b64 v[6:7], v169 offset:9600
	s_waitcnt lgkmcnt(0)
	v_sub_f32_e32 v9, v35, v6
	v_add_u32_e32 v2, 0xb0, v166
	v_ashrrev_i32_e32 v3, 31, v2
	v_sub_f32_e32 v8, v34, v6
	v_lshlrev_b64 v[10:11], 11, v[2:3]
	v_sub_f32_e32 v3, v39, v6
	v_sub_f32_e32 v2, v38, v6
	v_sub_f32_e32 v13, v37, v6
	v_sub_f32_e32 v12, v36, v6
	v_pk_mul_f32 v[8:9], v[6:7], v[8:9] op_sel:[1,0]
	v_sub_f32_e32 v5, v41, v6
	v_sub_f32_e32 v4, v40, v6
	v_pk_mul_f32 v[2:3], v[6:7], v[2:3] op_sel:[1,0]
	v_pk_mul_f32 v[12:13], v[6:7], v[12:13] op_sel:[1,0]
	v_pk_fma_f32 v[8:9], v[146:147], v[8:9], v[150:151]
	v_pk_mul_f32 v[4:5], v[6:7], v[4:5] op_sel:[1,0]
	v_pk_fma_f32 v[2:3], v[154:155], v[2:3], v[158:159]
	v_pk_fma_f32 v[12:13], v[148:149], v[12:13], v[152:153]
	v_cndmask_b32_e32 v28, v208, v8, vcc
	v_cndmask_b32_e32 v29, v208, v9, vcc
	v_lshl_add_u64 v[8:9], s[88:89], 0, v[10:11]
	v_pk_fma_f32 v[4:5], v[156:157], v[4:5], v[160:161]
	v_cndmask_b32_e32 v16, v208, v2, vcc
	v_cndmask_b32_e32 v17, v208, v3, vcc
	v_cndmask_b32_e32 v26, v208, v12, vcc
	v_cndmask_b32_e32 v27, v208, v13, vcc
	v_cvt_pk_bf16_f32 v2, v16, v17
	v_lshl_add_u64 v[12:13], v[8:9], 0, v[164:165]
	v_cndmask_b32_e32 v14, v208, v4, vcc
	v_cndmask_b32_e32 v15, v208, v5, vcc
	v_cvt_pk_bf16_f32 v3, v14, v15
	v_cvt_pk_bf16_f32 v4, v28, v29
	v_cvt_pk_bf16_f32 v5, v26, v27
	global_store_dwordx4 v[12:13], v[2:5], off sc1
	v_lshlrev_b32_e32 v8, 16, v2
	v_sub_f32_e32 v8, v16, v8
	v_and_b32_e32 v2, 0xffff0000, v2
	v_sub_f32_e32 v2, v17, v2
	v_mul_f32_e32 v8, 0x45000000, v8
	v_mul_f32_e32 v9, 0x45000000, v2
	v_mov_b32_e32 v2, v179
	v_cvt_pk_fp8_f32 v2, v8, v9
	v_lshlrev_b32_e32 v8, 16, v3
	v_and_b32_e32 v3, 0xffff0000, v3
	v_sub_f32_e32 v8, v14, v8
	v_sub_f32_e32 v3, v15, v3
	v_mul_f32_e32 v8, 0x45000000, v8
	v_mul_f32_e32 v3, 0x45000000, v3
	v_cvt_pk_fp8_f32 v2, v8, v3 op_sel:[0,0,1]
	v_lshlrev_b32_e32 v3, 16, v4
	v_sub_f32_e32 v3, v28, v3
	v_mul_f32_e32 v8, 0x45000000, v3
	v_and_b32_e32 v3, 0xffff0000, v4
	v_sub_f32_e32 v3, v29, v3
	v_mul_f32_e32 v4, 0x45000000, v3
	v_mov_b32_e32 v3, v179
	v_cvt_pk_fp8_f32 v3, v8, v4
	v_lshlrev_b32_e32 v4, 16, v5
	v_and_b32_e32 v5, 0xffff0000, v5
	v_sub_f32_e32 v4, v26, v4
	v_sub_f32_e32 v5, v27, v5
	v_mul_f32_e32 v4, 0x45000000, v4
	v_mul_f32_e32 v5, 0x45000000, v5
	v_cvt_pk_fp8_f32 v3, v4, v5 op_sel:[0,0,1]
	v_sub_f32_e32 v5, v23, v6
	v_sub_f32_e32 v4, v22, v6
	v_sub_f32_e32 v9, v25, v6
	v_sub_f32_e32 v8, v24, v6
	v_sub_f32_e32 v15, v19, v6
	v_sub_f32_e32 v14, v18, v6
	v_sub_f32_e32 v17, v21, v6
	v_sub_f32_e32 v16, v20, v6
	v_pk_mul_f32 v[8:9], v[6:7], v[8:9] op_sel:[1,0]
	v_pk_mul_f32 v[4:5], v[6:7], v[4:5] op_sel:[1,0]
	v_pk_mul_f32 v[16:17], v[6:7], v[16:17] op_sel:[1,0]
	v_pk_mul_f32 v[6:7], v[6:7], v[14:15] op_sel:[1,0]
	v_pk_fma_f32 v[4:5], v[138:139], v[4:5], v[142:143]
	v_pk_fma_f32 v[6:7], v[130:131], v[6:7], v[134:135]
	v_cndmask_b32_e32 v4, v208, v4, vcc
	v_cndmask_b32_e32 v5, v208, v5, vcc
	v_cndmask_b32_e32 v18, v208, v6, vcc
	v_cvt_pk_bf16_f32 v6, v4, v5
	v_pk_fma_f32 v[8:9], v[140:141], v[8:9], v[144:145]
	v_lshlrev_b32_e32 v20, 16, v6
	v_sub_f32_e32 v4, v4, v20
	v_mul_f32_e32 v20, 0x45000000, v4
	v_and_b32_e32 v4, 0xffff0000, v6
	v_sub_f32_e32 v4, v5, v4
	v_mul_f32_e32 v5, 0x45000000, v4
	v_mov_b32_e32 v4, v179
	v_pk_fma_f32 v[14:15], v[132:133], v[16:17], v[136:137]
	v_cndmask_b32_e32 v16, v208, v8, vcc
	v_cndmask_b32_e32 v17, v208, v9, vcc
	v_cndmask_b32_e32 v19, v208, v7, vcc
	v_cvt_pk_bf16_f32 v7, v16, v17
	v_cvt_pk_fp8_f32 v4, v20, v5
	v_lshlrev_b32_e32 v5, 16, v7
	v_sub_f32_e32 v5, v16, v5
	v_and_b32_e32 v16, 0xffff0000, v7
	v_sub_f32_e32 v16, v17, v16
	v_mul_f32_e32 v5, 0x45000000, v5
	v_mul_f32_e32 v16, 0x45000000, v16
	v_cvt_pk_bf16_f32 v8, v18, v19
	v_cvt_pk_fp8_f32 v4, v5, v16 op_sel:[0,0,1]
	v_lshlrev_b32_e32 v5, 16, v8
	v_sub_f32_e32 v5, v18, v5
	v_mul_f32_e32 v16, 0x45000000, v5
	v_and_b32_e32 v5, 0xffff0000, v8
	v_sub_f32_e32 v5, v19, v5
	v_mul_f32_e32 v17, 0x45000000, v5
	v_mov_b32_e32 v5, v179
	v_cndmask_b32_e32 v14, v208, v14, vcc
	v_cndmask_b32_e32 v15, v208, v15, vcc
	v_cvt_pk_bf16_f32 v9, v14, v15
	v_cvt_pk_fp8_f32 v5, v16, v17
	v_lshlrev_b32_e32 v16, 16, v9
	v_sub_f32_e32 v14, v14, v16
	v_and_b32_e32 v16, 0xffff0000, v9
	v_sub_f32_e32 v15, v15, v16
	v_mul_f32_e32 v14, 0x45000000, v14
	v_mul_f32_e32 v15, 0x45000000, v15
	v_cvt_pk_fp8_f32 v5, v14, v15 op_sel:[0,0,1]
	global_store_dwordx4 v[12:13], v[6:9], off offset:256 sc1
	s_nop 1
	v_lshl_add_u64 v[6:7], s[18:19], 0, v[10:11]
	v_lshl_add_u64 v[6:7], v[6:7], 0, v[162:163]
	global_store_dwordx4 v[6:7], v[2:5], off sc1

.LBB0_1131:
	v_mul_f32_e32 v147, 0xbfb8aa3b, v126
	v_exp_f32_e32 v147, v147
	v_lshl_or_b32 v148, s28, 7, v144
	v_lshl_add_u32 v146, s29, 8, v142
	v_ashrrev_i32_e32 v149, 31, v148
	v_add_f32_e32 v147, 1.0, v147
	v_rcp_f32_e32 v147, v147
	v_mov_b64_e32 v[140:141], s[8:9]
	v_mad_i64_i32 v[150:151], s[0:1], v146, s30, v[140:141]
	v_mul_f32_e32 v126, v126, v147
	v_mul_f32_e32 v122, v126, v122
	v_mul_f32_e32 v126, 0xbfb8aa3b, v118
	v_exp_f32_e32 v126, v126
	s_andn2_b64 vcc, exec, s[4:5]
	v_add_f32_e32 v126, 1.0, v126
	v_rcp_f32_e32 v126, v126
	s_nop 0
	v_mul_f32_e32 v118, v118, v126
	v_mul_f32_e32 v118, v118, v114
	v_mul_f32_e32 v114, 0xbfb8aa3b, v127
	v_exp_f32_e32 v114, v114
	s_nop 0
	v_add_f32_e32 v114, 1.0, v114
	v_rcp_f32_e32 v114, v114
	s_nop 0
	v_mul_f32_e32 v114, v127, v114
	v_mul_f32_e32 v123, v114, v123
	v_mul_f32_e32 v114, 0xbfb8aa3b, v119
	v_exp_f32_e32 v114, v114
	s_nop 0
	v_add_f32_e32 v114, 1.0, v114
	v_rcp_f32_e32 v114, v114
	s_nop 0
	v_mul_f32_e32 v114, v119, v114
	v_mul_f32_e32 v119, v114, v115
	v_mul_f32_e32 v114, 0xbfb8aa3b, v128
	v_exp_f32_e32 v114, v114
	s_nop 0
	v_add_f32_e32 v114, 1.0, v114
	v_rcp_f32_e32 v114, v114
	s_nop 0
	v_mul_f32_e32 v114, v128, v114
	v_mul_f32_e32 v124, v114, v124
	v_mul_f32_e32 v114, 0xbfb8aa3b, v120
	v_exp_f32_e32 v114, v114
	s_nop 0
	v_add_f32_e32 v114, 1.0, v114
	v_rcp_f32_e32 v114, v114
	s_nop 0
	v_mul_f32_e32 v114, v120, v114
	v_mul_f32_e32 v126, v114, v116
	v_mul_f32_e32 v114, 0xbfb8aa3b, v129
	v_exp_f32_e32 v114, v114
	v_cvt_pk_bf16_f32 v116, v122, v123
	s_nop 0
	v_add_f32_e32 v114, 1.0, v114
	v_rcp_f32_e32 v114, v114
	s_nop 0
	v_mul_f32_e32 v114, v129, v114
	v_mul_f32_e32 v125, v114, v125
	v_mul_f32_e32 v114, 0xbfb8aa3b, v121
	v_exp_f32_e32 v114, v114
	s_nop 0
	v_add_f32_e32 v114, 1.0, v114
	v_rcp_f32_e32 v114, v114
	s_nop 0
	v_mul_f32_e32 v114, v121, v114
	v_mul_f32_e32 v127, v114, v117
	v_lshlrev_b64 v[114:115], 1, v[148:149]
	v_lshl_add_u64 v[120:121], v[150:151], 0, v[114:115]
	v_cvt_pk_bf16_f32 v117, v124, v125
	v_cvt_pk_bf16_f32 v118, v118, v119
	v_cvt_pk_bf16_f32 v119, v126, v127
	global_store_dwordx4 v[120:121], v[116:119], off sc1
	s_nop 1
	v_mul_f32_e32 v118, 0xbfb8aa3b, v110
	v_exp_f32_e32 v118, v118
	v_or_b32_e32 v116, 16, v146
	v_mad_i64_i32 v[116:117], s[0:1], v116, s30, v[140:141]
	v_add_f32_e32 v118, 1.0, v118
	v_rcp_f32_e32 v118, v118
	s_nop 0
	v_mul_f32_e32 v110, v110, v118
	v_mul_f32_e32 v106, v110, v106
	v_mul_f32_e32 v110, 0xbfb8aa3b, v102
	v_exp_f32_e32 v110, v110
	s_nop 0
	v_add_f32_e32 v110, 1.0, v110
	v_rcp_f32_e32 v110, v110
	s_nop 0
	v_mul_f32_e32 v102, v102, v110
	v_mul_f32_e32 v110, v102, v98
	v_mul_f32_e32 v98, 0xbfb8aa3b, v111
	v_mul_f32_e32 v102, 0xbfb8aa3b, v103
	v_exp_f32_e32 v98, v98
	v_exp_f32_e32 v102, v102
	v_add_f32_e32 v98, 1.0, v98
	v_add_f32_e32 v102, 1.0, v102
	v_rcp_f32_e32 v98, v98
	v_rcp_f32_e32 v102, v102
	v_mul_f32_e32 v98, v111, v98
	v_mul_f32_e32 v102, v103, v102
	v_mul_f32_e32 v98, v98, v107
	v_mul_f32_e32 v107, v102, v99
	v_mul_f32_e32 v102, 0xbfb8aa3b, v104
	v_exp_f32_e32 v102, v102
	v_mul_f32_e32 v99, 0xbfb8aa3b, v112
	v_exp_f32_e32 v99, v99
	v_cvt_pk_bf16_f32 v98, v106, v98
	v_add_f32_e32 v102, 1.0, v102
	v_rcp_f32_e32 v102, v102
	v_add_f32_e32 v99, 1.0, v99
	v_rcp_f32_e32 v99, v99
	v_mul_f32_e32 v102, v104, v102
	v_mul_f32_e32 v104, v102, v100
	v_mul_f32_e32 v100, 0xbfb8aa3b, v113
	v_exp_f32_e32 v100, v100
	v_mul_f32_e32 v102, 0xbfb8aa3b, v105
	v_exp_f32_e32 v102, v102
	v_mul_f32_e32 v99, v112, v99
	v_add_f32_e32 v100, 1.0, v100
	v_rcp_f32_e32 v100, v100
	v_add_f32_e32 v102, 1.0, v102
	v_rcp_f32_e32 v102, v102
	v_mul_f32_e32 v99, v99, v108
	v_mul_f32_e32 v100, v113, v100
	v_mul_f32_e32 v100, v100, v109
	v_mul_f32_e32 v102, v105, v102
	v_mul_f32_e32 v101, v102, v101
	v_lshl_add_u64 v[102:103], v[116:117], 0, v[114:115]
	v_cvt_pk_bf16_f32 v99, v99, v100
	v_cvt_pk_bf16_f32 v100, v110, v107
	v_cvt_pk_bf16_f32 v101, v104, v101
	global_store_dwordx4 v[102:103], v[98:101], off sc1
	s_nop 1
	v_mul_f32_e32 v100, 0xbfb8aa3b, v94
	v_exp_f32_e32 v100, v100
	v_or_b32_e32 v98, 32, v146
	v_mad_i64_i32 v[98:99], s[0:1], v98, s30, v[140:141]
	v_add_f32_e32 v100, 1.0, v100
	v_rcp_f32_e32 v100, v100
	s_nop 0
	v_mul_f32_e32 v94, v94, v100
	v_mul_f32_e32 v90, v94, v90
	v_mul_f32_e32 v94, 0xbfb8aa3b, v86
	v_exp_f32_e32 v94, v94
	s_nop 0
	v_add_f32_e32 v94, 1.0, v94
	v_rcp_f32_e32 v94, v94
	s_nop 0
	v_mul_f32_e32 v86, v86, v94
	v_mul_f32_e32 v94, v86, v82
	v_mul_f32_e32 v82, 0xbfb8aa3b, v95
	v_mul_f32_e32 v86, 0xbfb8aa3b, v87
	v_exp_f32_e32 v82, v82
	v_exp_f32_e32 v86, v86
	v_add_f32_e32 v82, 1.0, v82
	v_add_f32_e32 v86, 1.0, v86
	v_rcp_f32_e32 v82, v82
	v_rcp_f32_e32 v86, v86
	v_mul_f32_e32 v82, v95, v82
	v_mul_f32_e32 v86, v87, v86
	v_mul_f32_e32 v82, v82, v91
	v_mul_f32_e32 v91, v86, v83
	v_mul_f32_e32 v86, 0xbfb8aa3b, v88
	v_exp_f32_e32 v86, v86
	v_mul_f32_e32 v83, 0xbfb8aa3b, v96
	v_exp_f32_e32 v83, v83
	v_cvt_pk_bf16_f32 v82, v90, v82
	v_add_f32_e32 v86, 1.0, v86
	v_rcp_f32_e32 v86, v86
	v_add_f32_e32 v83, 1.0, v83
	v_rcp_f32_e32 v83, v83
	v_mul_f32_e32 v86, v88, v86
	v_mul_f32_e32 v88, v86, v84
	v_mul_f32_e32 v84, 0xbfb8aa3b, v97
	v_exp_f32_e32 v84, v84
	v_mul_f32_e32 v86, 0xbfb8aa3b, v89
	v_exp_f32_e32 v86, v86
	v_mul_f32_e32 v83, v96, v83
	v_add_f32_e32 v84, 1.0, v84
	v_rcp_f32_e32 v84, v84
	v_add_f32_e32 v86, 1.0, v86
	v_rcp_f32_e32 v86, v86
	v_mul_f32_e32 v83, v83, v92
	v_mul_f32_e32 v84, v97, v84
	v_mul_f32_e32 v84, v84, v93
	v_mul_f32_e32 v86, v89, v86
	v_mul_f32_e32 v85, v86, v85
	v_lshl_add_u64 v[86:87], v[98:99], 0, v[114:115]
	v_cvt_pk_bf16_f32 v83, v83, v84
	v_cvt_pk_bf16_f32 v84, v94, v91
	v_cvt_pk_bf16_f32 v85, v88, v85
	global_store_dwordx4 v[86:87], v[82:85], off sc1
	s_nop 1
	v_mul_f32_e32 v84, 0xbfb8aa3b, v78
	v_exp_f32_e32 v84, v84
	v_or_b32_e32 v82, 48, v146
	v_mad_i64_i32 v[82:83], s[0:1], v82, s30, v[140:141]
	v_add_f32_e32 v84, 1.0, v84
	v_rcp_f32_e32 v84, v84
	s_nop 0
	v_mul_f32_e32 v78, v78, v84
	v_mul_f32_e32 v74, v78, v74
	v_mul_f32_e32 v78, 0xbfb8aa3b, v70
	v_exp_f32_e32 v78, v78
	s_nop 0
	v_add_f32_e32 v78, 1.0, v78
	v_rcp_f32_e32 v78, v78
	s_nop 0
	v_mul_f32_e32 v70, v70, v78
	v_mul_f32_e32 v78, v70, v66
	v_mul_f32_e32 v66, 0xbfb8aa3b, v79
	v_mul_f32_e32 v70, 0xbfb8aa3b, v71
	v_exp_f32_e32 v66, v66
	v_exp_f32_e32 v70, v70
	v_add_f32_e32 v66, 1.0, v66
	v_add_f32_e32 v70, 1.0, v70
	v_rcp_f32_e32 v66, v66
	v_rcp_f32_e32 v70, v70
	v_mul_f32_e32 v66, v79, v66
	v_mul_f32_e32 v70, v71, v70
	v_mul_f32_e32 v66, v66, v75
	v_mul_f32_e32 v75, v70, v67
	v_mul_f32_e32 v70, 0xbfb8aa3b, v72
	v_exp_f32_e32 v70, v70
	v_mul_f32_e32 v67, 0xbfb8aa3b, v80
	v_exp_f32_e32 v67, v67
	v_cvt_pk_bf16_f32 v66, v74, v66
	v_add_f32_e32 v70, 1.0, v70
	v_rcp_f32_e32 v70, v70
	v_add_f32_e32 v67, 1.0, v67
	v_rcp_f32_e32 v67, v67
	v_mul_f32_e32 v70, v72, v70
	v_mul_f32_e32 v72, v70, v68
	v_mul_f32_e32 v68, 0xbfb8aa3b, v81
	v_exp_f32_e32 v68, v68
	v_mul_f32_e32 v70, 0xbfb8aa3b, v73
	v_exp_f32_e32 v70, v70
	v_mul_f32_e32 v67, v80, v67
	v_add_f32_e32 v68, 1.0, v68
	v_rcp_f32_e32 v68, v68
	v_add_f32_e32 v70, 1.0, v70
	v_rcp_f32_e32 v70, v70
	v_mul_f32_e32 v67, v67, v76
	v_mul_f32_e32 v68, v81, v68
	v_mul_f32_e32 v68, v68, v77
	v_mul_f32_e32 v70, v73, v70
	v_mul_f32_e32 v69, v70, v69
	v_lshl_add_u64 v[70:71], v[82:83], 0, v[114:115]
	v_cvt_pk_bf16_f32 v67, v67, v68
	v_cvt_pk_bf16_f32 v68, v78, v75
	v_cvt_pk_bf16_f32 v69, v72, v69
	global_store_dwordx4 v[70:71], v[66:69], off sc1
	s_nop 1
	v_mul_f32_e32 v68, 0xbfb8aa3b, v62
	v_exp_f32_e32 v68, v68
	v_add_u32_e32 v66, 0x80, v146
	v_mad_i64_i32 v[66:67], s[0:1], v66, s30, v[140:141]
	v_add_f32_e32 v68, 1.0, v68
	v_rcp_f32_e32 v68, v68
	s_nop 0
	v_mul_f32_e32 v62, v62, v68
	v_mul_f32_e32 v58, v62, v58
	v_mul_f32_e32 v62, 0xbfb8aa3b, v54
	v_exp_f32_e32 v62, v62
	s_nop 0
	v_add_f32_e32 v62, 1.0, v62
	v_rcp_f32_e32 v62, v62
	s_nop 0
	v_mul_f32_e32 v54, v54, v62
	v_mul_f32_e32 v62, v54, v50
	v_mul_f32_e32 v50, 0xbfb8aa3b, v63
	v_mul_f32_e32 v54, 0xbfb8aa3b, v55
	v_exp_f32_e32 v50, v50
	v_exp_f32_e32 v54, v54
	v_add_f32_e32 v50, 1.0, v50
	v_add_f32_e32 v54, 1.0, v54
	v_rcp_f32_e32 v50, v50
	v_rcp_f32_e32 v54, v54
	v_mul_f32_e32 v50, v63, v50
	v_mul_f32_e32 v54, v55, v54
	v_mul_f32_e32 v50, v50, v59
	v_mul_f32_e32 v59, v54, v51
	v_mul_f32_e32 v54, 0xbfb8aa3b, v56
	v_exp_f32_e32 v54, v54
	v_mul_f32_e32 v51, 0xbfb8aa3b, v64
	v_exp_f32_e32 v51, v51
	v_cvt_pk_bf16_f32 v50, v58, v50
	v_add_f32_e32 v54, 1.0, v54
	v_rcp_f32_e32 v54, v54
	v_add_f32_e32 v51, 1.0, v51
	v_rcp_f32_e32 v51, v51
	v_mul_f32_e32 v54, v56, v54
	v_mul_f32_e32 v56, v54, v52
	v_mul_f32_e32 v52, 0xbfb8aa3b, v65
	v_exp_f32_e32 v52, v52
	v_mul_f32_e32 v54, 0xbfb8aa3b, v57
	v_exp_f32_e32 v54, v54
	v_mul_f32_e32 v51, v64, v51
	v_add_f32_e32 v52, 1.0, v52
	v_rcp_f32_e32 v52, v52
	v_add_f32_e32 v54, 1.0, v54
	v_rcp_f32_e32 v54, v54
	v_mul_f32_e32 v51, v51, v60
	v_mul_f32_e32 v52, v65, v52
	v_mul_f32_e32 v52, v52, v61
	v_mul_f32_e32 v54, v57, v54
	v_mul_f32_e32 v53, v54, v53
	v_lshl_add_u64 v[54:55], v[66:67], 0, v[114:115]
	v_cvt_pk_bf16_f32 v51, v51, v52
	v_cvt_pk_bf16_f32 v52, v62, v59
	v_cvt_pk_bf16_f32 v53, v56, v53
	global_store_dwordx4 v[54:55], v[50:53], off sc1
	s_nop 1
	v_mul_f32_e32 v52, 0xbfb8aa3b, v46
	v_exp_f32_e32 v52, v52
	v_add_u32_e32 v50, 0x90, v146
	v_mad_i64_i32 v[50:51], s[0:1], v50, s30, v[140:141]
	v_add_f32_e32 v52, 1.0, v52
	v_rcp_f32_e32 v52, v52
	s_nop 0
	v_mul_f32_e32 v46, v46, v52
	v_mul_f32_e32 v42, v46, v42
	v_mul_f32_e32 v46, 0xbfb8aa3b, v38
	v_exp_f32_e32 v46, v46
	s_nop 0
	v_add_f32_e32 v46, 1.0, v46
	v_rcp_f32_e32 v46, v46
	s_nop 0
	v_mul_f32_e32 v38, v38, v46
	v_mul_f32_e32 v46, v38, v34
	v_mul_f32_e32 v34, 0xbfb8aa3b, v47
	v_mul_f32_e32 v38, 0xbfb8aa3b, v39
	v_exp_f32_e32 v34, v34
	v_exp_f32_e32 v38, v38
	v_add_f32_e32 v34, 1.0, v34
	v_add_f32_e32 v38, 1.0, v38
	v_rcp_f32_e32 v34, v34
	v_rcp_f32_e32 v38, v38
	v_mul_f32_e32 v34, v47, v34
	v_mul_f32_e32 v38, v39, v38
	v_mul_f32_e32 v34, v34, v43
	v_mul_f32_e32 v43, v38, v35
	v_mul_f32_e32 v38, 0xbfb8aa3b, v40
	v_exp_f32_e32 v38, v38
	v_mul_f32_e32 v35, 0xbfb8aa3b, v48
	v_exp_f32_e32 v35, v35
	v_cvt_pk_bf16_f32 v34, v42, v34
	v_add_f32_e32 v38, 1.0, v38
	v_rcp_f32_e32 v38, v38
	v_add_f32_e32 v35, 1.0, v35
	v_rcp_f32_e32 v35, v35
	v_mul_f32_e32 v38, v40, v38
	v_mul_f32_e32 v40, v38, v36
	v_mul_f32_e32 v36, 0xbfb8aa3b, v49
	v_exp_f32_e32 v36, v36
	v_mul_f32_e32 v38, 0xbfb8aa3b, v41
	v_exp_f32_e32 v38, v38
	v_mul_f32_e32 v35, v48, v35
	v_add_f32_e32 v36, 1.0, v36
	v_rcp_f32_e32 v36, v36
	v_add_f32_e32 v38, 1.0, v38
	v_rcp_f32_e32 v38, v38
	v_mul_f32_e32 v35, v35, v44
	v_mul_f32_e32 v36, v49, v36
	v_mul_f32_e32 v36, v36, v45
	v_mul_f32_e32 v38, v41, v38
	v_mul_f32_e32 v37, v38, v37
	v_lshl_add_u64 v[38:39], v[50:51], 0, v[114:115]
	v_cvt_pk_bf16_f32 v35, v35, v36
	v_cvt_pk_bf16_f32 v36, v46, v43
	v_cvt_pk_bf16_f32 v37, v40, v37
	global_store_dwordx4 v[38:39], v[34:37], off sc1
	s_nop 1
	v_mul_f32_e32 v36, 0xbfb8aa3b, v30
	v_exp_f32_e32 v36, v36
	v_add_u32_e32 v34, 0xa0, v146
	v_mad_i64_i32 v[34:35], s[0:1], v34, s30, v[140:141]
	v_add_f32_e32 v36, 1.0, v36
	v_rcp_f32_e32 v36, v36
	s_nop 0
	v_mul_f32_e32 v30, v30, v36
	v_mul_f32_e32 v26, v30, v26
	v_mul_f32_e32 v30, 0xbfb8aa3b, v22
	v_exp_f32_e32 v30, v30
	s_nop 0
	v_add_f32_e32 v30, 1.0, v30
	v_rcp_f32_e32 v30, v30
	s_nop 0
	v_mul_f32_e32 v22, v22, v30
	v_mul_f32_e32 v30, v22, v18
	v_mul_f32_e32 v18, 0xbfb8aa3b, v31
	v_mul_f32_e32 v22, 0xbfb8aa3b, v23
	v_exp_f32_e32 v18, v18
	v_exp_f32_e32 v22, v22
	v_add_f32_e32 v18, 1.0, v18
	v_add_f32_e32 v22, 1.0, v22
	v_rcp_f32_e32 v18, v18
	v_rcp_f32_e32 v22, v22
	v_mul_f32_e32 v18, v31, v18
	v_mul_f32_e32 v22, v23, v22
	v_mul_f32_e32 v18, v18, v27
	v_mul_f32_e32 v27, v22, v19
	v_mul_f32_e32 v22, 0xbfb8aa3b, v24
	v_exp_f32_e32 v22, v22
	v_mul_f32_e32 v19, 0xbfb8aa3b, v32
	v_exp_f32_e32 v19, v19
	v_cvt_pk_bf16_f32 v18, v26, v18
	v_add_f32_e32 v22, 1.0, v22
	v_rcp_f32_e32 v22, v22
	v_add_f32_e32 v19, 1.0, v19
	v_rcp_f32_e32 v19, v19
	v_mul_f32_e32 v22, v24, v22
	v_mul_f32_e32 v24, v22, v20
	v_mul_f32_e32 v20, 0xbfb8aa3b, v33
	v_exp_f32_e32 v20, v20
	v_mul_f32_e32 v22, 0xbfb8aa3b, v25
	v_exp_f32_e32 v22, v22
	v_mul_f32_e32 v19, v32, v19
	v_add_f32_e32 v20, 1.0, v20
	v_rcp_f32_e32 v20, v20
	v_add_f32_e32 v22, 1.0, v22
	v_rcp_f32_e32 v22, v22
	v_mul_f32_e32 v19, v19, v28
	v_mul_f32_e32 v20, v33, v20
	v_mul_f32_e32 v20, v20, v29
	v_mul_f32_e32 v22, v25, v22
	v_mul_f32_e32 v21, v22, v21
	v_lshl_add_u64 v[22:23], v[34:35], 0, v[114:115]
	v_cvt_pk_bf16_f32 v19, v19, v20
	v_cvt_pk_bf16_f32 v20, v30, v27
	v_cvt_pk_bf16_f32 v21, v24, v21
	global_store_dwordx4 v[22:23], v[18:21], off sc1
	s_nop 1
	v_mul_f32_e32 v20, 0xbfb8aa3b, v14
	v_exp_f32_e32 v20, v20
	v_add_u32_e32 v18, 0xb0, v146
	v_mad_i64_i32 v[18:19], s[0:1], v18, s30, v[140:141]
	v_add_f32_e32 v20, 1.0, v20
	v_rcp_f32_e32 v20, v20
	s_mov_b64 s[0:1], -1
	v_mul_f32_e32 v14, v14, v20
	v_mul_f32_e32 v10, v14, v10
	v_mul_f32_e32 v14, 0xbfb8aa3b, v6
	v_exp_f32_e32 v14, v14
	s_nop 0
	v_add_f32_e32 v14, 1.0, v14
	v_rcp_f32_e32 v14, v14
	s_nop 0
	v_mul_f32_e32 v6, v6, v14
	v_mul_f32_e32 v14, v6, v2
	v_mul_f32_e32 v2, 0xbfb8aa3b, v15
	v_mul_f32_e32 v6, 0xbfb8aa3b, v7
	v_exp_f32_e32 v2, v2
	v_exp_f32_e32 v6, v6
	v_add_f32_e32 v2, 1.0, v2
	v_add_f32_e32 v6, 1.0, v6
	v_rcp_f32_e32 v2, v2
	v_rcp_f32_e32 v6, v6
	v_mul_f32_e32 v2, v15, v2
	v_mul_f32_e32 v6, v7, v6
	v_mul_f32_e32 v2, v2, v11
	v_mul_f32_e32 v11, v6, v3
	v_mul_f32_e32 v6, 0xbfb8aa3b, v8
	v_exp_f32_e32 v6, v6
	v_mul_f32_e32 v3, 0xbfb8aa3b, v16
	v_exp_f32_e32 v3, v3
	v_cvt_pk_bf16_f32 v2, v10, v2
	v_add_f32_e32 v6, 1.0, v6
	v_rcp_f32_e32 v6, v6
	v_add_f32_e32 v3, 1.0, v3
	v_rcp_f32_e32 v3, v3
	v_mul_f32_e32 v6, v8, v6
	v_mul_f32_e32 v8, v6, v4
	v_mul_f32_e32 v4, 0xbfb8aa3b, v17
	v_mul_f32_e32 v6, 0xbfb8aa3b, v9
	v_exp_f32_e32 v4, v4
	v_exp_f32_e32 v6, v6
	v_mul_f32_e32 v3, v16, v3
	v_mul_f32_e32 v3, v3, v12
	v_add_f32_e32 v4, 1.0, v4
	v_add_f32_e32 v6, 1.0, v6
	v_rcp_f32_e32 v4, v4
	v_rcp_f32_e32 v6, v6
	v_mul_f32_e32 v4, v17, v4
	v_mul_f32_e32 v6, v9, v6
	v_mul_f32_e32 v4, v4, v13
	v_mul_f32_e32 v5, v6, v5
	v_lshl_add_u64 v[6:7], v[18:19], 0, v[114:115]
	v_cvt_pk_bf16_f32 v3, v3, v4
	v_cvt_pk_bf16_f32 v4, v14, v11
	v_cvt_pk_bf16_f32 v5, v8, v5
	global_store_dwordx4 v[6:7], v[2:5], off sc1
	s_cbranch_vccnz .LBB0_1124
	s_andn2_b64 vcc, exec, s[6:7]
	s_cbranch_vccnz .LBB0_1123
	s_barrier
	s_branch .LBB0_1123

.LBB0_1152:
	v_lshl_add_u32 v146, s44, 8, v142
	v_lshl_or_b32 v140, s43, 8, v144
	v_ashrrev_i32_e32 v141, 31, v140
	v_ashrrev_i32_e32 v147, 31, v146
	v_lshl_add_u64 v[148:149], v[140:141], 1, s[6:7]
	v_lshlrev_b64 v[140:141], 12, v[146:147]
	v_lshl_add_u64 v[140:141], v[148:149], 0, v[140:141]
	v_pk_add_f32 v[128:129], v[128:129], 0 op_sel_hi:[1,0]
	v_pk_add_f32 v[126:127], v[126:127], 0 op_sel_hi:[1,0]
	v_pk_add_f32 v[150:151], v[124:125], 0 op_sel_hi:[1,0]
	v_pk_add_f32 v[124:125], v[122:123], 0 op_sel_hi:[1,0]
	v_cvt_pk_bf16_f32 v122, v126, v127
	v_cvt_pk_bf16_f32 v123, v128, v129
	v_pk_add_f32 v[118:119], v[118:119], 0 op_sel_hi:[1,0]
	v_cvt_pk_bf16_f32 v124, v124, v125
	v_cvt_pk_bf16_f32 v125, v150, v151
	global_store_dwordx4 v[140:141], v[122:125], off sc1
	v_pk_add_f32 v[120:121], v[120:121], 0 op_sel_hi:[1,0]
	v_pk_add_f32 v[114:115], v[114:115], 0 op_sel_hi:[1,0]
	v_pk_add_f32 v[122:123], v[112:113], 0 op_sel_hi:[1,0]
	v_pk_add_f32 v[112:113], v[110:111], 0 op_sel_hi:[1,0]
	v_cvt_pk_bf16_f32 v110, v118, v119
	v_cvt_pk_bf16_f32 v111, v120, v121
	v_pk_add_f32 v[102:103], v[102:103], 0 op_sel_hi:[1,0]
	v_cvt_pk_bf16_f32 v112, v112, v113
	v_cvt_pk_bf16_f32 v113, v122, v123
	global_store_dwordx4 v[140:141], v[110:113], off offset:256 sc1
	v_pk_add_f32 v[104:105], v[104:105], 0 op_sel_hi:[1,0]
	v_pk_add_f32 v[98:99], v[98:99], 0 op_sel_hi:[1,0]
	v_or_b32_e32 v110, 16, v146
	v_ashrrev_i32_e32 v111, 31, v110
	v_lshlrev_b64 v[110:111], 12, v[110:111]
	v_lshl_add_u64 v[110:111], v[148:149], 0, v[110:111]
	v_pk_add_f32 v[112:113], v[116:117], 0 op_sel_hi:[1,0]
	v_pk_add_f32 v[116:117], v[108:109], 0 op_sel_hi:[1,0]
	v_pk_add_f32 v[108:109], v[106:107], 0 op_sel_hi:[1,0]
	v_cvt_pk_bf16_f32 v106, v114, v115
	v_cvt_pk_bf16_f32 v107, v112, v113
	v_pk_add_f32 v[86:87], v[86:87], 0 op_sel_hi:[1,0]
	v_cvt_pk_bf16_f32 v108, v108, v109
	v_cvt_pk_bf16_f32 v109, v116, v117
	global_store_dwordx4 v[110:111], v[106:109], off sc1
	v_pk_add_f32 v[88:89], v[88:89], 0 op_sel_hi:[1,0]
	v_pk_add_f32 v[82:83], v[82:83], 0 op_sel_hi:[1,0]
	v_pk_add_f32 v[106:107], v[96:97], 0 op_sel_hi:[1,0]
	v_pk_add_f32 v[96:97], v[94:95], 0 op_sel_hi:[1,0]
	v_cvt_pk_bf16_f32 v94, v102, v103
	v_cvt_pk_bf16_f32 v95, v104, v105
	v_pk_add_f32 v[72:73], v[72:73], 0 op_sel_hi:[1,0]
	v_cvt_pk_bf16_f32 v96, v96, v97
	v_cvt_pk_bf16_f32 v97, v106, v107
	global_store_dwordx4 v[110:111], v[94:97], off offset:256 sc1
	v_pk_add_f32 v[70:71], v[70:71], 0 op_sel_hi:[1,0]
	s_mov_b64 s[14:15], 0x80000
	v_or_b32_e32 v94, 32, v146
	v_ashrrev_i32_e32 v95, 31, v94
	v_lshlrev_b64 v[94:95], 12, v[94:95]
	v_lshl_add_u64 v[94:95], v[148:149], 0, v[94:95]
	v_pk_add_f32 v[96:97], v[100:101], 0 op_sel_hi:[1,0]
	v_pk_add_f32 v[100:101], v[92:93], 0 op_sel_hi:[1,0]
	v_pk_add_f32 v[92:93], v[90:91], 0 op_sel_hi:[1,0]
	v_cvt_pk_bf16_f32 v90, v98, v99
	v_cvt_pk_bf16_f32 v91, v96, v97
	v_pk_add_f32 v[62:63], v[62:63], 0 op_sel_hi:[1,0]
	v_cvt_pk_bf16_f32 v92, v92, v93
	v_cvt_pk_bf16_f32 v93, v100, v101
	global_store_dwordx4 v[94:95], v[90:93], off sc1
	v_pk_add_f32 v[64:65], v[64:65], 0 op_sel_hi:[1,0]
	v_pk_add_f32 v[56:57], v[56:57], 0 op_sel_hi:[1,0]
	v_pk_add_f32 v[90:91], v[80:81], 0 op_sel_hi:[1,0]
	v_pk_add_f32 v[80:81], v[78:79], 0 op_sel_hi:[1,0]
	v_cvt_pk_bf16_f32 v78, v86, v87
	v_cvt_pk_bf16_f32 v79, v88, v89
	v_pk_add_f32 v[54:55], v[54:55], 0 op_sel_hi:[1,0]
	v_cvt_pk_bf16_f32 v80, v80, v81
	v_cvt_pk_bf16_f32 v81, v90, v91
	global_store_dwordx4 v[94:95], v[78:81], off offset:256 sc1
	v_pk_add_f32 v[50:51], v[50:51], 0 op_sel_hi:[1,0]
	v_pk_add_f32 v[40:41], v[40:41], 0 op_sel_hi:[1,0]
	v_or_b32_e32 v78, 48, v146
	v_ashrrev_i32_e32 v79, 31, v78
	v_lshlrev_b64 v[78:79], 12, v[78:79]
	v_lshl_add_u64 v[78:79], v[148:149], 0, v[78:79]
	v_pk_add_f32 v[80:81], v[84:85], 0 op_sel_hi:[1,0]
	v_pk_add_f32 v[84:85], v[76:77], 0 op_sel_hi:[1,0]
	v_pk_add_f32 v[76:77], v[74:75], 0 op_sel_hi:[1,0]
	v_cvt_pk_bf16_f32 v74, v82, v83
	v_cvt_pk_bf16_f32 v75, v80, v81
	v_pk_add_f32 v[38:39], v[38:39], 0 op_sel_hi:[1,0]
	v_cvt_pk_bf16_f32 v76, v76, v77
	v_cvt_pk_bf16_f32 v77, v84, v85
	global_store_dwordx4 v[78:79], v[74:77], off sc1
	v_pk_add_f32 v[34:35], v[34:35], 0 op_sel_hi:[1,0]
	v_pk_add_f32 v[24:25], v[24:25], 0 op_sel_hi:[1,0]
	v_pk_add_f32 v[74:75], v[68:69], 0 op_sel_hi:[1,0]
	v_pk_add_f32 v[68:69], v[66:67], 0 op_sel_hi:[1,0]
	v_cvt_pk_bf16_f32 v66, v70, v71
	v_cvt_pk_bf16_f32 v67, v72, v73
	v_pk_add_f32 v[22:23], v[22:23], 0 op_sel_hi:[1,0]
	v_cvt_pk_bf16_f32 v68, v68, v69
	v_cvt_pk_bf16_f32 v69, v74, v75
	global_store_dwordx4 v[78:79], v[66:69], off offset:256 sc1
	v_pk_add_f32 v[18:19], v[18:19], 0 op_sel_hi:[1,0]
	v_pk_add_f32 v[8:9], v[8:9], 0 op_sel_hi:[1,0]
	v_lshl_add_u64 v[66:67], v[140:141], 0, s[14:15]
	s_mov_b32 s14, 0x80000
	v_pk_add_f32 v[68:69], v[60:61], 0 op_sel_hi:[1,0]
	v_pk_add_f32 v[60:61], v[58:59], 0 op_sel_hi:[1,0]
	v_cvt_pk_bf16_f32 v58, v62, v63
	v_add_co_u32_e32 v62, vcc, s14, v140
	v_cvt_pk_bf16_f32 v59, v64, v65
	v_cvt_pk_bf16_f32 v60, v60, v61
	v_cvt_pk_bf16_f32 v61, v68, v69
	s_mov_b64 s[14:15], 0x90000
	s_nop 0
	v_addc_co_u32_e32 v63, vcc, 0, v141, vcc
	global_store_dwordx4 v[62:63], v[58:61], off sc1
	v_pk_add_f32 v[6:7], v[6:7], 0 op_sel_hi:[1,0]
	s_nop 0
	v_pk_add_f32 v[58:59], v[48:49], 0 op_sel_hi:[1,0]
	v_pk_add_f32 v[48:49], v[46:47], 0 op_sel_hi:[1,0]
	v_cvt_pk_bf16_f32 v46, v54, v55
	v_cvt_pk_bf16_f32 v47, v56, v57
	s_nop 0
	v_cvt_pk_bf16_f32 v48, v48, v49
	v_cvt_pk_bf16_f32 v49, v58, v59
	global_store_dwordx4 v[66:67], v[46:49], off offset:256 sc1
	s_nop 1
	v_lshl_add_u64 v[46:47], v[140:141], 0, s[14:15]
	v_pk_add_f32 v[48:49], v[52:53], 0 op_sel_hi:[1,0]
	s_mov_b32 s14, 0x90000
	v_pk_add_f32 v[52:53], v[44:45], 0 op_sel_hi:[1,0]
	v_pk_add_f32 v[44:45], v[42:43], 0 op_sel_hi:[1,0]
	v_cvt_pk_bf16_f32 v42, v50, v51
	v_cvt_pk_bf16_f32 v43, v48, v49
	v_add_co_u32_e32 v48, vcc, s14, v140
	v_cvt_pk_bf16_f32 v44, v44, v45
	v_cvt_pk_bf16_f32 v45, v52, v53
	s_mov_b64 s[14:15], 0xa0000
	s_nop 0
	v_addc_co_u32_e32 v49, vcc, 0, v141, vcc
	global_store_dwordx4 v[48:49], v[42:45], off sc1
	s_nop 1
	v_pk_add_f32 v[42:43], v[32:33], 0 op_sel_hi:[1,0]
	v_pk_add_f32 v[32:33], v[30:31], 0 op_sel_hi:[1,0]
	v_cvt_pk_bf16_f32 v30, v38, v39
	v_cvt_pk_bf16_f32 v31, v40, v41
	s_nop 0
	v_cvt_pk_bf16_f32 v32, v32, v33
	v_cvt_pk_bf16_f32 v33, v42, v43
	global_store_dwordx4 v[46:47], v[30:33], off offset:256 sc1
	s_nop 1
	v_lshl_add_u64 v[30:31], v[140:141], 0, s[14:15]
	v_pk_add_f32 v[32:33], v[36:37], 0 op_sel_hi:[1,0]
	s_mov_b32 s14, 0xa0000
	v_pk_add_f32 v[36:37], v[28:29], 0 op_sel_hi:[1,0]
	v_pk_add_f32 v[28:29], v[26:27], 0 op_sel_hi:[1,0]
	v_cvt_pk_bf16_f32 v26, v34, v35
	v_cvt_pk_bf16_f32 v27, v32, v33
	v_add_co_u32_e32 v32, vcc, s14, v140
	v_cvt_pk_bf16_f32 v28, v28, v29
	v_cvt_pk_bf16_f32 v29, v36, v37
	s_mov_b64 s[14:15], 0xb0000
	s_nop 0
	v_addc_co_u32_e32 v33, vcc, 0, v141, vcc
	global_store_dwordx4 v[32:33], v[26:29], off sc1
	s_nop 1
	v_pk_add_f32 v[26:27], v[16:17], 0 op_sel_hi:[1,0]
	v_pk_add_f32 v[16:17], v[14:15], 0 op_sel_hi:[1,0]
	v_cvt_pk_bf16_f32 v14, v22, v23
	v_cvt_pk_bf16_f32 v15, v24, v25
	s_nop 0
	v_cvt_pk_bf16_f32 v16, v16, v17
	v_cvt_pk_bf16_f32 v17, v26, v27
	global_store_dwordx4 v[30:31], v[14:17], off offset:256 sc1
	s_nop 1
	v_lshl_add_u64 v[14:15], v[140:141], 0, s[14:15]
	v_pk_add_f32 v[16:17], v[20:21], 0 op_sel_hi:[1,0]
	s_mov_b32 s14, 0xb0000
	v_pk_add_f32 v[20:21], v[12:13], 0 op_sel_hi:[1,0]
	v_pk_add_f32 v[12:13], v[10:11], 0 op_sel_hi:[1,0]
	v_cvt_pk_bf16_f32 v10, v18, v19
	v_cvt_pk_bf16_f32 v11, v16, v17
	v_add_co_u32_e32 v16, vcc, s14, v140
	v_cvt_pk_bf16_f32 v12, v12, v13
	v_cvt_pk_bf16_f32 v13, v20, v21
	s_mov_b64 s[14:15], -1
	s_nop 0
	v_addc_co_u32_e32 v17, vcc, 0, v141, vcc
	global_store_dwordx4 v[16:17], v[10:13], off sc1
	s_andn2_b64 vcc, exec, s[18:19]
	s_nop 0
	v_pk_add_f32 v[10:11], v[4:5], 0 op_sel_hi:[1,0]
	v_pk_add_f32 v[4:5], v[2:3], 0 op_sel_hi:[1,0]
	v_cvt_pk_bf16_f32 v2, v6, v7
	v_cvt_pk_bf16_f32 v3, v8, v9
	s_nop 0
	v_cvt_pk_bf16_f32 v4, v4, v5
	v_cvt_pk_bf16_f32 v5, v10, v11
	global_store_dwordx4 v[14:15], v[2:5], off offset:256 sc1
	s_cbranch_vccnz .LBB0_1141
	s_andn2_b64 vcc, exec, s[0:1]
	s_cbranch_vccnz .LBB0_1140
	s_barrier
	s_branch .LBB0_1140

.LBB0_1188:
	s_andn2_saveexec_b64 s[6:7], s[6:7]
	s_cbranch_execz .LBB0_1208
	s_mov_b64 s[6:7], exec
	s_waitcnt lgkmcnt(0)
	s_waitcnt vmcnt(0)
	v_mbcnt_lo_u32_b32 v3, s6, 0
	v_mbcnt_hi_u32_b32 v3, s7, v3
	v_cmp_eq_u32_e32 vcc, 0, v3
	s_and_saveexec_b64 s[8:9], vcc
	s_cbranch_execz .LBB0_1191
	s_bcnt1_i32_b64 s5, s[6:7]
	v_readlane_b32 s6, v253, 60
	v_mov_b32_e32 v4, s5
	v_readlane_b32 s7, v253, 61
	s_nop 4
	global_atomic_add v4, v179, v4, s[6:7] sc0

.LBB0_1271:
	s_or_b64 exec, exec, s[0:1]
	s_waitcnt lgkmcnt(0)
	s_barrier
	v_lshl_add_u32 v169, v168, 3, 0
	ds_read_b64 v[172:173], v169 offset:8192
	v_add_u32_e32 v166, s88, v168
	v_ashrrev_i32_e32 v167, 31, v166
	v_lshlrev_b64 v[174:175], 11, v[166:167]
	s_waitcnt lgkmcnt(1)
	v_cmp_eq_u32_e32 vcc, 0, v171
	s_waitcnt lgkmcnt(0)
	v_sub_f32_e32 v7, v7, v172
	v_sub_f32_e32 v6, v6, v172
	v_pk_mul_f32 v[6:7], v[172:173], v[6:7] op_sel:[1,0]
	v_sub_f32_e32 v3, v3, v172
	v_sub_f32_e32 v2, v2, v172
	v_sub_f32_e32 v9, v9, v172
	v_sub_f32_e32 v8, v8, v172
	s_waitcnt vmcnt(5)
	v_pk_fma_f32 v[6:7], v[154:155], v[6:7], v[158:159]
	v_sub_f32_e32 v5, v5, v172
	v_sub_f32_e32 v4, v4, v172
	v_pk_mul_f32 v[2:3], v[172:173], v[2:3] op_sel:[1,0]
	v_pk_mul_f32 v[8:9], v[172:173], v[8:9] op_sel:[1,0]
	v_pk_mul_f32 v[4:5], v[172:173], v[4:5] op_sel:[1,0]
	s_waitcnt vmcnt(4)
	v_pk_fma_f32 v[2:3], v[146:147], v[2:3], v[150:151]
	v_cndmask_b32_e32 v167, v208, v6, vcc
	v_cndmask_b32_e32 v168, v208, v7, vcc
	v_lshl_add_u64 v[6:7], s[34:35], 0, v[174:175]
	v_pk_fma_f32 v[8:9], v[156:157], v[8:9], v[160:161]
	v_pk_fma_f32 v[4:5], v[148:149], v[4:5], v[152:153]
	v_cndmask_b32_e32 v178, v208, v2, vcc
	v_cvt_pk_bf16_f32 v2, v167, v168
	v_lshl_add_u64 v[170:171], v[6:7], 0, v[164:165]
	v_cndmask_b32_e32 v8, v208, v8, vcc
	v_cndmask_b32_e32 v9, v208, v9, vcc
	v_cndmask_b32_e32 v176, v208, v4, vcc
	v_cndmask_b32_e32 v177, v208, v5, vcc
	v_cndmask_b32_e32 v185, v208, v3, vcc
	v_cvt_pk_bf16_f32 v3, v8, v9
	v_cvt_pk_bf16_f32 v4, v178, v185
	v_cvt_pk_bf16_f32 v5, v176, v177
	global_store_dwordx4 v[170:171], v[2:5], off sc1
	v_lshlrev_b32_e32 v6, 16, v2
	v_sub_f32_e32 v6, v167, v6
	v_and_b32_e32 v2, 0xffff0000, v2
	v_sub_f32_e32 v2, v168, v2
	v_mul_f32_e32 v6, 0x45000000, v6
	v_mul_f32_e32 v7, 0x45000000, v2
	v_mov_b32_e32 v2, v179
	v_cvt_pk_fp8_f32 v2, v6, v7
	v_lshlrev_b32_e32 v6, 16, v3
	v_and_b32_e32 v3, 0xffff0000, v3
	v_sub_f32_e32 v6, v8, v6
	v_sub_f32_e32 v3, v9, v3
	v_mul_f32_e32 v6, 0x45000000, v6
	v_mul_f32_e32 v3, 0x45000000, v3
	v_cvt_pk_fp8_f32 v2, v6, v3 op_sel:[0,0,1]
	v_lshlrev_b32_e32 v3, 16, v4
	v_sub_f32_e32 v3, v178, v3
	v_mul_f32_e32 v6, 0x45000000, v3
	v_and_b32_e32 v3, 0xffff0000, v4
	v_sub_f32_e32 v3, v185, v3
	v_mul_f32_e32 v4, 0x45000000, v3
	v_mov_b32_e32 v3, v179
	v_cvt_pk_fp8_f32 v3, v6, v4
	v_lshlrev_b32_e32 v4, 16, v5
	v_and_b32_e32 v5, 0xffff0000, v5
	v_sub_f32_e32 v4, v176, v4
	v_sub_f32_e32 v5, v177, v5
	v_mul_f32_e32 v4, 0x45000000, v4
	v_mul_f32_e32 v5, 0x45000000, v5
	v_cvt_pk_fp8_f32 v3, v4, v5 op_sel:[0,0,1]
	v_sub_f32_e32 v5, v19, v172
	v_sub_f32_e32 v4, v18, v172
	v_sub_f32_e32 v7, v21, v172
	v_sub_f32_e32 v6, v20, v172
	v_pk_mul_f32 v[6:7], v[172:173], v[6:7] op_sel:[1,0]
	v_pk_mul_f32 v[4:5], v[172:173], v[4:5] op_sel:[1,0]
	s_waitcnt vmcnt(1)
	v_pk_fma_f32 v[6:7], v[140:141], v[6:7], v[144:145]
	v_pk_fma_f32 v[4:5], v[138:139], v[4:5], v[142:143]
	v_sub_f32_e32 v8, v14, v172
	v_sub_f32_e32 v14, v16, v172
	v_cndmask_b32_e32 v16, v208, v6, vcc
	v_cndmask_b32_e32 v4, v208, v4, vcc
	v_cndmask_b32_e32 v5, v208, v5, vcc
	v_cvt_pk_bf16_f32 v6, v4, v5
	v_sub_f32_e32 v9, v15, v172
	v_lshlrev_b32_e32 v20, 16, v6
	v_sub_f32_e32 v4, v4, v20
	v_mul_f32_e32 v20, 0x45000000, v4
	v_and_b32_e32 v4, 0xffff0000, v6
	v_sub_f32_e32 v4, v5, v4
	v_mul_f32_e32 v5, 0x45000000, v4
	v_mov_b32_e32 v4, v179
	v_sub_f32_e32 v15, v17, v172
	v_cndmask_b32_e32 v17, v208, v7, vcc
	v_cvt_pk_bf16_f32 v7, v16, v17
	v_cvt_pk_fp8_f32 v4, v20, v5
	v_lshlrev_b32_e32 v5, 16, v7
	v_sub_f32_e32 v5, v16, v5
	v_and_b32_e32 v16, 0xffff0000, v7
	v_pk_mul_f32 v[8:9], v[172:173], v[8:9] op_sel:[1,0]
	v_sub_f32_e32 v16, v17, v16
	v_pk_fma_f32 v[8:9], v[130:131], v[8:9], v[134:135]
	v_mul_f32_e32 v5, 0x45000000, v5
	v_mul_f32_e32 v16, 0x45000000, v16
	v_cndmask_b32_e32 v18, v208, v8, vcc
	v_cndmask_b32_e32 v19, v208, v9, vcc
	v_cvt_pk_bf16_f32 v8, v18, v19
	v_cvt_pk_fp8_f32 v4, v5, v16 op_sel:[0,0,1]
	v_lshlrev_b32_e32 v5, 16, v8
	v_sub_f32_e32 v5, v18, v5
	v_mul_f32_e32 v16, 0x45000000, v5
	v_and_b32_e32 v5, 0xffff0000, v8
	v_pk_mul_f32 v[14:15], v[172:173], v[14:15] op_sel:[1,0]
	v_sub_f32_e32 v5, v19, v5
	v_pk_fma_f32 v[14:15], v[132:133], v[14:15], v[136:137]
	v_mul_f32_e32 v17, 0x45000000, v5
	v_mov_b32_e32 v5, v179
	v_cndmask_b32_e32 v14, v208, v14, vcc
	v_cndmask_b32_e32 v15, v208, v15, vcc
	v_cvt_pk_bf16_f32 v9, v14, v15
	v_cvt_pk_fp8_f32 v5, v16, v17
	v_lshlrev_b32_e32 v16, 16, v9
	v_sub_f32_e32 v14, v14, v16
	v_and_b32_e32 v16, 0xffff0000, v9
	v_sub_f32_e32 v15, v15, v16
	v_mul_f32_e32 v14, 0x45000000, v14
	v_mul_f32_e32 v15, 0x45000000, v15
	v_cvt_pk_fp8_f32 v5, v14, v15 op_sel:[0,0,1]
	global_store_dwordx4 v[170:171], v[6:9], off offset:256 sc1
	s_nop 1
	v_lshl_add_u64 v[6:7], s[28:29], 0, v[174:175]
	v_lshl_add_u64 v[6:7], v[6:7], 0, v[162:163]
	global_store_dwordx4 v[6:7], v[2:5], off sc1
	ds_read_b64 v[6:7], v169 offset:8320
	s_waitcnt lgkmcnt(0)
	v_sub_f32_e32 v9, v35, v6
	v_add_u32_e32 v2, 16, v166
	v_ashrrev_i32_e32 v3, 31, v2
	v_sub_f32_e32 v8, v34, v6
	v_lshlrev_b64 v[14:15], 11, v[2:3]
	v_sub_f32_e32 v3, v39, v6
	v_sub_f32_e32 v2, v38, v6
	v_sub_f32_e32 v17, v37, v6
	v_sub_f32_e32 v16, v36, v6
	v_pk_mul_f32 v[8:9], v[6:7], v[8:9] op_sel:[1,0]
	v_sub_f32_e32 v5, v41, v6
	v_sub_f32_e32 v4, v40, v6
	v_pk_mul_f32 v[2:3], v[6:7], v[2:3] op_sel:[1,0]
	v_pk_mul_f32 v[16:17], v[6:7], v[16:17] op_sel:[1,0]
	v_pk_fma_f32 v[8:9], v[146:147], v[8:9], v[150:151]
	v_pk_mul_f32 v[4:5], v[6:7], v[4:5] op_sel:[1,0]
	v_pk_fma_f32 v[2:3], v[154:155], v[2:3], v[158:159]
	v_pk_fma_f32 v[16:17], v[148:149], v[16:17], v[152:153]
	v_cndmask_b32_e32 v36, v208, v8, vcc
	v_cndmask_b32_e32 v37, v208, v9, vcc
	v_lshl_add_u64 v[8:9], s[34:35], 0, v[14:15]
	v_pk_fma_f32 v[4:5], v[156:157], v[4:5], v[160:161]
	v_cndmask_b32_e32 v20, v208, v2, vcc
	v_cndmask_b32_e32 v21, v208, v3, vcc
	v_cndmask_b32_e32 v34, v208, v16, vcc
	v_cndmask_b32_e32 v35, v208, v17, vcc
	v_cvt_pk_bf16_f32 v2, v20, v21
	v_lshl_add_u64 v[16:17], v[8:9], 0, v[164:165]
	v_cndmask_b32_e32 v18, v208, v4, vcc
	v_cndmask_b32_e32 v19, v208, v5, vcc
	v_cvt_pk_bf16_f32 v3, v18, v19
	v_cvt_pk_bf16_f32 v4, v36, v37
	v_cvt_pk_bf16_f32 v5, v34, v35
	global_store_dwordx4 v[16:17], v[2:5], off sc1
	v_lshlrev_b32_e32 v8, 16, v2
	v_sub_f32_e32 v8, v20, v8
	v_and_b32_e32 v2, 0xffff0000, v2
	v_sub_f32_e32 v2, v21, v2
	v_mul_f32_e32 v8, 0x45000000, v8
	v_mul_f32_e32 v9, 0x45000000, v2
	v_mov_b32_e32 v2, v179
	v_cvt_pk_fp8_f32 v2, v8, v9
	v_lshlrev_b32_e32 v8, 16, v3
	v_and_b32_e32 v3, 0xffff0000, v3
	v_sub_f32_e32 v8, v18, v8
	v_sub_f32_e32 v3, v19, v3
	v_mul_f32_e32 v8, 0x45000000, v8
	v_mul_f32_e32 v3, 0x45000000, v3
	v_cvt_pk_fp8_f32 v2, v8, v3 op_sel:[0,0,1]
	v_lshlrev_b32_e32 v3, 16, v4
	v_sub_f32_e32 v3, v36, v3
	v_mul_f32_e32 v8, 0x45000000, v3
	v_and_b32_e32 v3, 0xffff0000, v4
	v_sub_f32_e32 v3, v37, v3
	v_mul_f32_e32 v4, 0x45000000, v3
	v_mov_b32_e32 v3, v179
	v_cvt_pk_fp8_f32 v3, v8, v4
	v_lshlrev_b32_e32 v4, 16, v5
	v_and_b32_e32 v5, 0xffff0000, v5
	v_sub_f32_e32 v4, v34, v4
	v_sub_f32_e32 v5, v35, v5
	v_mul_f32_e32 v4, 0x45000000, v4
	v_mul_f32_e32 v5, 0x45000000, v5
	v_cvt_pk_fp8_f32 v3, v4, v5 op_sel:[0,0,1]
	v_sub_f32_e32 v5, v47, v6
	v_sub_f32_e32 v4, v46, v6
	v_sub_f32_e32 v9, v49, v6
	v_sub_f32_e32 v8, v48, v6
	v_sub_f32_e32 v19, v43, v6
	v_sub_f32_e32 v18, v42, v6
	v_sub_f32_e32 v21, v45, v6
	v_sub_f32_e32 v20, v44, v6
	v_pk_mul_f32 v[8:9], v[6:7], v[8:9] op_sel:[1,0]
	v_pk_mul_f32 v[4:5], v[6:7], v[4:5] op_sel:[1,0]
	v_pk_mul_f32 v[20:21], v[6:7], v[20:21] op_sel:[1,0]
	v_pk_mul_f32 v[6:7], v[6:7], v[18:19] op_sel:[1,0]
	v_pk_fma_f32 v[4:5], v[138:139], v[4:5], v[142:143]
	v_pk_fma_f32 v[6:7], v[130:131], v[6:7], v[134:135]
	v_cndmask_b32_e32 v4, v208, v4, vcc
	v_cndmask_b32_e32 v5, v208, v5, vcc
	v_cndmask_b32_e32 v34, v208, v6, vcc
	v_cvt_pk_bf16_f32 v6, v4, v5
	v_pk_fma_f32 v[8:9], v[140:141], v[8:9], v[144:145]
	v_lshlrev_b32_e32 v36, 16, v6
	v_sub_f32_e32 v4, v4, v36
	v_mul_f32_e32 v36, 0x45000000, v4
	v_and_b32_e32 v4, 0xffff0000, v6
	v_sub_f32_e32 v4, v5, v4
	v_mul_f32_e32 v5, 0x45000000, v4
	v_mov_b32_e32 v4, v179
	v_pk_fma_f32 v[18:19], v[132:133], v[20:21], v[136:137]
	v_cndmask_b32_e32 v20, v208, v8, vcc
	v_cndmask_b32_e32 v21, v208, v9, vcc
	v_cndmask_b32_e32 v35, v208, v7, vcc
	v_cvt_pk_bf16_f32 v7, v20, v21
	v_cvt_pk_fp8_f32 v4, v36, v5
	v_lshlrev_b32_e32 v5, 16, v7
	v_sub_f32_e32 v5, v20, v5
	v_and_b32_e32 v20, 0xffff0000, v7
	v_sub_f32_e32 v20, v21, v20
	v_mul_f32_e32 v5, 0x45000000, v5
	v_mul_f32_e32 v20, 0x45000000, v20
	v_cvt_pk_bf16_f32 v8, v34, v35
	v_cvt_pk_fp8_f32 v4, v5, v20 op_sel:[0,0,1]
	v_lshlrev_b32_e32 v5, 16, v8
	v_sub_f32_e32 v5, v34, v5
	v_mul_f32_e32 v20, 0x45000000, v5
	v_and_b32_e32 v5, 0xffff0000, v8
	v_sub_f32_e32 v5, v35, v5
	v_mul_f32_e32 v21, 0x45000000, v5
	v_mov_b32_e32 v5, v179
	v_cndmask_b32_e32 v18, v208, v18, vcc
	v_cndmask_b32_e32 v19, v208, v19, vcc
	v_cvt_pk_bf16_f32 v9, v18, v19
	v_cvt_pk_fp8_f32 v5, v20, v21
	v_lshlrev_b32_e32 v20, 16, v9
	v_sub_f32_e32 v18, v18, v20
	v_and_b32_e32 v20, 0xffff0000, v9
	v_sub_f32_e32 v19, v19, v20
	v_mul_f32_e32 v18, 0x45000000, v18
	v_mul_f32_e32 v19, 0x45000000, v19
	v_cvt_pk_fp8_f32 v5, v18, v19 op_sel:[0,0,1]
	global_store_dwordx4 v[16:17], v[6:9], off offset:256 sc1
	s_nop 1
	v_lshl_add_u64 v[6:7], s[28:29], 0, v[14:15]
	v_lshl_add_u64 v[6:7], v[6:7], 0, v[162:163]
	global_store_dwordx4 v[6:7], v[2:5], off sc1
	ds_read_b64 v[6:7], v169 offset:8448
	s_waitcnt lgkmcnt(0)
	v_sub_f32_e32 v9, v59, v6
	v_add_u32_e32 v2, 32, v166
	v_ashrrev_i32_e32 v3, 31, v2
	v_sub_f32_e32 v8, v58, v6
	v_lshlrev_b64 v[14:15], 11, v[2:3]
	v_sub_f32_e32 v3, v63, v6
	v_sub_f32_e32 v2, v62, v6
	v_sub_f32_e32 v17, v61, v6
	v_sub_f32_e32 v16, v60, v6
	v_pk_mul_f32 v[8:9], v[6:7], v[8:9] op_sel:[1,0]
	v_sub_f32_e32 v5, v65, v6
	v_sub_f32_e32 v4, v64, v6
	v_pk_mul_f32 v[2:3], v[6:7], v[2:3] op_sel:[1,0]
	v_pk_mul_f32 v[16:17], v[6:7], v[16:17] op_sel:[1,0]
	v_pk_fma_f32 v[8:9], v[146:147], v[8:9], v[150:151]
	v_pk_mul_f32 v[4:5], v[6:7], v[4:5] op_sel:[1,0]
	v_pk_fma_f32 v[2:3], v[154:155], v[2:3], v[158:159]
	v_pk_fma_f32 v[16:17], v[148:149], v[16:17], v[152:153]
	v_cndmask_b32_e32 v36, v208, v8, vcc
	v_cndmask_b32_e32 v37, v208, v9, vcc
	v_lshl_add_u64 v[8:9], s[34:35], 0, v[14:15]
	v_pk_fma_f32 v[4:5], v[156:157], v[4:5], v[160:161]
	v_cndmask_b32_e32 v20, v208, v2, vcc
	v_cndmask_b32_e32 v21, v208, v3, vcc
	v_cndmask_b32_e32 v34, v208, v16, vcc
	v_cndmask_b32_e32 v35, v208, v17, vcc
	v_cvt_pk_bf16_f32 v2, v20, v21
	v_lshl_add_u64 v[16:17], v[8:9], 0, v[164:165]
	v_cndmask_b32_e32 v18, v208, v4, vcc
	v_cndmask_b32_e32 v19, v208, v5, vcc
	v_cvt_pk_bf16_f32 v3, v18, v19
	v_cvt_pk_bf16_f32 v4, v36, v37
	v_cvt_pk_bf16_f32 v5, v34, v35
	global_store_dwordx4 v[16:17], v[2:5], off sc1
	v_lshlrev_b32_e32 v8, 16, v2
	v_sub_f32_e32 v8, v20, v8
	v_and_b32_e32 v2, 0xffff0000, v2
	v_sub_f32_e32 v2, v21, v2
	v_mul_f32_e32 v8, 0x45000000, v8
	v_mul_f32_e32 v9, 0x45000000, v2
	v_mov_b32_e32 v2, v179
	v_cvt_pk_fp8_f32 v2, v8, v9
	v_lshlrev_b32_e32 v8, 16, v3
	v_and_b32_e32 v3, 0xffff0000, v3
	v_sub_f32_e32 v8, v18, v8
	v_sub_f32_e32 v3, v19, v3
	v_mul_f32_e32 v8, 0x45000000, v8
	v_mul_f32_e32 v3, 0x45000000, v3
	v_cvt_pk_fp8_f32 v2, v8, v3 op_sel:[0,0,1]
	v_lshlrev_b32_e32 v3, 16, v4
	v_sub_f32_e32 v3, v36, v3
	v_mul_f32_e32 v8, 0x45000000, v3
	v_and_b32_e32 v3, 0xffff0000, v4
	v_sub_f32_e32 v3, v37, v3
	v_mul_f32_e32 v4, 0x45000000, v3
	v_mov_b32_e32 v3, v179
	v_cvt_pk_fp8_f32 v3, v8, v4
	v_lshlrev_b32_e32 v4, 16, v5
	v_and_b32_e32 v5, 0xffff0000, v5
	v_sub_f32_e32 v4, v34, v4
	v_sub_f32_e32 v5, v35, v5
	v_mul_f32_e32 v4, 0x45000000, v4
	v_mul_f32_e32 v5, 0x45000000, v5
	v_cvt_pk_fp8_f32 v3, v4, v5 op_sel:[0,0,1]
	v_sub_f32_e32 v5, v71, v6
	v_sub_f32_e32 v4, v70, v6
	v_sub_f32_e32 v9, v73, v6
	v_sub_f32_e32 v8, v72, v6
	v_sub_f32_e32 v19, v67, v6
	v_sub_f32_e32 v18, v66, v6
	v_sub_f32_e32 v21, v69, v6
	v_sub_f32_e32 v20, v68, v6
	v_pk_mul_f32 v[8:9], v[6:7], v[8:9] op_sel:[1,0]
	v_pk_mul_f32 v[4:5], v[6:7], v[4:5] op_sel:[1,0]
	v_pk_mul_f32 v[20:21], v[6:7], v[20:21] op_sel:[1,0]
	v_pk_mul_f32 v[6:7], v[6:7], v[18:19] op_sel:[1,0]
	v_pk_fma_f32 v[4:5], v[138:139], v[4:5], v[142:143]
	v_pk_fma_f32 v[6:7], v[130:131], v[6:7], v[134:135]
	v_cndmask_b32_e32 v4, v208, v4, vcc
	v_cndmask_b32_e32 v5, v208, v5, vcc
	v_cndmask_b32_e32 v34, v208, v6, vcc
	v_cvt_pk_bf16_f32 v6, v4, v5
	v_pk_fma_f32 v[8:9], v[140:141], v[8:9], v[144:145]
	v_lshlrev_b32_e32 v36, 16, v6
	v_sub_f32_e32 v4, v4, v36
	v_mul_f32_e32 v36, 0x45000000, v4
	v_and_b32_e32 v4, 0xffff0000, v6
	v_sub_f32_e32 v4, v5, v4
	v_mul_f32_e32 v5, 0x45000000, v4
	v_mov_b32_e32 v4, v179
	v_pk_fma_f32 v[18:19], v[132:133], v[20:21], v[136:137]
	v_cndmask_b32_e32 v20, v208, v8, vcc
	v_cndmask_b32_e32 v21, v208, v9, vcc
	v_cndmask_b32_e32 v35, v208, v7, vcc
	v_cvt_pk_bf16_f32 v7, v20, v21
	v_cvt_pk_fp8_f32 v4, v36, v5
	v_lshlrev_b32_e32 v5, 16, v7
	v_sub_f32_e32 v5, v20, v5
	v_and_b32_e32 v20, 0xffff0000, v7
	v_sub_f32_e32 v20, v21, v20
	v_mul_f32_e32 v5, 0x45000000, v5
	v_mul_f32_e32 v20, 0x45000000, v20
	v_cvt_pk_bf16_f32 v8, v34, v35
	v_cvt_pk_fp8_f32 v4, v5, v20 op_sel:[0,0,1]
	v_lshlrev_b32_e32 v5, 16, v8
	v_sub_f32_e32 v5, v34, v5
	v_mul_f32_e32 v20, 0x45000000, v5
	v_and_b32_e32 v5, 0xffff0000, v8
	v_sub_f32_e32 v5, v35, v5
	v_mul_f32_e32 v21, 0x45000000, v5
	v_mov_b32_e32 v5, v179
	v_cndmask_b32_e32 v18, v208, v18, vcc
	v_cndmask_b32_e32 v19, v208, v19, vcc
	v_cvt_pk_bf16_f32 v9, v18, v19
	v_cvt_pk_fp8_f32 v5, v20, v21
	v_lshlrev_b32_e32 v20, 16, v9
	v_sub_f32_e32 v18, v18, v20
	v_and_b32_e32 v20, 0xffff0000, v9
	v_sub_f32_e32 v19, v19, v20
	v_mul_f32_e32 v18, 0x45000000, v18
	v_mul_f32_e32 v19, 0x45000000, v19
	v_cvt_pk_fp8_f32 v5, v18, v19 op_sel:[0,0,1]
	global_store_dwordx4 v[16:17], v[6:9], off offset:256 sc1
	s_nop 1
	v_lshl_add_u64 v[6:7], s[28:29], 0, v[14:15]
	v_lshl_add_u64 v[6:7], v[6:7], 0, v[162:163]
	global_store_dwordx4 v[6:7], v[2:5], off sc1
	ds_read_b64 v[6:7], v169 offset:8576
	s_waitcnt lgkmcnt(0)
	v_sub_f32_e32 v9, v83, v6
	v_add_u32_e32 v2, 48, v166
	v_ashrrev_i32_e32 v3, 31, v2
	v_sub_f32_e32 v8, v82, v6
	v_lshlrev_b64 v[14:15], 11, v[2:3]
	v_sub_f32_e32 v3, v87, v6
	v_sub_f32_e32 v2, v86, v6
	v_sub_f32_e32 v17, v85, v6
	v_sub_f32_e32 v16, v84, v6
	v_pk_mul_f32 v[8:9], v[6:7], v[8:9] op_sel:[1,0]
	v_sub_f32_e32 v5, v89, v6
	v_sub_f32_e32 v4, v88, v6
	v_pk_mul_f32 v[2:3], v[6:7], v[2:3] op_sel:[1,0]
	v_pk_mul_f32 v[16:17], v[6:7], v[16:17] op_sel:[1,0]
	v_pk_fma_f32 v[8:9], v[146:147], v[8:9], v[150:151]
	v_pk_mul_f32 v[4:5], v[6:7], v[4:5] op_sel:[1,0]
	v_pk_fma_f32 v[2:3], v[154:155], v[2:3], v[158:159]
	v_pk_fma_f32 v[16:17], v[148:149], v[16:17], v[152:153]
	v_cndmask_b32_e32 v36, v208, v8, vcc
	v_cndmask_b32_e32 v37, v208, v9, vcc
	v_lshl_add_u64 v[8:9], s[34:35], 0, v[14:15]
	v_pk_fma_f32 v[4:5], v[156:157], v[4:5], v[160:161]
	v_cndmask_b32_e32 v20, v208, v2, vcc
	v_cndmask_b32_e32 v21, v208, v3, vcc
	v_cndmask_b32_e32 v34, v208, v16, vcc
	v_cndmask_b32_e32 v35, v208, v17, vcc
	v_cvt_pk_bf16_f32 v2, v20, v21
	v_lshl_add_u64 v[16:17], v[8:9], 0, v[164:165]
	v_cndmask_b32_e32 v18, v208, v4, vcc
	v_cndmask_b32_e32 v19, v208, v5, vcc
	v_cvt_pk_bf16_f32 v3, v18, v19
	v_cvt_pk_bf16_f32 v4, v36, v37
	v_cvt_pk_bf16_f32 v5, v34, v35
	global_store_dwordx4 v[16:17], v[2:5], off sc1
	v_lshlrev_b32_e32 v8, 16, v2
	v_sub_f32_e32 v8, v20, v8
	v_and_b32_e32 v2, 0xffff0000, v2
	v_sub_f32_e32 v2, v21, v2
	v_mul_f32_e32 v8, 0x45000000, v8
	v_mul_f32_e32 v9, 0x45000000, v2
	v_mov_b32_e32 v2, v179
	v_cvt_pk_fp8_f32 v2, v8, v9
	v_lshlrev_b32_e32 v8, 16, v3
	v_and_b32_e32 v3, 0xffff0000, v3
	v_sub_f32_e32 v8, v18, v8
	v_sub_f32_e32 v3, v19, v3
	v_mul_f32_e32 v8, 0x45000000, v8
	v_mul_f32_e32 v3, 0x45000000, v3
	v_cvt_pk_fp8_f32 v2, v8, v3 op_sel:[0,0,1]
	v_lshlrev_b32_e32 v3, 16, v4
	v_sub_f32_e32 v3, v36, v3
	v_mul_f32_e32 v8, 0x45000000, v3
	v_and_b32_e32 v3, 0xffff0000, v4
	v_sub_f32_e32 v3, v37, v3
	v_mul_f32_e32 v4, 0x45000000, v3
	v_mov_b32_e32 v3, v179
	v_cvt_pk_fp8_f32 v3, v8, v4
	v_lshlrev_b32_e32 v4, 16, v5
	v_and_b32_e32 v5, 0xffff0000, v5
	v_sub_f32_e32 v4, v34, v4
	v_sub_f32_e32 v5, v35, v5
	v_mul_f32_e32 v4, 0x45000000, v4
	v_mul_f32_e32 v5, 0x45000000, v5
	v_cvt_pk_fp8_f32 v3, v4, v5 op_sel:[0,0,1]
	v_sub_f32_e32 v5, v95, v6
	v_sub_f32_e32 v4, v94, v6
	v_sub_f32_e32 v9, v97, v6
	v_sub_f32_e32 v8, v96, v6
	v_sub_f32_e32 v19, v91, v6
	v_sub_f32_e32 v18, v90, v6
	v_sub_f32_e32 v21, v93, v6
	v_sub_f32_e32 v20, v92, v6
	v_pk_mul_f32 v[8:9], v[6:7], v[8:9] op_sel:[1,0]
	v_pk_mul_f32 v[4:5], v[6:7], v[4:5] op_sel:[1,0]
	v_pk_mul_f32 v[20:21], v[6:7], v[20:21] op_sel:[1,0]
	v_pk_mul_f32 v[6:7], v[6:7], v[18:19] op_sel:[1,0]
	v_pk_fma_f32 v[4:5], v[138:139], v[4:5], v[142:143]
	v_pk_fma_f32 v[6:7], v[130:131], v[6:7], v[134:135]
	v_cndmask_b32_e32 v4, v208, v4, vcc
	v_cndmask_b32_e32 v5, v208, v5, vcc
	v_cndmask_b32_e32 v34, v208, v6, vcc
	v_cvt_pk_bf16_f32 v6, v4, v5
	v_pk_fma_f32 v[8:9], v[140:141], v[8:9], v[144:145]
	v_lshlrev_b32_e32 v36, 16, v6
	v_sub_f32_e32 v4, v4, v36
	v_mul_f32_e32 v36, 0x45000000, v4
	v_and_b32_e32 v4, 0xffff0000, v6
	v_sub_f32_e32 v4, v5, v4
	v_mul_f32_e32 v5, 0x45000000, v4
	v_mov_b32_e32 v4, v179
	v_pk_fma_f32 v[18:19], v[132:133], v[20:21], v[136:137]
	v_cndmask_b32_e32 v20, v208, v8, vcc
	v_cndmask_b32_e32 v21, v208, v9, vcc
	v_cndmask_b32_e32 v35, v208, v7, vcc
	v_cvt_pk_bf16_f32 v7, v20, v21
	v_cvt_pk_fp8_f32 v4, v36, v5
	v_lshlrev_b32_e32 v5, 16, v7
	v_sub_f32_e32 v5, v20, v5
	v_and_b32_e32 v20, 0xffff0000, v7
	v_sub_f32_e32 v20, v21, v20
	v_mul_f32_e32 v5, 0x45000000, v5
	v_mul_f32_e32 v20, 0x45000000, v20
	v_cvt_pk_bf16_f32 v8, v34, v35
	v_cvt_pk_fp8_f32 v4, v5, v20 op_sel:[0,0,1]
	v_lshlrev_b32_e32 v5, 16, v8
	v_sub_f32_e32 v5, v34, v5
	v_mul_f32_e32 v20, 0x45000000, v5
	v_and_b32_e32 v5, 0xffff0000, v8
	v_sub_f32_e32 v5, v35, v5
	v_mul_f32_e32 v21, 0x45000000, v5
	v_mov_b32_e32 v5, v179
	v_cndmask_b32_e32 v18, v208, v18, vcc
	v_cndmask_b32_e32 v19, v208, v19, vcc
	v_cvt_pk_bf16_f32 v9, v18, v19
	v_cvt_pk_fp8_f32 v5, v20, v21
	v_lshlrev_b32_e32 v20, 16, v9
	v_sub_f32_e32 v18, v18, v20
	v_and_b32_e32 v20, 0xffff0000, v9
	v_sub_f32_e32 v19, v19, v20
	v_mul_f32_e32 v18, 0x45000000, v18
	v_mul_f32_e32 v19, 0x45000000, v19
	v_cvt_pk_fp8_f32 v5, v18, v19 op_sel:[0,0,1]
	global_store_dwordx4 v[16:17], v[6:9], off offset:256 sc1
	s_nop 1
	v_lshl_add_u64 v[6:7], s[28:29], 0, v[14:15]
	v_lshl_add_u64 v[6:7], v[6:7], 0, v[162:163]
	global_store_dwordx4 v[6:7], v[2:5], off sc1
	ds_read_b64 v[6:7], v169 offset:9216
	s_waitcnt lgkmcnt(0)
	v_sub_f32_e32 v9, v107, v6
	v_add_u32_e32 v2, 0x80, v166
	v_ashrrev_i32_e32 v3, 31, v2
	v_sub_f32_e32 v8, v106, v6
	v_lshlrev_b64 v[14:15], 11, v[2:3]
	v_sub_f32_e32 v3, v111, v6
	v_sub_f32_e32 v2, v110, v6
	v_sub_f32_e32 v17, v109, v6
	v_sub_f32_e32 v16, v108, v6
	v_pk_mul_f32 v[8:9], v[6:7], v[8:9] op_sel:[1,0]
	v_sub_f32_e32 v5, v113, v6
	v_sub_f32_e32 v4, v112, v6
	v_pk_mul_f32 v[2:3], v[6:7], v[2:3] op_sel:[1,0]
	v_pk_mul_f32 v[16:17], v[6:7], v[16:17] op_sel:[1,0]
	v_pk_fma_f32 v[8:9], v[146:147], v[8:9], v[150:151]
	v_pk_mul_f32 v[4:5], v[6:7], v[4:5] op_sel:[1,0]
	v_pk_fma_f32 v[2:3], v[154:155], v[2:3], v[158:159]
	v_pk_fma_f32 v[16:17], v[148:149], v[16:17], v[152:153]
	v_cndmask_b32_e32 v36, v208, v8, vcc
	v_cndmask_b32_e32 v37, v208, v9, vcc
	v_lshl_add_u64 v[8:9], s[34:35], 0, v[14:15]
	v_pk_fma_f32 v[4:5], v[156:157], v[4:5], v[160:161]
	v_cndmask_b32_e32 v20, v208, v2, vcc
	v_cndmask_b32_e32 v21, v208, v3, vcc
	v_cndmask_b32_e32 v34, v208, v16, vcc
	v_cndmask_b32_e32 v35, v208, v17, vcc
	v_cvt_pk_bf16_f32 v2, v20, v21
	v_lshl_add_u64 v[16:17], v[8:9], 0, v[164:165]
	v_cndmask_b32_e32 v18, v208, v4, vcc
	v_cndmask_b32_e32 v19, v208, v5, vcc
	v_cvt_pk_bf16_f32 v3, v18, v19
	v_cvt_pk_bf16_f32 v4, v36, v37
	v_cvt_pk_bf16_f32 v5, v34, v35
	global_store_dwordx4 v[16:17], v[2:5], off sc1
	v_lshlrev_b32_e32 v8, 16, v2
	v_sub_f32_e32 v8, v20, v8
	v_and_b32_e32 v2, 0xffff0000, v2
	v_sub_f32_e32 v2, v21, v2
	v_mul_f32_e32 v8, 0x45000000, v8
	v_mul_f32_e32 v9, 0x45000000, v2
	v_mov_b32_e32 v2, v179
	v_cvt_pk_fp8_f32 v2, v8, v9
	v_lshlrev_b32_e32 v8, 16, v3
	v_and_b32_e32 v3, 0xffff0000, v3
	v_sub_f32_e32 v8, v18, v8
	v_sub_f32_e32 v3, v19, v3
	v_mul_f32_e32 v8, 0x45000000, v8
	v_mul_f32_e32 v3, 0x45000000, v3
	v_cvt_pk_fp8_f32 v2, v8, v3 op_sel:[0,0,1]
	v_lshlrev_b32_e32 v3, 16, v4
	v_sub_f32_e32 v3, v36, v3
	v_mul_f32_e32 v8, 0x45000000, v3
	v_and_b32_e32 v3, 0xffff0000, v4
	v_sub_f32_e32 v3, v37, v3
	v_mul_f32_e32 v4, 0x45000000, v3
	v_mov_b32_e32 v3, v179
	v_cvt_pk_fp8_f32 v3, v8, v4
	v_lshlrev_b32_e32 v4, 16, v5
	v_and_b32_e32 v5, 0xffff0000, v5
	v_sub_f32_e32 v4, v34, v4
	v_sub_f32_e32 v5, v35, v5
	v_mul_f32_e32 v4, 0x45000000, v4
	v_mul_f32_e32 v5, 0x45000000, v5
	v_cvt_pk_fp8_f32 v3, v4, v5 op_sel:[0,0,1]
	v_sub_f32_e32 v5, v123, v6
	v_sub_f32_e32 v4, v122, v6
	v_sub_f32_e32 v9, v125, v6
	v_sub_f32_e32 v8, v124, v6
	v_sub_f32_e32 v19, v115, v6
	v_sub_f32_e32 v18, v114, v6
	v_sub_f32_e32 v21, v117, v6
	v_sub_f32_e32 v20, v116, v6
	v_pk_mul_f32 v[8:9], v[6:7], v[8:9] op_sel:[1,0]
	v_pk_mul_f32 v[4:5], v[6:7], v[4:5] op_sel:[1,0]
	v_pk_mul_f32 v[20:21], v[6:7], v[20:21] op_sel:[1,0]
	v_pk_mul_f32 v[6:7], v[6:7], v[18:19] op_sel:[1,0]
	v_pk_fma_f32 v[4:5], v[138:139], v[4:5], v[142:143]
	v_pk_fma_f32 v[6:7], v[130:131], v[6:7], v[134:135]
	v_cndmask_b32_e32 v4, v208, v4, vcc
	v_cndmask_b32_e32 v5, v208, v5, vcc
	v_cndmask_b32_e32 v34, v208, v6, vcc
	v_cvt_pk_bf16_f32 v6, v4, v5
	v_pk_fma_f32 v[8:9], v[140:141], v[8:9], v[144:145]
	v_lshlrev_b32_e32 v36, 16, v6
	v_sub_f32_e32 v4, v4, v36
	v_mul_f32_e32 v36, 0x45000000, v4
	v_and_b32_e32 v4, 0xffff0000, v6
	v_sub_f32_e32 v4, v5, v4
	v_mul_f32_e32 v5, 0x45000000, v4
	v_mov_b32_e32 v4, v179
	v_pk_fma_f32 v[18:19], v[132:133], v[20:21], v[136:137]
	v_cndmask_b32_e32 v20, v208, v8, vcc
	v_cndmask_b32_e32 v21, v208, v9, vcc
	v_cndmask_b32_e32 v35, v208, v7, vcc
	v_cvt_pk_bf16_f32 v7, v20, v21
	v_cvt_pk_fp8_f32 v4, v36, v5
	v_lshlrev_b32_e32 v5, 16, v7
	v_sub_f32_e32 v5, v20, v5
	v_and_b32_e32 v20, 0xffff0000, v7
	v_sub_f32_e32 v20, v21, v20
	v_mul_f32_e32 v5, 0x45000000, v5
	v_mul_f32_e32 v20, 0x45000000, v20
	v_cvt_pk_bf16_f32 v8, v34, v35
	v_cvt_pk_fp8_f32 v4, v5, v20 op_sel:[0,0,1]
	v_lshlrev_b32_e32 v5, 16, v8
	v_sub_f32_e32 v5, v34, v5
	v_mul_f32_e32 v20, 0x45000000, v5
	v_and_b32_e32 v5, 0xffff0000, v8
	v_sub_f32_e32 v5, v35, v5
	v_mul_f32_e32 v21, 0x45000000, v5
	v_mov_b32_e32 v5, v179
	v_cndmask_b32_e32 v18, v208, v18, vcc
	v_cndmask_b32_e32 v19, v208, v19, vcc
	v_cvt_pk_bf16_f32 v9, v18, v19
	v_cvt_pk_fp8_f32 v5, v20, v21
	v_lshlrev_b32_e32 v20, 16, v9
	v_sub_f32_e32 v18, v18, v20
	v_and_b32_e32 v20, 0xffff0000, v9
	v_sub_f32_e32 v19, v19, v20
	v_mul_f32_e32 v18, 0x45000000, v18
	v_mul_f32_e32 v19, 0x45000000, v19
	v_cvt_pk_fp8_f32 v5, v18, v19 op_sel:[0,0,1]
	global_store_dwordx4 v[16:17], v[6:9], off offset:256 sc1
	s_nop 1
	v_lshl_add_u64 v[6:7], s[28:29], 0, v[14:15]
	v_lshl_add_u64 v[6:7], v[6:7], 0, v[162:163]
	global_store_dwordx4 v[6:7], v[2:5], off sc1
	ds_read_b64 v[6:7], v169 offset:9344
	s_waitcnt lgkmcnt(0)
	v_sub_f32_e32 v9, v119, v6
	v_add_u32_e32 v2, 0x90, v166
	v_ashrrev_i32_e32 v3, 31, v2
	v_sub_f32_e32 v8, v118, v6
	v_lshlrev_b64 v[14:15], 11, v[2:3]
	v_sub_f32_e32 v3, v127, v6
	v_sub_f32_e32 v2, v126, v6
	v_sub_f32_e32 v17, v121, v6
	v_sub_f32_e32 v16, v120, v6
	v_pk_mul_f32 v[8:9], v[6:7], v[8:9] op_sel:[1,0]
	v_sub_f32_e32 v5, v129, v6
	v_sub_f32_e32 v4, v128, v6
	v_pk_mul_f32 v[2:3], v[6:7], v[2:3] op_sel:[1,0]
	v_pk_mul_f32 v[16:17], v[6:7], v[16:17] op_sel:[1,0]
	v_pk_fma_f32 v[8:9], v[146:147], v[8:9], v[150:151]
	v_pk_mul_f32 v[4:5], v[6:7], v[4:5] op_sel:[1,0]
	v_pk_fma_f32 v[2:3], v[154:155], v[2:3], v[158:159]
	v_pk_fma_f32 v[16:17], v[148:149], v[16:17], v[152:153]
	v_cndmask_b32_e32 v36, v208, v8, vcc
	v_cndmask_b32_e32 v37, v208, v9, vcc
	v_lshl_add_u64 v[8:9], s[34:35], 0, v[14:15]
	v_pk_fma_f32 v[4:5], v[156:157], v[4:5], v[160:161]
	v_cndmask_b32_e32 v20, v208, v2, vcc
	v_cndmask_b32_e32 v21, v208, v3, vcc
	v_cndmask_b32_e32 v34, v208, v16, vcc
	v_cndmask_b32_e32 v35, v208, v17, vcc
	v_cvt_pk_bf16_f32 v2, v20, v21
	v_lshl_add_u64 v[16:17], v[8:9], 0, v[164:165]
	v_cndmask_b32_e32 v18, v208, v4, vcc
	v_cndmask_b32_e32 v19, v208, v5, vcc
	v_cvt_pk_bf16_f32 v3, v18, v19
	v_cvt_pk_bf16_f32 v4, v36, v37
	v_cvt_pk_bf16_f32 v5, v34, v35
	global_store_dwordx4 v[16:17], v[2:5], off sc1
	v_lshlrev_b32_e32 v8, 16, v2
	v_sub_f32_e32 v8, v20, v8
	v_and_b32_e32 v2, 0xffff0000, v2
	v_sub_f32_e32 v2, v21, v2
	v_mul_f32_e32 v8, 0x45000000, v8
	v_mul_f32_e32 v9, 0x45000000, v2
	v_mov_b32_e32 v2, v179
	v_cvt_pk_fp8_f32 v2, v8, v9
	v_lshlrev_b32_e32 v8, 16, v3
	v_and_b32_e32 v3, 0xffff0000, v3
	v_sub_f32_e32 v8, v18, v8
	v_sub_f32_e32 v3, v19, v3
	v_mul_f32_e32 v8, 0x45000000, v8
	v_mul_f32_e32 v3, 0x45000000, v3
	v_cvt_pk_fp8_f32 v2, v8, v3 op_sel:[0,0,1]
	v_lshlrev_b32_e32 v3, 16, v4
	v_sub_f32_e32 v3, v36, v3
	v_mul_f32_e32 v8, 0x45000000, v3
	v_and_b32_e32 v3, 0xffff0000, v4
	v_sub_f32_e32 v3, v37, v3
	v_mul_f32_e32 v4, 0x45000000, v3
	v_mov_b32_e32 v3, v179
	v_cvt_pk_fp8_f32 v3, v8, v4
	v_lshlrev_b32_e32 v4, 16, v5
	v_and_b32_e32 v5, 0xffff0000, v5
	v_sub_f32_e32 v4, v34, v4
	v_sub_f32_e32 v5, v35, v5
	v_mul_f32_e32 v4, 0x45000000, v4
	v_mul_f32_e32 v5, 0x45000000, v5
	v_cvt_pk_fp8_f32 v3, v4, v5 op_sel:[0,0,1]
	v_sub_f32_e32 v5, v103, v6
	v_sub_f32_e32 v4, v102, v6
	v_sub_f32_e32 v9, v105, v6
	v_sub_f32_e32 v8, v104, v6
	v_sub_f32_e32 v19, v99, v6
	v_sub_f32_e32 v18, v98, v6
	v_sub_f32_e32 v21, v101, v6
	v_sub_f32_e32 v20, v100, v6
	v_pk_mul_f32 v[8:9], v[6:7], v[8:9] op_sel:[1,0]
	v_pk_mul_f32 v[4:5], v[6:7], v[4:5] op_sel:[1,0]
	v_pk_mul_f32 v[20:21], v[6:7], v[20:21] op_sel:[1,0]
	v_pk_mul_f32 v[6:7], v[6:7], v[18:19] op_sel:[1,0]
	v_pk_fma_f32 v[4:5], v[138:139], v[4:5], v[142:143]
	v_pk_fma_f32 v[6:7], v[130:131], v[6:7], v[134:135]
	v_cndmask_b32_e32 v4, v208, v4, vcc
	v_cndmask_b32_e32 v5, v208, v5, vcc
	v_cndmask_b32_e32 v34, v208, v6, vcc
	v_cvt_pk_bf16_f32 v6, v4, v5
	v_pk_fma_f32 v[8:9], v[140:141], v[8:9], v[144:145]
	v_lshlrev_b32_e32 v36, 16, v6
	v_sub_f32_e32 v4, v4, v36
	v_mul_f32_e32 v36, 0x45000000, v4
	v_and_b32_e32 v4, 0xffff0000, v6
	v_sub_f32_e32 v4, v5, v4
	v_mul_f32_e32 v5, 0x45000000, v4
	v_mov_b32_e32 v4, v179
	v_pk_fma_f32 v[18:19], v[132:133], v[20:21], v[136:137]
	v_cndmask_b32_e32 v20, v208, v8, vcc
	v_cndmask_b32_e32 v21, v208, v9, vcc
	v_cndmask_b32_e32 v35, v208, v7, vcc
	v_cvt_pk_bf16_f32 v7, v20, v21
	v_cvt_pk_fp8_f32 v4, v36, v5
	v_lshlrev_b32_e32 v5, 16, v7
	v_sub_f32_e32 v5, v20, v5
	v_and_b32_e32 v20, 0xffff0000, v7
	v_sub_f32_e32 v20, v21, v20
	v_mul_f32_e32 v5, 0x45000000, v5
	v_mul_f32_e32 v20, 0x45000000, v20
	v_cvt_pk_bf16_f32 v8, v34, v35
	v_cvt_pk_fp8_f32 v4, v5, v20 op_sel:[0,0,1]
	v_lshlrev_b32_e32 v5, 16, v8
	v_sub_f32_e32 v5, v34, v5
	v_mul_f32_e32 v20, 0x45000000, v5
	v_and_b32_e32 v5, 0xffff0000, v8
	v_sub_f32_e32 v5, v35, v5
	v_mul_f32_e32 v21, 0x45000000, v5
	v_mov_b32_e32 v5, v179
	v_cndmask_b32_e32 v18, v208, v18, vcc
	v_cndmask_b32_e32 v19, v208, v19, vcc
	v_cvt_pk_bf16_f32 v9, v18, v19
	v_cvt_pk_fp8_f32 v5, v20, v21
	v_lshlrev_b32_e32 v20, 16, v9
	v_sub_f32_e32 v18, v18, v20
	v_and_b32_e32 v20, 0xffff0000, v9
	v_sub_f32_e32 v19, v19, v20
	v_mul_f32_e32 v18, 0x45000000, v18
	v_mul_f32_e32 v19, 0x45000000, v19
	v_cvt_pk_fp8_f32 v5, v18, v19 op_sel:[0,0,1]
	global_store_dwordx4 v[16:17], v[6:9], off offset:256 sc1
	s_nop 1
	v_lshl_add_u64 v[6:7], s[28:29], 0, v[14:15]
	v_lshl_add_u64 v[6:7], v[6:7], 0, v[162:163]
	global_store_dwordx4 v[6:7], v[2:5], off sc1
	ds_read_b64 v[6:7], v169 offset:9472
	s_waitcnt lgkmcnt(0)
	v_sub_f32_e32 v9, v75, v6
	v_add_u32_e32 v2, 0xa0, v166
	v_ashrrev_i32_e32 v3, 31, v2
	v_sub_f32_e32 v8, v74, v6
	v_lshlrev_b64 v[14:15], 11, v[2:3]
	v_sub_f32_e32 v3, v79, v6
	v_sub_f32_e32 v2, v78, v6
	v_sub_f32_e32 v17, v77, v6
	v_sub_f32_e32 v16, v76, v6
	v_pk_mul_f32 v[8:9], v[6:7], v[8:9] op_sel:[1,0]
	v_sub_f32_e32 v5, v81, v6
	v_sub_f32_e32 v4, v80, v6
	v_pk_mul_f32 v[2:3], v[6:7], v[2:3] op_sel:[1,0]
	v_pk_mul_f32 v[16:17], v[6:7], v[16:17] op_sel:[1,0]
	v_pk_fma_f32 v[8:9], v[146:147], v[8:9], v[150:151]
	v_pk_mul_f32 v[4:5], v[6:7], v[4:5] op_sel:[1,0]
	v_pk_fma_f32 v[2:3], v[154:155], v[2:3], v[158:159]
	v_pk_fma_f32 v[16:17], v[148:149], v[16:17], v[152:153]
	v_cndmask_b32_e32 v36, v208, v8, vcc
	v_cndmask_b32_e32 v37, v208, v9, vcc
	v_lshl_add_u64 v[8:9], s[34:35], 0, v[14:15]
	v_pk_fma_f32 v[4:5], v[156:157], v[4:5], v[160:161]
	v_cndmask_b32_e32 v20, v208, v2, vcc
	v_cndmask_b32_e32 v21, v208, v3, vcc
	v_cndmask_b32_e32 v34, v208, v16, vcc
	v_cndmask_b32_e32 v35, v208, v17, vcc
	v_cvt_pk_bf16_f32 v2, v20, v21
	v_lshl_add_u64 v[16:17], v[8:9], 0, v[164:165]
	v_cndmask_b32_e32 v18, v208, v4, vcc
	v_cndmask_b32_e32 v19, v208, v5, vcc
	v_cvt_pk_bf16_f32 v3, v18, v19
	v_cvt_pk_bf16_f32 v4, v36, v37
	v_cvt_pk_bf16_f32 v5, v34, v35
	global_store_dwordx4 v[16:17], v[2:5], off sc1
	v_lshlrev_b32_e32 v8, 16, v2
	v_sub_f32_e32 v8, v20, v8
	v_and_b32_e32 v2, 0xffff0000, v2
	v_sub_f32_e32 v2, v21, v2
	v_mul_f32_e32 v8, 0x45000000, v8
	v_mul_f32_e32 v9, 0x45000000, v2
	v_mov_b32_e32 v2, v179
	v_cvt_pk_fp8_f32 v2, v8, v9
	v_lshlrev_b32_e32 v8, 16, v3
	v_and_b32_e32 v3, 0xffff0000, v3
	v_sub_f32_e32 v8, v18, v8
	v_sub_f32_e32 v3, v19, v3
	v_mul_f32_e32 v8, 0x45000000, v8
	v_mul_f32_e32 v3, 0x45000000, v3
	v_cvt_pk_fp8_f32 v2, v8, v3 op_sel:[0,0,1]
	v_lshlrev_b32_e32 v3, 16, v4
	v_sub_f32_e32 v3, v36, v3
	v_mul_f32_e32 v8, 0x45000000, v3
	v_and_b32_e32 v3, 0xffff0000, v4
	v_sub_f32_e32 v3, v37, v3
	v_mul_f32_e32 v4, 0x45000000, v3
	v_mov_b32_e32 v3, v179
	v_cvt_pk_fp8_f32 v3, v8, v4
	v_lshlrev_b32_e32 v4, 16, v5
	v_and_b32_e32 v5, 0xffff0000, v5
	v_sub_f32_e32 v4, v34, v4
	v_sub_f32_e32 v5, v35, v5
	v_mul_f32_e32 v4, 0x45000000, v4
	v_mul_f32_e32 v5, 0x45000000, v5
	v_cvt_pk_fp8_f32 v3, v4, v5 op_sel:[0,0,1]
	v_sub_f32_e32 v5, v55, v6
	v_sub_f32_e32 v4, v54, v6
	v_sub_f32_e32 v9, v57, v6
	v_sub_f32_e32 v8, v56, v6
	v_sub_f32_e32 v19, v51, v6
	v_sub_f32_e32 v18, v50, v6
	v_sub_f32_e32 v21, v53, v6
	v_sub_f32_e32 v20, v52, v6
	v_pk_mul_f32 v[8:9], v[6:7], v[8:9] op_sel:[1,0]
	v_pk_mul_f32 v[4:5], v[6:7], v[4:5] op_sel:[1,0]
	v_pk_mul_f32 v[20:21], v[6:7], v[20:21] op_sel:[1,0]
	v_pk_mul_f32 v[6:7], v[6:7], v[18:19] op_sel:[1,0]
	v_pk_fma_f32 v[4:5], v[138:139], v[4:5], v[142:143]
	v_pk_fma_f32 v[6:7], v[130:131], v[6:7], v[134:135]
	v_cndmask_b32_e32 v4, v208, v4, vcc
	v_cndmask_b32_e32 v5, v208, v5, vcc
	v_cndmask_b32_e32 v34, v208, v6, vcc
	v_cvt_pk_bf16_f32 v6, v4, v5
	v_pk_fma_f32 v[8:9], v[140:141], v[8:9], v[144:145]
	v_lshlrev_b32_e32 v36, 16, v6
	v_sub_f32_e32 v4, v4, v36
	v_mul_f32_e32 v36, 0x45000000, v4
	v_and_b32_e32 v4, 0xffff0000, v6
	v_sub_f32_e32 v4, v5, v4
	v_mul_f32_e32 v5, 0x45000000, v4
	v_mov_b32_e32 v4, v179
	v_pk_fma_f32 v[18:19], v[132:133], v[20:21], v[136:137]
	v_cndmask_b32_e32 v20, v208, v8, vcc
	v_cndmask_b32_e32 v21, v208, v9, vcc
	v_cndmask_b32_e32 v35, v208, v7, vcc
	v_cvt_pk_bf16_f32 v7, v20, v21
	v_cvt_pk_fp8_f32 v4, v36, v5
	v_lshlrev_b32_e32 v5, 16, v7
	v_sub_f32_e32 v5, v20, v5
	v_and_b32_e32 v20, 0xffff0000, v7
	v_sub_f32_e32 v20, v21, v20
	v_mul_f32_e32 v5, 0x45000000, v5
	v_mul_f32_e32 v20, 0x45000000, v20
	v_cvt_pk_bf16_f32 v8, v34, v35
	v_cvt_pk_fp8_f32 v4, v5, v20 op_sel:[0,0,1]
	v_lshlrev_b32_e32 v5, 16, v8
	v_sub_f32_e32 v5, v34, v5
	v_mul_f32_e32 v20, 0x45000000, v5
	v_and_b32_e32 v5, 0xffff0000, v8
	v_sub_f32_e32 v5, v35, v5
	v_mul_f32_e32 v21, 0x45000000, v5
	v_mov_b32_e32 v5, v179
	v_cndmask_b32_e32 v18, v208, v18, vcc
	v_cndmask_b32_e32 v19, v208, v19, vcc
	v_cvt_pk_bf16_f32 v9, v18, v19
	v_cvt_pk_fp8_f32 v5, v20, v21
	v_lshlrev_b32_e32 v20, 16, v9
	v_sub_f32_e32 v18, v18, v20
	v_and_b32_e32 v20, 0xffff0000, v9
	v_sub_f32_e32 v19, v19, v20
	v_mul_f32_e32 v18, 0x45000000, v18
	v_mul_f32_e32 v19, 0x45000000, v19
	v_cvt_pk_fp8_f32 v5, v18, v19 op_sel:[0,0,1]
	global_store_dwordx4 v[16:17], v[6:9], off offset:256 sc1
	s_nop 1
	v_lshl_add_u64 v[6:7], s[28:29], 0, v[14:15]
	v_lshl_add_u64 v[6:7], v[6:7], 0, v[162:163]
	global_store_dwordx4 v[6:7], v[2:5], off sc1
	ds_read_b64 v[6:7], v169 offset:9600
	s_waitcnt lgkmcnt(0)
	v_sub_f32_e32 v9, v27, v6
	v_add_u32_e32 v2, 0xb0, v166
	v_ashrrev_i32_e32 v3, 31, v2
	v_sub_f32_e32 v8, v26, v6
	v_lshlrev_b64 v[14:15], 11, v[2:3]
	v_sub_f32_e32 v3, v31, v6
	v_sub_f32_e32 v2, v30, v6
	v_sub_f32_e32 v17, v29, v6
	v_sub_f32_e32 v16, v28, v6
	v_pk_mul_f32 v[8:9], v[6:7], v[8:9] op_sel:[1,0]
	v_sub_f32_e32 v5, v33, v6
	v_sub_f32_e32 v4, v32, v6
	v_pk_mul_f32 v[2:3], v[6:7], v[2:3] op_sel:[1,0]
	v_pk_mul_f32 v[16:17], v[6:7], v[16:17] op_sel:[1,0]
	v_pk_fma_f32 v[8:9], v[146:147], v[8:9], v[150:151]
	v_pk_mul_f32 v[4:5], v[6:7], v[4:5] op_sel:[1,0]
	v_pk_fma_f32 v[2:3], v[154:155], v[2:3], v[158:159]
	v_pk_fma_f32 v[16:17], v[148:149], v[16:17], v[152:153]
	v_cndmask_b32_e32 v28, v208, v8, vcc
	v_cndmask_b32_e32 v29, v208, v9, vcc
	v_lshl_add_u64 v[8:9], s[34:35], 0, v[14:15]
	v_pk_fma_f32 v[4:5], v[156:157], v[4:5], v[160:161]
	v_cndmask_b32_e32 v20, v208, v2, vcc
	v_cndmask_b32_e32 v21, v208, v3, vcc
	v_cndmask_b32_e32 v26, v208, v16, vcc
	v_cndmask_b32_e32 v27, v208, v17, vcc
	v_cvt_pk_bf16_f32 v2, v20, v21
	v_lshl_add_u64 v[16:17], v[8:9], 0, v[164:165]
	v_cndmask_b32_e32 v18, v208, v4, vcc
	v_cndmask_b32_e32 v19, v208, v5, vcc
	v_cvt_pk_bf16_f32 v3, v18, v19
	v_cvt_pk_bf16_f32 v4, v28, v29
	v_cvt_pk_bf16_f32 v5, v26, v27
	global_store_dwordx4 v[16:17], v[2:5], off sc1
	v_lshlrev_b32_e32 v8, 16, v2
	v_sub_f32_e32 v8, v20, v8
	v_and_b32_e32 v2, 0xffff0000, v2
	v_sub_f32_e32 v2, v21, v2
	v_mul_f32_e32 v8, 0x45000000, v8
	v_mul_f32_e32 v9, 0x45000000, v2
	v_mov_b32_e32 v2, v179
	v_cvt_pk_fp8_f32 v2, v8, v9
	v_lshlrev_b32_e32 v8, 16, v3
	v_and_b32_e32 v3, 0xffff0000, v3
	v_sub_f32_e32 v8, v18, v8
	v_sub_f32_e32 v3, v19, v3
	v_mul_f32_e32 v8, 0x45000000, v8
	v_mul_f32_e32 v3, 0x45000000, v3
	v_cvt_pk_fp8_f32 v2, v8, v3 op_sel:[0,0,1]
	v_lshlrev_b32_e32 v3, 16, v4
	v_sub_f32_e32 v3, v28, v3
	v_mul_f32_e32 v8, 0x45000000, v3
	v_and_b32_e32 v3, 0xffff0000, v4
	v_sub_f32_e32 v3, v29, v3
	v_mul_f32_e32 v4, 0x45000000, v3
	v_mov_b32_e32 v3, v179
	v_cvt_pk_fp8_f32 v3, v8, v4
	v_lshlrev_b32_e32 v4, 16, v5
	v_and_b32_e32 v5, 0xffff0000, v5
	v_sub_f32_e32 v4, v26, v4
	v_sub_f32_e32 v5, v27, v5
	v_mul_f32_e32 v4, 0x45000000, v4
	v_mul_f32_e32 v5, 0x45000000, v5
	v_cvt_pk_fp8_f32 v3, v4, v5 op_sel:[0,0,1]
	v_sub_f32_e32 v5, v23, v6
	v_sub_f32_e32 v4, v22, v6
	v_sub_f32_e32 v9, v25, v6
	v_sub_f32_e32 v8, v24, v6
	v_sub_f32_e32 v11, v11, v6
	v_sub_f32_e32 v10, v10, v6
	v_sub_f32_e32 v13, v13, v6
	v_sub_f32_e32 v12, v12, v6
	v_pk_mul_f32 v[8:9], v[6:7], v[8:9] op_sel:[1,0]
	v_pk_mul_f32 v[4:5], v[6:7], v[4:5] op_sel:[1,0]
	v_pk_mul_f32 v[12:13], v[6:7], v[12:13] op_sel:[1,0]
	v_pk_mul_f32 v[6:7], v[6:7], v[10:11] op_sel:[1,0]
	v_pk_fma_f32 v[4:5], v[138:139], v[4:5], v[142:143]
	v_pk_fma_f32 v[6:7], v[130:131], v[6:7], v[134:135]
	v_cndmask_b32_e32 v4, v208, v4, vcc
	v_cndmask_b32_e32 v5, v208, v5, vcc
	v_cndmask_b32_e32 v18, v208, v6, vcc
	v_cvt_pk_bf16_f32 v6, v4, v5
	v_pk_fma_f32 v[8:9], v[140:141], v[8:9], v[144:145]
	v_lshlrev_b32_e32 v20, 16, v6
	v_sub_f32_e32 v4, v4, v20
	v_mul_f32_e32 v20, 0x45000000, v4
	v_and_b32_e32 v4, 0xffff0000, v6
	v_sub_f32_e32 v4, v5, v4
	v_mul_f32_e32 v5, 0x45000000, v4
	v_mov_b32_e32 v4, v179
	v_pk_fma_f32 v[10:11], v[132:133], v[12:13], v[136:137]
	v_cndmask_b32_e32 v12, v208, v8, vcc
	v_cndmask_b32_e32 v13, v208, v9, vcc
	v_cndmask_b32_e32 v19, v208, v7, vcc
	v_cvt_pk_bf16_f32 v7, v12, v13
	v_cvt_pk_fp8_f32 v4, v20, v5
	v_lshlrev_b32_e32 v5, 16, v7
	v_sub_f32_e32 v5, v12, v5
	v_and_b32_e32 v12, 0xffff0000, v7
	v_sub_f32_e32 v12, v13, v12
	v_mul_f32_e32 v5, 0x45000000, v5
	v_mul_f32_e32 v12, 0x45000000, v12
	v_cvt_pk_bf16_f32 v8, v18, v19
	v_cvt_pk_fp8_f32 v4, v5, v12 op_sel:[0,0,1]
	v_lshlrev_b32_e32 v5, 16, v8
	v_sub_f32_e32 v5, v18, v5
	v_mul_f32_e32 v12, 0x45000000, v5
	v_and_b32_e32 v5, 0xffff0000, v8
	v_sub_f32_e32 v5, v19, v5
	v_mul_f32_e32 v13, 0x45000000, v5
	v_mov_b32_e32 v5, v179
	v_cndmask_b32_e32 v10, v208, v10, vcc
	v_cndmask_b32_e32 v11, v208, v11, vcc
	v_cvt_pk_bf16_f32 v9, v10, v11
	v_cvt_pk_fp8_f32 v5, v12, v13
	v_lshlrev_b32_e32 v12, 16, v9
	v_sub_f32_e32 v10, v10, v12
	v_and_b32_e32 v12, 0xffff0000, v9
	v_sub_f32_e32 v11, v11, v12
	v_mul_f32_e32 v10, 0x45000000, v10
	v_mul_f32_e32 v11, 0x45000000, v11
	v_cvt_pk_fp8_f32 v5, v10, v11 op_sel:[0,0,1]
	global_store_dwordx4 v[16:17], v[6:9], off offset:256 sc1
	s_nop 1
	v_lshl_add_u64 v[6:7], s[28:29], 0, v[14:15]
	v_lshl_add_u64 v[6:7], v[6:7], 0, v[162:163]
	global_store_dwordx4 v[6:7], v[2:5], off sc1

.LBB0_1336:
	s_or_b64 exec, exec, s[0:1]
	s_waitcnt lgkmcnt(0)
	s_barrier
	v_lshl_add_u32 v167, v166, 3, 0
	ds_read_b64 v[170:171], v167 offset:8192
	s_lshl_b64 s[0:1], s[24:25], 2
	v_add_u32_e32 v164, s20, v166
	s_add_u32 s0, s72, s0
	v_ashrrev_i32_e32 v165, 31, v164
	s_waitcnt lgkmcnt(0)
	v_sub_f32_e32 v7, v7, v170
	v_sub_f32_e32 v6, v6, v170
	v_sub_f32_e32 v9, v9, v170
	v_sub_f32_e32 v8, v8, v170
	s_addc_u32 s1, s73, s1
	v_pk_mul_f32 v[8:9], v[170:171], v[8:9] op_sel:[1,0]
	v_pk_mul_f32 v[6:7], v[170:171], v[6:7] op_sel:[1,0]
	v_sub_f32_e32 v3, v3, v170
	v_sub_f32_e32 v2, v2, v170
	v_sub_f32_e32 v5, v5, v170
	v_sub_f32_e32 v4, v4, v170
	v_cmp_eq_u32_e32 vcc, 0, v169
	v_lshlrev_b64 v[168:169], 12, v[164:165]
	s_waitcnt vmcnt(5)
	v_pk_fma_f32 v[6:7], v[154:155], v[6:7], v[158:159]
	v_pk_fma_f32 v[8:9], v[156:157], v[8:9], v[160:161]
	v_pk_mul_f32 v[4:5], v[170:171], v[4:5] op_sel:[1,0]
	v_pk_mul_f32 v[2:3], v[170:171], v[2:3] op_sel:[1,0]
	v_lshl_add_u64 v[168:169], s[0:1], 0, v[168:169]
	s_waitcnt vmcnt(4)
	v_pk_fma_f32 v[172:173], v[146:147], v[2:3], v[150:151]
	v_pk_fma_f32 v[174:175], v[148:149], v[4:5], v[152:153]
	v_cndmask_b32_e32 v5, v208, v9, vcc
	v_cndmask_b32_e32 v4, v208, v8, vcc
	v_cndmask_b32_e32 v3, v208, v7, vcc
	v_cndmask_b32_e32 v2, v208, v6, vcc
	v_lshl_add_u64 v[168:169], v[168:169], 0, v[162:163]
	v_cndmask_b32_e32 v9, v208, v175, vcc
	v_cndmask_b32_e32 v8, v208, v174, vcc
	v_cndmask_b32_e32 v7, v208, v173, vcc
	v_cndmask_b32_e32 v6, v208, v172, vcc
	global_store_dwordx4 v[168:169], v[2:5], off sc1
	global_store_dwordx4 v[168:169], v[6:9], off offset:16 sc1
	s_nop 0
	v_sub_f32_e32 v3, v23, v170
	v_sub_f32_e32 v2, v22, v170
	v_sub_f32_e32 v5, v25, v170
	v_sub_f32_e32 v4, v24, v170
	v_pk_mul_f32 v[4:5], v[170:171], v[4:5] op_sel:[1,0]
	v_pk_mul_f32 v[2:3], v[170:171], v[2:3] op_sel:[1,0]
	v_sub_f32_e32 v7, v19, v170
	v_sub_f32_e32 v6, v18, v170
	v_sub_f32_e32 v9, v21, v170
	v_sub_f32_e32 v8, v20, v170
	s_waitcnt vmcnt(2)
	v_pk_fma_f32 v[2:3], v[138:139], v[2:3], v[142:143]
	v_pk_fma_f32 v[4:5], v[140:141], v[4:5], v[144:145]
	v_pk_mul_f32 v[8:9], v[170:171], v[8:9] op_sel:[1,0]
	v_pk_mul_f32 v[6:7], v[170:171], v[6:7] op_sel:[1,0]
	v_pk_fma_f32 v[8:9], v[132:133], v[8:9], v[136:137]
	v_pk_fma_f32 v[6:7], v[130:131], v[6:7], v[134:135]
	v_cndmask_b32_e32 v5, v208, v5, vcc
	v_cndmask_b32_e32 v4, v208, v4, vcc
	v_cndmask_b32_e32 v3, v208, v3, vcc
	v_cndmask_b32_e32 v2, v208, v2, vcc
	v_cndmask_b32_e32 v9, v208, v9, vcc
	v_cndmask_b32_e32 v8, v208, v8, vcc
	v_cndmask_b32_e32 v7, v208, v7, vcc
	v_cndmask_b32_e32 v6, v208, v6, vcc
	global_store_dwordx4 v[168:169], v[2:5], off offset:512 sc1
	global_store_dwordx4 v[168:169], v[6:9], off offset:528 sc1
	ds_read_b64 v[18:19], v167 offset:8320
	v_add_u32_e32 v20, 16, v164
	v_ashrrev_i32_e32 v21, 31, v20
	v_lshlrev_b64 v[20:21], 12, v[20:21]
	v_lshl_add_u64 v[20:21], s[0:1], 0, v[20:21]
	s_waitcnt lgkmcnt(0)
	v_sub_f32_e32 v3, v39, v18
	v_sub_f32_e32 v2, v38, v18
	v_sub_f32_e32 v5, v41, v18
	v_sub_f32_e32 v4, v40, v18
	v_pk_mul_f32 v[4:5], v[18:19], v[4:5] op_sel:[1,0]
	v_pk_mul_f32 v[2:3], v[18:19], v[2:3] op_sel:[1,0]
	v_sub_f32_e32 v7, v35, v18
	v_sub_f32_e32 v6, v34, v18
	v_sub_f32_e32 v9, v37, v18
	v_sub_f32_e32 v8, v36, v18
	v_pk_fma_f32 v[2:3], v[154:155], v[2:3], v[158:159]
	v_pk_fma_f32 v[4:5], v[156:157], v[4:5], v[160:161]
	v_pk_mul_f32 v[8:9], v[18:19], v[8:9] op_sel:[1,0]
	v_pk_mul_f32 v[6:7], v[18:19], v[6:7] op_sel:[1,0]
	v_pk_fma_f32 v[8:9], v[148:149], v[8:9], v[152:153]
	v_pk_fma_f32 v[6:7], v[146:147], v[6:7], v[150:151]
	v_cndmask_b32_e32 v5, v208, v5, vcc
	v_cndmask_b32_e32 v4, v208, v4, vcc
	v_cndmask_b32_e32 v3, v208, v3, vcc
	v_cndmask_b32_e32 v2, v208, v2, vcc
	v_lshl_add_u64 v[20:21], v[20:21], 0, v[162:163]
	v_cndmask_b32_e32 v9, v208, v9, vcc
	v_cndmask_b32_e32 v8, v208, v8, vcc
	v_cndmask_b32_e32 v7, v208, v7, vcc
	v_cndmask_b32_e32 v6, v208, v6, vcc
	global_store_dwordx4 v[20:21], v[2:5], off sc1
	global_store_dwordx4 v[20:21], v[6:9], off offset:16 sc1
	s_nop 0
	v_sub_f32_e32 v3, v47, v18
	v_sub_f32_e32 v2, v46, v18
	v_sub_f32_e32 v5, v49, v18
	v_sub_f32_e32 v4, v48, v18
	v_pk_mul_f32 v[4:5], v[18:19], v[4:5] op_sel:[1,0]
	v_pk_mul_f32 v[2:3], v[18:19], v[2:3] op_sel:[1,0]
	v_sub_f32_e32 v7, v43, v18
	v_sub_f32_e32 v6, v42, v18
	v_sub_f32_e32 v9, v45, v18
	v_sub_f32_e32 v8, v44, v18
	v_pk_fma_f32 v[2:3], v[138:139], v[2:3], v[142:143]
	v_pk_fma_f32 v[4:5], v[140:141], v[4:5], v[144:145]
	v_pk_mul_f32 v[8:9], v[18:19], v[8:9] op_sel:[1,0]
	v_pk_mul_f32 v[6:7], v[18:19], v[6:7] op_sel:[1,0]
	v_pk_fma_f32 v[8:9], v[132:133], v[8:9], v[136:137]
	v_pk_fma_f32 v[6:7], v[130:131], v[6:7], v[134:135]
	v_cndmask_b32_e32 v5, v208, v5, vcc
	v_cndmask_b32_e32 v4, v208, v4, vcc
	v_cndmask_b32_e32 v3, v208, v3, vcc
	v_cndmask_b32_e32 v2, v208, v2, vcc
	v_cndmask_b32_e32 v9, v208, v9, vcc
	v_cndmask_b32_e32 v8, v208, v8, vcc
	v_cndmask_b32_e32 v7, v208, v7, vcc
	v_cndmask_b32_e32 v6, v208, v6, vcc
	global_store_dwordx4 v[20:21], v[2:5], off offset:512 sc1
	global_store_dwordx4 v[20:21], v[6:9], off offset:528 sc1
	ds_read_b64 v[18:19], v167 offset:8448
	v_add_u32_e32 v20, 32, v164
	v_ashrrev_i32_e32 v21, 31, v20
	v_lshlrev_b64 v[20:21], 12, v[20:21]
	v_lshl_add_u64 v[20:21], s[0:1], 0, v[20:21]
	s_waitcnt lgkmcnt(0)
	v_sub_f32_e32 v3, v63, v18
	v_sub_f32_e32 v2, v62, v18
	v_sub_f32_e32 v5, v65, v18
	v_sub_f32_e32 v4, v64, v18
	v_pk_mul_f32 v[4:5], v[18:19], v[4:5] op_sel:[1,0]
	v_pk_mul_f32 v[2:3], v[18:19], v[2:3] op_sel:[1,0]
	v_sub_f32_e32 v7, v59, v18
	v_sub_f32_e32 v6, v58, v18
	v_sub_f32_e32 v9, v61, v18
	v_sub_f32_e32 v8, v60, v18
	v_pk_fma_f32 v[2:3], v[154:155], v[2:3], v[158:159]
	v_pk_fma_f32 v[4:5], v[156:157], v[4:5], v[160:161]
	v_pk_mul_f32 v[8:9], v[18:19], v[8:9] op_sel:[1,0]
	v_pk_mul_f32 v[6:7], v[18:19], v[6:7] op_sel:[1,0]
	v_pk_fma_f32 v[8:9], v[148:149], v[8:9], v[152:153]
	v_pk_fma_f32 v[6:7], v[146:147], v[6:7], v[150:151]
	v_cndmask_b32_e32 v5, v208, v5, vcc
	v_cndmask_b32_e32 v4, v208, v4, vcc
	v_cndmask_b32_e32 v3, v208, v3, vcc
	v_cndmask_b32_e32 v2, v208, v2, vcc
	v_lshl_add_u64 v[20:21], v[20:21], 0, v[162:163]
	v_cndmask_b32_e32 v9, v208, v9, vcc
	v_cndmask_b32_e32 v8, v208, v8, vcc
	v_cndmask_b32_e32 v7, v208, v7, vcc
	v_cndmask_b32_e32 v6, v208, v6, vcc
	global_store_dwordx4 v[20:21], v[2:5], off sc1
	global_store_dwordx4 v[20:21], v[6:9], off offset:16 sc1
	s_nop 0
	v_sub_f32_e32 v3, v79, v18
	v_sub_f32_e32 v2, v78, v18
	v_sub_f32_e32 v5, v81, v18
	v_sub_f32_e32 v4, v80, v18
	v_pk_mul_f32 v[4:5], v[18:19], v[4:5] op_sel:[1,0]
	v_pk_mul_f32 v[2:3], v[18:19], v[2:3] op_sel:[1,0]
	v_sub_f32_e32 v7, v75, v18
	v_sub_f32_e32 v6, v74, v18
	v_sub_f32_e32 v9, v77, v18
	v_sub_f32_e32 v8, v76, v18
	v_pk_fma_f32 v[2:3], v[138:139], v[2:3], v[142:143]
	v_pk_fma_f32 v[4:5], v[140:141], v[4:5], v[144:145]
	v_pk_mul_f32 v[8:9], v[18:19], v[8:9] op_sel:[1,0]
	v_pk_mul_f32 v[6:7], v[18:19], v[6:7] op_sel:[1,0]
	v_pk_fma_f32 v[8:9], v[132:133], v[8:9], v[136:137]
	v_pk_fma_f32 v[6:7], v[130:131], v[6:7], v[134:135]
	v_cndmask_b32_e32 v5, v208, v5, vcc
	v_cndmask_b32_e32 v4, v208, v4, vcc
	v_cndmask_b32_e32 v3, v208, v3, vcc
	v_cndmask_b32_e32 v2, v208, v2, vcc
	v_cndmask_b32_e32 v9, v208, v9, vcc
	v_cndmask_b32_e32 v8, v208, v8, vcc
	v_cndmask_b32_e32 v7, v208, v7, vcc
	v_cndmask_b32_e32 v6, v208, v6, vcc
	global_store_dwordx4 v[20:21], v[2:5], off offset:512 sc1
	global_store_dwordx4 v[20:21], v[6:9], off offset:528 sc1
	ds_read_b64 v[18:19], v167 offset:8576
	v_add_u32_e32 v20, 48, v164
	v_ashrrev_i32_e32 v21, 31, v20
	v_lshlrev_b64 v[20:21], 12, v[20:21]
	v_lshl_add_u64 v[20:21], s[0:1], 0, v[20:21]
	s_waitcnt lgkmcnt(0)
	v_sub_f32_e32 v3, v95, v18
	v_sub_f32_e32 v2, v94, v18
	v_sub_f32_e32 v5, v97, v18
	v_sub_f32_e32 v4, v96, v18
	v_pk_mul_f32 v[4:5], v[18:19], v[4:5] op_sel:[1,0]
	v_pk_mul_f32 v[2:3], v[18:19], v[2:3] op_sel:[1,0]
	v_sub_f32_e32 v7, v91, v18
	v_sub_f32_e32 v6, v90, v18
	v_sub_f32_e32 v9, v93, v18
	v_sub_f32_e32 v8, v92, v18
	v_pk_fma_f32 v[2:3], v[154:155], v[2:3], v[158:159]
	v_pk_fma_f32 v[4:5], v[156:157], v[4:5], v[160:161]
	v_pk_mul_f32 v[8:9], v[18:19], v[8:9] op_sel:[1,0]
	v_pk_mul_f32 v[6:7], v[18:19], v[6:7] op_sel:[1,0]
	v_pk_fma_f32 v[8:9], v[148:149], v[8:9], v[152:153]
	v_pk_fma_f32 v[6:7], v[146:147], v[6:7], v[150:151]
	v_cndmask_b32_e32 v5, v208, v5, vcc
	v_cndmask_b32_e32 v4, v208, v4, vcc
	v_cndmask_b32_e32 v3, v208, v3, vcc
	v_cndmask_b32_e32 v2, v208, v2, vcc
	v_lshl_add_u64 v[20:21], v[20:21], 0, v[162:163]
	v_cndmask_b32_e32 v9, v208, v9, vcc
	v_cndmask_b32_e32 v8, v208, v8, vcc
	v_cndmask_b32_e32 v7, v208, v7, vcc
	v_cndmask_b32_e32 v6, v208, v6, vcc
	global_store_dwordx4 v[20:21], v[2:5], off sc1
	global_store_dwordx4 v[20:21], v[6:9], off offset:16 sc1
	s_nop 0
	v_sub_f32_e32 v3, v103, v18
	v_sub_f32_e32 v2, v102, v18
	v_sub_f32_e32 v5, v105, v18
	v_sub_f32_e32 v4, v104, v18
	v_pk_mul_f32 v[4:5], v[18:19], v[4:5] op_sel:[1,0]
	v_pk_mul_f32 v[2:3], v[18:19], v[2:3] op_sel:[1,0]
	v_sub_f32_e32 v7, v99, v18
	v_sub_f32_e32 v6, v98, v18
	v_sub_f32_e32 v9, v101, v18
	v_sub_f32_e32 v8, v100, v18
	v_pk_fma_f32 v[2:3], v[138:139], v[2:3], v[142:143]
	v_pk_fma_f32 v[4:5], v[140:141], v[4:5], v[144:145]
	v_pk_mul_f32 v[8:9], v[18:19], v[8:9] op_sel:[1,0]
	v_pk_mul_f32 v[6:7], v[18:19], v[6:7] op_sel:[1,0]
	v_pk_fma_f32 v[8:9], v[132:133], v[8:9], v[136:137]
	v_pk_fma_f32 v[6:7], v[130:131], v[6:7], v[134:135]
	v_cndmask_b32_e32 v5, v208, v5, vcc
	v_cndmask_b32_e32 v4, v208, v4, vcc
	v_cndmask_b32_e32 v3, v208, v3, vcc
	v_cndmask_b32_e32 v2, v208, v2, vcc
	v_cndmask_b32_e32 v9, v208, v9, vcc
	v_cndmask_b32_e32 v8, v208, v8, vcc
	v_cndmask_b32_e32 v7, v208, v7, vcc
	v_cndmask_b32_e32 v6, v208, v6, vcc
	global_store_dwordx4 v[20:21], v[2:5], off offset:512 sc1
	global_store_dwordx4 v[20:21], v[6:9], off offset:528 sc1
	ds_read_b64 v[18:19], v167 offset:9216
	v_add_u32_e32 v20, 0x80, v164
	v_ashrrev_i32_e32 v21, 31, v20
	v_lshlrev_b64 v[20:21], 12, v[20:21]
	v_lshl_add_u64 v[20:21], s[0:1], 0, v[20:21]
	s_waitcnt lgkmcnt(0)
	v_sub_f32_e32 v3, v119, v18
	v_sub_f32_e32 v2, v118, v18
	v_sub_f32_e32 v5, v121, v18
	v_sub_f32_e32 v4, v120, v18
	v_pk_mul_f32 v[4:5], v[18:19], v[4:5] op_sel:[1,0]
	v_pk_mul_f32 v[2:3], v[18:19], v[2:3] op_sel:[1,0]
	v_sub_f32_e32 v7, v115, v18
	v_sub_f32_e32 v6, v114, v18
	v_sub_f32_e32 v9, v117, v18
	v_sub_f32_e32 v8, v116, v18
	v_pk_fma_f32 v[2:3], v[154:155], v[2:3], v[158:159]
	v_pk_fma_f32 v[4:5], v[156:157], v[4:5], v[160:161]
	v_pk_mul_f32 v[8:9], v[18:19], v[8:9] op_sel:[1,0]
	v_pk_mul_f32 v[6:7], v[18:19], v[6:7] op_sel:[1,0]
	v_pk_fma_f32 v[8:9], v[148:149], v[8:9], v[152:153]
	v_pk_fma_f32 v[6:7], v[146:147], v[6:7], v[150:151]
	v_cndmask_b32_e32 v5, v208, v5, vcc
	v_cndmask_b32_e32 v4, v208, v4, vcc
	v_cndmask_b32_e32 v3, v208, v3, vcc
	v_cndmask_b32_e32 v2, v208, v2, vcc
	v_lshl_add_u64 v[20:21], v[20:21], 0, v[162:163]
	v_cndmask_b32_e32 v9, v208, v9, vcc
	v_cndmask_b32_e32 v8, v208, v8, vcc
	v_cndmask_b32_e32 v7, v208, v7, vcc
	v_cndmask_b32_e32 v6, v208, v6, vcc
	global_store_dwordx4 v[20:21], v[2:5], off sc1
	global_store_dwordx4 v[20:21], v[6:9], off offset:16 sc1
	s_nop 0
	v_sub_f32_e32 v3, v127, v18
	v_sub_f32_e32 v2, v126, v18
	v_sub_f32_e32 v5, v129, v18
	v_sub_f32_e32 v4, v128, v18
	v_pk_mul_f32 v[4:5], v[18:19], v[4:5] op_sel:[1,0]
	v_pk_mul_f32 v[2:3], v[18:19], v[2:3] op_sel:[1,0]
	v_sub_f32_e32 v7, v123, v18
	v_sub_f32_e32 v6, v122, v18
	v_sub_f32_e32 v9, v125, v18
	v_sub_f32_e32 v8, v124, v18
	v_pk_fma_f32 v[2:3], v[138:139], v[2:3], v[142:143]
	v_pk_fma_f32 v[4:5], v[140:141], v[4:5], v[144:145]
	v_pk_mul_f32 v[8:9], v[18:19], v[8:9] op_sel:[1,0]
	v_pk_mul_f32 v[6:7], v[18:19], v[6:7] op_sel:[1,0]
	v_pk_fma_f32 v[8:9], v[132:133], v[8:9], v[136:137]
	v_pk_fma_f32 v[6:7], v[130:131], v[6:7], v[134:135]
	v_cndmask_b32_e32 v5, v208, v5, vcc
	v_cndmask_b32_e32 v4, v208, v4, vcc
	v_cndmask_b32_e32 v3, v208, v3, vcc
	v_cndmask_b32_e32 v2, v208, v2, vcc
	v_cndmask_b32_e32 v9, v208, v9, vcc
	v_cndmask_b32_e32 v8, v208, v8, vcc
	v_cndmask_b32_e32 v7, v208, v7, vcc
	v_cndmask_b32_e32 v6, v208, v6, vcc
	global_store_dwordx4 v[20:21], v[2:5], off offset:512 sc1
	global_store_dwordx4 v[20:21], v[6:9], off offset:528 sc1
	ds_read_b64 v[18:19], v167 offset:9344
	v_add_u32_e32 v20, 0x90, v164
	v_ashrrev_i32_e32 v21, 31, v20
	v_lshlrev_b64 v[20:21], 12, v[20:21]
	v_lshl_add_u64 v[20:21], s[0:1], 0, v[20:21]
	s_waitcnt lgkmcnt(0)
	v_sub_f32_e32 v3, v111, v18
	v_sub_f32_e32 v2, v110, v18
	v_sub_f32_e32 v5, v113, v18
	v_sub_f32_e32 v4, v112, v18
	v_pk_mul_f32 v[4:5], v[18:19], v[4:5] op_sel:[1,0]
	v_pk_mul_f32 v[2:3], v[18:19], v[2:3] op_sel:[1,0]
	v_sub_f32_e32 v7, v107, v18
	v_sub_f32_e32 v6, v106, v18
	v_sub_f32_e32 v9, v109, v18
	v_sub_f32_e32 v8, v108, v18
	v_pk_fma_f32 v[2:3], v[154:155], v[2:3], v[158:159]
	v_pk_fma_f32 v[4:5], v[156:157], v[4:5], v[160:161]
	v_pk_mul_f32 v[8:9], v[18:19], v[8:9] op_sel:[1,0]
	v_pk_mul_f32 v[6:7], v[18:19], v[6:7] op_sel:[1,0]
	v_pk_fma_f32 v[8:9], v[148:149], v[8:9], v[152:153]
	v_pk_fma_f32 v[6:7], v[146:147], v[6:7], v[150:151]
	v_cndmask_b32_e32 v5, v208, v5, vcc
	v_cndmask_b32_e32 v4, v208, v4, vcc
	v_cndmask_b32_e32 v3, v208, v3, vcc
	v_cndmask_b32_e32 v2, v208, v2, vcc
	v_lshl_add_u64 v[20:21], v[20:21], 0, v[162:163]
	v_cndmask_b32_e32 v9, v208, v9, vcc
	v_cndmask_b32_e32 v8, v208, v8, vcc
	v_cndmask_b32_e32 v7, v208, v7, vcc
	v_cndmask_b32_e32 v6, v208, v6, vcc
	global_store_dwordx4 v[20:21], v[2:5], off sc1
	global_store_dwordx4 v[20:21], v[6:9], off offset:16 sc1
	s_nop 0
	v_sub_f32_e32 v3, v87, v18
	v_sub_f32_e32 v2, v86, v18
	v_sub_f32_e32 v5, v89, v18
	v_sub_f32_e32 v4, v88, v18
	v_pk_mul_f32 v[4:5], v[18:19], v[4:5] op_sel:[1,0]
	v_pk_mul_f32 v[2:3], v[18:19], v[2:3] op_sel:[1,0]
	v_sub_f32_e32 v7, v83, v18
	v_sub_f32_e32 v6, v82, v18
	v_sub_f32_e32 v9, v85, v18
	v_sub_f32_e32 v8, v84, v18
	v_pk_fma_f32 v[2:3], v[138:139], v[2:3], v[142:143]
	v_pk_fma_f32 v[4:5], v[140:141], v[4:5], v[144:145]
	v_pk_mul_f32 v[8:9], v[18:19], v[8:9] op_sel:[1,0]
	v_pk_mul_f32 v[6:7], v[18:19], v[6:7] op_sel:[1,0]
	v_pk_fma_f32 v[8:9], v[132:133], v[8:9], v[136:137]
	v_pk_fma_f32 v[6:7], v[130:131], v[6:7], v[134:135]
	v_cndmask_b32_e32 v5, v208, v5, vcc
	v_cndmask_b32_e32 v4, v208, v4, vcc
	v_cndmask_b32_e32 v3, v208, v3, vcc
	v_cndmask_b32_e32 v2, v208, v2, vcc
	v_cndmask_b32_e32 v9, v208, v9, vcc
	v_cndmask_b32_e32 v8, v208, v8, vcc
	v_cndmask_b32_e32 v7, v208, v7, vcc
	v_cndmask_b32_e32 v6, v208, v6, vcc
	global_store_dwordx4 v[20:21], v[2:5], off offset:512 sc1
	global_store_dwordx4 v[20:21], v[6:9], off offset:528 sc1
	ds_read_b64 v[18:19], v167 offset:9472
	v_add_u32_e32 v20, 0xa0, v164
	v_ashrrev_i32_e32 v21, 31, v20
	v_lshlrev_b64 v[20:21], 12, v[20:21]
	v_lshl_add_u64 v[20:21], s[0:1], 0, v[20:21]
	s_waitcnt lgkmcnt(0)
	v_sub_f32_e32 v3, v71, v18
	v_sub_f32_e32 v2, v70, v18
	v_sub_f32_e32 v5, v73, v18
	v_sub_f32_e32 v4, v72, v18
	v_pk_mul_f32 v[4:5], v[18:19], v[4:5] op_sel:[1,0]
	v_pk_mul_f32 v[2:3], v[18:19], v[2:3] op_sel:[1,0]
	v_sub_f32_e32 v7, v67, v18
	v_sub_f32_e32 v6, v66, v18
	v_sub_f32_e32 v9, v69, v18
	v_sub_f32_e32 v8, v68, v18
	v_pk_fma_f32 v[2:3], v[154:155], v[2:3], v[158:159]
	v_pk_fma_f32 v[4:5], v[156:157], v[4:5], v[160:161]
	v_pk_mul_f32 v[8:9], v[18:19], v[8:9] op_sel:[1,0]
	v_pk_mul_f32 v[6:7], v[18:19], v[6:7] op_sel:[1,0]
	v_pk_fma_f32 v[8:9], v[148:149], v[8:9], v[152:153]
	v_pk_fma_f32 v[6:7], v[146:147], v[6:7], v[150:151]
	v_cndmask_b32_e32 v5, v208, v5, vcc
	v_cndmask_b32_e32 v4, v208, v4, vcc
	v_cndmask_b32_e32 v3, v208, v3, vcc
	v_cndmask_b32_e32 v2, v208, v2, vcc
	v_lshl_add_u64 v[20:21], v[20:21], 0, v[162:163]
	v_cndmask_b32_e32 v9, v208, v9, vcc
	v_cndmask_b32_e32 v8, v208, v8, vcc
	v_cndmask_b32_e32 v7, v208, v7, vcc
	v_cndmask_b32_e32 v6, v208, v6, vcc
	global_store_dwordx4 v[20:21], v[2:5], off sc1
	global_store_dwordx4 v[20:21], v[6:9], off offset:16 sc1
	s_nop 0
	v_sub_f32_e32 v3, v55, v18
	v_sub_f32_e32 v2, v54, v18
	v_sub_f32_e32 v5, v57, v18
	v_sub_f32_e32 v4, v56, v18
	v_pk_mul_f32 v[4:5], v[18:19], v[4:5] op_sel:[1,0]
	v_pk_mul_f32 v[2:3], v[18:19], v[2:3] op_sel:[1,0]
	v_sub_f32_e32 v7, v51, v18
	v_sub_f32_e32 v6, v50, v18
	v_sub_f32_e32 v9, v53, v18
	v_sub_f32_e32 v8, v52, v18
	v_pk_fma_f32 v[2:3], v[138:139], v[2:3], v[142:143]
	v_pk_fma_f32 v[4:5], v[140:141], v[4:5], v[144:145]
	v_pk_mul_f32 v[8:9], v[18:19], v[8:9] op_sel:[1,0]
	v_pk_mul_f32 v[6:7], v[18:19], v[6:7] op_sel:[1,0]
	v_pk_fma_f32 v[8:9], v[132:133], v[8:9], v[136:137]
	v_pk_fma_f32 v[6:7], v[130:131], v[6:7], v[134:135]
	v_cndmask_b32_e32 v5, v208, v5, vcc
	v_cndmask_b32_e32 v4, v208, v4, vcc
	v_cndmask_b32_e32 v3, v208, v3, vcc
	v_cndmask_b32_e32 v2, v208, v2, vcc
	v_cndmask_b32_e32 v9, v208, v9, vcc
	v_cndmask_b32_e32 v8, v208, v8, vcc
	v_cndmask_b32_e32 v7, v208, v7, vcc
	v_cndmask_b32_e32 v6, v208, v6, vcc
	global_store_dwordx4 v[20:21], v[2:5], off offset:512 sc1
	global_store_dwordx4 v[20:21], v[6:9], off offset:528 sc1
	ds_read_b64 v[18:19], v167 offset:9600
	v_add_u32_e32 v20, 0xb0, v164
	v_ashrrev_i32_e32 v21, 31, v20
	v_lshlrev_b64 v[20:21], 12, v[20:21]
	v_lshl_add_u64 v[20:21], s[0:1], 0, v[20:21]
	s_waitcnt lgkmcnt(0)
	v_sub_f32_e32 v3, v31, v18
	v_sub_f32_e32 v2, v30, v18
	v_sub_f32_e32 v5, v33, v18
	v_sub_f32_e32 v4, v32, v18
	v_pk_mul_f32 v[4:5], v[18:19], v[4:5] op_sel:[1,0]
	v_pk_mul_f32 v[2:3], v[18:19], v[2:3] op_sel:[1,0]
	v_sub_f32_e32 v7, v27, v18
	v_sub_f32_e32 v6, v26, v18
	v_sub_f32_e32 v9, v29, v18
	v_sub_f32_e32 v8, v28, v18
	v_pk_fma_f32 v[2:3], v[154:155], v[2:3], v[158:159]
	v_pk_fma_f32 v[4:5], v[156:157], v[4:5], v[160:161]
	v_pk_mul_f32 v[8:9], v[18:19], v[8:9] op_sel:[1,0]
	v_pk_mul_f32 v[6:7], v[18:19], v[6:7] op_sel:[1,0]
	v_pk_fma_f32 v[8:9], v[148:149], v[8:9], v[152:153]
	v_pk_fma_f32 v[6:7], v[146:147], v[6:7], v[150:151]
	v_cndmask_b32_e32 v5, v208, v5, vcc
	v_cndmask_b32_e32 v4, v208, v4, vcc
	v_cndmask_b32_e32 v3, v208, v3, vcc
	v_cndmask_b32_e32 v2, v208, v2, vcc
	v_lshl_add_u64 v[20:21], v[20:21], 0, v[162:163]
	v_cndmask_b32_e32 v9, v208, v9, vcc
	v_cndmask_b32_e32 v8, v208, v8, vcc
	v_cndmask_b32_e32 v7, v208, v7, vcc
	v_cndmask_b32_e32 v6, v208, v6, vcc
	global_store_dwordx4 v[20:21], v[2:5], off sc1
	global_store_dwordx4 v[20:21], v[6:9], off offset:16 sc1
	s_nop 0
	v_sub_f32_e32 v3, v15, v18
	v_sub_f32_e32 v2, v14, v18
	v_sub_f32_e32 v5, v17, v18
	v_sub_f32_e32 v4, v16, v18
	v_pk_mul_f32 v[4:5], v[18:19], v[4:5] op_sel:[1,0]
	v_pk_mul_f32 v[2:3], v[18:19], v[2:3] op_sel:[1,0]
	v_sub_f32_e32 v7, v11, v18
	v_sub_f32_e32 v6, v10, v18
	v_sub_f32_e32 v9, v13, v18
	v_sub_f32_e32 v8, v12, v18
	v_pk_fma_f32 v[2:3], v[138:139], v[2:3], v[142:143]
	v_pk_fma_f32 v[4:5], v[140:141], v[4:5], v[144:145]
	v_pk_mul_f32 v[8:9], v[18:19], v[8:9] op_sel:[1,0]
	v_pk_mul_f32 v[6:7], v[18:19], v[6:7] op_sel:[1,0]
	v_pk_fma_f32 v[8:9], v[132:133], v[8:9], v[136:137]
	v_pk_fma_f32 v[6:7], v[130:131], v[6:7], v[134:135]
	v_cndmask_b32_e32 v5, v208, v5, vcc
	v_cndmask_b32_e32 v4, v208, v4, vcc
	v_cndmask_b32_e32 v3, v208, v3, vcc
	v_cndmask_b32_e32 v2, v208, v2, vcc
	v_cndmask_b32_e32 v9, v208, v9, vcc
	v_cndmask_b32_e32 v8, v208, v8, vcc
	v_cndmask_b32_e32 v7, v208, v7, vcc
	v_cndmask_b32_e32 v6, v208, v6, vcc
	global_store_dwordx4 v[20:21], v[2:5], off offset:512 sc1
	global_store_dwordx4 v[20:21], v[6:9], off offset:528 sc1
